# v19+v22 on top of v13: SGU mixer rewritten by hand (LN params staged in LDS, conflict-free VT layout, pipelined LDS reads, prefetched loads); prologue weight transpose rewritten as WG-cooperative 128x
# speedup vs baseline: 1.0062x; 1.0062x over previous
; __device__ __forceinline__ void p0_prologue(const Frame& F, const Args& A) {
;     const int lane = lane_opaque();
;     LAS float* scr = (LAS float*)(F.lds + F.wave * 16384);
;     constexpr int I_IN = (D / 64) * (INC / 32), I_OUT = (D / 64) * (D / 32), I_GU = (D / 64) * (2 * FF / 32), I_D = (FF / 64) * (D / 32), I_PG = I_OUT, I_PP = (PLE / 64) * (D / 32);
;     constexpr int I_LAYER = I_IN + I_OUT + I_GU + I_D + I_PG + I_PP;
;     for (int it = F.gw; it < DEPTH * I_LAYER; it += F.NGW) {
;         const int l = DEPTH - 1 - it / I_LAYER; int r = I_LAYER - 1 - it % I_LAYER;
;         unsigned char* wl = (unsigned char*)(F.ws + WS_W + (size_t)l * W_LAYER);
;         if (r < I_IN) { const int nb = INC / 32, kb = r / nb, rg = r % nb, pn = rg >> 3, j = rg & 7;
;             const int src = pn < 4 ? 256 * pn + 32 * j : pn < 8 ? (j < 4 ? 1024 : 2048) + 128 * (pn - 4) + 32 * (j & 3) : pn < 10 ? 1536 + 256 * (pn - 8) + 32 * j
;                           : pn < 14 ? (j < 4 ? 2560 : 3072) + 128 * (pn - 10) + 32 * (j & 3) : 3584 + 256 * (pn - 14) + 32 * j;
;             p0_transpose_item(A.in[3] + (size_t)l * D * INC, INC, D, A.in[2] + l * D, (bf16*)(wl + WO_IN), 64 * kb, src, 32 * rg, scr, lane); continue; } r -= I_IN;
;         if (r < I_OUT) { const int nb = D / 32, kb = r / nb, rg = r % nb;
;             p0_transpose_item(A.in[15] + (size_t)l * D * D, D, D, nullptr, (bf16*)(wl + WO_OUT), 64 * kb, 32 * rg, 32 * rg, scr, lane); continue; } r -= I_OUT;
;         if (r < I_GU) { const int nb = 2 * FF / 32, kb = r / nb, rg = r % nb;
;             const int pn = rg >> 3, j = rg & 7; const float* src = (j < 4 ? A.in[17] : A.in[18]) + (size_t)l * D * FF;
;             p0_transpose_item(src, FF, D, A.in[16] + l * D, (bf16*)(wl + WO_GU), 64 * kb, 128 * pn + 32 * (j & 3), 32 * rg, scr, lane); continue; } r -= I_GU;
;         if (r < I_D) { const int nb = D / 32, kb = r / nb, rg = r % nb;
;             p0_transpose_item(A.in[19] + (size_t)l * FF * D, D, FF, nullptr, (bf16*)(wl + WO_D), 64 * kb, 32 * rg, 32 * rg, scr, lane); continue; } r -= I_D;
;         if (r < I_PG) { const int nb = D / 32, kb = r / nb, rg = r % nb;
;             p0_transpose_item(A.in[21] + (size_t)l * D * D, D, D, A.in[20] + l * D, (bf16*)(wl + WO_PG), 64 * kb, 32 * rg, 32 * rg, scr, lane); continue; } r -= I_PG;
;         { const int nb = D / 32, kb = r / nb, rg = r % nb;
.LBB0_14:
	v_writelane_b32 v253, s12, 26
	s_lshl_b32 s0, s2, 3
	s_lshl_b32 s84, s86, 3
	v_writelane_b32 v253, s13, 27
	v_writelane_b32 v253, s14, 28
	v_writelane_b32 v253, s15, 29
	v_writelane_b32 v253, s16, 30
	v_writelane_b32 v253, s17, 31
	v_writelane_b32 v253, s18, 32
	v_writelane_b32 v253, s19, 33
	v_writelane_b32 v253, s20, 34
	v_writelane_b32 v253, s21, 35
	v_writelane_b32 v253, s22, 36
	v_writelane_b32 v253, s23, 37
	v_writelane_b32 v253, s24, 38
	v_writelane_b32 v253, s25, 39
	v_writelane_b32 v253, s26, 40
	v_writelane_b32 v253, s27, 41
	s_nop 0
	v_readlane_b32 s1, v253, 0
	s_add_i32 s82, s1, s0
	v_readlane_b32 s4, v253, 3
	s_cmp_lt_i32 s4, 1
	v_readlane_b32 s5, v253, 4
	s_cselect_b64 s[8:9], -1, 0
	s_cmp_gt_i32 s4, 0
	s_cselect_b64 s[0:1], -1, 0
	s_cmp_lt_i32 s5, 1
	s_cselect_b64 s[4:5], -1, 0
	s_or_b64 s[0:1], s[0:1], s[4:5]
	s_and_b64 vcc, exec, s[0:1]
	s_cbranch_vccnz .LBB0_89
	s_mov_b32 s14, s82
	s_mov_b64 s[0:1], s[88:89]
	v_readlane_b32 s18, v253, 0
	s_mov_b64 s[12:13], s[90:91]
	v_mbcnt_lo_u32_b32 v32, -1, 0
	v_mbcnt_hi_u32_b32 v32, -1, v32
	v_mbcnt_lo_u32_b32 v1, -1, 0
	v_mbcnt_hi_u32_b32 v1, -1, v1
	v_lshlrev_b32_e32 v2, 4, v1
	v_and_b32_e32 v3, 31, v1
	v_lshlrev_b32_e32 v4, 10, v1
	v_add_u32_e32 v9, 0x10000, v4
	v_lshrrev_b32_e32 v6, 5, v1
	v_lshlrev_b32_e32 v5, 8, v6
	v_lshl_add_u32 v5, v3, 3, v5
	v_readlane_b32 s92, v253, 1
	v_readlane_b32 s93, v253, 2
	v_readlane_b32 s95, v253, 0
	s_nop 4
	s_sub_u32 s92, s92, 0xd8
	s_subb_u32 s93, s93, 0
	s_mov_b32 s94, s2
	s_mov_b32 s96, 0
	s_lshl_b32 s0, s95, 13
	v_add_u32_e32 v5, s0, v5
	v_add_u32_e32 v12, 0x10000, v5
	s_cmp_ge_u32 s94, 6336
	s_cbranch_scc1 .Lp0_done
	s_mov_b32 s97, s94
	s_mov_b32 s3, s97
	s_mov_b32 s4, 3
	s_sub_u32 vcc_lo, s3, 1584
	s_cmp_ge_u32 s3, 1584
	s_cselect_b32 s3, vcc_lo, s3
	s_cselect_b32 vcc_lo, 1, 0
	s_sub_u32 s4, s4, vcc_lo
	s_sub_u32 vcc_lo, s3, 1584
	s_cmp_ge_u32 s3, 1584
	s_cselect_b32 s3, vcc_lo, s3
	s_cselect_b32 vcc_lo, 1, 0
	s_sub_u32 s4, s4, vcc_lo
	s_sub_u32 vcc_lo, s3, 1584
	s_cmp_ge_u32 s3, 1584
	s_cselect_b32 s3, vcc_lo, s3
	s_cselect_b32 vcc_lo, 1, 0
	s_sub_u32 s4, s4, vcc_lo
	s_sub_u32 s3, 1583, s3
	s_cmp_lt_u32 s3, 256
	s_cbranch_scc1 .Lp0_in_0_0
	s_cmp_lt_u32 s3, 384
	s_cbranch_scc1 .Lp0_out_0_0
	s_cmp_lt_u32 s3, 1088
	s_cbranch_scc1 .Lp0_gu_0_0
	s_cmp_lt_u32 s3, 1440
	s_cbranch_scc1 .Lp0_d_0_0
	s_cmp_lt_u32 s3, 1568
	s_cbranch_scc1 .Lp0_pg_0_0
	s_sub_u32 s3, s3, 1568
	s_lshr_b32 s5, s3, 3
	s_and_b32 s15, s3, 7
	s_movk_i32 s34, 176
	s_mov_b32 s35, 0
	s_movk_i32 s85, 2048
	s_movk_i32 s87, 256
	s_mov_b32 s0, 102760448
	s_mov_b32 s1, 2097152
	s_lshl_b32 s71, s15, 1
	s_add_u32 s72, s71, 1
	s_branch .Lp0_dec_0_0
.Lp0_in_0_0:
	s_lshr_b32 s5, s3, 4
	s_and_b32 s15, s3, 15
	s_movk_i32 s34, 24
	s_movk_i32 s35, 16
	s_movk_i32 s85, 4096
	s_movk_i32 s87, 2048
	s_mov_b32 s0, 0
	s_mov_b32 s1, 33554432
	s_lshl_b32 s71, s15, 1
	s_add_u32 s72, s71, 1
	s_lshl_b32 s97, s15, 1
	s_mov_b32 s71, s97
	s_lshl_b32 vcc_lo, s97, 1
	s_sub_u32 vcc_hi, vcc_lo, 8
	s_cmp_ge_u32 s97, 8
	s_cselect_b32 s71, vcc_hi, s71
	s_add_u32 vcc_hi, s97, 4
	s_cmp_ge_u32 s97, 12
	s_cselect_b32 s71, vcc_hi, s71
	s_sub_u32 vcc_hi, vcc_lo, 23
	s_cmp_ge_u32 s97, 16
	s_cselect_b32 s71, vcc_hi, s71
	s_sub_u32 vcc_hi, vcc_lo, 20
	s_cmp_ge_u32 s97, 20
	s_cselect_b32 s71, vcc_hi, s71
	s_sub_u32 vcc_hi, vcc_lo, 27
	s_cmp_ge_u32 s97, 24
	s_cselect_b32 s71, vcc_hi, s71
	s_add_u32 vcc_hi, s97, 0
	s_cmp_ge_u32 s97, 28
	s_cselect_b32 s71, vcc_hi, s71
	s_lshl_b32 s97, s15, 1
	s_add_u32 s97, s97, 1
	s_mov_b32 s72, s97
	s_lshl_b32 vcc_lo, s97, 1
	s_sub_u32 vcc_hi, vcc_lo, 8
	s_cmp_ge_u32 s97, 8
	s_cselect_b32 s72, vcc_hi, s72
	s_add_u32 vcc_hi, s97, 4
	s_cmp_ge_u32 s97, 12
	s_cselect_b32 s72, vcc_hi, s72
	s_sub_u32 vcc_hi, vcc_lo, 23
	s_cmp_ge_u32 s97, 16
	s_cselect_b32 s72, vcc_hi, s72
	s_sub_u32 vcc_hi, vcc_lo, 20
	s_cmp_ge_u32 s97, 20
	s_cselect_b32 s72, vcc_hi, s72
	s_sub_u32 vcc_hi, vcc_lo, 27
	s_cmp_ge_u32 s97, 24
	s_cselect_b32 s72, vcc_hi, s72
	s_add_u32 vcc_hi, s97, 0
	s_cmp_ge_u32 s97, 28
	s_cselect_b32 s72, vcc_hi, s72
	s_branch .Lp0_dec_0_0
.Lp0_out_0_0:
	s_sub_u32 s3, s3, 256
	s_lshr_b32 s5, s3, 3
	s_and_b32 s15, s3, 7
	s_movk_i32 s34, 120
	s_mov_b32 s35, 0
	s_movk_i32 s85, 2048
	s_movk_i32 s87, 2048
	s_mov_b32 s0, 16777216
	s_mov_b32 s1, 16777216
	s_lshl_b32 s71, s15, 1
	s_add_u32 s72, s71, 1
	s_branch .Lp0_dec_0_0
.Lp0_gu_0_0:
	s_sub_u32 s3, s3, 384
	s_mul_i32 s5, s3, 1490
	s_lshr_b32 s5, s5, 16
	s_mul_i32 s97, s5, 44
	s_sub_u32 s15, s3, s97
	s_movk_i32 s35, 0x80
	s_movk_i32 s85, 0x1600
	s_movk_i32 s87, 0x800
	s_mov_b32 s0, 25165824
	s_mov_b32 s1, 46137344
	s_sub_u32 s97, s15, 22
	s_cmp_ge_u32 s15, 22
	s_cselect_b32 s15, s97, s15
	s_cselect_b32 s97, 1, 0
	s_lshl_b32 s34, s97, 3
	s_add_u32 s34, s34, 0x88
	s_lshl_b32 s71, s15, 2
	s_add_u32 s71, s71, s97
	s_add_u32 s72, s71, 2
	s_branch .Lp0_dec_0_0
.Lp0_d_0_0:
	s_sub_u32 s3, s3, 1088
	s_lshr_b32 s5, s3, 3
	s_and_b32 s15, s3, 7
	s_movk_i32 s34, 152
	s_mov_b32 s35, 0
	s_movk_i32 s85, 2048
	s_movk_i32 s87, 5632
	s_mov_b32 s0, 71303168
	s_mov_b32 s1, 46137344
	s_lshl_b32 s71, s15, 1
	s_add_u32 s72, s71, 1
	s_branch .Lp0_dec_0_0
.Lp0_pg_0_0:
	s_sub_u32 s3, s3, 1440
	s_lshr_b32 s5, s3, 3
	s_and_b32 s15, s3, 7
	s_movk_i32 s34, 168
	s_movk_i32 s35, 160
	s_movk_i32 s85, 2048
	s_movk_i32 s87, 2048
	s_mov_b32 s0, 94371840
	s_mov_b32 s1, 16777216
	s_lshl_b32 s71, s15, 1
	s_add_u32 s72, s71, 1
.Lp0_dec_0_0:
	s_load_dwordx2 s[36:37], s[92:93], s34
	s_cmp_eq_u32 s35, 0
	s_cbranch_scc1 .Lp0_ng_0_0
	s_load_dwordx2 s[38:39], s[92:93], s35
; __device__ __forceinline__ void p0_transpose_item(const float* W, int ldw, int K, const float* gain, bf16* WT, int k0, int n0, int drow0, LAS float* scr, int lane) {
;     float wv[32];
; #pragma unroll
; __device__ __forceinline__ void p0_prologue(const Frame& F, const Args& A) {
;     ...
;     for (int it = F.gw; it < DEPTH * I_LAYER; it += F.NGW) {
;         const int l = DEPTH - 1 - it / I_LAYER; int r = I_LAYER - 1 - it % I_LAYER;
;         unsigned char* wl = (unsigned char*)(F.ws + WS_W + (size_t)l * W_LAYER);
;         if (r < I_IN) { const int nb = INC / 32, kb = r / nb, rg = r % nb, pn = rg >> 3, j = rg & 7;
;             const int src = pn < 4 ? 256 * pn + 32 * j : pn < 8 ? (j < 4 ? 1024 : 2048) + 128 * (pn - 4) + 32 * (j & 3) : pn < 10 ? 1536 + 256 * (pn - 8) + 32 * j
;                           : pn < 14 ? (j < 4 ? 2560 : 3072) + 128 * (pn - 10) + 32 * (j & 3) : 3584 + 256 * (pn - 14) + 32 * j;
;             p0_transpose_item(A.in[3] + (size_t)l * D * INC, INC, D, A.in[2] + l * D, (bf16*)(wl + WO_IN), 64 * kb, src, 32 * rg, scr, lane); continue; } r -= I_IN;
;         if (r < I_OUT) { const int nb = D / 32, kb = r / nb, rg = r % nb;
;             p0_transpose_item(A.in[15] + (size_t)l * D * D, D, D, nullptr, (bf16*)(wl + WO_OUT), 64 * kb, 32 * rg, 32 * rg, scr, lane); continue; } r -= I_OUT;
;         if (r < I_GU) { const int nb = 2 * FF / 32, kb = r / nb, rg = r % nb;
;             const int pn = rg >> 3, j = rg & 7; const float* src = (j < 4 ? A.in[17] : A.in[18]) + (size_t)l * D * FF;
;             p0_transpose_item(src, FF, D, A.in[16] + l * D, (bf16*)(wl + WO_GU), 64 * kb, 128 * pn + 32 * (j & 3), 32 * rg, scr, lane); continue; } r -= I_GU;
;         if (r < I_D) { const int nb = D / 32, kb = r / nb, rg = r % nb;
;             p0_transpose_item(A.in[19] + (size_t)l * FF * D, D, FF, nullptr, (bf16*)(wl + WO_D), 64 * kb, 32 * rg, 32 * rg, scr, lane); continue; } r -= I_D;
;         if (r < I_PG) { const int nb = D / 32, kb = r / nb, rg = r % nb;
;             p0_transpose_item(A.in[21] + (size_t)l * D * D, D, D, A.in[20] + l * D, (bf16*)(wl + WO_PG), 64 * kb, 32 * rg, 32 * rg, scr, lane); continue; } r -= I_PG;
;         { const int nb = D / 32, kb = r / nb, rg = r % nb;
;             p0_transpose_item(A.in[22] + (size_t)l * PLE * D, D, PLE, nullptr, (bf16*)(wl + WO_PP), 64 * kb, 32 * rg, 32 * rg, scr, lane); }
;     }
.Lp0_ng_0_0:
	s_mul_i32 s97, s4, 103809024
	s_add_u32 s97, s97, s0
	s_add_u32 s97, s97, 16777216
	s_lshl_b32 vcc_lo, s5, 8
	s_add_u32 s97, s97, vcc_lo
	s_add_u32 s68, s90, s97
	s_addc_u32 s69, s91, 0
	s_lshl_b32 s70, s87, 1
	s_lshl_b32 vcc_lo, s5, 7
	s_lshl_b32 vcc_hi, s95, 4
	s_add_u32 vcc_lo, vcc_lo, vcc_hi
	s_mul_i32 s0, vcc_lo, s85
	s_lshl_b32 s15, s15, 8
	s_add_u32 s0, s0, s15
	s_lshl_b32 s0, s0, 2
	s_mul_i32 s1, s1, s4
	s_add_u32 s0, s0, s1
	s_lshl_b32 s85, s85, 2
	s_lshl_b32 vcc_lo, vcc_lo, 2
	s_lshl_b32 s97, s4, 13
	s_add_u32 s97, s97, vcc_lo
	s_waitcnt lgkmcnt(0)
	s_add_u32 s0, s36, s0
	s_addc_u32 s1, s37, 0
	s_cmp_eq_u32 s35, 0
	s_cbranch_scc1 .Lp0_g1_0_0
	s_add_u32 vcc_lo, s38, s97
	s_addc_u32 vcc_hi, s39, 0
	s_load_dwordx16 s[36:51], vcc, 0x0
	s_branch .Lp0_g2_0_0
.Lp0_g1_0_0:
	s_mov_b32 s36, 1.0
	s_mov_b32 s37, 1.0
	s_mov_b32 s38, 1.0
	s_mov_b32 s39, 1.0
	s_mov_b32 s40, 1.0
	s_mov_b32 s41, 1.0
	s_mov_b32 s42, 1.0
	s_mov_b32 s43, 1.0
	s_mov_b32 s44, 1.0
	s_mov_b32 s45, 1.0
	s_mov_b32 s46, 1.0
	s_mov_b32 s47, 1.0
	s_mov_b32 s48, 1.0
	s_mov_b32 s49, 1.0
	s_mov_b32 s50, 1.0
	s_mov_b32 s51, 1.0
.Lp0_g2_0_0:
	global_load_dwordx4 v[40:43], v2, s[0:1] nt
	s_add_u32 s0, s0, s85
	s_addc_u32 s1, s1, 0
	global_load_dwordx4 v[44:47], v2, s[0:1] nt
	s_add_u32 s0, s0, s85
	s_addc_u32 s1, s1, 0
	global_load_dwordx4 v[48:51], v2, s[0:1] nt
	s_add_u32 s0, s0, s85
	s_addc_u32 s1, s1, 0
	global_load_dwordx4 v[52:55], v2, s[0:1] nt
	s_add_u32 s0, s0, s85
	s_addc_u32 s1, s1, 0
	global_load_dwordx4 v[56:59], v2, s[0:1] nt
	s_add_u32 s0, s0, s85
	s_addc_u32 s1, s1, 0
	global_load_dwordx4 v[60:63], v2, s[0:1] nt
	s_add_u32 s0, s0, s85
	s_addc_u32 s1, s1, 0
	global_load_dwordx4 v[64:67], v2, s[0:1] nt
	s_add_u32 s0, s0, s85
	s_addc_u32 s1, s1, 0
	global_load_dwordx4 v[68:71], v2, s[0:1] nt
	s_add_u32 s0, s0, s85
	s_addc_u32 s1, s1, 0
	global_load_dwordx4 v[72:75], v2, s[0:1] nt
	s_add_u32 s0, s0, s85
	s_addc_u32 s1, s1, 0
	global_load_dwordx4 v[76:79], v2, s[0:1] nt
	s_add_u32 s0, s0, s85
	s_addc_u32 s1, s1, 0
	global_load_dwordx4 v[80:83], v2, s[0:1] nt
	s_add_u32 s0, s0, s85
	s_addc_u32 s1, s1, 0
	global_load_dwordx4 v[84:87], v2, s[0:1] nt
	s_add_u32 s0, s0, s85
	s_addc_u32 s1, s1, 0
	global_load_dwordx4 v[88:91], v2, s[0:1] nt
	s_add_u32 s0, s0, s85
	s_addc_u32 s1, s1, 0
	global_load_dwordx4 v[92:95], v2, s[0:1] nt
	s_add_u32 s0, s0, s85
	s_addc_u32 s1, s1, 0
	global_load_dwordx4 v[96:99], v2, s[0:1] nt
	s_add_u32 s0, s0, s85
	s_addc_u32 s1, s1, 0
	global_load_dwordx4 v[100:103], v2, s[0:1] nt
	s_add_u32 s97, s94, s86
	s_cmp_ge_u32 s97, 6336
	s_cbranch_scc1 .Lp0_body0
	s_mov_b32 s3, s97
	s_mov_b32 s4, 3
	s_sub_u32 vcc_lo, s3, 1584
	s_cmp_ge_u32 s3, 1584
	s_cselect_b32 s3, vcc_lo, s3
	s_cselect_b32 vcc_lo, 1, 0
	s_sub_u32 s4, s4, vcc_lo
	s_sub_u32 vcc_lo, s3, 1584
	s_cmp_ge_u32 s3, 1584
	s_cselect_b32 s3, vcc_lo, s3
	s_cselect_b32 vcc_lo, 1, 0
	s_sub_u32 s4, s4, vcc_lo
	s_sub_u32 vcc_lo, s3, 1584
	s_cmp_ge_u32 s3, 1584
	s_cselect_b32 s3, vcc_lo, s3
	s_cselect_b32 vcc_lo, 1, 0
	s_sub_u32 s4, s4, vcc_lo
	s_sub_u32 s3, 1583, s3
	s_cmp_lt_u32 s3, 256
	s_cbranch_scc1 .Lp0_in_1_1
	s_cmp_lt_u32 s3, 384
	s_cbranch_scc1 .Lp0_out_1_1
	s_cmp_lt_u32 s3, 1088
	s_cbranch_scc1 .Lp0_gu_1_1
	s_cmp_lt_u32 s3, 1440
	s_cbranch_scc1 .Lp0_d_1_1
	s_cmp_lt_u32 s3, 1568
	s_cbranch_scc1 .Lp0_pg_1_1
	s_sub_u32 s3, s3, 1568
	s_lshr_b32 s5, s3, 3
	s_and_b32 s15, s3, 7
	s_movk_i32 s34, 176
	s_mov_b32 s35, 0
	s_movk_i32 s85, 2048
	s_movk_i32 s87, 256
	s_mov_b32 s0, 102760448
	s_mov_b32 s1, 2097152
	s_lshl_b32 s76, s15, 1
	s_add_u32 s77, s76, 1
	s_branch .Lp0_dec_1_1
.Lp0_in_1_1:
	s_lshr_b32 s5, s3, 4
	s_and_b32 s15, s3, 15
	s_movk_i32 s34, 24
	s_movk_i32 s35, 16
	s_movk_i32 s85, 4096
	s_movk_i32 s87, 2048
	s_mov_b32 s0, 0
	s_mov_b32 s1, 33554432
	s_lshl_b32 s76, s15, 1
	s_add_u32 s77, s76, 1
	s_lshl_b32 s97, s15, 1
	s_mov_b32 s76, s97
	s_lshl_b32 vcc_lo, s97, 1
	s_sub_u32 vcc_hi, vcc_lo, 8
	s_cmp_ge_u32 s97, 8
	s_cselect_b32 s76, vcc_hi, s76
	s_add_u32 vcc_hi, s97, 4
	s_cmp_ge_u32 s97, 12
	s_cselect_b32 s76, vcc_hi, s76
	s_sub_u32 vcc_hi, vcc_lo, 23
	s_cmp_ge_u32 s97, 16
	s_cselect_b32 s76, vcc_hi, s76
	s_sub_u32 vcc_hi, vcc_lo, 20
	s_cmp_ge_u32 s97, 20
	s_cselect_b32 s76, vcc_hi, s76
	s_sub_u32 vcc_hi, vcc_lo, 27
	s_cmp_ge_u32 s97, 24
	s_cselect_b32 s76, vcc_hi, s76
	s_add_u32 vcc_hi, s97, 0
	s_cmp_ge_u32 s97, 28
	s_cselect_b32 s76, vcc_hi, s76
	s_lshl_b32 s97, s15, 1
	s_add_u32 s97, s97, 1
	s_mov_b32 s77, s97
	s_lshl_b32 vcc_lo, s97, 1
	s_sub_u32 vcc_hi, vcc_lo, 8
	s_cmp_ge_u32 s97, 8
	s_cselect_b32 s77, vcc_hi, s77
	s_add_u32 vcc_hi, s97, 4
	s_cmp_ge_u32 s97, 12
	s_cselect_b32 s77, vcc_hi, s77
	s_sub_u32 vcc_hi, vcc_lo, 23
	s_cmp_ge_u32 s97, 16
	s_cselect_b32 s77, vcc_hi, s77
	s_sub_u32 vcc_hi, vcc_lo, 20
	s_cmp_ge_u32 s97, 20
	s_cselect_b32 s77, vcc_hi, s77
	s_sub_u32 vcc_hi, vcc_lo, 27
	s_cmp_ge_u32 s97, 24
	s_cselect_b32 s77, vcc_hi, s77
	s_add_u32 vcc_hi, s97, 0
	s_cmp_ge_u32 s97, 28
	s_cselect_b32 s77, vcc_hi, s77
	s_branch .Lp0_dec_1_1
.Lp0_out_1_1:
	s_sub_u32 s3, s3, 256
	s_lshr_b32 s5, s3, 3
	s_and_b32 s15, s3, 7
	s_movk_i32 s34, 120
	s_mov_b32 s35, 0
	s_movk_i32 s85, 2048
	s_movk_i32 s87, 2048
	s_mov_b32 s0, 16777216
	s_mov_b32 s1, 16777216
	s_lshl_b32 s76, s15, 1
	s_add_u32 s77, s76, 1
	s_branch .Lp0_dec_1_1
.Lp0_gu_1_1:
	s_sub_u32 s3, s3, 384
	s_mul_i32 s5, s3, 1490
	s_lshr_b32 s5, s5, 16
	s_mul_i32 s97, s5, 44
	s_sub_u32 s15, s3, s97
	s_movk_i32 s35, 0x80
	s_movk_i32 s85, 0x1600
	s_movk_i32 s87, 0x800
	s_mov_b32 s0, 25165824
	s_mov_b32 s1, 46137344
	s_sub_u32 s97, s15, 22
	s_cmp_ge_u32 s15, 22
	s_cselect_b32 s15, s97, s15
	s_cselect_b32 s97, 1, 0
	s_lshl_b32 s34, s97, 3
	s_add_u32 s34, s34, 0x88
	s_lshl_b32 s76, s15, 2
	s_add_u32 s76, s76, s97
	s_add_u32 s77, s76, 2
	s_branch .Lp0_dec_1_1
; __device__ __forceinline__ void p0_transpose_item(const float* W, int ldw, int K, const float* gain, bf16* WT, int k0, int n0, int drow0, LAS float* scr, int lane) {
;     float wv[32];
; #pragma unroll
; __device__ __forceinline__ void p0_prologue(const Frame& F, const Args& A) {
;     ...
;     for (int it = F.gw; it < DEPTH * I_LAYER; it += F.NGW) {
;         const int l = DEPTH - 1 - it / I_LAYER; int r = I_LAYER - 1 - it % I_LAYER;
;         unsigned char* wl = (unsigned char*)(F.ws + WS_W + (size_t)l * W_LAYER);
;         if (r < I_IN) { const int nb = INC / 32, kb = r / nb, rg = r % nb, pn = rg >> 3, j = rg & 7;
;             const int src = pn < 4 ? 256 * pn + 32 * j : pn < 8 ? (j < 4 ? 1024 : 2048) + 128 * (pn - 4) + 32 * (j & 3) : pn < 10 ? 1536 + 256 * (pn - 8) + 32 * j
;                           : pn < 14 ? (j < 4 ? 2560 : 3072) + 128 * (pn - 10) + 32 * (j & 3) : 3584 + 256 * (pn - 14) + 32 * j;
;             p0_transpose_item(A.in[3] + (size_t)l * D * INC, INC, D, A.in[2] + l * D, (bf16*)(wl + WO_IN), 64 * kb, src, 32 * rg, scr, lane); continue; } r -= I_IN;
;         if (r < I_OUT) { const int nb = D / 32, kb = r / nb, rg = r % nb;
;             p0_transpose_item(A.in[15] + (size_t)l * D * D, D, D, nullptr, (bf16*)(wl + WO_OUT), 64 * kb, 32 * rg, 32 * rg, scr, lane); continue; } r -= I_OUT;
;         if (r < I_GU) { const int nb = 2 * FF / 32, kb = r / nb, rg = r % nb;
;             const int pn = rg >> 3, j = rg & 7; const float* src = (j < 4 ? A.in[17] : A.in[18]) + (size_t)l * D * FF;
;             p0_transpose_item(src, FF, D, A.in[16] + l * D, (bf16*)(wl + WO_GU), 64 * kb, 128 * pn + 32 * (j & 3), 32 * rg, scr, lane); continue; } r -= I_GU;
;         if (r < I_D) { const int nb = D / 32, kb = r / nb, rg = r % nb;
;             p0_transpose_item(A.in[19] + (size_t)l * FF * D, D, FF, nullptr, (bf16*)(wl + WO_D), 64 * kb, 32 * rg, 32 * rg, scr, lane); continue; } r -= I_D;
;         if (r < I_PG) { const int nb = D / 32, kb = r / nb, rg = r % nb;
;             p0_transpose_item(A.in[21] + (size_t)l * D * D, D, D, A.in[20] + l * D, (bf16*)(wl + WO_PG), 64 * kb, 32 * rg, 32 * rg, scr, lane); continue; } r -= I_PG;
;         { const int nb = D / 32, kb = r / nb, rg = r % nb;
;             p0_transpose_item(A.in[22] + (size_t)l * PLE * D, D, PLE, nullptr, (bf16*)(wl + WO_PP), 64 * kb, 32 * rg, 32 * rg, scr, lane); }
;     }
.Lp0_d_1_1:
	s_sub_u32 s3, s3, 1088
	s_lshr_b32 s5, s3, 3
	s_and_b32 s15, s3, 7
	s_movk_i32 s34, 152
	s_mov_b32 s35, 0
	s_movk_i32 s85, 2048
	s_movk_i32 s87, 5632
	s_mov_b32 s0, 71303168
	s_mov_b32 s1, 46137344
	s_lshl_b32 s76, s15, 1
	s_add_u32 s77, s76, 1
	s_branch .Lp0_dec_1_1
.Lp0_pg_1_1:
	s_sub_u32 s3, s3, 1440
	s_lshr_b32 s5, s3, 3
	s_and_b32 s15, s3, 7
	s_movk_i32 s34, 168
	s_movk_i32 s35, 160
	s_movk_i32 s85, 2048
	s_movk_i32 s87, 2048
	s_mov_b32 s0, 94371840
	s_mov_b32 s1, 16777216
	s_lshl_b32 s76, s15, 1
	s_add_u32 s77, s76, 1
.Lp0_dec_1_1:
	s_load_dwordx2 s[16:17], s[92:93], s34
	s_cmp_eq_u32 s35, 0
	s_cbranch_scc1 .Lp0_ng_1_1
	s_load_dwordx2 s[18:19], s[92:93], s35
.Lp0_ng_1_1:
	s_mul_i32 s97, s4, 103809024
	s_add_u32 s97, s97, s0
	s_add_u32 s97, s97, 16777216
	s_lshl_b32 vcc_lo, s5, 8
	s_add_u32 s97, s97, vcc_lo
	s_add_u32 s73, s90, s97
	s_addc_u32 s74, s91, 0
	s_lshl_b32 s75, s87, 1
	s_lshl_b32 vcc_lo, s5, 7
	s_lshl_b32 vcc_hi, s95, 4
	s_add_u32 vcc_lo, vcc_lo, vcc_hi
	s_mul_i32 s0, vcc_lo, s85
	s_lshl_b32 s15, s15, 8
	s_add_u32 s0, s0, s15
	s_lshl_b32 s0, s0, 2
	s_mul_i32 s1, s1, s4
	s_add_u32 s0, s0, s1
	s_lshl_b32 s85, s85, 2
	s_lshl_b32 vcc_lo, vcc_lo, 2
	s_lshl_b32 s97, s4, 13
	s_add_u32 s97, s97, vcc_lo
	s_waitcnt lgkmcnt(0)
	s_add_u32 s0, s16, s0
	s_addc_u32 s1, s17, 0
	s_cmp_eq_u32 s35, 0
	s_cbranch_scc1 .Lp0_g1_1_1
	s_add_u32 vcc_lo, s18, s97
	s_addc_u32 vcc_hi, s19, 0
	s_load_dwordx16 s[16:31], vcc, 0x0
	s_branch .Lp0_g2_1_1
.Lp0_g1_1_1:
	s_mov_b32 s16, 1.0
	s_mov_b32 s17, 1.0
	s_mov_b32 s18, 1.0
	s_mov_b32 s19, 1.0
	s_mov_b32 s20, 1.0
	s_mov_b32 s21, 1.0
	s_mov_b32 s22, 1.0
	s_mov_b32 s23, 1.0
	s_mov_b32 s24, 1.0
	s_mov_b32 s25, 1.0
	s_mov_b32 s26, 1.0
	s_mov_b32 s27, 1.0
	s_mov_b32 s28, 1.0
	s_mov_b32 s29, 1.0
	s_mov_b32 s30, 1.0
	s_mov_b32 s31, 1.0
.Lp0_g2_1_1:
	global_load_dwordx4 v[104:107], v2, s[0:1] nt
	s_add_u32 s0, s0, s85
	s_addc_u32 s1, s1, 0
	global_load_dwordx4 v[108:111], v2, s[0:1] nt
	s_add_u32 s0, s0, s85
	s_addc_u32 s1, s1, 0
	global_load_dwordx4 v[112:115], v2, s[0:1] nt
	s_add_u32 s0, s0, s85
	s_addc_u32 s1, s1, 0
	global_load_dwordx4 v[116:119], v2, s[0:1] nt
	s_add_u32 s0, s0, s85
	s_addc_u32 s1, s1, 0
	global_load_dwordx4 v[120:123], v2, s[0:1] nt
	s_add_u32 s0, s0, s85
	s_addc_u32 s1, s1, 0
	global_load_dwordx4 v[124:127], v2, s[0:1] nt
	s_add_u32 s0, s0, s85
	s_addc_u32 s1, s1, 0
	global_load_dwordx4 v[128:131], v2, s[0:1] nt
	s_add_u32 s0, s0, s85
	s_addc_u32 s1, s1, 0
	global_load_dwordx4 v[132:135], v2, s[0:1] nt
	s_add_u32 s0, s0, s85
	s_addc_u32 s1, s1, 0
	global_load_dwordx4 v[136:139], v2, s[0:1] nt
	s_add_u32 s0, s0, s85
	s_addc_u32 s1, s1, 0
	global_load_dwordx4 v[140:143], v2, s[0:1] nt
	s_add_u32 s0, s0, s85
	s_addc_u32 s1, s1, 0
	global_load_dwordx4 v[144:147], v2, s[0:1] nt
	s_add_u32 s0, s0, s85
	s_addc_u32 s1, s1, 0
	global_load_dwordx4 v[148:151], v2, s[0:1] nt
	s_add_u32 s0, s0, s85
	s_addc_u32 s1, s1, 0
	global_load_dwordx4 v[152:155], v2, s[0:1] nt
	s_add_u32 s0, s0, s85
	s_addc_u32 s1, s1, 0
	global_load_dwordx4 v[156:159], v2, s[0:1] nt
	s_add_u32 s0, s0, s85
	s_addc_u32 s1, s1, 0
	global_load_dwordx4 v[160:163], v2, s[0:1] nt
	s_add_u32 s0, s0, s85
	s_addc_u32 s1, s1, 0
	global_load_dwordx4 v[164:167], v2, s[0:1] nt
.Lp0_body0:
	s_min_u32 vcc_lo, s96, 2
	s_lshl_b32 vcc_lo, vcc_lo, 4
	s_add_u32 vcc_hi, s94, s86
	s_cmp_lt_u32 vcc_hi, 6336
	s_cselect_b32 vcc_hi, 16, 0
	s_add_u32 vcc_lo, vcc_lo, vcc_hi
	s_cmp_eq_u32 vcc_lo, 48
	s_cbranch_scc1 .Lp0_w48_0
	s_cmp_eq_u32 vcc_lo, 32
	s_cbranch_scc1 .Lp0_w32_0
	s_cmp_eq_u32 vcc_lo, 16
	s_cbranch_scc1 .Lp0_w16_0
	s_waitcnt vmcnt(0)
	s_branch .Lp0_wd_0
.Lp0_w16_0:
	s_waitcnt vmcnt(16)
	s_branch .Lp0_wd_0
.Lp0_w32_0:
	s_waitcnt vmcnt(32)
	s_branch .Lp0_wd_0
.Lp0_w48_0:
	s_waitcnt vmcnt(48)
; __device__ __forceinline__ unsigned cvt_pk_bf16(float lo, float hi) { return __builtin_bit_cast(unsigned, __builtin_convertvector((f32x2_t){lo, hi}, bf16x2_t)); }
; #define GAS __attribute__((address_space(1)))
; #define LAS __attribute__((address_space(3)))
; __device__ __forceinline__ void p0_transpose_item(const float* W, int ldw, int K, const float* gain, bf16* WT, int k0, int n0, int drow0, LAS float* scr, int lane) {
;     ...
;     for (int i = 0; i < 32; ++i) { const int kk = 2 * i + (lane >> 5); scr[kk * 33 + (lane & 31)] = wv[i] * __shfl(gk, kk); }
;     ...
;     for (int j = 0; j < 4; ++j) { const int n = (lane >> 3) + 8 * j; const LAS float* s = scr + (8 * c) * 33 + n;
;         v4u o; o.x = cvt_pk_bf16(s[0 * 33], s[1 * 33]); o.y = cvt_pk_bf16(s[2 * 33], s[3 * 33]); o.z = cvt_pk_bf16(s[4 * 33], s[5 * 33]); o.w = cvt_pk_bf16(s[6 * 33], s[7 * 33]);
;         *(GAS v4u*)(WT + (size_t)(drow0 + n) * K + k0 + 8 * c) = o; }
.Lp0_wd_0:
	s_waitcnt lgkmcnt(0)
	s_mov_b32 s78, s68
	s_mov_b32 s79, s69
	s_mov_b32 s80, s70
	s_mov_b32 s81, s71
	s_mov_b32 s83, s72
	s_lshl_b32 s97, s95, 2
	s_add_u32 vcc_lo, s97, 0
	v_xor_b32_e32 v8, vcc_lo, v3
	v_lshl_add_u32 v10, v8, 3, v4
	v_mul_f32_e32 v40, s36, v40
	v_mul_f32_e32 v44, s37, v44
	v_mul_f32_e32 v48, s38, v48
	v_mul_f32_e32 v52, s39, v52
	v_cvt_pk_bf16_f32 v16, v40, v44
	v_cvt_pk_bf16_f32 v17, v48, v52
	ds_write_b64 v10, v[16:17]
	v_mul_f32_e32 v41, s36, v41
	v_mul_f32_e32 v45, s37, v45
	v_mul_f32_e32 v49, s38, v49
	v_mul_f32_e32 v53, s39, v53
	v_cvt_pk_bf16_f32 v18, v41, v45
	v_cvt_pk_bf16_f32 v19, v49, v53
	ds_write_b64 v10, v[18:19] offset:256
	v_mul_f32_e32 v42, s36, v42
	v_mul_f32_e32 v46, s37, v46
	v_mul_f32_e32 v50, s38, v50
	v_mul_f32_e32 v54, s39, v54
	v_cvt_pk_bf16_f32 v20, v42, v46
	v_cvt_pk_bf16_f32 v21, v50, v54
	ds_write_b64 v10, v[20:21] offset:512
	v_mul_f32_e32 v43, s36, v43
	v_mul_f32_e32 v47, s37, v47
	v_mul_f32_e32 v51, s38, v51
	v_mul_f32_e32 v55, s39, v55
	v_cvt_pk_bf16_f32 v22, v43, v47
	v_cvt_pk_bf16_f32 v23, v51, v55
	ds_write_b64 v10, v[22:23] offset:768
	s_add_u32 vcc_lo, s97, 1
	v_xor_b32_e32 v8, vcc_lo, v3
	v_lshl_add_u32 v10, v8, 3, v4
	v_mul_f32_e32 v56, s40, v56
	v_mul_f32_e32 v60, s41, v60
	v_mul_f32_e32 v64, s42, v64
	v_mul_f32_e32 v68, s43, v68
	v_cvt_pk_bf16_f32 v16, v56, v60
	v_cvt_pk_bf16_f32 v17, v64, v68
	ds_write_b64 v10, v[16:17]
	v_mul_f32_e32 v57, s40, v57
	v_mul_f32_e32 v61, s41, v61
	v_mul_f32_e32 v65, s42, v65
	v_mul_f32_e32 v69, s43, v69
	v_cvt_pk_bf16_f32 v18, v57, v61
	v_cvt_pk_bf16_f32 v19, v65, v69
	ds_write_b64 v10, v[18:19] offset:256
	v_mul_f32_e32 v58, s40, v58
	v_mul_f32_e32 v62, s41, v62
	v_mul_f32_e32 v66, s42, v66
	v_mul_f32_e32 v70, s43, v70
	v_cvt_pk_bf16_f32 v20, v58, v62
	v_cvt_pk_bf16_f32 v21, v66, v70
	ds_write_b64 v10, v[20:21] offset:512
	v_mul_f32_e32 v59, s40, v59
	v_mul_f32_e32 v63, s41, v63
	v_mul_f32_e32 v67, s42, v67
	v_mul_f32_e32 v71, s43, v71
	v_cvt_pk_bf16_f32 v22, v59, v63
	v_cvt_pk_bf16_f32 v23, v67, v71
	ds_write_b64 v10, v[22:23] offset:768
	s_add_u32 vcc_lo, s97, 2
	v_xor_b32_e32 v8, vcc_lo, v3
	v_lshl_add_u32 v10, v8, 3, v4
	v_mul_f32_e32 v72, s44, v72
	v_mul_f32_e32 v76, s45, v76
	v_mul_f32_e32 v80, s46, v80
	v_mul_f32_e32 v84, s47, v84
	v_cvt_pk_bf16_f32 v16, v72, v76
	v_cvt_pk_bf16_f32 v17, v80, v84
	ds_write_b64 v10, v[16:17]
	v_mul_f32_e32 v73, s44, v73
	v_mul_f32_e32 v77, s45, v77
	v_mul_f32_e32 v81, s46, v81
	v_mul_f32_e32 v85, s47, v85
	v_cvt_pk_bf16_f32 v18, v73, v77
	v_cvt_pk_bf16_f32 v19, v81, v85
	ds_write_b64 v10, v[18:19] offset:256
	v_mul_f32_e32 v74, s44, v74
	v_mul_f32_e32 v78, s45, v78
	v_mul_f32_e32 v82, s46, v82
	v_mul_f32_e32 v86, s47, v86
	v_cvt_pk_bf16_f32 v20, v74, v78
	v_cvt_pk_bf16_f32 v21, v82, v86
	ds_write_b64 v10, v[20:21] offset:512
	v_mul_f32_e32 v75, s44, v75
	v_mul_f32_e32 v79, s45, v79
	v_mul_f32_e32 v83, s46, v83
	v_mul_f32_e32 v87, s47, v87
	v_cvt_pk_bf16_f32 v22, v75, v79
	v_cvt_pk_bf16_f32 v23, v83, v87
	ds_write_b64 v10, v[22:23] offset:768
	s_add_u32 vcc_lo, s97, 3
	v_xor_b32_e32 v8, vcc_lo, v3
	v_lshl_add_u32 v10, v8, 3, v4
	v_mul_f32_e32 v88, s48, v88
	v_mul_f32_e32 v92, s49, v92
	v_mul_f32_e32 v96, s50, v96
	v_mul_f32_e32 v100, s51, v100
	v_cvt_pk_bf16_f32 v16, v88, v92
	v_cvt_pk_bf16_f32 v17, v96, v100
	ds_write_b64 v10, v[16:17]
	v_mul_f32_e32 v89, s48, v89
	v_mul_f32_e32 v93, s49, v93
	v_mul_f32_e32 v97, s50, v97
	v_mul_f32_e32 v101, s51, v101
	v_cvt_pk_bf16_f32 v18, v89, v93
	v_cvt_pk_bf16_f32 v19, v97, v101
	ds_write_b64 v10, v[18:19] offset:256
	v_mul_f32_e32 v90, s48, v90
	v_mul_f32_e32 v94, s49, v94
	v_mul_f32_e32 v98, s50, v98
	v_mul_f32_e32 v102, s51, v102
	v_cvt_pk_bf16_f32 v20, v90, v94
	v_cvt_pk_bf16_f32 v21, v98, v102
	ds_write_b64 v10, v[20:21] offset:512
	v_mul_f32_e32 v91, s48, v91
	v_mul_f32_e32 v95, s49, v95
	v_mul_f32_e32 v99, s50, v99
	v_mul_f32_e32 v103, s51, v103
	v_cvt_pk_bf16_f32 v22, v91, v95
	v_cvt_pk_bf16_f32 v23, v99, v103
	ds_write_b64 v10, v[22:23] offset:768
	s_lshl_b32 vcc_lo, s86, 1
	s_add_u32 s97, s94, vcc_lo
	s_cmp_ge_u32 s97, 6336
	s_cbranch_scc1 .Lp0_nf_0
	s_mov_b32 s3, s97
	s_mov_b32 s4, 3
	s_sub_u32 vcc_lo, s3, 1584
	s_cmp_ge_u32 s3, 1584
	s_cselect_b32 s3, vcc_lo, s3
	s_cselect_b32 vcc_lo, 1, 0
	s_sub_u32 s4, s4, vcc_lo
	s_sub_u32 vcc_lo, s3, 1584
	s_cmp_ge_u32 s3, 1584
	s_cselect_b32 s3, vcc_lo, s3
	s_cselect_b32 vcc_lo, 1, 0
	s_sub_u32 s4, s4, vcc_lo
	s_sub_u32 vcc_lo, s3, 1584
	s_cmp_ge_u32 s3, 1584
	s_cselect_b32 s3, vcc_lo, s3
	s_cselect_b32 vcc_lo, 1, 0
	s_sub_u32 s4, s4, vcc_lo
	s_sub_u32 s3, 1583, s3
	s_cmp_lt_u32 s3, 256
	s_cbranch_scc1 .Lp0_in_0_2
	s_cmp_lt_u32 s3, 384
	s_cbranch_scc1 .Lp0_out_0_2
	s_cmp_lt_u32 s3, 1088
	s_cbranch_scc1 .Lp0_gu_0_2
	s_cmp_lt_u32 s3, 1440
	s_cbranch_scc1 .Lp0_d_0_2
	s_cmp_lt_u32 s3, 1568
	s_cbranch_scc1 .Lp0_pg_0_2
	s_sub_u32 s3, s3, 1568
	s_lshr_b32 s5, s3, 3
	s_and_b32 s15, s3, 7
	s_movk_i32 s34, 176
	s_mov_b32 s35, 0
	s_movk_i32 s85, 2048
	s_movk_i32 s87, 256
	s_mov_b32 s0, 102760448
	s_mov_b32 s1, 2097152
	s_lshl_b32 s71, s15, 1
	s_add_u32 s72, s71, 1
	s_branch .Lp0_dec_0_2

; __device__ __forceinline__ unsigned cvt_pk_bf16(float lo, float hi) { return __builtin_bit_cast(unsigned, __builtin_convertvector((f32x2_t){lo, hi}, bf16x2_t)); }
; #define GAS __attribute__((address_space(1)))
; #define LAS __attribute__((address_space(3)))
; __device__ __forceinline__ void p0_transpose_item(const float* W, int ldw, int K, const float* gain, bf16* WT, int k0, int n0, int drow0, LAS float* scr, int lane) {
;     ...
;     for (int j = 0; j < 4; ++j) { const int n = (lane >> 3) + 8 * j; const LAS float* s = scr + (8 * c) * 33 + n;
;         v4u o; o.x = cvt_pk_bf16(s[0 * 33], s[1 * 33]); o.y = cvt_pk_bf16(s[2 * 33], s[3 * 33]); o.z = cvt_pk_bf16(s[4 * 33], s[5 * 33]); o.w = cvt_pk_bf16(s[6 * 33], s[7 * 33]);
;         *(GAS v4u*)(WT + (size_t)(drow0 + n) * K + k0 + 8 * c) = o; }
.Lp0_g2_0_2:
	global_load_dwordx4 v[40:43], v2, s[0:1] nt
	s_add_u32 s0, s0, s85
	s_addc_u32 s1, s1, 0
	global_load_dwordx4 v[44:47], v2, s[0:1] nt
	s_add_u32 s0, s0, s85
	s_addc_u32 s1, s1, 0
	global_load_dwordx4 v[48:51], v2, s[0:1] nt
	s_add_u32 s0, s0, s85
	s_addc_u32 s1, s1, 0
	global_load_dwordx4 v[52:55], v2, s[0:1] nt
	s_add_u32 s0, s0, s85
	s_addc_u32 s1, s1, 0
	global_load_dwordx4 v[56:59], v2, s[0:1] nt
	s_add_u32 s0, s0, s85
	s_addc_u32 s1, s1, 0
	global_load_dwordx4 v[60:63], v2, s[0:1] nt
	s_add_u32 s0, s0, s85
	s_addc_u32 s1, s1, 0
	global_load_dwordx4 v[64:67], v2, s[0:1] nt
	s_add_u32 s0, s0, s85
	s_addc_u32 s1, s1, 0
	global_load_dwordx4 v[68:71], v2, s[0:1] nt
	s_add_u32 s0, s0, s85
	s_addc_u32 s1, s1, 0
	global_load_dwordx4 v[72:75], v2, s[0:1] nt
	s_add_u32 s0, s0, s85
	s_addc_u32 s1, s1, 0
	global_load_dwordx4 v[76:79], v2, s[0:1] nt
	s_add_u32 s0, s0, s85
	s_addc_u32 s1, s1, 0
	global_load_dwordx4 v[80:83], v2, s[0:1] nt
	s_add_u32 s0, s0, s85
	s_addc_u32 s1, s1, 0
	global_load_dwordx4 v[84:87], v2, s[0:1] nt
	s_add_u32 s0, s0, s85
	s_addc_u32 s1, s1, 0
	global_load_dwordx4 v[88:91], v2, s[0:1] nt
	s_add_u32 s0, s0, s85
	s_addc_u32 s1, s1, 0
	global_load_dwordx4 v[92:95], v2, s[0:1] nt
	s_add_u32 s0, s0, s85
	s_addc_u32 s1, s1, 0
	global_load_dwordx4 v[96:99], v2, s[0:1] nt
	s_add_u32 s0, s0, s85
	s_addc_u32 s1, s1, 0
	global_load_dwordx4 v[100:103], v2, s[0:1] nt
.Lp0_nf_0:
	s_waitcnt lgkmcnt(0)
	s_barrier
	s_cmp_lt_u32 s95, 4
	s_cselect_b32 s97, s81, s83
	s_lshl_b32 s97, s97, 7
	s_and_b32 vcc_lo, s95, 3
	s_lshl_b32 vcc_lo, vcc_lo, 5
	s_add_u32 s97, s97, vcc_lo
	s_mul_i32 vcc_lo, s97, s80
	s_add_u32 s0, s78, vcc_lo
	s_addc_u32 s1, s79, 0
	v_mul_u32_u24_e32 v7, s80, v6
	s_lshl_b32 s85, s80, 1
	ds_read_b64 v[168:169], v5
	ds_read_b64 v[170:171], v5 offset:512
	ds_read_b64 v[172:173], v5 offset:1024
	ds_read_b64 v[174:175], v5 offset:1536
	ds_read_b64 v[176:177], v5 offset:2048
	ds_read_b64 v[178:179], v5 offset:2560
	ds_read_b64 v[180:181], v5 offset:3072
	ds_read_b64 v[182:183], v5 offset:3584
	ds_read_b64 v[184:185], v5 offset:4096
	ds_read_b64 v[186:187], v5 offset:4608
	ds_read_b64 v[188:189], v5 offset:5120
	ds_read_b64 v[190:191], v5 offset:5632
	ds_read_b64 v[192:193], v5 offset:6144
	ds_read_b64 v[194:195], v5 offset:6656
	ds_read_b64 v[196:197], v5 offset:7168
	ds_read_b64 v[198:199], v5 offset:7680
	s_lshl_b32 s87, s95, 3
	s_waitcnt lgkmcnt(0)
	s_add_u32 vcc_lo, s87, 0
	s_and_b32 vcc_lo, vcc_lo, 31
	v_xor_b32_e32 v8, vcc_lo, v3
	v_lshl_add_u32 v11, v8, 3, v7
	global_store_dwordx2 v11, v[168:169], s[0:1]
	s_add_u32 s0, s0, s85
	s_addc_u32 s1, s1, 0
	global_store_dwordx2 v11, v[170:171], s[0:1]
	s_add_u32 s0, s0, s85
	s_addc_u32 s1, s1, 0
	s_add_u32 vcc_lo, s87, 1
	s_and_b32 vcc_lo, vcc_lo, 31
	v_xor_b32_e32 v8, vcc_lo, v3
	v_lshl_add_u32 v11, v8, 3, v7
	global_store_dwordx2 v11, v[172:173], s[0:1]
	s_add_u32 s0, s0, s85
	s_addc_u32 s1, s1, 0
	global_store_dwordx2 v11, v[174:175], s[0:1]
	s_add_u32 s0, s0, s85
	s_addc_u32 s1, s1, 0
	s_add_u32 vcc_lo, s87, 2
	s_and_b32 vcc_lo, vcc_lo, 31
	v_xor_b32_e32 v8, vcc_lo, v3
	v_lshl_add_u32 v11, v8, 3, v7
	global_store_dwordx2 v11, v[176:177], s[0:1]
	s_add_u32 s0, s0, s85
	s_addc_u32 s1, s1, 0
	global_store_dwordx2 v11, v[178:179], s[0:1]
	s_add_u32 s0, s0, s85
	s_addc_u32 s1, s1, 0
	s_add_u32 vcc_lo, s87, 3
	s_and_b32 vcc_lo, vcc_lo, 31
	v_xor_b32_e32 v8, vcc_lo, v3
	v_lshl_add_u32 v11, v8, 3, v7
	global_store_dwordx2 v11, v[180:181], s[0:1]
	s_add_u32 s0, s0, s85
	s_addc_u32 s1, s1, 0
	global_store_dwordx2 v11, v[182:183], s[0:1]
	s_add_u32 s0, s0, s85
	s_addc_u32 s1, s1, 0
	s_add_u32 vcc_lo, s87, 4
	s_and_b32 vcc_lo, vcc_lo, 31
	v_xor_b32_e32 v8, vcc_lo, v3
	v_lshl_add_u32 v11, v8, 3, v7
	global_store_dwordx2 v11, v[184:185], s[0:1]
	s_add_u32 s0, s0, s85
	s_addc_u32 s1, s1, 0
	global_store_dwordx2 v11, v[186:187], s[0:1]
	s_add_u32 s0, s0, s85
	s_addc_u32 s1, s1, 0
	s_add_u32 vcc_lo, s87, 5
	s_and_b32 vcc_lo, vcc_lo, 31
	v_xor_b32_e32 v8, vcc_lo, v3
	v_lshl_add_u32 v11, v8, 3, v7
	global_store_dwordx2 v11, v[188:189], s[0:1]
	s_add_u32 s0, s0, s85
	s_addc_u32 s1, s1, 0
	global_store_dwordx2 v11, v[190:191], s[0:1]
	s_add_u32 s0, s0, s85
	s_addc_u32 s1, s1, 0
	s_add_u32 vcc_lo, s87, 6
	s_and_b32 vcc_lo, vcc_lo, 31
	v_xor_b32_e32 v8, vcc_lo, v3
	v_lshl_add_u32 v11, v8, 3, v7
	global_store_dwordx2 v11, v[192:193], s[0:1]
	s_add_u32 s0, s0, s85
	s_addc_u32 s1, s1, 0
	global_store_dwordx2 v11, v[194:195], s[0:1]
	s_add_u32 s0, s0, s85
	s_addc_u32 s1, s1, 0
	s_add_u32 vcc_lo, s87, 7
	s_and_b32 vcc_lo, vcc_lo, 31
	v_xor_b32_e32 v8, vcc_lo, v3
	v_lshl_add_u32 v11, v8, 3, v7
	global_store_dwordx2 v11, v[196:197], s[0:1]
	s_add_u32 s0, s0, s85
	s_addc_u32 s1, s1, 0
	global_store_dwordx2 v11, v[198:199], s[0:1]
	s_add_u32 s96, s96, 1
	s_add_u32 s94, s94, s86
	s_cmp_ge_u32 s94, 6336
	s_cbranch_scc1 .Lp0_done

; __device__ __forceinline__ unsigned cvt_pk_bf16(float lo, float hi) { return __builtin_bit_cast(unsigned, __builtin_convertvector((f32x2_t){lo, hi}, bf16x2_t)); }
; #define GAS __attribute__((address_space(1)))
; #define LAS __attribute__((address_space(3)))
; __device__ __forceinline__ void p0_transpose_item(const float* W, int ldw, int K, const float* gain, bf16* WT, int k0, int n0, int drow0, LAS float* scr, int lane) {
;     ...
;     for (int i = 0; i < 32; ++i) { const int kk = 2 * i + (lane >> 5); scr[kk * 33 + (lane & 31)] = wv[i] * __shfl(gk, kk); }
;     ...
;     for (int j = 0; j < 4; ++j) { const int n = (lane >> 3) + 8 * j; const LAS float* s = scr + (8 * c) * 33 + n;
;         v4u o; o.x = cvt_pk_bf16(s[0 * 33], s[1 * 33]); o.y = cvt_pk_bf16(s[2 * 33], s[3 * 33]); o.z = cvt_pk_bf16(s[4 * 33], s[5 * 33]); o.w = cvt_pk_bf16(s[6 * 33], s[7 * 33]);
;         *(GAS v4u*)(WT + (size_t)(drow0 + n) * K + k0 + 8 * c) = o; }
.Lp0_wd_1:
	s_waitcnt lgkmcnt(0)
	s_mov_b32 s78, s73
	s_mov_b32 s79, s74
	s_mov_b32 s80, s75
	s_mov_b32 s81, s76
	s_mov_b32 s83, s77
	s_lshl_b32 s97, s95, 2
	s_add_u32 vcc_lo, s97, 0
	v_xor_b32_e32 v8, vcc_lo, v3
	v_lshl_add_u32 v10, v8, 3, v9
	v_mul_f32_e32 v104, s16, v104
	v_mul_f32_e32 v108, s17, v108
	v_mul_f32_e32 v112, s18, v112
	v_mul_f32_e32 v116, s19, v116
	v_cvt_pk_bf16_f32 v16, v104, v108
	v_cvt_pk_bf16_f32 v17, v112, v116
	ds_write_b64 v10, v[16:17]
	v_mul_f32_e32 v105, s16, v105
	v_mul_f32_e32 v109, s17, v109
	v_mul_f32_e32 v113, s18, v113
	v_mul_f32_e32 v117, s19, v117
	v_cvt_pk_bf16_f32 v18, v105, v109
	v_cvt_pk_bf16_f32 v19, v113, v117
	ds_write_b64 v10, v[18:19] offset:256
	v_mul_f32_e32 v106, s16, v106
	v_mul_f32_e32 v110, s17, v110
	v_mul_f32_e32 v114, s18, v114
	v_mul_f32_e32 v118, s19, v118
	v_cvt_pk_bf16_f32 v20, v106, v110
	v_cvt_pk_bf16_f32 v21, v114, v118
	ds_write_b64 v10, v[20:21] offset:512
	v_mul_f32_e32 v107, s16, v107
	v_mul_f32_e32 v111, s17, v111
	v_mul_f32_e32 v115, s18, v115
	v_mul_f32_e32 v119, s19, v119
	v_cvt_pk_bf16_f32 v22, v107, v111
	v_cvt_pk_bf16_f32 v23, v115, v119
	ds_write_b64 v10, v[22:23] offset:768
	s_add_u32 vcc_lo, s97, 1
	v_xor_b32_e32 v8, vcc_lo, v3
	v_lshl_add_u32 v10, v8, 3, v9
	v_mul_f32_e32 v120, s20, v120
	v_mul_f32_e32 v124, s21, v124
	v_mul_f32_e32 v128, s22, v128
	v_mul_f32_e32 v132, s23, v132
	v_cvt_pk_bf16_f32 v16, v120, v124
	v_cvt_pk_bf16_f32 v17, v128, v132
	ds_write_b64 v10, v[16:17]
	v_mul_f32_e32 v121, s20, v121
	v_mul_f32_e32 v125, s21, v125
	v_mul_f32_e32 v129, s22, v129
	v_mul_f32_e32 v133, s23, v133
	v_cvt_pk_bf16_f32 v18, v121, v125
	v_cvt_pk_bf16_f32 v19, v129, v133
	ds_write_b64 v10, v[18:19] offset:256
	v_mul_f32_e32 v122, s20, v122
	v_mul_f32_e32 v126, s21, v126
	v_mul_f32_e32 v130, s22, v130
	v_mul_f32_e32 v134, s23, v134
	v_cvt_pk_bf16_f32 v20, v122, v126
	v_cvt_pk_bf16_f32 v21, v130, v134
	ds_write_b64 v10, v[20:21] offset:512
	v_mul_f32_e32 v123, s20, v123
	v_mul_f32_e32 v127, s21, v127
	v_mul_f32_e32 v131, s22, v131
	v_mul_f32_e32 v135, s23, v135
	v_cvt_pk_bf16_f32 v22, v123, v127
	v_cvt_pk_bf16_f32 v23, v131, v135
	ds_write_b64 v10, v[22:23] offset:768
	s_add_u32 vcc_lo, s97, 2
	v_xor_b32_e32 v8, vcc_lo, v3
	v_lshl_add_u32 v10, v8, 3, v9
	v_mul_f32_e32 v136, s24, v136
	v_mul_f32_e32 v140, s25, v140
	v_mul_f32_e32 v144, s26, v144
	v_mul_f32_e32 v148, s27, v148
	v_cvt_pk_bf16_f32 v16, v136, v140
	v_cvt_pk_bf16_f32 v17, v144, v148
	ds_write_b64 v10, v[16:17]
	v_mul_f32_e32 v137, s24, v137
	v_mul_f32_e32 v141, s25, v141
	v_mul_f32_e32 v145, s26, v145
	v_mul_f32_e32 v149, s27, v149
	v_cvt_pk_bf16_f32 v18, v137, v141
	v_cvt_pk_bf16_f32 v19, v145, v149
	ds_write_b64 v10, v[18:19] offset:256
	v_mul_f32_e32 v138, s24, v138
	v_mul_f32_e32 v142, s25, v142
	v_mul_f32_e32 v146, s26, v146
	v_mul_f32_e32 v150, s27, v150
	v_cvt_pk_bf16_f32 v20, v138, v142
	v_cvt_pk_bf16_f32 v21, v146, v150
	ds_write_b64 v10, v[20:21] offset:512
	v_mul_f32_e32 v139, s24, v139
	v_mul_f32_e32 v143, s25, v143
	v_mul_f32_e32 v147, s26, v147
	v_mul_f32_e32 v151, s27, v151
	v_cvt_pk_bf16_f32 v22, v139, v143
	v_cvt_pk_bf16_f32 v23, v147, v151
	ds_write_b64 v10, v[22:23] offset:768
	s_add_u32 vcc_lo, s97, 3
	v_xor_b32_e32 v8, vcc_lo, v3
	v_lshl_add_u32 v10, v8, 3, v9
	v_mul_f32_e32 v152, s28, v152
	v_mul_f32_e32 v156, s29, v156
	v_mul_f32_e32 v160, s30, v160
	v_mul_f32_e32 v164, s31, v164
	v_cvt_pk_bf16_f32 v16, v152, v156
	v_cvt_pk_bf16_f32 v17, v160, v164
	ds_write_b64 v10, v[16:17]
	v_mul_f32_e32 v153, s28, v153
	v_mul_f32_e32 v157, s29, v157
	v_mul_f32_e32 v161, s30, v161
	v_mul_f32_e32 v165, s31, v165
	v_cvt_pk_bf16_f32 v18, v153, v157
	v_cvt_pk_bf16_f32 v19, v161, v165
	ds_write_b64 v10, v[18:19] offset:256
	v_mul_f32_e32 v154, s28, v154
	v_mul_f32_e32 v158, s29, v158
	v_mul_f32_e32 v162, s30, v162
	v_mul_f32_e32 v166, s31, v166
	v_cvt_pk_bf16_f32 v20, v154, v158
	v_cvt_pk_bf16_f32 v21, v162, v166
	ds_write_b64 v10, v[20:21] offset:512
	v_mul_f32_e32 v155, s28, v155
	v_mul_f32_e32 v159, s29, v159
	v_mul_f32_e32 v163, s30, v163
	v_mul_f32_e32 v167, s31, v167
	v_cvt_pk_bf16_f32 v22, v155, v159
	v_cvt_pk_bf16_f32 v23, v163, v167
	ds_write_b64 v10, v[22:23] offset:768
	s_lshl_b32 vcc_lo, s86, 1
	s_add_u32 s97, s94, vcc_lo
	s_cmp_ge_u32 s97, 6336
	s_cbranch_scc1 .Lp0_nf_1
	s_mov_b32 s3, s97
	s_mov_b32 s4, 3
	s_sub_u32 vcc_lo, s3, 1584
	s_cmp_ge_u32 s3, 1584
	s_cselect_b32 s3, vcc_lo, s3
	s_cselect_b32 vcc_lo, 1, 0
	s_sub_u32 s4, s4, vcc_lo
	s_sub_u32 vcc_lo, s3, 1584
	s_cmp_ge_u32 s3, 1584
	s_cselect_b32 s3, vcc_lo, s3
	s_cselect_b32 vcc_lo, 1, 0
	s_sub_u32 s4, s4, vcc_lo
	s_sub_u32 vcc_lo, s3, 1584
	s_cmp_ge_u32 s3, 1584
	s_cselect_b32 s3, vcc_lo, s3
	s_cselect_b32 vcc_lo, 1, 0
	s_sub_u32 s4, s4, vcc_lo
	s_sub_u32 s3, 1583, s3
	s_cmp_lt_u32 s3, 256
	s_cbranch_scc1 .Lp0_in_1_3
	s_cmp_lt_u32 s3, 384
	s_cbranch_scc1 .Lp0_out_1_3
	s_cmp_lt_u32 s3, 1088
	s_cbranch_scc1 .Lp0_gu_1_3
	s_cmp_lt_u32 s3, 1440
	s_cbranch_scc1 .Lp0_d_1_3
	s_cmp_lt_u32 s3, 1568
	s_cbranch_scc1 .Lp0_pg_1_3
	s_sub_u32 s3, s3, 1568
	s_lshr_b32 s5, s3, 3
	s_and_b32 s15, s3, 7
	s_movk_i32 s34, 176
	s_mov_b32 s35, 0
	s_movk_i32 s85, 2048
	s_movk_i32 s87, 256
	s_mov_b32 s0, 102760448
	s_mov_b32 s1, 2097152
	s_lshl_b32 s76, s15, 1
	s_add_u32 s77, s76, 1
	s_branch .Lp0_dec_1_3

; __device__ __forceinline__ unsigned cvt_pk_bf16(float lo, float hi) { return __builtin_bit_cast(unsigned, __builtin_convertvector((f32x2_t){lo, hi}, bf16x2_t)); }
; #define GAS __attribute__((address_space(1)))
; #define LAS __attribute__((address_space(3)))
; __device__ __forceinline__ void p0_transpose_item(const float* W, int ldw, int K, const float* gain, bf16* WT, int k0, int n0, int drow0, LAS float* scr, int lane) {
;     ...
;     for (int j = 0; j < 4; ++j) { const int n = (lane >> 3) + 8 * j; const LAS float* s = scr + (8 * c) * 33 + n;
;         v4u o; o.x = cvt_pk_bf16(s[0 * 33], s[1 * 33]); o.y = cvt_pk_bf16(s[2 * 33], s[3 * 33]); o.z = cvt_pk_bf16(s[4 * 33], s[5 * 33]); o.w = cvt_pk_bf16(s[6 * 33], s[7 * 33]);
;         *(GAS v4u*)(WT + (size_t)(drow0 + n) * K + k0 + 8 * c) = o; }
; __device__ __forceinline__ void p0_prologue(const Frame& F, const Args& A) {
;     ...
;     { const float* x = A.in[0]; bf16* hb = (bf16*)(F.ws + WS_HB0); float* ss = (float*)(F.ws + WS_SS);
;         for (int m = F.gw; m < M; m += F.NGW) {
;             const GAS f32x4* xr = (const GAS f32x4*)(x + (size_t)m * D) + lane;
;             GAS v2u* hrow = (GAS v2u*)(hb + (size_t)m * D) + lane;
.Lp0_nf_1:
	s_waitcnt lgkmcnt(0)
	s_barrier
	s_cmp_lt_u32 s95, 4
	s_cselect_b32 s97, s81, s83
	s_lshl_b32 s97, s97, 7
	s_and_b32 vcc_lo, s95, 3
	s_lshl_b32 vcc_lo, vcc_lo, 5
	s_add_u32 s97, s97, vcc_lo
	s_mul_i32 vcc_lo, s97, s80
	s_add_u32 s0, s78, vcc_lo
	s_addc_u32 s1, s79, 0
	v_mul_u32_u24_e32 v7, s80, v6
	s_lshl_b32 s85, s80, 1
	ds_read_b64 v[168:169], v12
	ds_read_b64 v[170:171], v12 offset:512
	ds_read_b64 v[172:173], v12 offset:1024
	ds_read_b64 v[174:175], v12 offset:1536
	ds_read_b64 v[176:177], v12 offset:2048
	ds_read_b64 v[178:179], v12 offset:2560
	ds_read_b64 v[180:181], v12 offset:3072
	ds_read_b64 v[182:183], v12 offset:3584
	ds_read_b64 v[184:185], v12 offset:4096
	ds_read_b64 v[186:187], v12 offset:4608
	ds_read_b64 v[188:189], v12 offset:5120
	ds_read_b64 v[190:191], v12 offset:5632
	ds_read_b64 v[192:193], v12 offset:6144
	ds_read_b64 v[194:195], v12 offset:6656
	ds_read_b64 v[196:197], v12 offset:7168
	ds_read_b64 v[198:199], v12 offset:7680
	s_lshl_b32 s87, s95, 3
	s_waitcnt lgkmcnt(0)
	s_add_u32 vcc_lo, s87, 0
	s_and_b32 vcc_lo, vcc_lo, 31
	v_xor_b32_e32 v8, vcc_lo, v3
	v_lshl_add_u32 v11, v8, 3, v7
	global_store_dwordx2 v11, v[168:169], s[0:1]
	s_add_u32 s0, s0, s85
	s_addc_u32 s1, s1, 0
	global_store_dwordx2 v11, v[170:171], s[0:1]
	s_add_u32 s0, s0, s85
	s_addc_u32 s1, s1, 0
	s_add_u32 vcc_lo, s87, 1
	s_and_b32 vcc_lo, vcc_lo, 31
	v_xor_b32_e32 v8, vcc_lo, v3
	v_lshl_add_u32 v11, v8, 3, v7
	global_store_dwordx2 v11, v[172:173], s[0:1]
	s_add_u32 s0, s0, s85
	s_addc_u32 s1, s1, 0
	global_store_dwordx2 v11, v[174:175], s[0:1]
	s_add_u32 s0, s0, s85
	s_addc_u32 s1, s1, 0
	s_add_u32 vcc_lo, s87, 2
	s_and_b32 vcc_lo, vcc_lo, 31
	v_xor_b32_e32 v8, vcc_lo, v3
	v_lshl_add_u32 v11, v8, 3, v7
	global_store_dwordx2 v11, v[176:177], s[0:1]
	s_add_u32 s0, s0, s85
	s_addc_u32 s1, s1, 0
	global_store_dwordx2 v11, v[178:179], s[0:1]
	s_add_u32 s0, s0, s85
	s_addc_u32 s1, s1, 0
	s_add_u32 vcc_lo, s87, 3
	s_and_b32 vcc_lo, vcc_lo, 31
	v_xor_b32_e32 v8, vcc_lo, v3
	v_lshl_add_u32 v11, v8, 3, v7
	global_store_dwordx2 v11, v[180:181], s[0:1]
	s_add_u32 s0, s0, s85
	s_addc_u32 s1, s1, 0
	global_store_dwordx2 v11, v[182:183], s[0:1]
	s_add_u32 s0, s0, s85
	s_addc_u32 s1, s1, 0
	s_add_u32 vcc_lo, s87, 4
	s_and_b32 vcc_lo, vcc_lo, 31
	v_xor_b32_e32 v8, vcc_lo, v3
	v_lshl_add_u32 v11, v8, 3, v7
	global_store_dwordx2 v11, v[184:185], s[0:1]
	s_add_u32 s0, s0, s85
	s_addc_u32 s1, s1, 0
	global_store_dwordx2 v11, v[186:187], s[0:1]
	s_add_u32 s0, s0, s85
	s_addc_u32 s1, s1, 0
	s_add_u32 vcc_lo, s87, 5
	s_and_b32 vcc_lo, vcc_lo, 31
	v_xor_b32_e32 v8, vcc_lo, v3
	v_lshl_add_u32 v11, v8, 3, v7
	global_store_dwordx2 v11, v[188:189], s[0:1]
	s_add_u32 s0, s0, s85
	s_addc_u32 s1, s1, 0
	global_store_dwordx2 v11, v[190:191], s[0:1]
	s_add_u32 s0, s0, s85
	s_addc_u32 s1, s1, 0
	s_add_u32 vcc_lo, s87, 6
	s_and_b32 vcc_lo, vcc_lo, 31
	v_xor_b32_e32 v8, vcc_lo, v3
	v_lshl_add_u32 v11, v8, 3, v7
	global_store_dwordx2 v11, v[192:193], s[0:1]
	s_add_u32 s0, s0, s85
	s_addc_u32 s1, s1, 0
	global_store_dwordx2 v11, v[194:195], s[0:1]
	s_add_u32 s0, s0, s85
	s_addc_u32 s1, s1, 0
	s_add_u32 vcc_lo, s87, 7
	s_and_b32 vcc_lo, vcc_lo, 31
	v_xor_b32_e32 v8, vcc_lo, v3
	v_lshl_add_u32 v11, v8, 3, v7
	global_store_dwordx2 v11, v[196:197], s[0:1]
	s_add_u32 s0, s0, s85
	s_addc_u32 s1, s1, 0
	global_store_dwordx2 v11, v[198:199], s[0:1]
	s_add_u32 s96, s96, 1
	s_add_u32 s94, s94, s86
	s_cmp_ge_u32 s94, 6336
	s_cbranch_scc1 .Lp0_done
	s_branch .Lp0_body0
.Lp0_done:
.LBB0_63:
	s_ashr_i32 s85, s84, 31
	s_ashr_i32 s15, s14, 31
	s_cmpk_gt_i32 s14, 0x7fff
	v_ashrrev_i32_e32 v33, 31, v32
	s_cbranch_scc1 .LBB0_68
	s_lshl_b64 s[16:17], s[14:15], 7
	v_lshl_add_u64 v[0:1], v[32:33], 2, s[16:17]
	s_mov_b64 s[16:17], 0x200000
	v_lshl_add_u64 v[0:1], v[0:1], 0, s[16:17]
	s_lshl_b64 s[16:17], s[84:85], 7
	s_lshl_b64 s[18:19], s[14:15], 13
	s_add_u32 s18, s52, s18
	s_addc_u32 s19, s53, s19
	v_lshl_add_u64 v[2:3], v[32:33], 4, s[18:19]
	s_mov_b64 s[18:19], 0x1000
	s_lshl_b64 s[20:21], s[14:15], 12
	v_cmp_gt_i32_e64 s[0:1], 32, v32
	v_cmp_eq_u32_e64 s[4:5], 0, v32
	v_lshl_add_u64 v[2:3], v[2:3], 0, s[18:19]
	s_lshl_b64 s[18:19], s[84:85], 13
	v_lshl_add_u64 v[4:5], v[32:33], 3, s[20:21]
	s_lshl_b64 s[20:21], s[84:85], 12
	s_mov_b32 s3, 0x1dc00000
	s_mov_b32 s24, s14
	s_branch .LBB0_66

; #define GAS __attribute__((address_space(1)))
; __device__ __forceinline__ int lane_opaque() { int l; asm volatile("v_mbcnt_lo_u32_b32 %0, -1, 0\n\tv_mbcnt_hi_u32_b32 %0, -1, %0" : "=v"(l)); return l; }
; __device__ __forceinline__ void unpack8(const v4u w, float (&f)[8]) { f[0] = bf_lo(w.x); f[1] = bf_hi(w.x); f[2] = bf_lo(w.y); f[3] = bf_hi(w.y); f[4] = bf_lo(w.z); f[5] = bf_hi(w.z); f[6] = bf_lo(w.w); f[7] = bf_hi(w.w); }
; __device__ __forceinline__ void mixer_shortconv(const Frame& F, const Args& A, int l, int chunk, const bf16* Z, bf16* MIX) {
;     const int lane = lane_opaque();
;     const int c8 = lane * 8, row0 = chunk * 128, pos0 = (chunk & 31) * 128, t0 = F.wave * 16;
;     const float* cw = A.in[8] + (size_t)l * 3 * GW;
;     float w0[8], w1[8], w2[8];
; #pragma unroll
;     for (int j = 0; j < 8; ++j) { w0[j] = cw[c8 + j]; w1[j] = cw[GW + c8 + j]; w2[j] = cw[2 * GW + c8 + j]; }
;     float xm2[8], xm1[8];
; #pragma unroll
;     for (int j = 0; j < 8; ++j) { xm2[j] = 0.f; xm1[j] = 0.f; }
; #pragma unroll
;     for (int dt = -2; dt < 16; ++dt) {
;         const int t = t0 + dt; const bool valid = (pos0 + t) >= 0;
;         const bf16* zr = Z + (size_t)(row0 + (valid ? t : 0)) * ZC;
;         float xv[8], x[8];
;         unpack8(*(const GAS v4u*)(zr + 1024 + c8), xv);
; __device__ __forceinline__ void mixer_sgu(const Frame& F, const Args& A, int l, int chunk, const bf16* Z, bf16* MIX) {
;     ...
;             const float* lg = A.in[4] + (size_t)(l * 4 + hd) * 128 + 32 * q; const float* lb = A.in[5] + (size_t)(l * 4 + hd) * 128 + 32 * q;
;             f32x4 g4v[8], b4v[8];
; #pragma unroll
;             for (int j = 0; j < 8; ++j) { g4v[j] = *(const GAS f32x4*)(lg + 4 * j); b4v[j] = *(const GAS f32x4*)(lb + 4 * j); }
; __global__ void __launch_bounds__(NTHR, 2) trunk_fwd(Args args) {
;     ...
;             for (int chunk_ = bid; chunk_ < (M / 128) * (((PROBE_DUP >> 1) & 1) + 1); chunk_ += P.G) { const int cq = chunk_ & (M / 128 - 1), chunk = (P.G == 256) ? ((cq & 7) * 32 + (cq >> 3)) : cq;
;                 mixer_shortconv(P, args, l, chunk, Z, MIX);
.LBB0_302:
	s_lshl_b32 s4, s26, 5
	s_and_b32 s4, s4, 0xe0
	s_bfe_u32 s5, s26, 0x50003
	s_or_b32 s36, s4, s5
	v_readlane_b32 s4, v253, 24
	s_and_b32 s21, s26, 0xff
	v_readlane_b32 s5, v253, 25
	s_and_b64 s[4:5], s[4:5], exec
	s_cselect_b32 s5, s36, s21
	s_lshl_b32 s21, s5, 7
	s_and_b32 s4, s21, 0xf80
	v_mbcnt_lo_u32_b32 v1, -1, 0
	v_mbcnt_hi_u32_b32 v1, -1, v1
	v_lshlrev_b32_e32 v2, 4, v1
	v_lshlrev_b32_e32 v3, 5, v1
	v_and_b32_e32 v4, 15, v1
	v_lshrrev_b32_e32 v5, 4, v1
	v_add_u32_e32 v150, s77, v1
	v_lshlrev_b32_e32 v151, 2, v150
	global_load_dword v152, v151, s[60:61]
	global_load_dword v153, v151, s[62:63]
	v_lshrrev_b32_e32 v154, 5, v150
	v_mul_u32_u24_e32 v154, 144, v154
	v_and_b32_e32 v155, 31, v150
	v_lshl_add_u32 v154, v155, 2, v154
	v_add_u32_e32 v154, 135168, v154
	v_readlane_b32 s42, v253, 44
	v_readlane_b32 s43, v253, 45
	v_or_b32_e32 v10, 0, v5
	v_xor_b32_e32 v10, v4, v10
	v_lshlrev_b32_e32 v10, 4, v10
	v_lshl_add_u32 v6, v5, 8, v10
	v_or_b32_e32 v10, 4, v5
	v_xor_b32_e32 v10, v4, v10
	v_lshlrev_b32_e32 v10, 4, v10
	v_lshl_add_u32 v7, v5, 8, v10
	v_or_b32_e32 v10, 8, v5
	v_xor_b32_e32 v10, v4, v10
	v_lshlrev_b32_e32 v10, 4, v10
	v_lshl_add_u32 v8, v5, 8, v10
	v_or_b32_e32 v10, 12, v5
	v_xor_b32_e32 v10, v4, v10
	v_lshlrev_b32_e32 v10, 4, v10
	v_lshl_add_u32 v9, v5, 8, v10
	s_lshl_b32 s36, s56, 10
	s_add_u32 s38, s54, s36
	s_addc_u32 s39, s55, 0
	s_add_i32 m0, s36, 0
	s_nop 0
	global_load_lds_dwordx4 v6, s[38:39]
	s_add_i32 m0, s36, 1024
	s_add_u32 s48, s38, 1024
	s_addc_u32 s49, s39, 0
	global_load_lds_dwordx4 v7, s[48:49]
	s_add_i32 m0, s36, 2048
	s_add_u32 s48, s38, 2048
	s_addc_u32 s49, s39, 0
	global_load_lds_dwordx4 v8, s[48:49]
	s_add_i32 m0, s36, 3072
	s_add_u32 s48, s38, 3072
	s_addc_u32 s49, s39, 0
	global_load_lds_dwordx4 v9, s[48:49]
	s_add_i32 m0, s36, 4096
	s_add_u32 s48, s38, 4096
	s_addc_u32 s49, s39, 0
	global_load_lds_dwordx4 v6, s[48:49]
	s_add_i32 m0, s36, 5120
	s_add_u32 s48, s38, 5120
	s_addc_u32 s49, s39, 0
	global_load_lds_dwordx4 v7, s[48:49]
	s_add_i32 m0, s36, 6144
	s_add_u32 s48, s38, 6144
	s_addc_u32 s49, s39, 0
	global_load_lds_dwordx4 v8, s[48:49]
	s_add_i32 m0, s36, 7168
	s_add_u32 s48, s38, 7168
	s_addc_u32 s49, s39, 0
	global_load_lds_dwordx4 v9, s[48:49]
	s_add_i32 m0, s36, 8192
	s_add_u32 s48, s38, 8192
	s_addc_u32 s49, s39, 0
	global_load_lds_dwordx4 v6, s[48:49]
	s_add_i32 m0, s36, 9216
	s_add_u32 s48, s38, 9216
	s_addc_u32 s49, s39, 0
	global_load_lds_dwordx4 v7, s[48:49]
	s_add_i32 m0, s36, 10240
	s_add_u32 s48, s38, 10240
	s_addc_u32 s49, s39, 0
	global_load_lds_dwordx4 v8, s[48:49]
	s_add_i32 m0, s36, 11264
	s_add_u32 s48, s38, 11264
	s_addc_u32 s49, s39, 0
	global_load_lds_dwordx4 v9, s[48:49]
	s_add_i32 m0, s36, 12288
	s_add_u32 s48, s38, 12288
	s_addc_u32 s49, s39, 0
	global_load_lds_dwordx4 v6, s[48:49]
	s_add_i32 m0, s36, 13312
	s_add_u32 s48, s38, 13312
	s_addc_u32 s49, s39, 0
	global_load_lds_dwordx4 v7, s[48:49]
	s_add_i32 m0, s36, 14336
	s_add_u32 s48, s38, 14336
	s_addc_u32 s49, s39, 0
	global_load_lds_dwordx4 v8, s[48:49]
	s_add_i32 m0, s36, 15360
	s_add_u32 s48, s38, 15360
	s_addc_u32 s49, s39, 0
	global_load_lds_dwordx4 v9, s[48:49]
	s_add_i32 s36, s21, s56
	s_lshl_b32 s84, s36, 12
	s_mov_b32 s85, 0
	s_add_u32 s46, s2, s84
	s_addc_u32 s47, s3, 0
	s_add_i32 s37, s4, s56
	s_cmp_lg_u32 s37, 0
	s_cselect_b64 s[40:41], -1, 0
	s_mul_i32 s37, s36, s33
	s_add_u32 s38, s82, s37
	s_addc_u32 s39, s83, 0
	global_load_dwordx4 v[100:103], v3, s[42:43]
	global_load_dwordx4 v[104:107], v3, s[42:43] offset:16
	global_load_dwordx4 v[108:111], v3, s[42:43] offset:2048
	global_load_dwordx4 v[112:115], v3, s[42:43] offset:2064
	s_add_u32 s48, s42, 0x1000
	s_addc_u32 s49, s43, 0
	global_load_dwordx4 v[116:119], v3, s[48:49]
	global_load_dwordx4 v[120:123], v3, s[48:49] offset:16
	s_sub_u32 s48, s38, 0x3000
	s_subb_u32 s49, s39, 0
	s_and_b64 vcc, s[40:41], exec
	s_cselect_b32 s48, s48, s38
	s_cselect_b32 s49, s49, s39
	global_load_dwordx4 v[12:15], v2, s[48:49] offset:2048
	s_sub_u32 s48, s38, 0x1800
	s_subb_u32 s49, s39, 0
	s_and_b64 vcc, s[40:41], exec
	s_cselect_b32 s48, s48, s38
	s_cselect_b32 s49, s49, s39
	global_load_dwordx4 v[16:19], v2, s[48:49] offset:2048
	s_mov_b64 s[48:49], s[38:39]
	global_load_dwordx4 v[20:23], v2, s[48:49] offset:2048
	global_load_dwordx4 v[52:55], v2, s[48:49] offset:3072
	s_add_u32 s48, s48, 0x1800
	s_addc_u32 s49, s49, 0
	global_load_dwordx4 v[24:27], v2, s[48:49] offset:2048
	global_load_dwordx4 v[56:59], v2, s[48:49] offset:3072
	s_add_u32 s48, s48, 0x1800
	s_addc_u32 s49, s49, 0
	global_load_dwordx4 v[28:31], v2, s[48:49] offset:2048
	global_load_dwordx4 v[60:63], v2, s[48:49] offset:3072
	s_add_u32 s48, s48, 0x1800
	s_addc_u32 s49, s49, 0
	global_load_dwordx4 v[32:35], v2, s[48:49] offset:2048
	global_load_dwordx4 v[64:67], v2, s[48:49] offset:3072
	s_add_u32 s48, s48, 0x1800
	s_addc_u32 s49, s49, 0
	global_load_dwordx4 v[36:39], v2, s[48:49] offset:2048
	global_load_dwordx4 v[68:71], v2, s[48:49] offset:3072
	s_add_u32 s48, s48, 0x1800
	s_addc_u32 s49, s49, 0
	global_load_dwordx4 v[40:43], v2, s[48:49] offset:2048
	global_load_dwordx4 v[72:75], v2, s[48:49] offset:3072
	s_add_u32 s48, s48, 0x1800
	s_addc_u32 s49, s49, 0
	global_load_dwordx4 v[44:47], v2, s[48:49] offset:2048
	global_load_dwordx4 v[76:79], v2, s[48:49] offset:3072
	s_add_u32 s48, s48, 0x1800
	s_addc_u32 s49, s49, 0
	global_load_dwordx4 v[48:51], v2, s[48:49] offset:2048
	global_load_dwordx4 v[80:83], v2, s[48:49] offset:3072
	s_add_u32 s48, s48, 0x1800
	s_addc_u32 s49, s49, 0
	s_waitcnt vmcnt(0)
; #define GAS __attribute__((address_space(1)))
; __device__ __forceinline__ void unpack8(const v4u w, float (&f)[8]) { f[0] = bf_lo(w.x); f[1] = bf_hi(w.x); f[2] = bf_lo(w.y); f[3] = bf_hi(w.y); f[4] = bf_lo(w.z); f[5] = bf_hi(w.z); f[6] = bf_lo(w.w); f[7] = bf_hi(w.w); }
; __device__ __forceinline__ v4u pack8(const float (&f)[8]) { v4u w; w.x = cvt_pk_bf16(f[0], f[1]); w.y = cvt_pk_bf16(f[2], f[3]); w.z = cvt_pk_bf16(f[4], f[5]); w.w = cvt_pk_bf16(f[6], f[7]); return w; }
; __device__ __forceinline__ void mixer_shortconv(const Frame& F, const Args& A, int l, int chunk, const bf16* Z, bf16* MIX) {
;     ...
;     for (int dt = -2; dt < 16; ++dt) {
;         const int t = t0 + dt; const bool valid = (pos0 + t) >= 0;
;         const bf16* zr = Z + (size_t)(row0 + (valid ? t : 0)) * ZC;
;         float xv[8], x[8];
;         unpack8(*(const GAS v4u*)(zr + 1024 + c8), xv);
; #pragma unroll
;         for (int j = 0; j < 8; ++j) x[j] = valid ? xv[j] : 0.f;
;         if (dt >= 0) { float bg[8], o[8]; unpack8(*(const GAS v4u*)(zr + 1536 + c8), bg);
; #pragma unroll
;             for (int j = 0; j < 8; ++j) o[j] = bg[j] * (w0[j] * xm2[j] + w1[j] * xm1[j] + w2[j] * x[j]);
;             *(GAS v4u*)(MIX + (size_t)(row0 + t) * D + 512 + c8) = pack8(o); }
; #pragma unroll
;         for (int j = 0; j < 8; ++j) { xm2[j] = xm1[j]; xm1[j] = x[j]; }
;     }
	v_lshlrev_b32_e32 v84, 16, v12
	v_and_b32_e32 v85, 0xffff0000, v12
	v_lshlrev_b32_e32 v86, 16, v13
	v_and_b32_e32 v87, 0xffff0000, v13
	v_lshlrev_b32_e32 v88, 16, v14
	v_and_b32_e32 v89, 0xffff0000, v14
	v_lshlrev_b32_e32 v90, 16, v15
	v_and_b32_e32 v91, 0xffff0000, v15
	v_cndmask_b32_e64 v84, 0, v84, s[40:41]
	v_cndmask_b32_e64 v85, 0, v85, s[40:41]
	v_cndmask_b32_e64 v86, 0, v86, s[40:41]
	v_cndmask_b32_e64 v87, 0, v87, s[40:41]
	v_cndmask_b32_e64 v88, 0, v88, s[40:41]
	v_cndmask_b32_e64 v89, 0, v89, s[40:41]
	v_cndmask_b32_e64 v90, 0, v90, s[40:41]
	v_cndmask_b32_e64 v91, 0, v91, s[40:41]
	v_lshlrev_b32_e32 v92, 16, v16
	v_and_b32_e32 v93, 0xffff0000, v16
	v_lshlrev_b32_e32 v94, 16, v17
	v_and_b32_e32 v95, 0xffff0000, v17
	v_lshlrev_b32_e32 v96, 16, v18
	v_and_b32_e32 v97, 0xffff0000, v18
	v_lshlrev_b32_e32 v98, 16, v19
	v_and_b32_e32 v99, 0xffff0000, v19
	v_cndmask_b32_e64 v92, 0, v92, s[40:41]
	v_cndmask_b32_e64 v93, 0, v93, s[40:41]
	v_cndmask_b32_e64 v94, 0, v94, s[40:41]
	v_cndmask_b32_e64 v95, 0, v95, s[40:41]
	v_cndmask_b32_e64 v96, 0, v96, s[40:41]
	v_cndmask_b32_e64 v97, 0, v97, s[40:41]
	v_cndmask_b32_e64 v98, 0, v98, s[40:41]
	v_cndmask_b32_e64 v99, 0, v99, s[40:41]
	v_lshlrev_b32_e32 v124, 16, v20
	v_and_b32_e32 v125, 0xffff0000, v20
	v_lshlrev_b32_e32 v126, 16, v21
	v_and_b32_e32 v127, 0xffff0000, v21
	v_lshlrev_b32_e32 v128, 16, v22
	v_and_b32_e32 v129, 0xffff0000, v22
	v_lshlrev_b32_e32 v130, 16, v23
	v_and_b32_e32 v131, 0xffff0000, v23
	v_lshlrev_b32_e32 v132, 16, v52
	v_and_b32_e32 v133, 0xffff0000, v52
	v_lshlrev_b32_e32 v134, 16, v53
	v_and_b32_e32 v135, 0xffff0000, v53
	v_lshlrev_b32_e32 v136, 16, v54
	v_and_b32_e32 v137, 0xffff0000, v54
	v_lshlrev_b32_e32 v138, 16, v55
	v_and_b32_e32 v139, 0xffff0000, v55
	v_mul_f32_e32 v140, v100, v84
	v_fmac_f32_e32 v140, v108, v92
	v_fmac_f32_e32 v140, v116, v124
	v_mul_f32_e32 v140, v132, v140
	v_mul_f32_e32 v141, v101, v85
	v_fmac_f32_e32 v141, v109, v93
	v_fmac_f32_e32 v141, v117, v125
	v_mul_f32_e32 v141, v133, v141
	v_mul_f32_e32 v142, v102, v86
	v_fmac_f32_e32 v142, v110, v94
	v_fmac_f32_e32 v142, v118, v126
	v_mul_f32_e32 v142, v134, v142
	v_mul_f32_e32 v143, v103, v87
	v_fmac_f32_e32 v143, v111, v95
	v_fmac_f32_e32 v143, v119, v127
	v_mul_f32_e32 v143, v135, v143
	v_mul_f32_e32 v144, v104, v88
	v_fmac_f32_e32 v144, v112, v96
	v_fmac_f32_e32 v144, v120, v128
	v_mul_f32_e32 v144, v136, v144
	v_mul_f32_e32 v145, v105, v89
	v_fmac_f32_e32 v145, v113, v97
	v_fmac_f32_e32 v145, v121, v129
	v_mul_f32_e32 v145, v137, v145
	v_mul_f32_e32 v146, v106, v90
	v_fmac_f32_e32 v146, v114, v98
	v_fmac_f32_e32 v146, v122, v130
	v_mul_f32_e32 v146, v138, v146
	v_mul_f32_e32 v147, v107, v91
	v_fmac_f32_e32 v147, v115, v99
	v_fmac_f32_e32 v147, v123, v131
	v_mul_f32_e32 v147, v139, v147
	v_cvt_pk_bf16_f32 v140, v140, v141
	v_cvt_pk_bf16_f32 v141, v142, v143
	v_cvt_pk_bf16_f32 v142, v144, v145
	v_cvt_pk_bf16_f32 v143, v146, v147
	global_store_dwordx4 v2, v[140:143], s[46:47] offset:1024
	s_add_u32 s46, s46, 0x1000
	s_addc_u32 s47, s47, 0
	global_load_dwordx4 v[20:23], v2, s[48:49] offset:2048
	global_load_dwordx4 v[52:55], v2, s[48:49] offset:3072
	s_add_u32 s48, s48, 0x1800
	s_addc_u32 s49, s49, 0
	v_lshlrev_b32_e32 v84, 16, v24
	v_and_b32_e32 v85, 0xffff0000, v24
	v_lshlrev_b32_e32 v86, 16, v25
	v_and_b32_e32 v87, 0xffff0000, v25
	v_lshlrev_b32_e32 v88, 16, v26
	v_and_b32_e32 v89, 0xffff0000, v26
	v_lshlrev_b32_e32 v90, 16, v27
	v_and_b32_e32 v91, 0xffff0000, v27
	v_lshlrev_b32_e32 v132, 16, v56
	v_and_b32_e32 v133, 0xffff0000, v56
	v_lshlrev_b32_e32 v134, 16, v57
	v_and_b32_e32 v135, 0xffff0000, v57
	v_lshlrev_b32_e32 v136, 16, v58
	v_and_b32_e32 v137, 0xffff0000, v58
	v_lshlrev_b32_e32 v138, 16, v59
	v_and_b32_e32 v139, 0xffff0000, v59
	v_mul_f32_e32 v140, v100, v92
	v_fmac_f32_e32 v140, v108, v124
	v_fmac_f32_e32 v140, v116, v84
	v_mul_f32_e32 v140, v132, v140
	v_mul_f32_e32 v141, v101, v93
	v_fmac_f32_e32 v141, v109, v125
	v_fmac_f32_e32 v141, v117, v85
	v_mul_f32_e32 v141, v133, v141
	v_mul_f32_e32 v142, v102, v94
	v_fmac_f32_e32 v142, v110, v126
	v_fmac_f32_e32 v142, v118, v86
	v_mul_f32_e32 v142, v134, v142
	v_mul_f32_e32 v143, v103, v95
	v_fmac_f32_e32 v143, v111, v127
	v_fmac_f32_e32 v143, v119, v87
	v_mul_f32_e32 v143, v135, v143
	v_mul_f32_e32 v144, v104, v96
	v_fmac_f32_e32 v144, v112, v128
	v_fmac_f32_e32 v144, v120, v88
	v_mul_f32_e32 v144, v136, v144
	v_mul_f32_e32 v145, v105, v97
	v_fmac_f32_e32 v145, v113, v129
	v_fmac_f32_e32 v145, v121, v89
	v_mul_f32_e32 v145, v137, v145
	v_mul_f32_e32 v146, v106, v98
	v_fmac_f32_e32 v146, v114, v130
	v_fmac_f32_e32 v146, v122, v90
	v_mul_f32_e32 v146, v138, v146
	v_mul_f32_e32 v147, v107, v99
	v_fmac_f32_e32 v147, v115, v131
	v_fmac_f32_e32 v147, v123, v91
	v_mul_f32_e32 v147, v139, v147
	v_cvt_pk_bf16_f32 v140, v140, v141
	v_cvt_pk_bf16_f32 v141, v142, v143
	v_cvt_pk_bf16_f32 v142, v144, v145
	v_cvt_pk_bf16_f32 v143, v146, v147
	global_store_dwordx4 v2, v[140:143], s[46:47] offset:1024
	s_add_u32 s46, s46, 0x1000
	s_addc_u32 s47, s47, 0
	global_load_dwordx4 v[24:27], v2, s[48:49] offset:2048
	global_load_dwordx4 v[56:59], v2, s[48:49] offset:3072
	s_add_u32 s48, s48, 0x1800
	s_addc_u32 s49, s49, 0
	v_lshlrev_b32_e32 v92, 16, v28
	v_and_b32_e32 v93, 0xffff0000, v28
	v_lshlrev_b32_e32 v94, 16, v29
	v_and_b32_e32 v95, 0xffff0000, v29
	v_lshlrev_b32_e32 v96, 16, v30
	v_and_b32_e32 v97, 0xffff0000, v30
	v_lshlrev_b32_e32 v98, 16, v31
	v_and_b32_e32 v99, 0xffff0000, v31
	v_lshlrev_b32_e32 v132, 16, v60
	v_and_b32_e32 v133, 0xffff0000, v60
	v_lshlrev_b32_e32 v134, 16, v61
	v_and_b32_e32 v135, 0xffff0000, v61
	v_lshlrev_b32_e32 v136, 16, v62
; #define GAS __attribute__((address_space(1)))
; __device__ __forceinline__ void unpack8(const v4u w, float (&f)[8]) { f[0] = bf_lo(w.x); f[1] = bf_hi(w.x); f[2] = bf_lo(w.y); f[3] = bf_hi(w.y); f[4] = bf_lo(w.z); f[5] = bf_hi(w.z); f[6] = bf_lo(w.w); f[7] = bf_hi(w.w); }
; __device__ __forceinline__ v4u pack8(const float (&f)[8]) { v4u w; w.x = cvt_pk_bf16(f[0], f[1]); w.y = cvt_pk_bf16(f[2], f[3]); w.z = cvt_pk_bf16(f[4], f[5]); w.w = cvt_pk_bf16(f[6], f[7]); return w; }
; __device__ __forceinline__ void mixer_shortconv(const Frame& F, const Args& A, int l, int chunk, const bf16* Z, bf16* MIX) {
;     ...
;     for (int dt = -2; dt < 16; ++dt) {
;         const int t = t0 + dt; const bool valid = (pos0 + t) >= 0;
;         const bf16* zr = Z + (size_t)(row0 + (valid ? t : 0)) * ZC;
;         float xv[8], x[8];
;         unpack8(*(const GAS v4u*)(zr + 1024 + c8), xv);
; #pragma unroll
;         for (int j = 0; j < 8; ++j) x[j] = valid ? xv[j] : 0.f;
;         if (dt >= 0) { float bg[8], o[8]; unpack8(*(const GAS v4u*)(zr + 1536 + c8), bg);
; #pragma unroll
;             for (int j = 0; j < 8; ++j) o[j] = bg[j] * (w0[j] * xm2[j] + w1[j] * xm1[j] + w2[j] * x[j]);
;             *(GAS v4u*)(MIX + (size_t)(row0 + t) * D + 512 + c8) = pack8(o); }
; #pragma unroll
;         for (int j = 0; j < 8; ++j) { xm2[j] = xm1[j]; xm1[j] = x[j]; }
;     }
	v_and_b32_e32 v137, 0xffff0000, v62
	v_lshlrev_b32_e32 v138, 16, v63
	v_and_b32_e32 v139, 0xffff0000, v63
	v_mul_f32_e32 v140, v100, v124
	v_fmac_f32_e32 v140, v108, v84
	v_fmac_f32_e32 v140, v116, v92
	v_mul_f32_e32 v140, v132, v140
	v_mul_f32_e32 v141, v101, v125
	v_fmac_f32_e32 v141, v109, v85
	v_fmac_f32_e32 v141, v117, v93
	v_mul_f32_e32 v141, v133, v141
	v_mul_f32_e32 v142, v102, v126
	v_fmac_f32_e32 v142, v110, v86
	v_fmac_f32_e32 v142, v118, v94
	v_mul_f32_e32 v142, v134, v142
	v_mul_f32_e32 v143, v103, v127
	v_fmac_f32_e32 v143, v111, v87
	v_fmac_f32_e32 v143, v119, v95
	v_mul_f32_e32 v143, v135, v143
	v_mul_f32_e32 v144, v104, v128
	v_fmac_f32_e32 v144, v112, v88
	v_fmac_f32_e32 v144, v120, v96
	v_mul_f32_e32 v144, v136, v144
	v_mul_f32_e32 v145, v105, v129
	v_fmac_f32_e32 v145, v113, v89
	v_fmac_f32_e32 v145, v121, v97
	v_mul_f32_e32 v145, v137, v145
	v_mul_f32_e32 v146, v106, v130
	v_fmac_f32_e32 v146, v114, v90
	v_fmac_f32_e32 v146, v122, v98
	v_mul_f32_e32 v146, v138, v146
	v_mul_f32_e32 v147, v107, v131
	v_fmac_f32_e32 v147, v115, v91
	v_fmac_f32_e32 v147, v123, v99
	v_mul_f32_e32 v147, v139, v147
	v_cvt_pk_bf16_f32 v140, v140, v141
	v_cvt_pk_bf16_f32 v141, v142, v143
	v_cvt_pk_bf16_f32 v142, v144, v145
	v_cvt_pk_bf16_f32 v143, v146, v147
	global_store_dwordx4 v2, v[140:143], s[46:47] offset:1024
	s_add_u32 s46, s46, 0x1000
	s_addc_u32 s47, s47, 0
	global_load_dwordx4 v[28:31], v2, s[48:49] offset:2048
	global_load_dwordx4 v[60:63], v2, s[48:49] offset:3072
	s_add_u32 s48, s48, 0x1800
	s_addc_u32 s49, s49, 0
	v_lshlrev_b32_e32 v124, 16, v32
	v_and_b32_e32 v125, 0xffff0000, v32
	v_lshlrev_b32_e32 v126, 16, v33
	v_and_b32_e32 v127, 0xffff0000, v33
	v_lshlrev_b32_e32 v128, 16, v34
	v_and_b32_e32 v129, 0xffff0000, v34
	v_lshlrev_b32_e32 v130, 16, v35
	v_and_b32_e32 v131, 0xffff0000, v35
	v_lshlrev_b32_e32 v132, 16, v64
	v_and_b32_e32 v133, 0xffff0000, v64
	v_lshlrev_b32_e32 v134, 16, v65
	v_and_b32_e32 v135, 0xffff0000, v65
	v_lshlrev_b32_e32 v136, 16, v66
	v_and_b32_e32 v137, 0xffff0000, v66
	v_lshlrev_b32_e32 v138, 16, v67
	v_and_b32_e32 v139, 0xffff0000, v67
	v_mul_f32_e32 v140, v100, v84
	v_fmac_f32_e32 v140, v108, v92
	v_fmac_f32_e32 v140, v116, v124
	v_mul_f32_e32 v140, v132, v140
	v_mul_f32_e32 v141, v101, v85
	v_fmac_f32_e32 v141, v109, v93
	v_fmac_f32_e32 v141, v117, v125
	v_mul_f32_e32 v141, v133, v141
	v_mul_f32_e32 v142, v102, v86
	v_fmac_f32_e32 v142, v110, v94
	v_fmac_f32_e32 v142, v118, v126
	v_mul_f32_e32 v142, v134, v142
	v_mul_f32_e32 v143, v103, v87
	v_fmac_f32_e32 v143, v111, v95
	v_fmac_f32_e32 v143, v119, v127
	v_mul_f32_e32 v143, v135, v143
	v_mul_f32_e32 v144, v104, v88
	v_fmac_f32_e32 v144, v112, v96
	v_fmac_f32_e32 v144, v120, v128
	v_mul_f32_e32 v144, v136, v144
	v_mul_f32_e32 v145, v105, v89
	v_fmac_f32_e32 v145, v113, v97
	v_fmac_f32_e32 v145, v121, v129
	v_mul_f32_e32 v145, v137, v145
	v_mul_f32_e32 v146, v106, v90
	v_fmac_f32_e32 v146, v114, v98
	v_fmac_f32_e32 v146, v122, v130
	v_mul_f32_e32 v146, v138, v146
	v_mul_f32_e32 v147, v107, v91
	v_fmac_f32_e32 v147, v115, v99
	v_fmac_f32_e32 v147, v123, v131
	v_mul_f32_e32 v147, v139, v147
	v_cvt_pk_bf16_f32 v140, v140, v141
	v_cvt_pk_bf16_f32 v141, v142, v143
	v_cvt_pk_bf16_f32 v142, v144, v145
	v_cvt_pk_bf16_f32 v143, v146, v147
	global_store_dwordx4 v2, v[140:143], s[46:47] offset:1024
	s_add_u32 s46, s46, 0x1000
	s_addc_u32 s47, s47, 0
	global_load_dwordx4 v[32:35], v2, s[48:49] offset:2048
	global_load_dwordx4 v[64:67], v2, s[48:49] offset:3072
	s_add_u32 s48, s48, 0x1800
	s_addc_u32 s49, s49, 0
	v_lshlrev_b32_e32 v84, 16, v36
	v_and_b32_e32 v85, 0xffff0000, v36
	v_lshlrev_b32_e32 v86, 16, v37
	v_and_b32_e32 v87, 0xffff0000, v37
	v_lshlrev_b32_e32 v88, 16, v38
	v_and_b32_e32 v89, 0xffff0000, v38
	v_lshlrev_b32_e32 v90, 16, v39
	v_and_b32_e32 v91, 0xffff0000, v39
	v_lshlrev_b32_e32 v132, 16, v68
	v_and_b32_e32 v133, 0xffff0000, v68
	v_lshlrev_b32_e32 v134, 16, v69
	v_and_b32_e32 v135, 0xffff0000, v69
	v_lshlrev_b32_e32 v136, 16, v70
	v_and_b32_e32 v137, 0xffff0000, v70
	v_lshlrev_b32_e32 v138, 16, v71
	v_and_b32_e32 v139, 0xffff0000, v71
	v_mul_f32_e32 v140, v100, v92
	v_fmac_f32_e32 v140, v108, v124
	v_fmac_f32_e32 v140, v116, v84
	v_mul_f32_e32 v140, v132, v140
	v_mul_f32_e32 v141, v101, v93
	v_fmac_f32_e32 v141, v109, v125
	v_fmac_f32_e32 v141, v117, v85
	v_mul_f32_e32 v141, v133, v141
	v_mul_f32_e32 v142, v102, v94
	v_fmac_f32_e32 v142, v110, v126
	v_fmac_f32_e32 v142, v118, v86
	v_mul_f32_e32 v142, v134, v142
	v_mul_f32_e32 v143, v103, v95
	v_fmac_f32_e32 v143, v111, v127
	v_fmac_f32_e32 v143, v119, v87
	v_mul_f32_e32 v143, v135, v143
	v_mul_f32_e32 v144, v104, v96
	v_fmac_f32_e32 v144, v112, v128
	v_fmac_f32_e32 v144, v120, v88
	v_mul_f32_e32 v144, v136, v144
	v_mul_f32_e32 v145, v105, v97
	v_fmac_f32_e32 v145, v113, v129
	v_fmac_f32_e32 v145, v121, v89
	v_mul_f32_e32 v145, v137, v145
	v_mul_f32_e32 v146, v106, v98
	v_fmac_f32_e32 v146, v114, v130
	v_fmac_f32_e32 v146, v122, v90
	v_mul_f32_e32 v146, v138, v146
	v_mul_f32_e32 v147, v107, v99
	v_fmac_f32_e32 v147, v115, v131
	v_fmac_f32_e32 v147, v123, v91
	v_mul_f32_e32 v147, v139, v147
	v_cvt_pk_bf16_f32 v140, v140, v141
	v_cvt_pk_bf16_f32 v141, v142, v143
	v_cvt_pk_bf16_f32 v142, v144, v145
	v_cvt_pk_bf16_f32 v143, v146, v147
	global_store_dwordx4 v2, v[140:143], s[46:47] offset:1024
	s_add_u32 s46, s46, 0x1000
	s_addc_u32 s47, s47, 0
	global_load_dwordx4 v[36:39], v2, s[48:49] offset:2048
	global_load_dwordx4 v[68:71], v2, s[48:49] offset:3072
	s_add_u32 s48, s48, 0x1800
	s_addc_u32 s49, s49, 0
	v_lshlrev_b32_e32 v92, 16, v40
	v_and_b32_e32 v93, 0xffff0000, v40
	v_lshlrev_b32_e32 v94, 16, v41
; #define GAS __attribute__((address_space(1)))
; __device__ __forceinline__ void unpack8(const v4u w, float (&f)[8]) { f[0] = bf_lo(w.x); f[1] = bf_hi(w.x); f[2] = bf_lo(w.y); f[3] = bf_hi(w.y); f[4] = bf_lo(w.z); f[5] = bf_hi(w.z); f[6] = bf_lo(w.w); f[7] = bf_hi(w.w); }
; __device__ __forceinline__ v4u pack8(const float (&f)[8]) { v4u w; w.x = cvt_pk_bf16(f[0], f[1]); w.y = cvt_pk_bf16(f[2], f[3]); w.z = cvt_pk_bf16(f[4], f[5]); w.w = cvt_pk_bf16(f[6], f[7]); return w; }
; __device__ __forceinline__ void mixer_shortconv(const Frame& F, const Args& A, int l, int chunk, const bf16* Z, bf16* MIX) {
;     ...
;     for (int dt = -2; dt < 16; ++dt) {
;         const int t = t0 + dt; const bool valid = (pos0 + t) >= 0;
;         const bf16* zr = Z + (size_t)(row0 + (valid ? t : 0)) * ZC;
;         float xv[8], x[8];
;         unpack8(*(const GAS v4u*)(zr + 1024 + c8), xv);
; #pragma unroll
;         for (int j = 0; j < 8; ++j) x[j] = valid ? xv[j] : 0.f;
;         if (dt >= 0) { float bg[8], o[8]; unpack8(*(const GAS v4u*)(zr + 1536 + c8), bg);
; #pragma unroll
;             for (int j = 0; j < 8; ++j) o[j] = bg[j] * (w0[j] * xm2[j] + w1[j] * xm1[j] + w2[j] * x[j]);
;             *(GAS v4u*)(MIX + (size_t)(row0 + t) * D + 512 + c8) = pack8(o); }
; #pragma unroll
;         for (int j = 0; j < 8; ++j) { xm2[j] = xm1[j]; xm1[j] = x[j]; }
;     }
; __device__ __forceinline__ void mixer_pool(const Frame& F, int l, int chunk, const bf16* Z, bf16* MIX) {
;     ...
;     const int i = lane & 15, g4 = lane >> 4, t = F.wave * 16 + i, row = chunk * 128 + t, pos = (chunk & 31) * 128 + t;
;     const bool prev_ok = ((chunk & 31) * 128 + F.wave * 16) > 0;
;     const bf16* pwt = (const bf16*)(F.ws + WS_PWT) + (size_t)l * 4 * 128 * 128 + (size_t)i * 128 + 8 * g4;
;     const bf16* zrow = Z + (size_t)row * ZC + 2560 + 8 * g4; bf16* orow = MIX + (size_t)row * D + 1536 + 4 * g4;
	v_and_b32_e32 v95, 0xffff0000, v41
	v_lshlrev_b32_e32 v96, 16, v42
	v_and_b32_e32 v97, 0xffff0000, v42
	v_lshlrev_b32_e32 v98, 16, v43
	v_and_b32_e32 v99, 0xffff0000, v43
	v_lshlrev_b32_e32 v132, 16, v72
	v_and_b32_e32 v133, 0xffff0000, v72
	v_lshlrev_b32_e32 v134, 16, v73
	v_and_b32_e32 v135, 0xffff0000, v73
	v_lshlrev_b32_e32 v136, 16, v74
	v_and_b32_e32 v137, 0xffff0000, v74
	v_lshlrev_b32_e32 v138, 16, v75
	v_and_b32_e32 v139, 0xffff0000, v75
	v_mul_f32_e32 v140, v100, v124
	v_fmac_f32_e32 v140, v108, v84
	v_fmac_f32_e32 v140, v116, v92
	v_mul_f32_e32 v140, v132, v140
	v_mul_f32_e32 v141, v101, v125
	v_fmac_f32_e32 v141, v109, v85
	v_fmac_f32_e32 v141, v117, v93
	v_mul_f32_e32 v141, v133, v141
	v_mul_f32_e32 v142, v102, v126
	v_fmac_f32_e32 v142, v110, v86
	v_fmac_f32_e32 v142, v118, v94
	v_mul_f32_e32 v142, v134, v142
	v_mul_f32_e32 v143, v103, v127
	v_fmac_f32_e32 v143, v111, v87
	v_fmac_f32_e32 v143, v119, v95
	v_mul_f32_e32 v143, v135, v143
	v_mul_f32_e32 v144, v104, v128
	v_fmac_f32_e32 v144, v112, v88
	v_fmac_f32_e32 v144, v120, v96
	v_mul_f32_e32 v144, v136, v144
	v_mul_f32_e32 v145, v105, v129
	v_fmac_f32_e32 v145, v113, v89
	v_fmac_f32_e32 v145, v121, v97
	v_mul_f32_e32 v145, v137, v145
	v_mul_f32_e32 v146, v106, v130
	v_fmac_f32_e32 v146, v114, v90
	v_fmac_f32_e32 v146, v122, v98
	v_mul_f32_e32 v146, v138, v146
	v_mul_f32_e32 v147, v107, v131
	v_fmac_f32_e32 v147, v115, v91
	v_fmac_f32_e32 v147, v123, v99
	v_mul_f32_e32 v147, v139, v147
	v_cvt_pk_bf16_f32 v140, v140, v141
	v_cvt_pk_bf16_f32 v141, v142, v143
	v_cvt_pk_bf16_f32 v142, v144, v145
	v_cvt_pk_bf16_f32 v143, v146, v147
	global_store_dwordx4 v2, v[140:143], s[46:47] offset:1024
	s_add_u32 s46, s46, 0x1000
	s_addc_u32 s47, s47, 0
	global_load_dwordx4 v[40:43], v2, s[48:49] offset:2048
	global_load_dwordx4 v[72:75], v2, s[48:49] offset:3072
	s_add_u32 s48, s48, 0x1800
	s_addc_u32 s49, s49, 0
	v_lshlrev_b32_e32 v124, 16, v44
	v_and_b32_e32 v125, 0xffff0000, v44
	v_lshlrev_b32_e32 v126, 16, v45
	v_and_b32_e32 v127, 0xffff0000, v45
	v_lshlrev_b32_e32 v128, 16, v46
	v_and_b32_e32 v129, 0xffff0000, v46
	v_lshlrev_b32_e32 v130, 16, v47
	v_and_b32_e32 v131, 0xffff0000, v47
	v_lshlrev_b32_e32 v132, 16, v76
	v_and_b32_e32 v133, 0xffff0000, v76
	v_lshlrev_b32_e32 v134, 16, v77
	v_and_b32_e32 v135, 0xffff0000, v77
	v_lshlrev_b32_e32 v136, 16, v78
	v_and_b32_e32 v137, 0xffff0000, v78
	v_lshlrev_b32_e32 v138, 16, v79
	v_and_b32_e32 v139, 0xffff0000, v79
	v_mul_f32_e32 v140, v100, v84
	v_fmac_f32_e32 v140, v108, v92
	v_fmac_f32_e32 v140, v116, v124
	v_mul_f32_e32 v140, v132, v140
	v_mul_f32_e32 v141, v101, v85
	v_fmac_f32_e32 v141, v109, v93
	v_fmac_f32_e32 v141, v117, v125
	v_mul_f32_e32 v141, v133, v141
	v_mul_f32_e32 v142, v102, v86
	v_fmac_f32_e32 v142, v110, v94
	v_fmac_f32_e32 v142, v118, v126
	v_mul_f32_e32 v142, v134, v142
	v_mul_f32_e32 v143, v103, v87
	v_fmac_f32_e32 v143, v111, v95
	v_fmac_f32_e32 v143, v119, v127
	v_mul_f32_e32 v143, v135, v143
	v_mul_f32_e32 v144, v104, v88
	v_fmac_f32_e32 v144, v112, v96
	v_fmac_f32_e32 v144, v120, v128
	v_mul_f32_e32 v144, v136, v144
	v_mul_f32_e32 v145, v105, v89
	v_fmac_f32_e32 v145, v113, v97
	v_fmac_f32_e32 v145, v121, v129
	v_mul_f32_e32 v145, v137, v145
	v_mul_f32_e32 v146, v106, v90
	v_fmac_f32_e32 v146, v114, v98
	v_fmac_f32_e32 v146, v122, v130
	v_mul_f32_e32 v146, v138, v146
	v_mul_f32_e32 v147, v107, v91
	v_fmac_f32_e32 v147, v115, v99
	v_fmac_f32_e32 v147, v123, v131
	v_mul_f32_e32 v147, v139, v147
	v_cvt_pk_bf16_f32 v140, v140, v141
	v_cvt_pk_bf16_f32 v141, v142, v143
	v_cvt_pk_bf16_f32 v142, v144, v145
	v_cvt_pk_bf16_f32 v143, v146, v147
	global_store_dwordx4 v2, v[140:143], s[46:47] offset:1024
	s_add_u32 s46, s46, 0x1000
	s_addc_u32 s47, s47, 0
	global_load_dwordx4 v[44:47], v2, s[48:49] offset:2048
	global_load_dwordx4 v[76:79], v2, s[48:49] offset:3072
	s_add_u32 s48, s48, 0x1800
	s_addc_u32 s49, s49, 0
	v_lshlrev_b32_e32 v84, 16, v48
	v_and_b32_e32 v85, 0xffff0000, v48
	v_lshlrev_b32_e32 v86, 16, v49
	v_and_b32_e32 v87, 0xffff0000, v49
	v_lshlrev_b32_e32 v88, 16, v50
	v_and_b32_e32 v89, 0xffff0000, v50
	v_lshlrev_b32_e32 v90, 16, v51
	v_and_b32_e32 v91, 0xffff0000, v51
	v_lshlrev_b32_e32 v132, 16, v80
	v_and_b32_e32 v133, 0xffff0000, v80
	v_lshlrev_b32_e32 v134, 16, v81
	v_and_b32_e32 v135, 0xffff0000, v81
	v_lshlrev_b32_e32 v136, 16, v82
	v_and_b32_e32 v137, 0xffff0000, v82
	v_lshlrev_b32_e32 v138, 16, v83
	v_and_b32_e32 v139, 0xffff0000, v83
	v_mul_f32_e32 v140, v100, v92
	v_fmac_f32_e32 v140, v108, v124
	v_fmac_f32_e32 v140, v116, v84
	v_mul_f32_e32 v140, v132, v140
	v_mul_f32_e32 v141, v101, v93
	v_fmac_f32_e32 v141, v109, v125
	v_fmac_f32_e32 v141, v117, v85
	v_mul_f32_e32 v141, v133, v141
	v_mul_f32_e32 v142, v102, v94
	v_fmac_f32_e32 v142, v110, v126
	v_fmac_f32_e32 v142, v118, v86
	v_mul_f32_e32 v142, v134, v142
	v_mul_f32_e32 v143, v103, v95
	v_fmac_f32_e32 v143, v111, v127
	v_fmac_f32_e32 v143, v119, v87
	v_mul_f32_e32 v143, v135, v143
	v_mul_f32_e32 v144, v104, v96
	v_fmac_f32_e32 v144, v112, v128
	v_fmac_f32_e32 v144, v120, v88
	v_mul_f32_e32 v144, v136, v144
	v_mul_f32_e32 v145, v105, v97
	v_fmac_f32_e32 v145, v113, v129
	v_fmac_f32_e32 v145, v121, v89
	v_mul_f32_e32 v145, v137, v145
	v_mul_f32_e32 v146, v106, v98
	v_fmac_f32_e32 v146, v114, v130
	v_fmac_f32_e32 v146, v122, v90
	v_mul_f32_e32 v146, v138, v146
	v_mul_f32_e32 v147, v107, v99
	v_fmac_f32_e32 v147, v115, v131
	v_fmac_f32_e32 v147, v123, v91
	v_mul_f32_e32 v147, v139, v147
	v_cvt_pk_bf16_f32 v140, v140, v141
	v_cvt_pk_bf16_f32 v141, v142, v143
	v_cvt_pk_bf16_f32 v142, v144, v145
	v_cvt_pk_bf16_f32 v143, v146, v147
	global_store_dwordx4 v2, v[140:143], s[46:47] offset:1024
	s_add_u32 s46, s46, 0x1000
	s_addc_u32 s47, s47, 0
	global_load_dwordx4 v[48:51], v2, s[48:49] offset:2048
	global_load_dwordx4 v[80:83], v2, s[48:49] offset:3072
	s_add_u32 s48, s48, 0x1800
	s_addc_u32 s49, s49, 0
	v_mul_u32_u24_e32 v11, 0x1800, v4
	v_lshl_add_u32 v11, v5, 4, v11
	s_add_u32 s38, s38, 0x1400
	s_addc_u32 s39, s39, 0
	s_sub_u32 s48, s38, 0x18000
	s_subb_u32 s49, s39, 0
	s_and_b64 vcc, s[40:41], exec
	s_cselect_b32 s48, s48, s38
	s_cselect_b32 s49, s49, s39
	s_waitcnt vmcnt(21)
; #define GAS __attribute__((address_space(1)))
; __device__ __forceinline__ void unpack8(const v4u w, float (&f)[8]) { f[0] = bf_lo(w.x); f[1] = bf_hi(w.x); f[2] = bf_lo(w.y); f[3] = bf_hi(w.y); f[4] = bf_lo(w.z); f[5] = bf_hi(w.z); f[6] = bf_lo(w.w); f[7] = bf_hi(w.w); }
; __device__ __forceinline__ v4u pack8(const float (&f)[8]) { v4u w; w.x = cvt_pk_bf16(f[0], f[1]); w.y = cvt_pk_bf16(f[2], f[3]); w.z = cvt_pk_bf16(f[4], f[5]); w.w = cvt_pk_bf16(f[6], f[7]); return w; }
; __device__ __forceinline__ void mixer_shortconv(const Frame& F, const Args& A, int l, int chunk, const bf16* Z, bf16* MIX) {
;     ...
;     for (int dt = -2; dt < 16; ++dt) {
;         const int t = t0 + dt; const bool valid = (pos0 + t) >= 0;
;         const bf16* zr = Z + (size_t)(row0 + (valid ? t : 0)) * ZC;
;         float xv[8], x[8];
;         unpack8(*(const GAS v4u*)(zr + 1024 + c8), xv);
; #pragma unroll
;         for (int j = 0; j < 8; ++j) x[j] = valid ? xv[j] : 0.f;
;         if (dt >= 0) { float bg[8], o[8]; unpack8(*(const GAS v4u*)(zr + 1536 + c8), bg);
; #pragma unroll
;             for (int j = 0; j < 8; ++j) o[j] = bg[j] * (w0[j] * xm2[j] + w1[j] * xm1[j] + w2[j] * x[j]);
;             *(GAS v4u*)(MIX + (size_t)(row0 + t) * D + 512 + c8) = pack8(o); }
; #pragma unroll
;         for (int j = 0; j < 8; ++j) { xm2[j] = xm1[j]; xm1[j] = x[j]; }
;     }
; template <int W> __device__ __forceinline__ void pool_group(const bf16* zrow  , const bf16* pw  , bf16* orow  , int pos, bool prev_ok) {
;     ...
;     for (int kk = 0; kk < 4; ++kk) { cw[kk] = *(const GAS v4u*)(zrow + 32 * kk); pv[kk] = prev_ok ? *(const GAS v4u*)(zrow + 32 * kk - (ptrdiff_t)16 * ZC) : (v4u){0u, 0u, 0u, 0u}; }
	v_lshlrev_b32_e32 v92, 16, v20
	v_and_b32_e32 v93, 0xffff0000, v20
	v_lshlrev_b32_e32 v94, 16, v21
	v_and_b32_e32 v95, 0xffff0000, v21
	v_lshlrev_b32_e32 v96, 16, v22
	v_and_b32_e32 v97, 0xffff0000, v22
	v_lshlrev_b32_e32 v98, 16, v23
	v_and_b32_e32 v99, 0xffff0000, v23
	v_lshlrev_b32_e32 v132, 16, v52
	v_and_b32_e32 v133, 0xffff0000, v52
	v_lshlrev_b32_e32 v134, 16, v53
	v_and_b32_e32 v135, 0xffff0000, v53
	v_lshlrev_b32_e32 v136, 16, v54
	v_and_b32_e32 v137, 0xffff0000, v54
	v_lshlrev_b32_e32 v138, 16, v55
	v_and_b32_e32 v139, 0xffff0000, v55
	v_mul_f32_e32 v140, v100, v124
	v_fmac_f32_e32 v140, v108, v84
	v_fmac_f32_e32 v140, v116, v92
	v_mul_f32_e32 v140, v132, v140
	v_mul_f32_e32 v141, v101, v125
	v_fmac_f32_e32 v141, v109, v85
	v_fmac_f32_e32 v141, v117, v93
	v_mul_f32_e32 v141, v133, v141
	v_mul_f32_e32 v142, v102, v126
	v_fmac_f32_e32 v142, v110, v86
	v_fmac_f32_e32 v142, v118, v94
	v_mul_f32_e32 v142, v134, v142
	v_mul_f32_e32 v143, v103, v127
	v_fmac_f32_e32 v143, v111, v87
	v_fmac_f32_e32 v143, v119, v95
	v_mul_f32_e32 v143, v135, v143
	v_mul_f32_e32 v144, v104, v128
	v_fmac_f32_e32 v144, v112, v88
	v_fmac_f32_e32 v144, v120, v96
	v_mul_f32_e32 v144, v136, v144
	v_mul_f32_e32 v145, v105, v129
	v_fmac_f32_e32 v145, v113, v89
	v_fmac_f32_e32 v145, v121, v97
	v_mul_f32_e32 v145, v137, v145
	v_mul_f32_e32 v146, v106, v130
	v_fmac_f32_e32 v146, v114, v90
	v_fmac_f32_e32 v146, v122, v98
	v_mul_f32_e32 v146, v138, v146
	v_mul_f32_e32 v147, v107, v131
	v_fmac_f32_e32 v147, v115, v91
	v_fmac_f32_e32 v147, v123, v99
	v_mul_f32_e32 v147, v139, v147
	v_cvt_pk_bf16_f32 v140, v140, v141
	v_cvt_pk_bf16_f32 v141, v142, v143
	v_cvt_pk_bf16_f32 v142, v144, v145
	v_cvt_pk_bf16_f32 v143, v146, v147
	global_store_dwordx4 v2, v[140:143], s[46:47] offset:1024
	s_add_u32 s46, s46, 0x1000
	s_addc_u32 s47, s47, 0
	global_load_dwordx4 v[12:15], v11, s[38:39]
	global_load_dwordx4 v[16:19], v11, s[48:49]
	s_waitcnt vmcnt(21)
	v_lshlrev_b32_e32 v124, 16, v24
	v_and_b32_e32 v125, 0xffff0000, v24
	v_lshlrev_b32_e32 v126, 16, v25
	v_and_b32_e32 v127, 0xffff0000, v25
	v_lshlrev_b32_e32 v128, 16, v26
	v_and_b32_e32 v129, 0xffff0000, v26
	v_lshlrev_b32_e32 v130, 16, v27
	v_and_b32_e32 v131, 0xffff0000, v27
	v_lshlrev_b32_e32 v132, 16, v56
	v_and_b32_e32 v133, 0xffff0000, v56
	v_lshlrev_b32_e32 v134, 16, v57
	v_and_b32_e32 v135, 0xffff0000, v57
	v_lshlrev_b32_e32 v136, 16, v58
	v_and_b32_e32 v137, 0xffff0000, v58
	v_lshlrev_b32_e32 v138, 16, v59
	v_and_b32_e32 v139, 0xffff0000, v59
	v_mul_f32_e32 v140, v100, v84
	v_fmac_f32_e32 v140, v108, v92
	v_fmac_f32_e32 v140, v116, v124
	v_mul_f32_e32 v140, v132, v140
	v_mul_f32_e32 v141, v101, v85
	v_fmac_f32_e32 v141, v109, v93
	v_fmac_f32_e32 v141, v117, v125
	v_mul_f32_e32 v141, v133, v141
	v_mul_f32_e32 v142, v102, v86
	v_fmac_f32_e32 v142, v110, v94
	v_fmac_f32_e32 v142, v118, v126
	v_mul_f32_e32 v142, v134, v142
	v_mul_f32_e32 v143, v103, v87
	v_fmac_f32_e32 v143, v111, v95
	v_fmac_f32_e32 v143, v119, v127
	v_mul_f32_e32 v143, v135, v143
	v_mul_f32_e32 v144, v104, v88
	v_fmac_f32_e32 v144, v112, v96
	v_fmac_f32_e32 v144, v120, v128
	v_mul_f32_e32 v144, v136, v144
	v_mul_f32_e32 v145, v105, v89
	v_fmac_f32_e32 v145, v113, v97
	v_fmac_f32_e32 v145, v121, v129
	v_mul_f32_e32 v145, v137, v145
	v_mul_f32_e32 v146, v106, v90
	v_fmac_f32_e32 v146, v114, v98
	v_fmac_f32_e32 v146, v122, v130
	v_mul_f32_e32 v146, v138, v146
	v_mul_f32_e32 v147, v107, v91
	v_fmac_f32_e32 v147, v115, v99
	v_fmac_f32_e32 v147, v123, v131
	v_mul_f32_e32 v147, v139, v147
	v_cvt_pk_bf16_f32 v140, v140, v141
	v_cvt_pk_bf16_f32 v141, v142, v143
	v_cvt_pk_bf16_f32 v142, v144, v145
	v_cvt_pk_bf16_f32 v143, v146, v147
	global_store_dwordx4 v2, v[140:143], s[46:47] offset:1024
	s_add_u32 s46, s46, 0x1000
	s_addc_u32 s47, s47, 0
	global_load_dwordx4 v[20:23], v11, s[38:39] offset:64
	global_load_dwordx4 v[24:27], v11, s[48:49] offset:64
	s_waitcnt vmcnt(21)
	v_lshlrev_b32_e32 v84, 16, v28
	v_and_b32_e32 v85, 0xffff0000, v28
	v_lshlrev_b32_e32 v86, 16, v29
	v_and_b32_e32 v87, 0xffff0000, v29
	v_lshlrev_b32_e32 v88, 16, v30
	v_and_b32_e32 v89, 0xffff0000, v30
	v_lshlrev_b32_e32 v90, 16, v31
	v_and_b32_e32 v91, 0xffff0000, v31
	v_lshlrev_b32_e32 v132, 16, v60
	v_and_b32_e32 v133, 0xffff0000, v60
	v_lshlrev_b32_e32 v134, 16, v61
	v_and_b32_e32 v135, 0xffff0000, v61
	v_lshlrev_b32_e32 v136, 16, v62
	v_and_b32_e32 v137, 0xffff0000, v62
	v_lshlrev_b32_e32 v138, 16, v63
	v_and_b32_e32 v139, 0xffff0000, v63
	v_mul_f32_e32 v140, v100, v92
	v_fmac_f32_e32 v140, v108, v124
	v_fmac_f32_e32 v140, v116, v84
	v_mul_f32_e32 v140, v132, v140
	v_mul_f32_e32 v141, v101, v93
	v_fmac_f32_e32 v141, v109, v125
	v_fmac_f32_e32 v141, v117, v85
	v_mul_f32_e32 v141, v133, v141
	v_mul_f32_e32 v142, v102, v94
	v_fmac_f32_e32 v142, v110, v126
	v_fmac_f32_e32 v142, v118, v86
	v_mul_f32_e32 v142, v134, v142
	v_mul_f32_e32 v143, v103, v95
	v_fmac_f32_e32 v143, v111, v127
	v_fmac_f32_e32 v143, v119, v87
	v_mul_f32_e32 v143, v135, v143
	v_mul_f32_e32 v144, v104, v96
	v_fmac_f32_e32 v144, v112, v128
	v_fmac_f32_e32 v144, v120, v88
	v_mul_f32_e32 v144, v136, v144
	v_mul_f32_e32 v145, v105, v97
	v_fmac_f32_e32 v145, v113, v129
	v_fmac_f32_e32 v145, v121, v89
	v_mul_f32_e32 v145, v137, v145
	v_mul_f32_e32 v146, v106, v98
	v_fmac_f32_e32 v146, v114, v130
	v_fmac_f32_e32 v146, v122, v90
	v_mul_f32_e32 v146, v138, v146
	v_mul_f32_e32 v147, v107, v99
	v_fmac_f32_e32 v147, v115, v131
	v_fmac_f32_e32 v147, v123, v91
	v_mul_f32_e32 v147, v139, v147
	v_cvt_pk_bf16_f32 v140, v140, v141
	v_cvt_pk_bf16_f32 v141, v142, v143
	v_cvt_pk_bf16_f32 v142, v144, v145
	v_cvt_pk_bf16_f32 v143, v146, v147
	global_store_dwordx4 v2, v[140:143], s[46:47] offset:1024
	s_add_u32 s46, s46, 0x1000
	s_addc_u32 s47, s47, 0
	s_waitcnt vmcnt(19)
; #define GAS __attribute__((address_space(1)))
; __device__ __forceinline__ void unpack8(const v4u w, float (&f)[8]) { f[0] = bf_lo(w.x); f[1] = bf_hi(w.x); f[2] = bf_lo(w.y); f[3] = bf_hi(w.y); f[4] = bf_lo(w.z); f[5] = bf_hi(w.z); f[6] = bf_lo(w.w); f[7] = bf_hi(w.w); }
; __device__ __forceinline__ v4u pack8(const float (&f)[8]) { v4u w; w.x = cvt_pk_bf16(f[0], f[1]); w.y = cvt_pk_bf16(f[2], f[3]); w.z = cvt_pk_bf16(f[4], f[5]); w.w = cvt_pk_bf16(f[6], f[7]); return w; }
; __device__ __forceinline__ void mixer_shortconv(const Frame& F, const Args& A, int l, int chunk, const bf16* Z, bf16* MIX) {
;     ...
;     for (int dt = -2; dt < 16; ++dt) {
;         const int t = t0 + dt; const bool valid = (pos0 + t) >= 0;
;         const bf16* zr = Z + (size_t)(row0 + (valid ? t : 0)) * ZC;
;         float xv[8], x[8];
;         unpack8(*(const GAS v4u*)(zr + 1024 + c8), xv);
; #pragma unroll
;         for (int j = 0; j < 8; ++j) x[j] = valid ? xv[j] : 0.f;
;         if (dt >= 0) { float bg[8], o[8]; unpack8(*(const GAS v4u*)(zr + 1536 + c8), bg);
; #pragma unroll
;             for (int j = 0; j < 8; ++j) o[j] = bg[j] * (w0[j] * xm2[j] + w1[j] * xm1[j] + w2[j] * x[j]);
;             *(GAS v4u*)(MIX + (size_t)(row0 + t) * D + 512 + c8) = pack8(o); }
; #pragma unroll
;         for (int j = 0; j < 8; ++j) { xm2[j] = xm1[j]; xm1[j] = x[j]; }
;     }
; template <int W> __device__ __forceinline__ void pool_group(const bf16* zrow  , const bf16* pw  , bf16* orow  , int pos, bool prev_ok) {
;     ...
;     for (int kk = 0; kk < 4; ++kk) { cw[kk] = *(const GAS v4u*)(zrow + 32 * kk); pv[kk] = prev_ok ? *(const GAS v4u*)(zrow + 32 * kk - (ptrdiff_t)16 * ZC) : (v4u){0u, 0u, 0u, 0u}; }
	v_lshlrev_b32_e32 v92, 16, v32
	v_and_b32_e32 v93, 0xffff0000, v32
	v_lshlrev_b32_e32 v94, 16, v33
	v_and_b32_e32 v95, 0xffff0000, v33
	v_lshlrev_b32_e32 v96, 16, v34
	v_and_b32_e32 v97, 0xffff0000, v34
	v_lshlrev_b32_e32 v98, 16, v35
	v_and_b32_e32 v99, 0xffff0000, v35
	v_lshlrev_b32_e32 v132, 16, v64
	v_and_b32_e32 v133, 0xffff0000, v64
	v_lshlrev_b32_e32 v134, 16, v65
	v_and_b32_e32 v135, 0xffff0000, v65
	v_lshlrev_b32_e32 v136, 16, v66
	v_and_b32_e32 v137, 0xffff0000, v66
	v_lshlrev_b32_e32 v138, 16, v67
	v_and_b32_e32 v139, 0xffff0000, v67
	v_mul_f32_e32 v140, v100, v124
	v_fmac_f32_e32 v140, v108, v84
	v_fmac_f32_e32 v140, v116, v92
	v_mul_f32_e32 v140, v132, v140
	v_mul_f32_e32 v141, v101, v125
	v_fmac_f32_e32 v141, v109, v85
	v_fmac_f32_e32 v141, v117, v93
	v_mul_f32_e32 v141, v133, v141
	v_mul_f32_e32 v142, v102, v126
	v_fmac_f32_e32 v142, v110, v86
	v_fmac_f32_e32 v142, v118, v94
	v_mul_f32_e32 v142, v134, v142
	v_mul_f32_e32 v143, v103, v127
	v_fmac_f32_e32 v143, v111, v87
	v_fmac_f32_e32 v143, v119, v95
	v_mul_f32_e32 v143, v135, v143
	v_mul_f32_e32 v144, v104, v128
	v_fmac_f32_e32 v144, v112, v88
	v_fmac_f32_e32 v144, v120, v96
	v_mul_f32_e32 v144, v136, v144
	v_mul_f32_e32 v145, v105, v129
	v_fmac_f32_e32 v145, v113, v89
	v_fmac_f32_e32 v145, v121, v97
	v_mul_f32_e32 v145, v137, v145
	v_mul_f32_e32 v146, v106, v130
	v_fmac_f32_e32 v146, v114, v90
	v_fmac_f32_e32 v146, v122, v98
	v_mul_f32_e32 v146, v138, v146
	v_mul_f32_e32 v147, v107, v131
	v_fmac_f32_e32 v147, v115, v91
	v_fmac_f32_e32 v147, v123, v99
	v_mul_f32_e32 v147, v139, v147
	v_cvt_pk_bf16_f32 v140, v140, v141
	v_cvt_pk_bf16_f32 v141, v142, v143
	v_cvt_pk_bf16_f32 v142, v144, v145
	v_cvt_pk_bf16_f32 v143, v146, v147
	global_store_dwordx4 v2, v[140:143], s[46:47] offset:1024
	s_add_u32 s46, s46, 0x1000
	s_addc_u32 s47, s47, 0
	global_load_dwordx4 v[28:31], v11, s[38:39] offset:128
	global_load_dwordx4 v[32:35], v11, s[48:49] offset:128
	s_waitcnt vmcnt(19)
	v_lshlrev_b32_e32 v124, 16, v36
	v_and_b32_e32 v125, 0xffff0000, v36
	v_lshlrev_b32_e32 v126, 16, v37
	v_and_b32_e32 v127, 0xffff0000, v37
	v_lshlrev_b32_e32 v128, 16, v38
	v_and_b32_e32 v129, 0xffff0000, v38
	v_lshlrev_b32_e32 v130, 16, v39
	v_and_b32_e32 v131, 0xffff0000, v39
	v_lshlrev_b32_e32 v132, 16, v68
	v_and_b32_e32 v133, 0xffff0000, v68
	v_lshlrev_b32_e32 v134, 16, v69
	v_and_b32_e32 v135, 0xffff0000, v69
	v_lshlrev_b32_e32 v136, 16, v70
	v_and_b32_e32 v137, 0xffff0000, v70
	v_lshlrev_b32_e32 v138, 16, v71
	v_and_b32_e32 v139, 0xffff0000, v71
	v_mul_f32_e32 v140, v100, v84
	v_fmac_f32_e32 v140, v108, v92
	v_fmac_f32_e32 v140, v116, v124
	v_mul_f32_e32 v140, v132, v140
	v_mul_f32_e32 v141, v101, v85
	v_fmac_f32_e32 v141, v109, v93
	v_fmac_f32_e32 v141, v117, v125
	v_mul_f32_e32 v141, v133, v141
	v_mul_f32_e32 v142, v102, v86
	v_fmac_f32_e32 v142, v110, v94
	v_fmac_f32_e32 v142, v118, v126
	v_mul_f32_e32 v142, v134, v142
	v_mul_f32_e32 v143, v103, v87
	v_fmac_f32_e32 v143, v111, v95
	v_fmac_f32_e32 v143, v119, v127
	v_mul_f32_e32 v143, v135, v143
	v_mul_f32_e32 v144, v104, v88
	v_fmac_f32_e32 v144, v112, v96
	v_fmac_f32_e32 v144, v120, v128
	v_mul_f32_e32 v144, v136, v144
	v_mul_f32_e32 v145, v105, v89
	v_fmac_f32_e32 v145, v113, v97
	v_fmac_f32_e32 v145, v121, v129
	v_mul_f32_e32 v145, v137, v145
	v_mul_f32_e32 v146, v106, v90
	v_fmac_f32_e32 v146, v114, v98
	v_fmac_f32_e32 v146, v122, v130
	v_mul_f32_e32 v146, v138, v146
	v_mul_f32_e32 v147, v107, v91
	v_fmac_f32_e32 v147, v115, v99
	v_fmac_f32_e32 v147, v123, v131
	v_mul_f32_e32 v147, v139, v147
	v_cvt_pk_bf16_f32 v140, v140, v141
	v_cvt_pk_bf16_f32 v141, v142, v143
	v_cvt_pk_bf16_f32 v142, v144, v145
	v_cvt_pk_bf16_f32 v143, v146, v147
	global_store_dwordx4 v2, v[140:143], s[46:47] offset:1024
	s_add_u32 s46, s46, 0x1000
	s_addc_u32 s47, s47, 0
	s_waitcnt vmcnt(17)
	v_lshlrev_b32_e32 v84, 16, v40
	v_and_b32_e32 v85, 0xffff0000, v40
	v_lshlrev_b32_e32 v86, 16, v41
	v_and_b32_e32 v87, 0xffff0000, v41
	v_lshlrev_b32_e32 v88, 16, v42
	v_and_b32_e32 v89, 0xffff0000, v42
	v_lshlrev_b32_e32 v90, 16, v43
	v_and_b32_e32 v91, 0xffff0000, v43
	v_lshlrev_b32_e32 v132, 16, v72
	v_and_b32_e32 v133, 0xffff0000, v72
	v_lshlrev_b32_e32 v134, 16, v73
	v_and_b32_e32 v135, 0xffff0000, v73
	v_lshlrev_b32_e32 v136, 16, v74
	v_and_b32_e32 v137, 0xffff0000, v74
	v_lshlrev_b32_e32 v138, 16, v75
	v_and_b32_e32 v139, 0xffff0000, v75
	v_mul_f32_e32 v140, v100, v92
	v_fmac_f32_e32 v140, v108, v124
	v_fmac_f32_e32 v140, v116, v84
	v_mul_f32_e32 v140, v132, v140
	v_mul_f32_e32 v141, v101, v93
	v_fmac_f32_e32 v141, v109, v125
	v_fmac_f32_e32 v141, v117, v85
	v_mul_f32_e32 v141, v133, v141
	v_mul_f32_e32 v142, v102, v94
	v_fmac_f32_e32 v142, v110, v126
	v_fmac_f32_e32 v142, v118, v86
	v_mul_f32_e32 v142, v134, v142
	v_mul_f32_e32 v143, v103, v95
	v_fmac_f32_e32 v143, v111, v127
	v_fmac_f32_e32 v143, v119, v87
	v_mul_f32_e32 v143, v135, v143
	v_mul_f32_e32 v144, v104, v96
	v_fmac_f32_e32 v144, v112, v128
	v_fmac_f32_e32 v144, v120, v88
	v_mul_f32_e32 v144, v136, v144
	v_mul_f32_e32 v145, v105, v97
	v_fmac_f32_e32 v145, v113, v129
	v_fmac_f32_e32 v145, v121, v89
	v_mul_f32_e32 v145, v137, v145
	v_mul_f32_e32 v146, v106, v98
	v_fmac_f32_e32 v146, v114, v130
	v_fmac_f32_e32 v146, v122, v90
	v_mul_f32_e32 v146, v138, v146
	v_mul_f32_e32 v147, v107, v99
	v_fmac_f32_e32 v147, v115, v131
	v_fmac_f32_e32 v147, v123, v91
	v_mul_f32_e32 v147, v139, v147
	v_cvt_pk_bf16_f32 v140, v140, v141
	v_cvt_pk_bf16_f32 v141, v142, v143
	v_cvt_pk_bf16_f32 v142, v144, v145
	v_cvt_pk_bf16_f32 v143, v146, v147
	global_store_dwordx4 v2, v[140:143], s[46:47] offset:1024
	s_add_u32 s46, s46, 0x1000
	s_addc_u32 s47, s47, 0
	global_load_dwordx4 v[36:39], v11, s[38:39] offset:192
	global_load_dwordx4 v[40:43], v11, s[48:49] offset:192
	s_waitcnt vmcnt(17)
; #define GAS __attribute__((address_space(1)))
; __device__ __forceinline__ v4u pack8(const float (&f)[8]) { v4u w; w.x = cvt_pk_bf16(f[0], f[1]); w.y = cvt_pk_bf16(f[2], f[3]); w.z = cvt_pk_bf16(f[4], f[5]); w.w = cvt_pk_bf16(f[6], f[7]); return w; }
; __device__ __forceinline__ void mixer_shortconv(const Frame& F, const Args& A, int l, int chunk, const bf16* Z, bf16* MIX) {
;     ...
;             for (int j = 0; j < 8; ++j) o[j] = bg[j] * (w0[j] * xm2[j] + w1[j] * xm1[j] + w2[j] * x[j]);
;             *(GAS v4u*)(MIX + (size_t)(row0 + t) * D + 512 + c8) = pack8(o); }
; template <int W> __device__ __forceinline__ void pool_group(const bf16* zrow  , const bf16* pw  , bf16* orow  , int pos, bool prev_ok) {
;     const float inv = 1.0f / (float)((pos + 1) < W ? (pos + 1) : W);
;     f32x4 acc[8];
; #pragma unroll
;     for (int dt = 0; dt < 8; ++dt) acc[dt] = (f32x4){0.f, 0.f, 0.f, 0.f};
;     v4u cw[4], pv[4], aw[2][8];
; #pragma unroll
;     for (int kk = 0; kk < 4; ++kk) { cw[kk] = *(const GAS v4u*)(zrow + 32 * kk); pv[kk] = prev_ok ? *(const GAS v4u*)(zrow + 32 * kk - (ptrdiff_t)16 * ZC) : (v4u){0u, 0u, 0u, 0u}; }
; #pragma unroll
;     for (int dt = 0; dt < 8; ++dt) aw[0][dt] = *(const GAS v4u*)(pw + (size_t)16 * dt * 128);
	v_lshlrev_b32_e32 v92, 16, v44
	v_and_b32_e32 v93, 0xffff0000, v44
	v_lshlrev_b32_e32 v94, 16, v45
	v_and_b32_e32 v95, 0xffff0000, v45
	v_lshlrev_b32_e32 v96, 16, v46
	v_and_b32_e32 v97, 0xffff0000, v46
	v_lshlrev_b32_e32 v98, 16, v47
	v_and_b32_e32 v99, 0xffff0000, v47
	v_lshlrev_b32_e32 v132, 16, v76
	v_and_b32_e32 v133, 0xffff0000, v76
	v_lshlrev_b32_e32 v134, 16, v77
	v_and_b32_e32 v135, 0xffff0000, v77
	v_lshlrev_b32_e32 v136, 16, v78
	v_and_b32_e32 v137, 0xffff0000, v78
	v_lshlrev_b32_e32 v138, 16, v79
	v_and_b32_e32 v139, 0xffff0000, v79
	v_mul_f32_e32 v140, v100, v124
	v_fmac_f32_e32 v140, v108, v84
	v_fmac_f32_e32 v140, v116, v92
	v_mul_f32_e32 v140, v132, v140
	v_mul_f32_e32 v141, v101, v125
	v_fmac_f32_e32 v141, v109, v85
	v_fmac_f32_e32 v141, v117, v93
	v_mul_f32_e32 v141, v133, v141
	v_mul_f32_e32 v142, v102, v126
	v_fmac_f32_e32 v142, v110, v86
	v_fmac_f32_e32 v142, v118, v94
	v_mul_f32_e32 v142, v134, v142
	v_mul_f32_e32 v143, v103, v127
	v_fmac_f32_e32 v143, v111, v87
	v_fmac_f32_e32 v143, v119, v95
	v_mul_f32_e32 v143, v135, v143
	v_mul_f32_e32 v144, v104, v128
	v_fmac_f32_e32 v144, v112, v88
	v_fmac_f32_e32 v144, v120, v96
	v_mul_f32_e32 v144, v136, v144
	v_mul_f32_e32 v145, v105, v129
	v_fmac_f32_e32 v145, v113, v89
	v_fmac_f32_e32 v145, v121, v97
	v_mul_f32_e32 v145, v137, v145
	v_mul_f32_e32 v146, v106, v130
	v_fmac_f32_e32 v146, v114, v90
	v_fmac_f32_e32 v146, v122, v98
	v_mul_f32_e32 v146, v138, v146
	v_mul_f32_e32 v147, v107, v131
	v_fmac_f32_e32 v147, v115, v91
	v_fmac_f32_e32 v147, v123, v99
	v_mul_f32_e32 v147, v139, v147
	v_cvt_pk_bf16_f32 v140, v140, v141
	v_cvt_pk_bf16_f32 v141, v142, v143
	v_cvt_pk_bf16_f32 v142, v144, v145
	v_cvt_pk_bf16_f32 v143, v146, v147
	global_store_dwordx4 v2, v[140:143], s[46:47] offset:1024
	s_add_u32 s46, s46, 0x1000
	s_addc_u32 s47, s47, 0
	s_waitcnt vmcnt(15)
	v_lshlrev_b32_e32 v124, 16, v48
	v_and_b32_e32 v125, 0xffff0000, v48
	v_lshlrev_b32_e32 v126, 16, v49
	v_and_b32_e32 v127, 0xffff0000, v49
	v_lshlrev_b32_e32 v128, 16, v50
	v_and_b32_e32 v129, 0xffff0000, v50
	v_lshlrev_b32_e32 v130, 16, v51
	v_and_b32_e32 v131, 0xffff0000, v51
	v_lshlrev_b32_e32 v132, 16, v80
	v_and_b32_e32 v133, 0xffff0000, v80
	v_lshlrev_b32_e32 v134, 16, v81
	v_and_b32_e32 v135, 0xffff0000, v81
	v_lshlrev_b32_e32 v136, 16, v82
	v_and_b32_e32 v137, 0xffff0000, v82
	v_lshlrev_b32_e32 v138, 16, v83
	v_and_b32_e32 v139, 0xffff0000, v83
	v_mul_f32_e32 v140, v100, v84
	v_fmac_f32_e32 v140, v108, v92
	v_fmac_f32_e32 v140, v116, v124
	v_mul_f32_e32 v140, v132, v140
	v_mul_f32_e32 v141, v101, v85
	v_fmac_f32_e32 v141, v109, v93
	v_fmac_f32_e32 v141, v117, v125
	v_mul_f32_e32 v141, v133, v141
	v_mul_f32_e32 v142, v102, v86
	v_fmac_f32_e32 v142, v110, v94
	v_fmac_f32_e32 v142, v118, v126
	v_mul_f32_e32 v142, v134, v142
	v_mul_f32_e32 v143, v103, v87
	v_fmac_f32_e32 v143, v111, v95
	v_fmac_f32_e32 v143, v119, v127
	v_mul_f32_e32 v143, v135, v143
	v_mul_f32_e32 v144, v104, v88
	v_fmac_f32_e32 v144, v112, v96
	v_fmac_f32_e32 v144, v120, v128
	v_mul_f32_e32 v144, v136, v144
	v_mul_f32_e32 v145, v105, v89
	v_fmac_f32_e32 v145, v113, v97
	v_fmac_f32_e32 v145, v121, v129
	v_mul_f32_e32 v145, v137, v145
	v_mul_f32_e32 v146, v106, v90
	v_fmac_f32_e32 v146, v114, v98
	v_fmac_f32_e32 v146, v122, v130
	v_mul_f32_e32 v146, v138, v146
	v_mul_f32_e32 v147, v107, v91
	v_fmac_f32_e32 v147, v115, v99
	v_fmac_f32_e32 v147, v123, v131
	v_mul_f32_e32 v147, v139, v147
	v_cvt_pk_bf16_f32 v140, v140, v141
	v_cvt_pk_bf16_f32 v141, v142, v143
	v_cvt_pk_bf16_f32 v142, v144, v145
	v_cvt_pk_bf16_f32 v143, v146, v147
	global_store_dwordx4 v2, v[140:143], s[46:47] offset:1024
	s_add_u32 s46, s46, 0x1000
	s_addc_u32 s47, s47, 0
	ds_write_b32 v154, v152
	ds_write_b32 v154, v153 offset:2304
	s_waitcnt lgkmcnt(0)
	s_barrier
	v_lshlrev_b32_e32 v142, 12, v4
	v_lshl_add_u32 v142, v5, 3, v142
	v_or_b32_e32 v10, 0, v5
	v_xor_b32_e32 v10, v4, v10
	v_lshlrev_b32_e32 v10, 4, v10
	v_lshl_add_u32 v143, v4, 8, v10
	v_or_b32_e32 v10, 4, v5
	v_xor_b32_e32 v10, v4, v10
	v_lshlrev_b32_e32 v10, 4, v10
	v_lshl_add_u32 v144, v4, 8, v10
	v_or_b32_e32 v10, 8, v5
	v_xor_b32_e32 v10, v4, v10
	v_lshlrev_b32_e32 v10, 4, v10
	v_lshl_add_u32 v145, v4, 8, v10
	v_or_b32_e32 v10, 12, v5
	v_xor_b32_e32 v10, v4, v10
	v_lshlrev_b32_e32 v10, 4, v10
	v_lshl_add_u32 v146, v4, 8, v10
	s_add_i32 s37, s4, s56
	v_add_u32_e32 v140, s37, v4
	v_add_u32_e32 v140, 1, v140
	s_add_u32 s46, s2, s84
	s_addc_u32 s47, s3, 0
	s_add_u32 s46, s46, 0xc00
	s_addc_u32 s47, s47, 0
	v_min_i32_e32 v139, 2, v140
	v_cvt_f32_i32_e32 v139, v139
	v_div_scale_f32 v1, s[42:43], v139, v139, 1.0
	v_rcp_f32_e32 v2, v1
	s_nop 0
	v_fma_f32 v7, -v1, v2, 1.0
	v_fmac_f32_e32 v2, v7, v2
	v_div_scale_f32 v3, vcc, 1.0, v139, 1.0
	v_mul_f32_e32 v6, v3, v2
	v_fma_f32 v7, -v1, v6, v3
	v_fmac_f32_e32 v6, v7, v2
	v_fma_f32 v1, -v1, v6, v3
	s_nop 1
	v_div_fmas_f32 v1, v1, v2, v6
	v_div_fixup_f32 v138, v1, v139, 1.0
	v_add_u32_e32 v147, 0, v143
	ds_read_b128 v[44:47], v147
	ds_read_b128 v[48:51], v147 offset:4096
	ds_read_b128 v[52:55], v147 offset:8192
	ds_read_b128 v[56:59], v147 offset:12288
	ds_read_b128 v[60:63], v147 offset:16384
	ds_read_b128 v[64:67], v147 offset:20480
	ds_read_b128 v[68:71], v147 offset:24576
	ds_read_b128 v[72:75], v147 offset:28672
	s_waitcnt vmcnt(13)
; #define GAS __attribute__((address_space(1)))
; __device__ __forceinline__ void unpack8(const v4u w, float (&f)[8]) { f[0] = bf_lo(w.x); f[1] = bf_hi(w.x); f[2] = bf_lo(w.y); f[3] = bf_hi(w.y); f[4] = bf_lo(w.z); f[5] = bf_hi(w.z); f[6] = bf_lo(w.w); f[7] = bf_hi(w.w); }
; __device__ __forceinline__ v4u pack8(const float (&f)[8]) { v4u w; w.x = cvt_pk_bf16(f[0], f[1]); w.y = cvt_pk_bf16(f[2], f[3]); w.z = cvt_pk_bf16(f[4], f[5]); w.w = cvt_pk_bf16(f[6], f[7]); return w; }
; template <int SH> __device__ __forceinline__ float row_shr(float v) { return __int_as_float(__builtin_amdgcn_update_dpp(0, __float_as_int(v), 0x110 + SH, 0xf, 0xf, true)); }
; template <int SH> __device__ __forceinline__ float row_shl(float v) { return __int_as_float(__builtin_amdgcn_update_dpp(0, __float_as_int(v), 0x100 + SH, 0xf, 0xf, true)); }
; template <int S> __device__ __forceinline__ void win_step(float (&c)[8], float (&p)[8]) {
; #pragma unroll
;     for (int j = 0; j < 8; ++j) { const float cn = c[j] + row_shr<S>(c[j]) + row_shl<16 - S>(p[j]); p[j] += row_shr<S>(p[j]); c[j] = cn; }
; }
; template <int W> __device__ __forceinline__ void pool_group(const bf16* zrow  , const bf16* pw  , bf16* orow  , int pos, bool prev_ok) {
;     ...
;     for (int kk = 0; kk < 4; ++kk) {
;         if (kk < 3) {
; #pragma unroll
;             for (int dt = 0; dt < 8; ++dt) aw[(kk + 1) & 1][dt] = *(const GAS v4u*)(pw + (size_t)16 * dt * 128 + 32 * (kk + 1)); }
;         float own[8], c[8], p[8];
;         unpack8(cw[kk], own); unpack8(pv[kk], p);
; #pragma unroll
;         for (int j = 0; j < 8; ++j) c[j] = own[j];
;         win_step<1>(c, p);
;         if (W >= 4) win_step<2>(c, p);
;         if (W >= 8) win_step<4>(c, p);
;         if (W >= 16) win_step<8>(c, p);
;         float pl[8];
; #pragma unroll
;         for (int j = 0; j < 8; ++j) pl[j] = c[j] * inv - own[j];
;         const v4u pwk = pack8(pl); const bf16x8 pf = __builtin_bit_cast(bf16x8, pwk);
; #pragma unroll
;         for (int dt = 0; dt < 8; ++dt) acc[dt] = __builtin_amdgcn_mfma_f32_16x16x32_bf16(__builtin_bit_cast(bf16x8, aw[kk & 1][dt]), pf, acc[dt], 0, 0, 0);
;     }
	v_lshlrev_b32_e32 v108, 16, v12
	v_and_b32_e32 v109, 0xffff0000, v12
	v_lshlrev_b32_e32 v110, 16, v13
	v_and_b32_e32 v111, 0xffff0000, v13
	v_lshlrev_b32_e32 v112, 16, v14
	v_and_b32_e32 v113, 0xffff0000, v14
	v_lshlrev_b32_e32 v114, 16, v15
	v_and_b32_e32 v115, 0xffff0000, v15
	v_lshlrev_b32_e32 v124, 16, v16
	v_and_b32_e32 v125, 0xffff0000, v16
	v_lshlrev_b32_e32 v126, 16, v17
	v_and_b32_e32 v127, 0xffff0000, v17
	v_lshlrev_b32_e32 v128, 16, v18
	v_and_b32_e32 v129, 0xffff0000, v18
	v_lshlrev_b32_e32 v130, 16, v19
	v_and_b32_e32 v131, 0xffff0000, v19
	v_cndmask_b32_e64 v124, 0, v124, s[40:41]
	v_cndmask_b32_e64 v125, 0, v125, s[40:41]
	v_cndmask_b32_e64 v126, 0, v126, s[40:41]
	v_cndmask_b32_e64 v127, 0, v127, s[40:41]
	v_cndmask_b32_e64 v128, 0, v128, s[40:41]
	v_cndmask_b32_e64 v129, 0, v129, s[40:41]
	v_cndmask_b32_e64 v130, 0, v130, s[40:41]
	v_cndmask_b32_e64 v131, 0, v131, s[40:41]
	global_load_dwordx4 v[12:15], v11, s[38:39] offset:256
	global_load_dwordx4 v[16:19], v11, s[48:49] offset:256
	v_mov_b32_e32 v116, v108
	v_mov_b32_e32 v117, v109
	v_mov_b32_e32 v118, v110
	v_mov_b32_e32 v119, v111
	v_mov_b32_e32 v120, v112
	v_mov_b32_e32 v121, v113
	v_mov_b32_e32 v122, v114
	v_mov_b32_e32 v123, v115
	v_add_f32_dpp v132, v116, v116 row_shr:1 row_mask:0xf bank_mask:0xf bound_ctrl:1
	v_add_f32_dpp v116, v124, v132 row_shl:15 row_mask:0xf bank_mask:0xf bound_ctrl:1
	v_add_f32_dpp v124, v124, v124 row_shr:1 row_mask:0xf bank_mask:0xf bound_ctrl:1
	v_add_f32_dpp v132, v117, v117 row_shr:1 row_mask:0xf bank_mask:0xf bound_ctrl:1
	v_add_f32_dpp v117, v125, v132 row_shl:15 row_mask:0xf bank_mask:0xf bound_ctrl:1
	v_add_f32_dpp v125, v125, v125 row_shr:1 row_mask:0xf bank_mask:0xf bound_ctrl:1
	v_add_f32_dpp v132, v118, v118 row_shr:1 row_mask:0xf bank_mask:0xf bound_ctrl:1
	v_add_f32_dpp v118, v126, v132 row_shl:15 row_mask:0xf bank_mask:0xf bound_ctrl:1
	v_add_f32_dpp v126, v126, v126 row_shr:1 row_mask:0xf bank_mask:0xf bound_ctrl:1
	v_add_f32_dpp v132, v119, v119 row_shr:1 row_mask:0xf bank_mask:0xf bound_ctrl:1
	v_add_f32_dpp v119, v127, v132 row_shl:15 row_mask:0xf bank_mask:0xf bound_ctrl:1
	v_add_f32_dpp v127, v127, v127 row_shr:1 row_mask:0xf bank_mask:0xf bound_ctrl:1
	v_add_f32_dpp v132, v120, v120 row_shr:1 row_mask:0xf bank_mask:0xf bound_ctrl:1
	v_add_f32_dpp v120, v128, v132 row_shl:15 row_mask:0xf bank_mask:0xf bound_ctrl:1
	v_add_f32_dpp v128, v128, v128 row_shr:1 row_mask:0xf bank_mask:0xf bound_ctrl:1
	v_add_f32_dpp v132, v121, v121 row_shr:1 row_mask:0xf bank_mask:0xf bound_ctrl:1
	v_add_f32_dpp v121, v129, v132 row_shl:15 row_mask:0xf bank_mask:0xf bound_ctrl:1
	v_add_f32_dpp v129, v129, v129 row_shr:1 row_mask:0xf bank_mask:0xf bound_ctrl:1
	v_add_f32_dpp v132, v122, v122 row_shr:1 row_mask:0xf bank_mask:0xf bound_ctrl:1
	v_add_f32_dpp v122, v130, v132 row_shl:15 row_mask:0xf bank_mask:0xf bound_ctrl:1
	v_add_f32_dpp v130, v130, v130 row_shr:1 row_mask:0xf bank_mask:0xf bound_ctrl:1
	v_add_f32_dpp v132, v123, v123 row_shr:1 row_mask:0xf bank_mask:0xf bound_ctrl:1
	v_add_f32_dpp v123, v131, v132 row_shl:15 row_mask:0xf bank_mask:0xf bound_ctrl:1
	v_add_f32_dpp v131, v131, v131 row_shr:1 row_mask:0xf bank_mask:0xf bound_ctrl:1
	v_fma_f32 v116, v116, v138, -v108
	v_fma_f32 v117, v117, v138, -v109
	v_fma_f32 v118, v118, v138, -v110
	v_fma_f32 v119, v119, v138, -v111
	v_fma_f32 v120, v120, v138, -v112
	v_fma_f32 v121, v121, v138, -v113
	v_fma_f32 v122, v122, v138, -v114
	v_fma_f32 v123, v123, v138, -v115
	v_cvt_pk_bf16_f32 v134, v116, v117
	v_cvt_pk_bf16_f32 v135, v118, v119
	v_cvt_pk_bf16_f32 v136, v120, v121
	v_cvt_pk_bf16_f32 v137, v122, v123
	s_waitcnt lgkmcnt(0)
	s_nop 0
	v_mfma_f32_16x16x32_bf16 v[76:79], v[44:47], v[134:137], 0
	v_mfma_f32_16x16x32_bf16 v[80:83], v[48:51], v[134:137], 0
	v_mfma_f32_16x16x32_bf16 v[84:87], v[52:55], v[134:137], 0
	v_mfma_f32_16x16x32_bf16 v[88:91], v[56:59], v[134:137], 0
	v_mfma_f32_16x16x32_bf16 v[92:95], v[60:63], v[134:137], 0
	v_mfma_f32_16x16x32_bf16 v[96:99], v[64:67], v[134:137], 0
	v_mfma_f32_16x16x32_bf16 v[100:103], v[68:71], v[134:137], 0
	v_mfma_f32_16x16x32_bf16 v[104:107], v[72:75], v[134:137], 0
	v_add_u32_e32 v147, 0, v144
	ds_read_b128 v[44:47], v147
	ds_read_b128 v[48:51], v147 offset:4096
	ds_read_b128 v[52:55], v147 offset:8192
	ds_read_b128 v[56:59], v147 offset:12288
	ds_read_b128 v[60:63], v147 offset:16384
	ds_read_b128 v[64:67], v147 offset:20480
	ds_read_b128 v[68:71], v147 offset:24576
	ds_read_b128 v[72:75], v147 offset:28672
	s_waitcnt vmcnt(12)
; #define GAS __attribute__((address_space(1)))
; __device__ __forceinline__ void unpack8(const v4u w, float (&f)[8]) { f[0] = bf_lo(w.x); f[1] = bf_hi(w.x); f[2] = bf_lo(w.y); f[3] = bf_hi(w.y); f[4] = bf_lo(w.z); f[5] = bf_hi(w.z); f[6] = bf_lo(w.w); f[7] = bf_hi(w.w); }
; __device__ __forceinline__ v4u pack8(const float (&f)[8]) { v4u w; w.x = cvt_pk_bf16(f[0], f[1]); w.y = cvt_pk_bf16(f[2], f[3]); w.z = cvt_pk_bf16(f[4], f[5]); w.w = cvt_pk_bf16(f[6], f[7]); return w; }
; template <int SH> __device__ __forceinline__ float row_shr(float v) { return __int_as_float(__builtin_amdgcn_update_dpp(0, __float_as_int(v), 0x110 + SH, 0xf, 0xf, true)); }
; template <int SH> __device__ __forceinline__ float row_shl(float v) { return __int_as_float(__builtin_amdgcn_update_dpp(0, __float_as_int(v), 0x100 + SH, 0xf, 0xf, true)); }
; template <int S> __device__ __forceinline__ void win_step(float (&c)[8], float (&p)[8]) {
; #pragma unroll
;     for (int j = 0; j < 8; ++j) { const float cn = c[j] + row_shr<S>(c[j]) + row_shl<16 - S>(p[j]); p[j] += row_shr<S>(p[j]); c[j] = cn; }
; }
; template <int W> __device__ __forceinline__ void pool_group(const bf16* zrow  , const bf16* pw  , bf16* orow  , int pos, bool prev_ok) {
;     ...
;     for (int kk = 0; kk < 4; ++kk) {
;         if (kk < 3) {
; #pragma unroll
;             for (int dt = 0; dt < 8; ++dt) aw[(kk + 1) & 1][dt] = *(const GAS v4u*)(pw + (size_t)16 * dt * 128 + 32 * (kk + 1)); }
;         float own[8], c[8], p[8];
;         unpack8(cw[kk], own); unpack8(pv[kk], p);
; #pragma unroll
;         for (int j = 0; j < 8; ++j) c[j] = own[j];
;         win_step<1>(c, p);
;         if (W >= 4) win_step<2>(c, p);
;         if (W >= 8) win_step<4>(c, p);
;         if (W >= 16) win_step<8>(c, p);
;         float pl[8];
; #pragma unroll
;         for (int j = 0; j < 8; ++j) pl[j] = c[j] * inv - own[j];
;         const v4u pwk = pack8(pl); const bf16x8 pf = __builtin_bit_cast(bf16x8, pwk);
; #pragma unroll
;         for (int dt = 0; dt < 8; ++dt) acc[dt] = __builtin_amdgcn_mfma_f32_16x16x32_bf16(__builtin_bit_cast(bf16x8, aw[kk & 1][dt]), pf, acc[dt], 0, 0, 0);
;     }
	v_lshlrev_b32_e32 v108, 16, v20
	v_and_b32_e32 v109, 0xffff0000, v20
	v_lshlrev_b32_e32 v110, 16, v21
	v_and_b32_e32 v111, 0xffff0000, v21
	v_lshlrev_b32_e32 v112, 16, v22
	v_and_b32_e32 v113, 0xffff0000, v22
	v_lshlrev_b32_e32 v114, 16, v23
	v_and_b32_e32 v115, 0xffff0000, v23
	v_lshlrev_b32_e32 v124, 16, v24
	v_and_b32_e32 v125, 0xffff0000, v24
	v_lshlrev_b32_e32 v126, 16, v25
	v_and_b32_e32 v127, 0xffff0000, v25
	v_lshlrev_b32_e32 v128, 16, v26
	v_and_b32_e32 v129, 0xffff0000, v26
	v_lshlrev_b32_e32 v130, 16, v27
	v_and_b32_e32 v131, 0xffff0000, v27
	v_cndmask_b32_e64 v124, 0, v124, s[40:41]
	v_cndmask_b32_e64 v125, 0, v125, s[40:41]
	v_cndmask_b32_e64 v126, 0, v126, s[40:41]
	v_cndmask_b32_e64 v127, 0, v127, s[40:41]
	v_cndmask_b32_e64 v128, 0, v128, s[40:41]
	v_cndmask_b32_e64 v129, 0, v129, s[40:41]
	v_cndmask_b32_e64 v130, 0, v130, s[40:41]
	v_cndmask_b32_e64 v131, 0, v131, s[40:41]
	global_load_dwordx4 v[20:23], v11, s[38:39] offset:320
	global_load_dwordx4 v[24:27], v11, s[48:49] offset:320
	v_mov_b32_e32 v116, v108
	v_mov_b32_e32 v117, v109
	v_mov_b32_e32 v118, v110
	v_mov_b32_e32 v119, v111
	v_mov_b32_e32 v120, v112
	v_mov_b32_e32 v121, v113
	v_mov_b32_e32 v122, v114
	v_mov_b32_e32 v123, v115
	v_add_f32_dpp v132, v116, v116 row_shr:1 row_mask:0xf bank_mask:0xf bound_ctrl:1
	v_add_f32_dpp v116, v124, v132 row_shl:15 row_mask:0xf bank_mask:0xf bound_ctrl:1
	v_add_f32_dpp v124, v124, v124 row_shr:1 row_mask:0xf bank_mask:0xf bound_ctrl:1
	v_add_f32_dpp v132, v117, v117 row_shr:1 row_mask:0xf bank_mask:0xf bound_ctrl:1
	v_add_f32_dpp v117, v125, v132 row_shl:15 row_mask:0xf bank_mask:0xf bound_ctrl:1
	v_add_f32_dpp v125, v125, v125 row_shr:1 row_mask:0xf bank_mask:0xf bound_ctrl:1
	v_add_f32_dpp v132, v118, v118 row_shr:1 row_mask:0xf bank_mask:0xf bound_ctrl:1
	v_add_f32_dpp v118, v126, v132 row_shl:15 row_mask:0xf bank_mask:0xf bound_ctrl:1
	v_add_f32_dpp v126, v126, v126 row_shr:1 row_mask:0xf bank_mask:0xf bound_ctrl:1
	v_add_f32_dpp v132, v119, v119 row_shr:1 row_mask:0xf bank_mask:0xf bound_ctrl:1
	v_add_f32_dpp v119, v127, v132 row_shl:15 row_mask:0xf bank_mask:0xf bound_ctrl:1
	v_add_f32_dpp v127, v127, v127 row_shr:1 row_mask:0xf bank_mask:0xf bound_ctrl:1
	v_add_f32_dpp v132, v120, v120 row_shr:1 row_mask:0xf bank_mask:0xf bound_ctrl:1
	v_add_f32_dpp v120, v128, v132 row_shl:15 row_mask:0xf bank_mask:0xf bound_ctrl:1
	v_add_f32_dpp v128, v128, v128 row_shr:1 row_mask:0xf bank_mask:0xf bound_ctrl:1
	v_add_f32_dpp v132, v121, v121 row_shr:1 row_mask:0xf bank_mask:0xf bound_ctrl:1
	v_add_f32_dpp v121, v129, v132 row_shl:15 row_mask:0xf bank_mask:0xf bound_ctrl:1
	v_add_f32_dpp v129, v129, v129 row_shr:1 row_mask:0xf bank_mask:0xf bound_ctrl:1
	v_add_f32_dpp v132, v122, v122 row_shr:1 row_mask:0xf bank_mask:0xf bound_ctrl:1
	v_add_f32_dpp v122, v130, v132 row_shl:15 row_mask:0xf bank_mask:0xf bound_ctrl:1
	v_add_f32_dpp v130, v130, v130 row_shr:1 row_mask:0xf bank_mask:0xf bound_ctrl:1
	v_add_f32_dpp v132, v123, v123 row_shr:1 row_mask:0xf bank_mask:0xf bound_ctrl:1
	v_add_f32_dpp v123, v131, v132 row_shl:15 row_mask:0xf bank_mask:0xf bound_ctrl:1
	v_add_f32_dpp v131, v131, v131 row_shr:1 row_mask:0xf bank_mask:0xf bound_ctrl:1
	v_fma_f32 v116, v116, v138, -v108
	v_fma_f32 v117, v117, v138, -v109
	v_fma_f32 v118, v118, v138, -v110
	v_fma_f32 v119, v119, v138, -v111
	v_fma_f32 v120, v120, v138, -v112
	v_fma_f32 v121, v121, v138, -v113
	v_fma_f32 v122, v122, v138, -v114
	v_fma_f32 v123, v123, v138, -v115
	v_cvt_pk_bf16_f32 v134, v116, v117
	v_cvt_pk_bf16_f32 v135, v118, v119
	v_cvt_pk_bf16_f32 v136, v120, v121
	v_cvt_pk_bf16_f32 v137, v122, v123
	s_waitcnt lgkmcnt(0)
	s_nop 0
	v_mfma_f32_16x16x32_bf16 v[76:79], v[44:47], v[134:137], v[76:79]
	v_mfma_f32_16x16x32_bf16 v[80:83], v[48:51], v[134:137], v[80:83]
	v_mfma_f32_16x16x32_bf16 v[84:87], v[52:55], v[134:137], v[84:87]
	v_mfma_f32_16x16x32_bf16 v[88:91], v[56:59], v[134:137], v[88:91]
	v_mfma_f32_16x16x32_bf16 v[92:95], v[60:63], v[134:137], v[92:95]
	v_mfma_f32_16x16x32_bf16 v[96:99], v[64:67], v[134:137], v[96:99]
	v_mfma_f32_16x16x32_bf16 v[100:103], v[68:71], v[134:137], v[100:103]
	v_mfma_f32_16x16x32_bf16 v[104:107], v[72:75], v[134:137], v[104:107]
	v_add_u32_e32 v147, 0, v145
	ds_read_b128 v[44:47], v147
	ds_read_b128 v[48:51], v147 offset:4096
	ds_read_b128 v[52:55], v147 offset:8192
	ds_read_b128 v[56:59], v147 offset:12288
	ds_read_b128 v[60:63], v147 offset:16384
	ds_read_b128 v[64:67], v147 offset:20480
	ds_read_b128 v[68:71], v147 offset:24576
	ds_read_b128 v[72:75], v147 offset:28672
	s_waitcnt vmcnt(10)
; #define GAS __attribute__((address_space(1)))
; __device__ __forceinline__ void unpack8(const v4u w, float (&f)[8]) { f[0] = bf_lo(w.x); f[1] = bf_hi(w.x); f[2] = bf_lo(w.y); f[3] = bf_hi(w.y); f[4] = bf_lo(w.z); f[5] = bf_hi(w.z); f[6] = bf_lo(w.w); f[7] = bf_hi(w.w); }
; __device__ __forceinline__ v4u pack8(const float (&f)[8]) { v4u w; w.x = cvt_pk_bf16(f[0], f[1]); w.y = cvt_pk_bf16(f[2], f[3]); w.z = cvt_pk_bf16(f[4], f[5]); w.w = cvt_pk_bf16(f[6], f[7]); return w; }
; template <int SH> __device__ __forceinline__ float row_shr(float v) { return __int_as_float(__builtin_amdgcn_update_dpp(0, __float_as_int(v), 0x110 + SH, 0xf, 0xf, true)); }
; template <int SH> __device__ __forceinline__ float row_shl(float v) { return __int_as_float(__builtin_amdgcn_update_dpp(0, __float_as_int(v), 0x100 + SH, 0xf, 0xf, true)); }
; template <int S> __device__ __forceinline__ void win_step(float (&c)[8], float (&p)[8]) {
; #pragma unroll
;     for (int j = 0; j < 8; ++j) { const float cn = c[j] + row_shr<S>(c[j]) + row_shl<16 - S>(p[j]); p[j] += row_shr<S>(p[j]); c[j] = cn; }
; }
; template <int W> __device__ __forceinline__ void pool_group(const bf16* zrow  , const bf16* pw  , bf16* orow  , int pos, bool prev_ok) {
;     ...
;     for (int kk = 0; kk < 4; ++kk) {
;         if (kk < 3) {
; #pragma unroll
;             for (int dt = 0; dt < 8; ++dt) aw[(kk + 1) & 1][dt] = *(const GAS v4u*)(pw + (size_t)16 * dt * 128 + 32 * (kk + 1)); }
;         float own[8], c[8], p[8];
;         unpack8(cw[kk], own); unpack8(pv[kk], p);
; #pragma unroll
;         for (int j = 0; j < 8; ++j) c[j] = own[j];
;         win_step<1>(c, p);
;         if (W >= 4) win_step<2>(c, p);
;         if (W >= 8) win_step<4>(c, p);
;         if (W >= 16) win_step<8>(c, p);
;         float pl[8];
; #pragma unroll
;         for (int j = 0; j < 8; ++j) pl[j] = c[j] * inv - own[j];
;         const v4u pwk = pack8(pl); const bf16x8 pf = __builtin_bit_cast(bf16x8, pwk);
; #pragma unroll
;         for (int dt = 0; dt < 8; ++dt) acc[dt] = __builtin_amdgcn_mfma_f32_16x16x32_bf16(__builtin_bit_cast(bf16x8, aw[kk & 1][dt]), pf, acc[dt], 0, 0, 0);
;     }
	v_lshlrev_b32_e32 v108, 16, v28
	v_and_b32_e32 v109, 0xffff0000, v28
	v_lshlrev_b32_e32 v110, 16, v29
	v_and_b32_e32 v111, 0xffff0000, v29
	v_lshlrev_b32_e32 v112, 16, v30
	v_and_b32_e32 v113, 0xffff0000, v30
	v_lshlrev_b32_e32 v114, 16, v31
	v_and_b32_e32 v115, 0xffff0000, v31
	v_lshlrev_b32_e32 v124, 16, v32
	v_and_b32_e32 v125, 0xffff0000, v32
	v_lshlrev_b32_e32 v126, 16, v33
	v_and_b32_e32 v127, 0xffff0000, v33
	v_lshlrev_b32_e32 v128, 16, v34
	v_and_b32_e32 v129, 0xffff0000, v34
	v_lshlrev_b32_e32 v130, 16, v35
	v_and_b32_e32 v131, 0xffff0000, v35
	v_cndmask_b32_e64 v124, 0, v124, s[40:41]
	v_cndmask_b32_e64 v125, 0, v125, s[40:41]
	v_cndmask_b32_e64 v126, 0, v126, s[40:41]
	v_cndmask_b32_e64 v127, 0, v127, s[40:41]
	v_cndmask_b32_e64 v128, 0, v128, s[40:41]
	v_cndmask_b32_e64 v129, 0, v129, s[40:41]
	v_cndmask_b32_e64 v130, 0, v130, s[40:41]
	v_cndmask_b32_e64 v131, 0, v131, s[40:41]
	global_load_dwordx4 v[28:31], v11, s[38:39] offset:384
	global_load_dwordx4 v[32:35], v11, s[48:49] offset:384
	v_mov_b32_e32 v116, v108
	v_mov_b32_e32 v117, v109
	v_mov_b32_e32 v118, v110
	v_mov_b32_e32 v119, v111
	v_mov_b32_e32 v120, v112
	v_mov_b32_e32 v121, v113
	v_mov_b32_e32 v122, v114
	v_mov_b32_e32 v123, v115
	v_add_f32_dpp v132, v116, v116 row_shr:1 row_mask:0xf bank_mask:0xf bound_ctrl:1
	v_add_f32_dpp v116, v124, v132 row_shl:15 row_mask:0xf bank_mask:0xf bound_ctrl:1
	v_add_f32_dpp v124, v124, v124 row_shr:1 row_mask:0xf bank_mask:0xf bound_ctrl:1
	v_add_f32_dpp v132, v117, v117 row_shr:1 row_mask:0xf bank_mask:0xf bound_ctrl:1
	v_add_f32_dpp v117, v125, v132 row_shl:15 row_mask:0xf bank_mask:0xf bound_ctrl:1
	v_add_f32_dpp v125, v125, v125 row_shr:1 row_mask:0xf bank_mask:0xf bound_ctrl:1
	v_add_f32_dpp v132, v118, v118 row_shr:1 row_mask:0xf bank_mask:0xf bound_ctrl:1
	v_add_f32_dpp v118, v126, v132 row_shl:15 row_mask:0xf bank_mask:0xf bound_ctrl:1
	v_add_f32_dpp v126, v126, v126 row_shr:1 row_mask:0xf bank_mask:0xf bound_ctrl:1
	v_add_f32_dpp v132, v119, v119 row_shr:1 row_mask:0xf bank_mask:0xf bound_ctrl:1
	v_add_f32_dpp v119, v127, v132 row_shl:15 row_mask:0xf bank_mask:0xf bound_ctrl:1
	v_add_f32_dpp v127, v127, v127 row_shr:1 row_mask:0xf bank_mask:0xf bound_ctrl:1
	v_add_f32_dpp v132, v120, v120 row_shr:1 row_mask:0xf bank_mask:0xf bound_ctrl:1
	v_add_f32_dpp v120, v128, v132 row_shl:15 row_mask:0xf bank_mask:0xf bound_ctrl:1
	v_add_f32_dpp v128, v128, v128 row_shr:1 row_mask:0xf bank_mask:0xf bound_ctrl:1
	v_add_f32_dpp v132, v121, v121 row_shr:1 row_mask:0xf bank_mask:0xf bound_ctrl:1
	v_add_f32_dpp v121, v129, v132 row_shl:15 row_mask:0xf bank_mask:0xf bound_ctrl:1
	v_add_f32_dpp v129, v129, v129 row_shr:1 row_mask:0xf bank_mask:0xf bound_ctrl:1
	v_add_f32_dpp v132, v122, v122 row_shr:1 row_mask:0xf bank_mask:0xf bound_ctrl:1
	v_add_f32_dpp v122, v130, v132 row_shl:15 row_mask:0xf bank_mask:0xf bound_ctrl:1
	v_add_f32_dpp v130, v130, v130 row_shr:1 row_mask:0xf bank_mask:0xf bound_ctrl:1
	v_add_f32_dpp v132, v123, v123 row_shr:1 row_mask:0xf bank_mask:0xf bound_ctrl:1
	v_add_f32_dpp v123, v131, v132 row_shl:15 row_mask:0xf bank_mask:0xf bound_ctrl:1
	v_add_f32_dpp v131, v131, v131 row_shr:1 row_mask:0xf bank_mask:0xf bound_ctrl:1
	v_fma_f32 v116, v116, v138, -v108
	v_fma_f32 v117, v117, v138, -v109
	v_fma_f32 v118, v118, v138, -v110
	v_fma_f32 v119, v119, v138, -v111
	v_fma_f32 v120, v120, v138, -v112
	v_fma_f32 v121, v121, v138, -v113
	v_fma_f32 v122, v122, v138, -v114
	v_fma_f32 v123, v123, v138, -v115
	v_cvt_pk_bf16_f32 v134, v116, v117
	v_cvt_pk_bf16_f32 v135, v118, v119
	v_cvt_pk_bf16_f32 v136, v120, v121
	v_cvt_pk_bf16_f32 v137, v122, v123
	s_waitcnt lgkmcnt(0)
	s_nop 0
	v_mfma_f32_16x16x32_bf16 v[76:79], v[44:47], v[134:137], v[76:79]
	v_mfma_f32_16x16x32_bf16 v[80:83], v[48:51], v[134:137], v[80:83]
	v_mfma_f32_16x16x32_bf16 v[84:87], v[52:55], v[134:137], v[84:87]
	v_mfma_f32_16x16x32_bf16 v[88:91], v[56:59], v[134:137], v[88:91]
	v_mfma_f32_16x16x32_bf16 v[92:95], v[60:63], v[134:137], v[92:95]
	v_mfma_f32_16x16x32_bf16 v[96:99], v[64:67], v[134:137], v[96:99]
	v_mfma_f32_16x16x32_bf16 v[100:103], v[68:71], v[134:137], v[100:103]
	v_mfma_f32_16x16x32_bf16 v[104:107], v[72:75], v[134:137], v[104:107]
	v_add_u32_e32 v147, 0, v146
	ds_read_b128 v[44:47], v147
	ds_read_b128 v[48:51], v147 offset:4096
	ds_read_b128 v[52:55], v147 offset:8192
	ds_read_b128 v[56:59], v147 offset:12288
	ds_read_b128 v[60:63], v147 offset:16384
	ds_read_b128 v[64:67], v147 offset:20480
	ds_read_b128 v[68:71], v147 offset:24576
	ds_read_b128 v[72:75], v147 offset:28672
	s_waitcnt vmcnt(8)
; __device__ __forceinline__ unsigned cvt_pk_bf16(float lo, float hi) { return __builtin_bit_cast(unsigned, __builtin_convertvector((f32x2_t){lo, hi}, bf16x2_t)); }
; #define GAS __attribute__((address_space(1)))
; __device__ __forceinline__ void unpack8(const v4u w, float (&f)[8]) { f[0] = bf_lo(w.x); f[1] = bf_hi(w.x); f[2] = bf_lo(w.y); f[3] = bf_hi(w.y); f[4] = bf_lo(w.z); f[5] = bf_hi(w.z); f[6] = bf_lo(w.w); f[7] = bf_hi(w.w); }
; __device__ __forceinline__ v4u pack8(const float (&f)[8]) { v4u w; w.x = cvt_pk_bf16(f[0], f[1]); w.y = cvt_pk_bf16(f[2], f[3]); w.z = cvt_pk_bf16(f[4], f[5]); w.w = cvt_pk_bf16(f[6], f[7]); return w; }
; template <int W> __device__ __forceinline__ void pool_group(const bf16* zrow  , const bf16* pw  , bf16* orow  , int pos, bool prev_ok) {
;     const float inv = 1.0f / (float)((pos + 1) < W ? (pos + 1) : W);
;     ...
;     for (int kk = 0; kk < 4; ++kk) {
;         if (kk < 3) {
; #pragma unroll
;             for (int dt = 0; dt < 8; ++dt) aw[(kk + 1) & 1][dt] = *(const GAS v4u*)(pw + (size_t)16 * dt * 128 + 32 * (kk + 1)); }
;         float own[8], c[8], p[8];
;         unpack8(cw[kk], own); unpack8(pv[kk], p);
; #pragma unroll
;         for (int j = 0; j < 8; ++j) c[j] = own[j];
;         win_step<1>(c, p);
;         if (W >= 4) win_step<2>(c, p);
;         if (W >= 8) win_step<4>(c, p);
;         if (W >= 16) win_step<8>(c, p);
;         float pl[8];
; #pragma unroll
;         for (int j = 0; j < 8; ++j) pl[j] = c[j] * inv - own[j];
;         const v4u pwk = pack8(pl); const bf16x8 pf = __builtin_bit_cast(bf16x8, pwk);
; #pragma unroll
;         for (int dt = 0; dt < 8; ++dt) acc[dt] = __builtin_amdgcn_mfma_f32_16x16x32_bf16(__builtin_bit_cast(bf16x8, aw[kk & 1][dt]), pf, acc[dt], 0, 0, 0);
;     }
; #pragma unroll
;     for (int dt = 0; dt < 8; ++dt) { v2u w; w.x = cvt_pk_bf16(acc[dt][0], acc[dt][1]); w.y = cvt_pk_bf16(acc[dt][2], acc[dt][3]); *(GAS v2u*)(orow + 16 * dt) = w; }
	v_lshlrev_b32_e32 v108, 16, v36
	v_and_b32_e32 v109, 0xffff0000, v36
	v_lshlrev_b32_e32 v110, 16, v37
	v_and_b32_e32 v111, 0xffff0000, v37
	v_lshlrev_b32_e32 v112, 16, v38
	v_and_b32_e32 v113, 0xffff0000, v38
	v_lshlrev_b32_e32 v114, 16, v39
	v_and_b32_e32 v115, 0xffff0000, v39
	v_lshlrev_b32_e32 v124, 16, v40
	v_and_b32_e32 v125, 0xffff0000, v40
	v_lshlrev_b32_e32 v126, 16, v41
	v_and_b32_e32 v127, 0xffff0000, v41
	v_lshlrev_b32_e32 v128, 16, v42
	v_and_b32_e32 v129, 0xffff0000, v42
	v_lshlrev_b32_e32 v130, 16, v43
	v_and_b32_e32 v131, 0xffff0000, v43
	v_cndmask_b32_e64 v124, 0, v124, s[40:41]
	v_cndmask_b32_e64 v125, 0, v125, s[40:41]
	v_cndmask_b32_e64 v126, 0, v126, s[40:41]
	v_cndmask_b32_e64 v127, 0, v127, s[40:41]
	v_cndmask_b32_e64 v128, 0, v128, s[40:41]
	v_cndmask_b32_e64 v129, 0, v129, s[40:41]
	v_cndmask_b32_e64 v130, 0, v130, s[40:41]
	v_cndmask_b32_e64 v131, 0, v131, s[40:41]
	global_load_dwordx4 v[36:39], v11, s[38:39] offset:448
	global_load_dwordx4 v[40:43], v11, s[48:49] offset:448
	v_mov_b32_e32 v116, v108
	v_mov_b32_e32 v117, v109
	v_mov_b32_e32 v118, v110
	v_mov_b32_e32 v119, v111
	v_mov_b32_e32 v120, v112
	v_mov_b32_e32 v121, v113
	v_mov_b32_e32 v122, v114
	v_mov_b32_e32 v123, v115
	v_add_f32_dpp v132, v116, v116 row_shr:1 row_mask:0xf bank_mask:0xf bound_ctrl:1
	v_add_f32_dpp v116, v124, v132 row_shl:15 row_mask:0xf bank_mask:0xf bound_ctrl:1
	v_add_f32_dpp v124, v124, v124 row_shr:1 row_mask:0xf bank_mask:0xf bound_ctrl:1
	v_add_f32_dpp v132, v117, v117 row_shr:1 row_mask:0xf bank_mask:0xf bound_ctrl:1
	v_add_f32_dpp v117, v125, v132 row_shl:15 row_mask:0xf bank_mask:0xf bound_ctrl:1
	v_add_f32_dpp v125, v125, v125 row_shr:1 row_mask:0xf bank_mask:0xf bound_ctrl:1
	v_add_f32_dpp v132, v118, v118 row_shr:1 row_mask:0xf bank_mask:0xf bound_ctrl:1
	v_add_f32_dpp v118, v126, v132 row_shl:15 row_mask:0xf bank_mask:0xf bound_ctrl:1
	v_add_f32_dpp v126, v126, v126 row_shr:1 row_mask:0xf bank_mask:0xf bound_ctrl:1
	v_add_f32_dpp v132, v119, v119 row_shr:1 row_mask:0xf bank_mask:0xf bound_ctrl:1
	v_add_f32_dpp v119, v127, v132 row_shl:15 row_mask:0xf bank_mask:0xf bound_ctrl:1
	v_add_f32_dpp v127, v127, v127 row_shr:1 row_mask:0xf bank_mask:0xf bound_ctrl:1
	v_add_f32_dpp v132, v120, v120 row_shr:1 row_mask:0xf bank_mask:0xf bound_ctrl:1
	v_add_f32_dpp v120, v128, v132 row_shl:15 row_mask:0xf bank_mask:0xf bound_ctrl:1
	v_add_f32_dpp v128, v128, v128 row_shr:1 row_mask:0xf bank_mask:0xf bound_ctrl:1
	v_add_f32_dpp v132, v121, v121 row_shr:1 row_mask:0xf bank_mask:0xf bound_ctrl:1
	v_add_f32_dpp v121, v129, v132 row_shl:15 row_mask:0xf bank_mask:0xf bound_ctrl:1
	v_add_f32_dpp v129, v129, v129 row_shr:1 row_mask:0xf bank_mask:0xf bound_ctrl:1
	v_add_f32_dpp v132, v122, v122 row_shr:1 row_mask:0xf bank_mask:0xf bound_ctrl:1
	v_add_f32_dpp v122, v130, v132 row_shl:15 row_mask:0xf bank_mask:0xf bound_ctrl:1
	v_add_f32_dpp v130, v130, v130 row_shr:1 row_mask:0xf bank_mask:0xf bound_ctrl:1
	v_add_f32_dpp v132, v123, v123 row_shr:1 row_mask:0xf bank_mask:0xf bound_ctrl:1
	v_add_f32_dpp v123, v131, v132 row_shl:15 row_mask:0xf bank_mask:0xf bound_ctrl:1
	v_add_f32_dpp v131, v131, v131 row_shr:1 row_mask:0xf bank_mask:0xf bound_ctrl:1
	v_fma_f32 v116, v116, v138, -v108
	v_fma_f32 v117, v117, v138, -v109
	v_fma_f32 v118, v118, v138, -v110
	v_fma_f32 v119, v119, v138, -v111
	v_fma_f32 v120, v120, v138, -v112
	v_fma_f32 v121, v121, v138, -v113
	v_fma_f32 v122, v122, v138, -v114
	v_fma_f32 v123, v123, v138, -v115
	v_cvt_pk_bf16_f32 v134, v116, v117
	v_cvt_pk_bf16_f32 v135, v118, v119
	v_cvt_pk_bf16_f32 v136, v120, v121
	v_cvt_pk_bf16_f32 v137, v122, v123
	s_waitcnt lgkmcnt(0)
	s_nop 0
	v_mfma_f32_16x16x32_bf16 v[76:79], v[44:47], v[134:137], v[76:79]
	v_mfma_f32_16x16x32_bf16 v[80:83], v[48:51], v[134:137], v[80:83]
	v_mfma_f32_16x16x32_bf16 v[84:87], v[52:55], v[134:137], v[84:87]
	v_mfma_f32_16x16x32_bf16 v[88:91], v[56:59], v[134:137], v[88:91]
	v_mfma_f32_16x16x32_bf16 v[92:95], v[60:63], v[134:137], v[92:95]
	v_mfma_f32_16x16x32_bf16 v[96:99], v[64:67], v[134:137], v[96:99]
	v_mfma_f32_16x16x32_bf16 v[100:103], v[68:71], v[134:137], v[100:103]
	v_mfma_f32_16x16x32_bf16 v[104:107], v[72:75], v[134:137], v[104:107]
	s_nop 7
	s_nop 1
	v_cvt_pk_bf16_f32 v132, v76, v77
	v_cvt_pk_bf16_f32 v133, v78, v79
	global_store_dwordx2 v142, v[132:133], s[46:47] offset:0
	s_nop 0
	v_cvt_pk_bf16_f32 v132, v80, v81
	v_cvt_pk_bf16_f32 v133, v82, v83
	global_store_dwordx2 v142, v[132:133], s[46:47] offset:32
	s_nop 0
	v_cvt_pk_bf16_f32 v132, v84, v85
	v_cvt_pk_bf16_f32 v133, v86, v87
	global_store_dwordx2 v142, v[132:133], s[46:47] offset:64
	s_nop 0
	v_cvt_pk_bf16_f32 v132, v88, v89
	v_cvt_pk_bf16_f32 v133, v90, v91
	global_store_dwordx2 v142, v[132:133], s[46:47] offset:96
	s_nop 0
	v_cvt_pk_bf16_f32 v132, v92, v93
	v_cvt_pk_bf16_f32 v133, v94, v95
	global_store_dwordx2 v142, v[132:133], s[46:47] offset:128
	s_nop 0
	v_cvt_pk_bf16_f32 v132, v96, v97
	v_cvt_pk_bf16_f32 v133, v98, v99
	global_store_dwordx2 v142, v[132:133], s[46:47] offset:160
	s_nop 0
	v_cvt_pk_bf16_f32 v132, v100, v101
	v_cvt_pk_bf16_f32 v133, v102, v103
	global_store_dwordx2 v142, v[132:133], s[46:47] offset:192
	s_nop 0
	v_cvt_pk_bf16_f32 v132, v104, v105
	v_cvt_pk_bf16_f32 v133, v106, v107
	global_store_dwordx2 v142, v[132:133], s[46:47] offset:224
	s_nop 0
	v_min_i32_e32 v139, 4, v140
	v_cvt_f32_i32_e32 v139, v139
	v_div_scale_f32 v1, s[42:43], v139, v139, 1.0
	v_rcp_f32_e32 v2, v1
	s_nop 0
	v_fma_f32 v7, -v1, v2, 1.0
	v_fmac_f32_e32 v2, v7, v2
	v_div_scale_f32 v3, vcc, 1.0, v139, 1.0
	v_mul_f32_e32 v6, v3, v2
	v_fma_f32 v7, -v1, v6, v3
	v_fmac_f32_e32 v6, v7, v2
	v_fma_f32 v1, -v1, v6, v3
	s_nop 1
	v_div_fmas_f32 v1, v1, v2, v6
	v_div_fixup_f32 v138, v1, v139, 1.0
	v_add_u32_e32 v147, 32768, v143
	ds_read_b128 v[44:47], v147
	ds_read_b128 v[48:51], v147 offset:4096
	ds_read_b128 v[52:55], v147 offset:8192
	ds_read_b128 v[56:59], v147 offset:12288
	ds_read_b128 v[60:63], v147 offset:16384
	ds_read_b128 v[64:67], v147 offset:20480
	ds_read_b128 v[68:71], v147 offset:24576
	ds_read_b128 v[72:75], v147 offset:28672
	s_waitcnt vmcnt(14)
; #define GAS __attribute__((address_space(1)))
; __device__ __forceinline__ void unpack8(const v4u w, float (&f)[8]) { f[0] = bf_lo(w.x); f[1] = bf_hi(w.x); f[2] = bf_lo(w.y); f[3] = bf_hi(w.y); f[4] = bf_lo(w.z); f[5] = bf_hi(w.z); f[6] = bf_lo(w.w); f[7] = bf_hi(w.w); }
; __device__ __forceinline__ v4u pack8(const float (&f)[8]) { v4u w; w.x = cvt_pk_bf16(f[0], f[1]); w.y = cvt_pk_bf16(f[2], f[3]); w.z = cvt_pk_bf16(f[4], f[5]); w.w = cvt_pk_bf16(f[6], f[7]); return w; }
; template <int SH> __device__ __forceinline__ float row_shr(float v) { return __int_as_float(__builtin_amdgcn_update_dpp(0, __float_as_int(v), 0x110 + SH, 0xf, 0xf, true)); }
; template <int SH> __device__ __forceinline__ float row_shl(float v) { return __int_as_float(__builtin_amdgcn_update_dpp(0, __float_as_int(v), 0x100 + SH, 0xf, 0xf, true)); }
; template <int S> __device__ __forceinline__ void win_step(float (&c)[8], float (&p)[8]) {
; #pragma unroll
;     for (int j = 0; j < 8; ++j) { const float cn = c[j] + row_shr<S>(c[j]) + row_shl<16 - S>(p[j]); p[j] += row_shr<S>(p[j]); c[j] = cn; }
; }
; template <int W> __device__ __forceinline__ void pool_group(const bf16* zrow  , const bf16* pw  , bf16* orow  , int pos, bool prev_ok) {
;     ...
;     for (int kk = 0; kk < 4; ++kk) {
;         if (kk < 3) {
; #pragma unroll
;             for (int dt = 0; dt < 8; ++dt) aw[(kk + 1) & 1][dt] = *(const GAS v4u*)(pw + (size_t)16 * dt * 128 + 32 * (kk + 1)); }
;         float own[8], c[8], p[8];
;         unpack8(cw[kk], own); unpack8(pv[kk], p);
; #pragma unroll
;         for (int j = 0; j < 8; ++j) c[j] = own[j];
;         win_step<1>(c, p);
;         if (W >= 4) win_step<2>(c, p);
;         if (W >= 8) win_step<4>(c, p);
;         if (W >= 16) win_step<8>(c, p);
;         float pl[8];
; #pragma unroll
;         for (int j = 0; j < 8; ++j) pl[j] = c[j] * inv - own[j];
;         const v4u pwk = pack8(pl); const bf16x8 pf = __builtin_bit_cast(bf16x8, pwk);
; #pragma unroll
;         for (int dt = 0; dt < 8; ++dt) acc[dt] = __builtin_amdgcn_mfma_f32_16x16x32_bf16(__builtin_bit_cast(bf16x8, aw[kk & 1][dt]), pf, acc[dt], 0, 0, 0);
;     }
	v_lshlrev_b32_e32 v108, 16, v12
	v_and_b32_e32 v109, 0xffff0000, v12
	v_lshlrev_b32_e32 v110, 16, v13
	v_and_b32_e32 v111, 0xffff0000, v13
	v_lshlrev_b32_e32 v112, 16, v14
	v_and_b32_e32 v113, 0xffff0000, v14
	v_lshlrev_b32_e32 v114, 16, v15
	v_and_b32_e32 v115, 0xffff0000, v15
	v_lshlrev_b32_e32 v124, 16, v16
	v_and_b32_e32 v125, 0xffff0000, v16
	v_lshlrev_b32_e32 v126, 16, v17
	v_and_b32_e32 v127, 0xffff0000, v17
	v_lshlrev_b32_e32 v128, 16, v18
	v_and_b32_e32 v129, 0xffff0000, v18
	v_lshlrev_b32_e32 v130, 16, v19
	v_and_b32_e32 v131, 0xffff0000, v19
	v_cndmask_b32_e64 v124, 0, v124, s[40:41]
	v_cndmask_b32_e64 v125, 0, v125, s[40:41]
	v_cndmask_b32_e64 v126, 0, v126, s[40:41]
	v_cndmask_b32_e64 v127, 0, v127, s[40:41]
	v_cndmask_b32_e64 v128, 0, v128, s[40:41]
	v_cndmask_b32_e64 v129, 0, v129, s[40:41]
	v_cndmask_b32_e64 v130, 0, v130, s[40:41]
	v_cndmask_b32_e64 v131, 0, v131, s[40:41]
	global_load_dwordx4 v[12:15], v11, s[38:39] offset:512
	global_load_dwordx4 v[16:19], v11, s[48:49] offset:512
	v_mov_b32_e32 v116, v108
	v_mov_b32_e32 v117, v109
	v_mov_b32_e32 v118, v110
	v_mov_b32_e32 v119, v111
	v_mov_b32_e32 v120, v112
	v_mov_b32_e32 v121, v113
	v_mov_b32_e32 v122, v114
	v_mov_b32_e32 v123, v115
	v_add_f32_dpp v132, v116, v116 row_shr:1 row_mask:0xf bank_mask:0xf bound_ctrl:1
	v_add_f32_dpp v116, v124, v132 row_shl:15 row_mask:0xf bank_mask:0xf bound_ctrl:1
	v_add_f32_dpp v124, v124, v124 row_shr:1 row_mask:0xf bank_mask:0xf bound_ctrl:1
	v_add_f32_dpp v132, v117, v117 row_shr:1 row_mask:0xf bank_mask:0xf bound_ctrl:1
	v_add_f32_dpp v117, v125, v132 row_shl:15 row_mask:0xf bank_mask:0xf bound_ctrl:1
	v_add_f32_dpp v125, v125, v125 row_shr:1 row_mask:0xf bank_mask:0xf bound_ctrl:1
	v_add_f32_dpp v132, v118, v118 row_shr:1 row_mask:0xf bank_mask:0xf bound_ctrl:1
	v_add_f32_dpp v118, v126, v132 row_shl:15 row_mask:0xf bank_mask:0xf bound_ctrl:1
	v_add_f32_dpp v126, v126, v126 row_shr:1 row_mask:0xf bank_mask:0xf bound_ctrl:1
	v_add_f32_dpp v132, v119, v119 row_shr:1 row_mask:0xf bank_mask:0xf bound_ctrl:1
	v_add_f32_dpp v119, v127, v132 row_shl:15 row_mask:0xf bank_mask:0xf bound_ctrl:1
	v_add_f32_dpp v127, v127, v127 row_shr:1 row_mask:0xf bank_mask:0xf bound_ctrl:1
	v_add_f32_dpp v132, v120, v120 row_shr:1 row_mask:0xf bank_mask:0xf bound_ctrl:1
	v_add_f32_dpp v120, v128, v132 row_shl:15 row_mask:0xf bank_mask:0xf bound_ctrl:1
	v_add_f32_dpp v128, v128, v128 row_shr:1 row_mask:0xf bank_mask:0xf bound_ctrl:1
	v_add_f32_dpp v132, v121, v121 row_shr:1 row_mask:0xf bank_mask:0xf bound_ctrl:1
	v_add_f32_dpp v121, v129, v132 row_shl:15 row_mask:0xf bank_mask:0xf bound_ctrl:1
	v_add_f32_dpp v129, v129, v129 row_shr:1 row_mask:0xf bank_mask:0xf bound_ctrl:1
	v_add_f32_dpp v132, v122, v122 row_shr:1 row_mask:0xf bank_mask:0xf bound_ctrl:1
	v_add_f32_dpp v122, v130, v132 row_shl:15 row_mask:0xf bank_mask:0xf bound_ctrl:1
	v_add_f32_dpp v130, v130, v130 row_shr:1 row_mask:0xf bank_mask:0xf bound_ctrl:1
	v_add_f32_dpp v132, v123, v123 row_shr:1 row_mask:0xf bank_mask:0xf bound_ctrl:1
	v_add_f32_dpp v123, v131, v132 row_shl:15 row_mask:0xf bank_mask:0xf bound_ctrl:1
	v_add_f32_dpp v131, v131, v131 row_shr:1 row_mask:0xf bank_mask:0xf bound_ctrl:1
	v_add_f32_dpp v132, v116, v116 row_shr:2 row_mask:0xf bank_mask:0xf bound_ctrl:1
	v_add_f32_dpp v116, v124, v132 row_shl:14 row_mask:0xf bank_mask:0xf bound_ctrl:1
	v_add_f32_dpp v124, v124, v124 row_shr:2 row_mask:0xf bank_mask:0xf bound_ctrl:1
	v_add_f32_dpp v132, v117, v117 row_shr:2 row_mask:0xf bank_mask:0xf bound_ctrl:1
	v_add_f32_dpp v117, v125, v132 row_shl:14 row_mask:0xf bank_mask:0xf bound_ctrl:1
	v_add_f32_dpp v125, v125, v125 row_shr:2 row_mask:0xf bank_mask:0xf bound_ctrl:1
	v_add_f32_dpp v132, v118, v118 row_shr:2 row_mask:0xf bank_mask:0xf bound_ctrl:1
	v_add_f32_dpp v118, v126, v132 row_shl:14 row_mask:0xf bank_mask:0xf bound_ctrl:1
	v_add_f32_dpp v126, v126, v126 row_shr:2 row_mask:0xf bank_mask:0xf bound_ctrl:1
	v_add_f32_dpp v132, v119, v119 row_shr:2 row_mask:0xf bank_mask:0xf bound_ctrl:1
	v_add_f32_dpp v119, v127, v132 row_shl:14 row_mask:0xf bank_mask:0xf bound_ctrl:1
	v_add_f32_dpp v127, v127, v127 row_shr:2 row_mask:0xf bank_mask:0xf bound_ctrl:1
	v_add_f32_dpp v132, v120, v120 row_shr:2 row_mask:0xf bank_mask:0xf bound_ctrl:1
	v_add_f32_dpp v120, v128, v132 row_shl:14 row_mask:0xf bank_mask:0xf bound_ctrl:1
	v_add_f32_dpp v128, v128, v128 row_shr:2 row_mask:0xf bank_mask:0xf bound_ctrl:1
	v_add_f32_dpp v132, v121, v121 row_shr:2 row_mask:0xf bank_mask:0xf bound_ctrl:1
	v_add_f32_dpp v121, v129, v132 row_shl:14 row_mask:0xf bank_mask:0xf bound_ctrl:1
	v_add_f32_dpp v129, v129, v129 row_shr:2 row_mask:0xf bank_mask:0xf bound_ctrl:1
	v_add_f32_dpp v132, v122, v122 row_shr:2 row_mask:0xf bank_mask:0xf bound_ctrl:1
	v_add_f32_dpp v122, v130, v132 row_shl:14 row_mask:0xf bank_mask:0xf bound_ctrl:1
	v_add_f32_dpp v130, v130, v130 row_shr:2 row_mask:0xf bank_mask:0xf bound_ctrl:1
	v_add_f32_dpp v132, v123, v123 row_shr:2 row_mask:0xf bank_mask:0xf bound_ctrl:1
	v_add_f32_dpp v123, v131, v132 row_shl:14 row_mask:0xf bank_mask:0xf bound_ctrl:1
	v_add_f32_dpp v131, v131, v131 row_shr:2 row_mask:0xf bank_mask:0xf bound_ctrl:1
	v_fma_f32 v116, v116, v138, -v108
	v_fma_f32 v117, v117, v138, -v109
	v_fma_f32 v118, v118, v138, -v110
	v_fma_f32 v119, v119, v138, -v111
	v_fma_f32 v120, v120, v138, -v112
	v_fma_f32 v121, v121, v138, -v113
	v_fma_f32 v122, v122, v138, -v114
	v_fma_f32 v123, v123, v138, -v115
	v_cvt_pk_bf16_f32 v134, v116, v117
	v_cvt_pk_bf16_f32 v135, v118, v119
	v_cvt_pk_bf16_f32 v136, v120, v121
	v_cvt_pk_bf16_f32 v137, v122, v123
	s_waitcnt lgkmcnt(0)
; #define GAS __attribute__((address_space(1)))
; __device__ __forceinline__ void unpack8(const v4u w, float (&f)[8]) { f[0] = bf_lo(w.x); f[1] = bf_hi(w.x); f[2] = bf_lo(w.y); f[3] = bf_hi(w.y); f[4] = bf_lo(w.z); f[5] = bf_hi(w.z); f[6] = bf_lo(w.w); f[7] = bf_hi(w.w); }
; __device__ __forceinline__ v4u pack8(const float (&f)[8]) { v4u w; w.x = cvt_pk_bf16(f[0], f[1]); w.y = cvt_pk_bf16(f[2], f[3]); w.z = cvt_pk_bf16(f[4], f[5]); w.w = cvt_pk_bf16(f[6], f[7]); return w; }
; template <int SH> __device__ __forceinline__ float row_shr(float v) { return __int_as_float(__builtin_amdgcn_update_dpp(0, __float_as_int(v), 0x110 + SH, 0xf, 0xf, true)); }
; template <int SH> __device__ __forceinline__ float row_shl(float v) { return __int_as_float(__builtin_amdgcn_update_dpp(0, __float_as_int(v), 0x100 + SH, 0xf, 0xf, true)); }
; template <int S> __device__ __forceinline__ void win_step(float (&c)[8], float (&p)[8]) {
; #pragma unroll
;     for (int j = 0; j < 8; ++j) { const float cn = c[j] + row_shr<S>(c[j]) + row_shl<16 - S>(p[j]); p[j] += row_shr<S>(p[j]); c[j] = cn; }
; }
; template <int W> __device__ __forceinline__ void pool_group(const bf16* zrow  , const bf16* pw  , bf16* orow  , int pos, bool prev_ok) {
;     ...
;     for (int kk = 0; kk < 4; ++kk) {
;         if (kk < 3) {
; #pragma unroll
;             for (int dt = 0; dt < 8; ++dt) aw[(kk + 1) & 1][dt] = *(const GAS v4u*)(pw + (size_t)16 * dt * 128 + 32 * (kk + 1)); }
;         float own[8], c[8], p[8];
;         unpack8(cw[kk], own); unpack8(pv[kk], p);
; #pragma unroll
;         for (int j = 0; j < 8; ++j) c[j] = own[j];
;         win_step<1>(c, p);
;         if (W >= 4) win_step<2>(c, p);
;         if (W >= 8) win_step<4>(c, p);
;         if (W >= 16) win_step<8>(c, p);
;         float pl[8];
; #pragma unroll
;         for (int j = 0; j < 8; ++j) pl[j] = c[j] * inv - own[j];
;         const v4u pwk = pack8(pl); const bf16x8 pf = __builtin_bit_cast(bf16x8, pwk);
; #pragma unroll
;         for (int dt = 0; dt < 8; ++dt) acc[dt] = __builtin_amdgcn_mfma_f32_16x16x32_bf16(__builtin_bit_cast(bf16x8, aw[kk & 1][dt]), pf, acc[dt], 0, 0, 0);
;     }
	s_nop 0
	v_mfma_f32_16x16x32_bf16 v[76:79], v[44:47], v[134:137], 0
	v_mfma_f32_16x16x32_bf16 v[80:83], v[48:51], v[134:137], 0
	v_mfma_f32_16x16x32_bf16 v[84:87], v[52:55], v[134:137], 0
	v_mfma_f32_16x16x32_bf16 v[88:91], v[56:59], v[134:137], 0
	v_mfma_f32_16x16x32_bf16 v[92:95], v[60:63], v[134:137], 0
	v_mfma_f32_16x16x32_bf16 v[96:99], v[64:67], v[134:137], 0
	v_mfma_f32_16x16x32_bf16 v[100:103], v[68:71], v[134:137], 0
	v_mfma_f32_16x16x32_bf16 v[104:107], v[72:75], v[134:137], 0
	v_add_u32_e32 v147, 32768, v144
	ds_read_b128 v[44:47], v147
	ds_read_b128 v[48:51], v147 offset:4096
	ds_read_b128 v[52:55], v147 offset:8192
	ds_read_b128 v[56:59], v147 offset:12288
	ds_read_b128 v[60:63], v147 offset:16384
	ds_read_b128 v[64:67], v147 offset:20480
	ds_read_b128 v[68:71], v147 offset:24576
	ds_read_b128 v[72:75], v147 offset:28672
	s_waitcnt vmcnt(14)
	v_lshlrev_b32_e32 v108, 16, v20
	v_and_b32_e32 v109, 0xffff0000, v20
	v_lshlrev_b32_e32 v110, 16, v21
	v_and_b32_e32 v111, 0xffff0000, v21
	v_lshlrev_b32_e32 v112, 16, v22
	v_and_b32_e32 v113, 0xffff0000, v22
	v_lshlrev_b32_e32 v114, 16, v23
	v_and_b32_e32 v115, 0xffff0000, v23
	v_lshlrev_b32_e32 v124, 16, v24
	v_and_b32_e32 v125, 0xffff0000, v24
	v_lshlrev_b32_e32 v126, 16, v25
	v_and_b32_e32 v127, 0xffff0000, v25
	v_lshlrev_b32_e32 v128, 16, v26
	v_and_b32_e32 v129, 0xffff0000, v26
	v_lshlrev_b32_e32 v130, 16, v27
	v_and_b32_e32 v131, 0xffff0000, v27
	v_cndmask_b32_e64 v124, 0, v124, s[40:41]
	v_cndmask_b32_e64 v125, 0, v125, s[40:41]
	v_cndmask_b32_e64 v126, 0, v126, s[40:41]
	v_cndmask_b32_e64 v127, 0, v127, s[40:41]
	v_cndmask_b32_e64 v128, 0, v128, s[40:41]
	v_cndmask_b32_e64 v129, 0, v129, s[40:41]
	v_cndmask_b32_e64 v130, 0, v130, s[40:41]
	v_cndmask_b32_e64 v131, 0, v131, s[40:41]
	global_load_dwordx4 v[20:23], v11, s[38:39] offset:576
	global_load_dwordx4 v[24:27], v11, s[48:49] offset:576
	v_mov_b32_e32 v116, v108
	v_mov_b32_e32 v117, v109
	v_mov_b32_e32 v118, v110
	v_mov_b32_e32 v119, v111
	v_mov_b32_e32 v120, v112
	v_mov_b32_e32 v121, v113
	v_mov_b32_e32 v122, v114
	v_mov_b32_e32 v123, v115
	v_add_f32_dpp v132, v116, v116 row_shr:1 row_mask:0xf bank_mask:0xf bound_ctrl:1
	v_add_f32_dpp v116, v124, v132 row_shl:15 row_mask:0xf bank_mask:0xf bound_ctrl:1
	v_add_f32_dpp v124, v124, v124 row_shr:1 row_mask:0xf bank_mask:0xf bound_ctrl:1
	v_add_f32_dpp v132, v117, v117 row_shr:1 row_mask:0xf bank_mask:0xf bound_ctrl:1
	v_add_f32_dpp v117, v125, v132 row_shl:15 row_mask:0xf bank_mask:0xf bound_ctrl:1
	v_add_f32_dpp v125, v125, v125 row_shr:1 row_mask:0xf bank_mask:0xf bound_ctrl:1
	v_add_f32_dpp v132, v118, v118 row_shr:1 row_mask:0xf bank_mask:0xf bound_ctrl:1
	v_add_f32_dpp v118, v126, v132 row_shl:15 row_mask:0xf bank_mask:0xf bound_ctrl:1
	v_add_f32_dpp v126, v126, v126 row_shr:1 row_mask:0xf bank_mask:0xf bound_ctrl:1
	v_add_f32_dpp v132, v119, v119 row_shr:1 row_mask:0xf bank_mask:0xf bound_ctrl:1
	v_add_f32_dpp v119, v127, v132 row_shl:15 row_mask:0xf bank_mask:0xf bound_ctrl:1
	v_add_f32_dpp v127, v127, v127 row_shr:1 row_mask:0xf bank_mask:0xf bound_ctrl:1
	v_add_f32_dpp v132, v120, v120 row_shr:1 row_mask:0xf bank_mask:0xf bound_ctrl:1
	v_add_f32_dpp v120, v128, v132 row_shl:15 row_mask:0xf bank_mask:0xf bound_ctrl:1
	v_add_f32_dpp v128, v128, v128 row_shr:1 row_mask:0xf bank_mask:0xf bound_ctrl:1
	v_add_f32_dpp v132, v121, v121 row_shr:1 row_mask:0xf bank_mask:0xf bound_ctrl:1
	v_add_f32_dpp v121, v129, v132 row_shl:15 row_mask:0xf bank_mask:0xf bound_ctrl:1
	v_add_f32_dpp v129, v129, v129 row_shr:1 row_mask:0xf bank_mask:0xf bound_ctrl:1
	v_add_f32_dpp v132, v122, v122 row_shr:1 row_mask:0xf bank_mask:0xf bound_ctrl:1
	v_add_f32_dpp v122, v130, v132 row_shl:15 row_mask:0xf bank_mask:0xf bound_ctrl:1
	v_add_f32_dpp v130, v130, v130 row_shr:1 row_mask:0xf bank_mask:0xf bound_ctrl:1
	v_add_f32_dpp v132, v123, v123 row_shr:1 row_mask:0xf bank_mask:0xf bound_ctrl:1
	v_add_f32_dpp v123, v131, v132 row_shl:15 row_mask:0xf bank_mask:0xf bound_ctrl:1
	v_add_f32_dpp v131, v131, v131 row_shr:1 row_mask:0xf bank_mask:0xf bound_ctrl:1
	v_add_f32_dpp v132, v116, v116 row_shr:2 row_mask:0xf bank_mask:0xf bound_ctrl:1
	v_add_f32_dpp v116, v124, v132 row_shl:14 row_mask:0xf bank_mask:0xf bound_ctrl:1
	v_add_f32_dpp v124, v124, v124 row_shr:2 row_mask:0xf bank_mask:0xf bound_ctrl:1
	v_add_f32_dpp v132, v117, v117 row_shr:2 row_mask:0xf bank_mask:0xf bound_ctrl:1
	v_add_f32_dpp v117, v125, v132 row_shl:14 row_mask:0xf bank_mask:0xf bound_ctrl:1
	v_add_f32_dpp v125, v125, v125 row_shr:2 row_mask:0xf bank_mask:0xf bound_ctrl:1
	v_add_f32_dpp v132, v118, v118 row_shr:2 row_mask:0xf bank_mask:0xf bound_ctrl:1
	v_add_f32_dpp v118, v126, v132 row_shl:14 row_mask:0xf bank_mask:0xf bound_ctrl:1
	v_add_f32_dpp v126, v126, v126 row_shr:2 row_mask:0xf bank_mask:0xf bound_ctrl:1
	v_add_f32_dpp v132, v119, v119 row_shr:2 row_mask:0xf bank_mask:0xf bound_ctrl:1
	v_add_f32_dpp v119, v127, v132 row_shl:14 row_mask:0xf bank_mask:0xf bound_ctrl:1
	v_add_f32_dpp v127, v127, v127 row_shr:2 row_mask:0xf bank_mask:0xf bound_ctrl:1
	v_add_f32_dpp v132, v120, v120 row_shr:2 row_mask:0xf bank_mask:0xf bound_ctrl:1
	v_add_f32_dpp v120, v128, v132 row_shl:14 row_mask:0xf bank_mask:0xf bound_ctrl:1
	v_add_f32_dpp v128, v128, v128 row_shr:2 row_mask:0xf bank_mask:0xf bound_ctrl:1
	v_add_f32_dpp v132, v121, v121 row_shr:2 row_mask:0xf bank_mask:0xf bound_ctrl:1
	v_add_f32_dpp v121, v129, v132 row_shl:14 row_mask:0xf bank_mask:0xf bound_ctrl:1
	v_add_f32_dpp v129, v129, v129 row_shr:2 row_mask:0xf bank_mask:0xf bound_ctrl:1
	v_add_f32_dpp v132, v122, v122 row_shr:2 row_mask:0xf bank_mask:0xf bound_ctrl:1
	v_add_f32_dpp v122, v130, v132 row_shl:14 row_mask:0xf bank_mask:0xf bound_ctrl:1
	v_add_f32_dpp v130, v130, v130 row_shr:2 row_mask:0xf bank_mask:0xf bound_ctrl:1
	v_add_f32_dpp v132, v123, v123 row_shr:2 row_mask:0xf bank_mask:0xf bound_ctrl:1
	v_add_f32_dpp v123, v131, v132 row_shl:14 row_mask:0xf bank_mask:0xf bound_ctrl:1
	v_add_f32_dpp v131, v131, v131 row_shr:2 row_mask:0xf bank_mask:0xf bound_ctrl:1
	v_fma_f32 v116, v116, v138, -v108
	v_fma_f32 v117, v117, v138, -v109
	v_fma_f32 v118, v118, v138, -v110
	v_fma_f32 v119, v119, v138, -v111
	v_fma_f32 v120, v120, v138, -v112
	v_fma_f32 v121, v121, v138, -v113
	v_fma_f32 v122, v122, v138, -v114
	v_fma_f32 v123, v123, v138, -v115
	v_cvt_pk_bf16_f32 v134, v116, v117
	v_cvt_pk_bf16_f32 v135, v118, v119
	v_cvt_pk_bf16_f32 v136, v120, v121
	v_cvt_pk_bf16_f32 v137, v122, v123
	s_waitcnt lgkmcnt(0)
; #define GAS __attribute__((address_space(1)))
; __device__ __forceinline__ void unpack8(const v4u w, float (&f)[8]) { f[0] = bf_lo(w.x); f[1] = bf_hi(w.x); f[2] = bf_lo(w.y); f[3] = bf_hi(w.y); f[4] = bf_lo(w.z); f[5] = bf_hi(w.z); f[6] = bf_lo(w.w); f[7] = bf_hi(w.w); }
; __device__ __forceinline__ v4u pack8(const float (&f)[8]) { v4u w; w.x = cvt_pk_bf16(f[0], f[1]); w.y = cvt_pk_bf16(f[2], f[3]); w.z = cvt_pk_bf16(f[4], f[5]); w.w = cvt_pk_bf16(f[6], f[7]); return w; }
; template <int SH> __device__ __forceinline__ float row_shr(float v) { return __int_as_float(__builtin_amdgcn_update_dpp(0, __float_as_int(v), 0x110 + SH, 0xf, 0xf, true)); }
; template <int SH> __device__ __forceinline__ float row_shl(float v) { return __int_as_float(__builtin_amdgcn_update_dpp(0, __float_as_int(v), 0x100 + SH, 0xf, 0xf, true)); }
; template <int S> __device__ __forceinline__ void win_step(float (&c)[8], float (&p)[8]) {
; #pragma unroll
;     for (int j = 0; j < 8; ++j) { const float cn = c[j] + row_shr<S>(c[j]) + row_shl<16 - S>(p[j]); p[j] += row_shr<S>(p[j]); c[j] = cn; }
; }
; template <int W> __device__ __forceinline__ void pool_group(const bf16* zrow  , const bf16* pw  , bf16* orow  , int pos, bool prev_ok) {
;     ...
;     for (int kk = 0; kk < 4; ++kk) {
;         if (kk < 3) {
; #pragma unroll
;             for (int dt = 0; dt < 8; ++dt) aw[(kk + 1) & 1][dt] = *(const GAS v4u*)(pw + (size_t)16 * dt * 128 + 32 * (kk + 1)); }
;         float own[8], c[8], p[8];
;         unpack8(cw[kk], own); unpack8(pv[kk], p);
; #pragma unroll
;         for (int j = 0; j < 8; ++j) c[j] = own[j];
;         win_step<1>(c, p);
;         if (W >= 4) win_step<2>(c, p);
;         if (W >= 8) win_step<4>(c, p);
;         if (W >= 16) win_step<8>(c, p);
;         float pl[8];
; #pragma unroll
;         for (int j = 0; j < 8; ++j) pl[j] = c[j] * inv - own[j];
;         const v4u pwk = pack8(pl); const bf16x8 pf = __builtin_bit_cast(bf16x8, pwk);
; #pragma unroll
;         for (int dt = 0; dt < 8; ++dt) acc[dt] = __builtin_amdgcn_mfma_f32_16x16x32_bf16(__builtin_bit_cast(bf16x8, aw[kk & 1][dt]), pf, acc[dt], 0, 0, 0);
;     }
	s_nop 0
	v_mfma_f32_16x16x32_bf16 v[76:79], v[44:47], v[134:137], v[76:79]
	v_mfma_f32_16x16x32_bf16 v[80:83], v[48:51], v[134:137], v[80:83]
	v_mfma_f32_16x16x32_bf16 v[84:87], v[52:55], v[134:137], v[84:87]
	v_mfma_f32_16x16x32_bf16 v[88:91], v[56:59], v[134:137], v[88:91]
	v_mfma_f32_16x16x32_bf16 v[92:95], v[60:63], v[134:137], v[92:95]
	v_mfma_f32_16x16x32_bf16 v[96:99], v[64:67], v[134:137], v[96:99]
	v_mfma_f32_16x16x32_bf16 v[100:103], v[68:71], v[134:137], v[100:103]
	v_mfma_f32_16x16x32_bf16 v[104:107], v[72:75], v[134:137], v[104:107]
	v_add_u32_e32 v147, 32768, v145
	ds_read_b128 v[44:47], v147
	ds_read_b128 v[48:51], v147 offset:4096
	ds_read_b128 v[52:55], v147 offset:8192
	ds_read_b128 v[56:59], v147 offset:12288
	ds_read_b128 v[60:63], v147 offset:16384
	ds_read_b128 v[64:67], v147 offset:20480
	ds_read_b128 v[68:71], v147 offset:24576
	ds_read_b128 v[72:75], v147 offset:28672
	s_waitcnt vmcnt(14)
	v_lshlrev_b32_e32 v108, 16, v28
	v_and_b32_e32 v109, 0xffff0000, v28
	v_lshlrev_b32_e32 v110, 16, v29
	v_and_b32_e32 v111, 0xffff0000, v29
	v_lshlrev_b32_e32 v112, 16, v30
	v_and_b32_e32 v113, 0xffff0000, v30
	v_lshlrev_b32_e32 v114, 16, v31
	v_and_b32_e32 v115, 0xffff0000, v31
	v_lshlrev_b32_e32 v124, 16, v32
	v_and_b32_e32 v125, 0xffff0000, v32
	v_lshlrev_b32_e32 v126, 16, v33
	v_and_b32_e32 v127, 0xffff0000, v33
	v_lshlrev_b32_e32 v128, 16, v34
	v_and_b32_e32 v129, 0xffff0000, v34
	v_lshlrev_b32_e32 v130, 16, v35
	v_and_b32_e32 v131, 0xffff0000, v35
	v_cndmask_b32_e64 v124, 0, v124, s[40:41]
	v_cndmask_b32_e64 v125, 0, v125, s[40:41]
	v_cndmask_b32_e64 v126, 0, v126, s[40:41]
	v_cndmask_b32_e64 v127, 0, v127, s[40:41]
	v_cndmask_b32_e64 v128, 0, v128, s[40:41]
	v_cndmask_b32_e64 v129, 0, v129, s[40:41]
	v_cndmask_b32_e64 v130, 0, v130, s[40:41]
	v_cndmask_b32_e64 v131, 0, v131, s[40:41]
	global_load_dwordx4 v[28:31], v11, s[38:39] offset:640
	global_load_dwordx4 v[32:35], v11, s[48:49] offset:640
	v_mov_b32_e32 v116, v108
	v_mov_b32_e32 v117, v109
	v_mov_b32_e32 v118, v110
	v_mov_b32_e32 v119, v111
	v_mov_b32_e32 v120, v112
	v_mov_b32_e32 v121, v113
	v_mov_b32_e32 v122, v114
	v_mov_b32_e32 v123, v115
	v_add_f32_dpp v132, v116, v116 row_shr:1 row_mask:0xf bank_mask:0xf bound_ctrl:1
	v_add_f32_dpp v116, v124, v132 row_shl:15 row_mask:0xf bank_mask:0xf bound_ctrl:1
	v_add_f32_dpp v124, v124, v124 row_shr:1 row_mask:0xf bank_mask:0xf bound_ctrl:1
	v_add_f32_dpp v132, v117, v117 row_shr:1 row_mask:0xf bank_mask:0xf bound_ctrl:1
	v_add_f32_dpp v117, v125, v132 row_shl:15 row_mask:0xf bank_mask:0xf bound_ctrl:1
	v_add_f32_dpp v125, v125, v125 row_shr:1 row_mask:0xf bank_mask:0xf bound_ctrl:1
	v_add_f32_dpp v132, v118, v118 row_shr:1 row_mask:0xf bank_mask:0xf bound_ctrl:1
	v_add_f32_dpp v118, v126, v132 row_shl:15 row_mask:0xf bank_mask:0xf bound_ctrl:1
	v_add_f32_dpp v126, v126, v126 row_shr:1 row_mask:0xf bank_mask:0xf bound_ctrl:1
	v_add_f32_dpp v132, v119, v119 row_shr:1 row_mask:0xf bank_mask:0xf bound_ctrl:1
	v_add_f32_dpp v119, v127, v132 row_shl:15 row_mask:0xf bank_mask:0xf bound_ctrl:1
	v_add_f32_dpp v127, v127, v127 row_shr:1 row_mask:0xf bank_mask:0xf bound_ctrl:1
	v_add_f32_dpp v132, v120, v120 row_shr:1 row_mask:0xf bank_mask:0xf bound_ctrl:1
	v_add_f32_dpp v120, v128, v132 row_shl:15 row_mask:0xf bank_mask:0xf bound_ctrl:1
	v_add_f32_dpp v128, v128, v128 row_shr:1 row_mask:0xf bank_mask:0xf bound_ctrl:1
	v_add_f32_dpp v132, v121, v121 row_shr:1 row_mask:0xf bank_mask:0xf bound_ctrl:1
	v_add_f32_dpp v121, v129, v132 row_shl:15 row_mask:0xf bank_mask:0xf bound_ctrl:1
	v_add_f32_dpp v129, v129, v129 row_shr:1 row_mask:0xf bank_mask:0xf bound_ctrl:1
	v_add_f32_dpp v132, v122, v122 row_shr:1 row_mask:0xf bank_mask:0xf bound_ctrl:1
	v_add_f32_dpp v122, v130, v132 row_shl:15 row_mask:0xf bank_mask:0xf bound_ctrl:1
	v_add_f32_dpp v130, v130, v130 row_shr:1 row_mask:0xf bank_mask:0xf bound_ctrl:1
	v_add_f32_dpp v132, v123, v123 row_shr:1 row_mask:0xf bank_mask:0xf bound_ctrl:1
	v_add_f32_dpp v123, v131, v132 row_shl:15 row_mask:0xf bank_mask:0xf bound_ctrl:1
	v_add_f32_dpp v131, v131, v131 row_shr:1 row_mask:0xf bank_mask:0xf bound_ctrl:1
	v_add_f32_dpp v132, v116, v116 row_shr:2 row_mask:0xf bank_mask:0xf bound_ctrl:1
	v_add_f32_dpp v116, v124, v132 row_shl:14 row_mask:0xf bank_mask:0xf bound_ctrl:1
	v_add_f32_dpp v124, v124, v124 row_shr:2 row_mask:0xf bank_mask:0xf bound_ctrl:1
	v_add_f32_dpp v132, v117, v117 row_shr:2 row_mask:0xf bank_mask:0xf bound_ctrl:1
	v_add_f32_dpp v117, v125, v132 row_shl:14 row_mask:0xf bank_mask:0xf bound_ctrl:1
	v_add_f32_dpp v125, v125, v125 row_shr:2 row_mask:0xf bank_mask:0xf bound_ctrl:1
	v_add_f32_dpp v132, v118, v118 row_shr:2 row_mask:0xf bank_mask:0xf bound_ctrl:1
	v_add_f32_dpp v118, v126, v132 row_shl:14 row_mask:0xf bank_mask:0xf bound_ctrl:1
	v_add_f32_dpp v126, v126, v126 row_shr:2 row_mask:0xf bank_mask:0xf bound_ctrl:1
	v_add_f32_dpp v132, v119, v119 row_shr:2 row_mask:0xf bank_mask:0xf bound_ctrl:1
	v_add_f32_dpp v119, v127, v132 row_shl:14 row_mask:0xf bank_mask:0xf bound_ctrl:1
	v_add_f32_dpp v127, v127, v127 row_shr:2 row_mask:0xf bank_mask:0xf bound_ctrl:1
	v_add_f32_dpp v132, v120, v120 row_shr:2 row_mask:0xf bank_mask:0xf bound_ctrl:1
	v_add_f32_dpp v120, v128, v132 row_shl:14 row_mask:0xf bank_mask:0xf bound_ctrl:1
	v_add_f32_dpp v128, v128, v128 row_shr:2 row_mask:0xf bank_mask:0xf bound_ctrl:1
	v_add_f32_dpp v132, v121, v121 row_shr:2 row_mask:0xf bank_mask:0xf bound_ctrl:1
	v_add_f32_dpp v121, v129, v132 row_shl:14 row_mask:0xf bank_mask:0xf bound_ctrl:1
	v_add_f32_dpp v129, v129, v129 row_shr:2 row_mask:0xf bank_mask:0xf bound_ctrl:1
	v_add_f32_dpp v132, v122, v122 row_shr:2 row_mask:0xf bank_mask:0xf bound_ctrl:1
	v_add_f32_dpp v122, v130, v132 row_shl:14 row_mask:0xf bank_mask:0xf bound_ctrl:1
	v_add_f32_dpp v130, v130, v130 row_shr:2 row_mask:0xf bank_mask:0xf bound_ctrl:1
	v_add_f32_dpp v132, v123, v123 row_shr:2 row_mask:0xf bank_mask:0xf bound_ctrl:1
	v_add_f32_dpp v123, v131, v132 row_shl:14 row_mask:0xf bank_mask:0xf bound_ctrl:1
	v_add_f32_dpp v131, v131, v131 row_shr:2 row_mask:0xf bank_mask:0xf bound_ctrl:1
	v_fma_f32 v116, v116, v138, -v108
	v_fma_f32 v117, v117, v138, -v109
	v_fma_f32 v118, v118, v138, -v110
	v_fma_f32 v119, v119, v138, -v111
	v_fma_f32 v120, v120, v138, -v112
	v_fma_f32 v121, v121, v138, -v113
	v_fma_f32 v122, v122, v138, -v114
	v_fma_f32 v123, v123, v138, -v115
	v_cvt_pk_bf16_f32 v134, v116, v117
	v_cvt_pk_bf16_f32 v135, v118, v119
	v_cvt_pk_bf16_f32 v136, v120, v121
	v_cvt_pk_bf16_f32 v137, v122, v123
	s_waitcnt lgkmcnt(0)
; #define GAS __attribute__((address_space(1)))
; __device__ __forceinline__ void unpack8(const v4u w, float (&f)[8]) { f[0] = bf_lo(w.x); f[1] = bf_hi(w.x); f[2] = bf_lo(w.y); f[3] = bf_hi(w.y); f[4] = bf_lo(w.z); f[5] = bf_hi(w.z); f[6] = bf_lo(w.w); f[7] = bf_hi(w.w); }
; __device__ __forceinline__ v4u pack8(const float (&f)[8]) { v4u w; w.x = cvt_pk_bf16(f[0], f[1]); w.y = cvt_pk_bf16(f[2], f[3]); w.z = cvt_pk_bf16(f[4], f[5]); w.w = cvt_pk_bf16(f[6], f[7]); return w; }
; template <int SH> __device__ __forceinline__ float row_shr(float v) { return __int_as_float(__builtin_amdgcn_update_dpp(0, __float_as_int(v), 0x110 + SH, 0xf, 0xf, true)); }
; template <int SH> __device__ __forceinline__ float row_shl(float v) { return __int_as_float(__builtin_amdgcn_update_dpp(0, __float_as_int(v), 0x100 + SH, 0xf, 0xf, true)); }
; template <int S> __device__ __forceinline__ void win_step(float (&c)[8], float (&p)[8]) {
; #pragma unroll
;     for (int j = 0; j < 8; ++j) { const float cn = c[j] + row_shr<S>(c[j]) + row_shl<16 - S>(p[j]); p[j] += row_shr<S>(p[j]); c[j] = cn; }
; }
; template <int W> __device__ __forceinline__ void pool_group(const bf16* zrow  , const bf16* pw  , bf16* orow  , int pos, bool prev_ok) {
;     ...
;     for (int kk = 0; kk < 4; ++kk) {
;         if (kk < 3) {
; #pragma unroll
;             for (int dt = 0; dt < 8; ++dt) aw[(kk + 1) & 1][dt] = *(const GAS v4u*)(pw + (size_t)16 * dt * 128 + 32 * (kk + 1)); }
;         float own[8], c[8], p[8];
;         unpack8(cw[kk], own); unpack8(pv[kk], p);
; #pragma unroll
;         for (int j = 0; j < 8; ++j) c[j] = own[j];
;         win_step<1>(c, p);
;         if (W >= 4) win_step<2>(c, p);
;         if (W >= 8) win_step<4>(c, p);
;         if (W >= 16) win_step<8>(c, p);
;         float pl[8];
; #pragma unroll
;         for (int j = 0; j < 8; ++j) pl[j] = c[j] * inv - own[j];
;         const v4u pwk = pack8(pl); const bf16x8 pf = __builtin_bit_cast(bf16x8, pwk);
; #pragma unroll
;         for (int dt = 0; dt < 8; ++dt) acc[dt] = __builtin_amdgcn_mfma_f32_16x16x32_bf16(__builtin_bit_cast(bf16x8, aw[kk & 1][dt]), pf, acc[dt], 0, 0, 0);
;     }
	s_nop 0
	v_mfma_f32_16x16x32_bf16 v[76:79], v[44:47], v[134:137], v[76:79]
	v_mfma_f32_16x16x32_bf16 v[80:83], v[48:51], v[134:137], v[80:83]
	v_mfma_f32_16x16x32_bf16 v[84:87], v[52:55], v[134:137], v[84:87]
	v_mfma_f32_16x16x32_bf16 v[88:91], v[56:59], v[134:137], v[88:91]
	v_mfma_f32_16x16x32_bf16 v[92:95], v[60:63], v[134:137], v[92:95]
	v_mfma_f32_16x16x32_bf16 v[96:99], v[64:67], v[134:137], v[96:99]
	v_mfma_f32_16x16x32_bf16 v[100:103], v[68:71], v[134:137], v[100:103]
	v_mfma_f32_16x16x32_bf16 v[104:107], v[72:75], v[134:137], v[104:107]
	v_add_u32_e32 v147, 32768, v146
	ds_read_b128 v[44:47], v147
	ds_read_b128 v[48:51], v147 offset:4096
	ds_read_b128 v[52:55], v147 offset:8192
	ds_read_b128 v[56:59], v147 offset:12288
	ds_read_b128 v[60:63], v147 offset:16384
	ds_read_b128 v[64:67], v147 offset:20480
	ds_read_b128 v[68:71], v147 offset:24576
	ds_read_b128 v[72:75], v147 offset:28672
	s_waitcnt vmcnt(14)
	v_lshlrev_b32_e32 v108, 16, v36
	v_and_b32_e32 v109, 0xffff0000, v36
	v_lshlrev_b32_e32 v110, 16, v37
	v_and_b32_e32 v111, 0xffff0000, v37
	v_lshlrev_b32_e32 v112, 16, v38
	v_and_b32_e32 v113, 0xffff0000, v38
	v_lshlrev_b32_e32 v114, 16, v39
	v_and_b32_e32 v115, 0xffff0000, v39
	v_lshlrev_b32_e32 v124, 16, v40
	v_and_b32_e32 v125, 0xffff0000, v40
	v_lshlrev_b32_e32 v126, 16, v41
	v_and_b32_e32 v127, 0xffff0000, v41
	v_lshlrev_b32_e32 v128, 16, v42
	v_and_b32_e32 v129, 0xffff0000, v42
	v_lshlrev_b32_e32 v130, 16, v43
	v_and_b32_e32 v131, 0xffff0000, v43
	v_cndmask_b32_e64 v124, 0, v124, s[40:41]
	v_cndmask_b32_e64 v125, 0, v125, s[40:41]
	v_cndmask_b32_e64 v126, 0, v126, s[40:41]
	v_cndmask_b32_e64 v127, 0, v127, s[40:41]
	v_cndmask_b32_e64 v128, 0, v128, s[40:41]
	v_cndmask_b32_e64 v129, 0, v129, s[40:41]
	v_cndmask_b32_e64 v130, 0, v130, s[40:41]
	v_cndmask_b32_e64 v131, 0, v131, s[40:41]
	global_load_dwordx4 v[36:39], v11, s[38:39] offset:704
	global_load_dwordx4 v[40:43], v11, s[48:49] offset:704
	v_mov_b32_e32 v116, v108
	v_mov_b32_e32 v117, v109
	v_mov_b32_e32 v118, v110
	v_mov_b32_e32 v119, v111
	v_mov_b32_e32 v120, v112
	v_mov_b32_e32 v121, v113
	v_mov_b32_e32 v122, v114
	v_mov_b32_e32 v123, v115
	v_add_f32_dpp v132, v116, v116 row_shr:1 row_mask:0xf bank_mask:0xf bound_ctrl:1
	v_add_f32_dpp v116, v124, v132 row_shl:15 row_mask:0xf bank_mask:0xf bound_ctrl:1
	v_add_f32_dpp v124, v124, v124 row_shr:1 row_mask:0xf bank_mask:0xf bound_ctrl:1
	v_add_f32_dpp v132, v117, v117 row_shr:1 row_mask:0xf bank_mask:0xf bound_ctrl:1
	v_add_f32_dpp v117, v125, v132 row_shl:15 row_mask:0xf bank_mask:0xf bound_ctrl:1
	v_add_f32_dpp v125, v125, v125 row_shr:1 row_mask:0xf bank_mask:0xf bound_ctrl:1
	v_add_f32_dpp v132, v118, v118 row_shr:1 row_mask:0xf bank_mask:0xf bound_ctrl:1
	v_add_f32_dpp v118, v126, v132 row_shl:15 row_mask:0xf bank_mask:0xf bound_ctrl:1
	v_add_f32_dpp v126, v126, v126 row_shr:1 row_mask:0xf bank_mask:0xf bound_ctrl:1
	v_add_f32_dpp v132, v119, v119 row_shr:1 row_mask:0xf bank_mask:0xf bound_ctrl:1
	v_add_f32_dpp v119, v127, v132 row_shl:15 row_mask:0xf bank_mask:0xf bound_ctrl:1
	v_add_f32_dpp v127, v127, v127 row_shr:1 row_mask:0xf bank_mask:0xf bound_ctrl:1
	v_add_f32_dpp v132, v120, v120 row_shr:1 row_mask:0xf bank_mask:0xf bound_ctrl:1
	v_add_f32_dpp v120, v128, v132 row_shl:15 row_mask:0xf bank_mask:0xf bound_ctrl:1
	v_add_f32_dpp v128, v128, v128 row_shr:1 row_mask:0xf bank_mask:0xf bound_ctrl:1
	v_add_f32_dpp v132, v121, v121 row_shr:1 row_mask:0xf bank_mask:0xf bound_ctrl:1
	v_add_f32_dpp v121, v129, v132 row_shl:15 row_mask:0xf bank_mask:0xf bound_ctrl:1
	v_add_f32_dpp v129, v129, v129 row_shr:1 row_mask:0xf bank_mask:0xf bound_ctrl:1
	v_add_f32_dpp v132, v122, v122 row_shr:1 row_mask:0xf bank_mask:0xf bound_ctrl:1
	v_add_f32_dpp v122, v130, v132 row_shl:15 row_mask:0xf bank_mask:0xf bound_ctrl:1
	v_add_f32_dpp v130, v130, v130 row_shr:1 row_mask:0xf bank_mask:0xf bound_ctrl:1
	v_add_f32_dpp v132, v123, v123 row_shr:1 row_mask:0xf bank_mask:0xf bound_ctrl:1
	v_add_f32_dpp v123, v131, v132 row_shl:15 row_mask:0xf bank_mask:0xf bound_ctrl:1
	v_add_f32_dpp v131, v131, v131 row_shr:1 row_mask:0xf bank_mask:0xf bound_ctrl:1
	v_add_f32_dpp v132, v116, v116 row_shr:2 row_mask:0xf bank_mask:0xf bound_ctrl:1
	v_add_f32_dpp v116, v124, v132 row_shl:14 row_mask:0xf bank_mask:0xf bound_ctrl:1
	v_add_f32_dpp v124, v124, v124 row_shr:2 row_mask:0xf bank_mask:0xf bound_ctrl:1
	v_add_f32_dpp v132, v117, v117 row_shr:2 row_mask:0xf bank_mask:0xf bound_ctrl:1
	v_add_f32_dpp v117, v125, v132 row_shl:14 row_mask:0xf bank_mask:0xf bound_ctrl:1
	v_add_f32_dpp v125, v125, v125 row_shr:2 row_mask:0xf bank_mask:0xf bound_ctrl:1
	v_add_f32_dpp v132, v118, v118 row_shr:2 row_mask:0xf bank_mask:0xf bound_ctrl:1
	v_add_f32_dpp v118, v126, v132 row_shl:14 row_mask:0xf bank_mask:0xf bound_ctrl:1
	v_add_f32_dpp v126, v126, v126 row_shr:2 row_mask:0xf bank_mask:0xf bound_ctrl:1
	v_add_f32_dpp v132, v119, v119 row_shr:2 row_mask:0xf bank_mask:0xf bound_ctrl:1
	v_add_f32_dpp v119, v127, v132 row_shl:14 row_mask:0xf bank_mask:0xf bound_ctrl:1
	v_add_f32_dpp v127, v127, v127 row_shr:2 row_mask:0xf bank_mask:0xf bound_ctrl:1
	v_add_f32_dpp v132, v120, v120 row_shr:2 row_mask:0xf bank_mask:0xf bound_ctrl:1
	v_add_f32_dpp v120, v128, v132 row_shl:14 row_mask:0xf bank_mask:0xf bound_ctrl:1
	v_add_f32_dpp v128, v128, v128 row_shr:2 row_mask:0xf bank_mask:0xf bound_ctrl:1
	v_add_f32_dpp v132, v121, v121 row_shr:2 row_mask:0xf bank_mask:0xf bound_ctrl:1
	v_add_f32_dpp v121, v129, v132 row_shl:14 row_mask:0xf bank_mask:0xf bound_ctrl:1
	v_add_f32_dpp v129, v129, v129 row_shr:2 row_mask:0xf bank_mask:0xf bound_ctrl:1
	v_add_f32_dpp v132, v122, v122 row_shr:2 row_mask:0xf bank_mask:0xf bound_ctrl:1
	v_add_f32_dpp v122, v130, v132 row_shl:14 row_mask:0xf bank_mask:0xf bound_ctrl:1
	v_add_f32_dpp v130, v130, v130 row_shr:2 row_mask:0xf bank_mask:0xf bound_ctrl:1
	v_add_f32_dpp v132, v123, v123 row_shr:2 row_mask:0xf bank_mask:0xf bound_ctrl:1
	v_add_f32_dpp v123, v131, v132 row_shl:14 row_mask:0xf bank_mask:0xf bound_ctrl:1
	v_add_f32_dpp v131, v131, v131 row_shr:2 row_mask:0xf bank_mask:0xf bound_ctrl:1
	v_fma_f32 v116, v116, v138, -v108
	v_fma_f32 v117, v117, v138, -v109
	v_fma_f32 v118, v118, v138, -v110
	v_fma_f32 v119, v119, v138, -v111
	v_fma_f32 v120, v120, v138, -v112
	v_fma_f32 v121, v121, v138, -v113
	v_fma_f32 v122, v122, v138, -v114
	v_fma_f32 v123, v123, v138, -v115
	v_cvt_pk_bf16_f32 v134, v116, v117
	v_cvt_pk_bf16_f32 v135, v118, v119
	v_cvt_pk_bf16_f32 v136, v120, v121
	v_cvt_pk_bf16_f32 v137, v122, v123
	s_waitcnt lgkmcnt(0)
; __device__ __forceinline__ unsigned cvt_pk_bf16(float lo, float hi) { return __builtin_bit_cast(unsigned, __builtin_convertvector((f32x2_t){lo, hi}, bf16x2_t)); }
; #define GAS __attribute__((address_space(1)))
; __device__ __forceinline__ void unpack8(const v4u w, float (&f)[8]) { f[0] = bf_lo(w.x); f[1] = bf_hi(w.x); f[2] = bf_lo(w.y); f[3] = bf_hi(w.y); f[4] = bf_lo(w.z); f[5] = bf_hi(w.z); f[6] = bf_lo(w.w); f[7] = bf_hi(w.w); }
; template <int W> __device__ __forceinline__ void pool_group(const bf16* zrow  , const bf16* pw  , bf16* orow  , int pos, bool prev_ok) {
;     const float inv = 1.0f / (float)((pos + 1) < W ? (pos + 1) : W);
;     ...
;     for (int kk = 0; kk < 4; ++kk) {
;         if (kk < 3) {
; #pragma unroll
;             for (int dt = 0; dt < 8; ++dt) aw[(kk + 1) & 1][dt] = *(const GAS v4u*)(pw + (size_t)16 * dt * 128 + 32 * (kk + 1)); }
;         float own[8], c[8], p[8];
;         unpack8(cw[kk], own); unpack8(pv[kk], p);
; #pragma unroll
;         for (int j = 0; j < 8; ++j) c[j] = own[j];
;         win_step<1>(c, p);
;     ...
;         for (int dt = 0; dt < 8; ++dt) acc[dt] = __builtin_amdgcn_mfma_f32_16x16x32_bf16(__builtin_bit_cast(bf16x8, aw[kk & 1][dt]), pf, acc[dt], 0, 0, 0);
;     }
; #pragma unroll
;     for (int dt = 0; dt < 8; ++dt) { v2u w; w.x = cvt_pk_bf16(acc[dt][0], acc[dt][1]); w.y = cvt_pk_bf16(acc[dt][2], acc[dt][3]); *(GAS v2u*)(orow + 16 * dt) = w; }
	s_nop 0
	v_mfma_f32_16x16x32_bf16 v[76:79], v[44:47], v[134:137], v[76:79]
	v_mfma_f32_16x16x32_bf16 v[80:83], v[48:51], v[134:137], v[80:83]
	v_mfma_f32_16x16x32_bf16 v[84:87], v[52:55], v[134:137], v[84:87]
	v_mfma_f32_16x16x32_bf16 v[88:91], v[56:59], v[134:137], v[88:91]
	v_mfma_f32_16x16x32_bf16 v[92:95], v[60:63], v[134:137], v[92:95]
	v_mfma_f32_16x16x32_bf16 v[96:99], v[64:67], v[134:137], v[96:99]
	v_mfma_f32_16x16x32_bf16 v[100:103], v[68:71], v[134:137], v[100:103]
	v_mfma_f32_16x16x32_bf16 v[104:107], v[72:75], v[134:137], v[104:107]
	s_nop 7
	s_nop 1
	v_cvt_pk_bf16_f32 v132, v76, v77
	v_cvt_pk_bf16_f32 v133, v78, v79
	global_store_dwordx2 v142, v[132:133], s[46:47] offset:256
	s_nop 0
	v_cvt_pk_bf16_f32 v132, v80, v81
	v_cvt_pk_bf16_f32 v133, v82, v83
	global_store_dwordx2 v142, v[132:133], s[46:47] offset:288
	s_nop 0
	v_cvt_pk_bf16_f32 v132, v84, v85
	v_cvt_pk_bf16_f32 v133, v86, v87
	global_store_dwordx2 v142, v[132:133], s[46:47] offset:320
	s_nop 0
	v_cvt_pk_bf16_f32 v132, v88, v89
	v_cvt_pk_bf16_f32 v133, v90, v91
	global_store_dwordx2 v142, v[132:133], s[46:47] offset:352
	s_nop 0
	v_cvt_pk_bf16_f32 v132, v92, v93
	v_cvt_pk_bf16_f32 v133, v94, v95
	global_store_dwordx2 v142, v[132:133], s[46:47] offset:384
	s_nop 0
	v_cvt_pk_bf16_f32 v132, v96, v97
	v_cvt_pk_bf16_f32 v133, v98, v99
	global_store_dwordx2 v142, v[132:133], s[46:47] offset:416
	s_nop 0
	v_cvt_pk_bf16_f32 v132, v100, v101
	v_cvt_pk_bf16_f32 v133, v102, v103
	global_store_dwordx2 v142, v[132:133], s[46:47] offset:448
	s_nop 0
	v_cvt_pk_bf16_f32 v132, v104, v105
	v_cvt_pk_bf16_f32 v133, v106, v107
	global_store_dwordx2 v142, v[132:133], s[46:47] offset:480
	s_nop 0
	v_min_i32_e32 v139, 8, v140
	v_cvt_f32_i32_e32 v139, v139
	v_div_scale_f32 v1, s[42:43], v139, v139, 1.0
	v_rcp_f32_e32 v2, v1
	s_nop 0
	v_fma_f32 v7, -v1, v2, 1.0
	v_fmac_f32_e32 v2, v7, v2
	v_div_scale_f32 v3, vcc, 1.0, v139, 1.0
	v_mul_f32_e32 v6, v3, v2
	v_fma_f32 v7, -v1, v6, v3
	v_fmac_f32_e32 v6, v7, v2
	v_fma_f32 v1, -v1, v6, v3
	s_nop 1
	v_div_fmas_f32 v1, v1, v2, v6
	v_div_fixup_f32 v138, v1, v139, 1.0
	v_add_u32_e32 v147, 65536, v143
	ds_read_b128 v[44:47], v147
	ds_read_b128 v[48:51], v147 offset:4096
	ds_read_b128 v[52:55], v147 offset:8192
	ds_read_b128 v[56:59], v147 offset:12288
	ds_read_b128 v[60:63], v147 offset:16384
	ds_read_b128 v[64:67], v147 offset:20480
	ds_read_b128 v[68:71], v147 offset:24576
	ds_read_b128 v[72:75], v147 offset:28672
	s_waitcnt vmcnt(14)
	v_lshlrev_b32_e32 v108, 16, v12
	v_and_b32_e32 v109, 0xffff0000, v12
	v_lshlrev_b32_e32 v110, 16, v13
	v_and_b32_e32 v111, 0xffff0000, v13
	v_lshlrev_b32_e32 v112, 16, v14
	v_and_b32_e32 v113, 0xffff0000, v14
	v_lshlrev_b32_e32 v114, 16, v15
	v_and_b32_e32 v115, 0xffff0000, v15
	v_lshlrev_b32_e32 v124, 16, v16
	v_and_b32_e32 v125, 0xffff0000, v16
	v_lshlrev_b32_e32 v126, 16, v17
	v_and_b32_e32 v127, 0xffff0000, v17
	v_lshlrev_b32_e32 v128, 16, v18
	v_and_b32_e32 v129, 0xffff0000, v18
	v_lshlrev_b32_e32 v130, 16, v19
	v_and_b32_e32 v131, 0xffff0000, v19
	v_cndmask_b32_e64 v124, 0, v124, s[40:41]
	v_cndmask_b32_e64 v125, 0, v125, s[40:41]
	v_cndmask_b32_e64 v126, 0, v126, s[40:41]
	v_cndmask_b32_e64 v127, 0, v127, s[40:41]
	v_cndmask_b32_e64 v128, 0, v128, s[40:41]
	v_cndmask_b32_e64 v129, 0, v129, s[40:41]
	v_cndmask_b32_e64 v130, 0, v130, s[40:41]
	v_cndmask_b32_e64 v131, 0, v131, s[40:41]
	global_load_dwordx4 v[12:15], v11, s[38:39] offset:768
	global_load_dwordx4 v[16:19], v11, s[48:49] offset:768
	v_mov_b32_e32 v116, v108
	v_mov_b32_e32 v117, v109
	v_mov_b32_e32 v118, v110
	v_mov_b32_e32 v119, v111
	v_mov_b32_e32 v120, v112
	v_mov_b32_e32 v121, v113
	v_mov_b32_e32 v122, v114
	v_mov_b32_e32 v123, v115
	v_add_f32_dpp v132, v116, v116 row_shr:1 row_mask:0xf bank_mask:0xf bound_ctrl:1
	v_add_f32_dpp v116, v124, v132 row_shl:15 row_mask:0xf bank_mask:0xf bound_ctrl:1
	v_add_f32_dpp v124, v124, v124 row_shr:1 row_mask:0xf bank_mask:0xf bound_ctrl:1
	v_add_f32_dpp v132, v117, v117 row_shr:1 row_mask:0xf bank_mask:0xf bound_ctrl:1
	v_add_f32_dpp v117, v125, v132 row_shl:15 row_mask:0xf bank_mask:0xf bound_ctrl:1
	v_add_f32_dpp v125, v125, v125 row_shr:1 row_mask:0xf bank_mask:0xf bound_ctrl:1
	v_add_f32_dpp v132, v118, v118 row_shr:1 row_mask:0xf bank_mask:0xf bound_ctrl:1
	v_add_f32_dpp v118, v126, v132 row_shl:15 row_mask:0xf bank_mask:0xf bound_ctrl:1
	v_add_f32_dpp v126, v126, v126 row_shr:1 row_mask:0xf bank_mask:0xf bound_ctrl:1
	v_add_f32_dpp v132, v119, v119 row_shr:1 row_mask:0xf bank_mask:0xf bound_ctrl:1
	v_add_f32_dpp v119, v127, v132 row_shl:15 row_mask:0xf bank_mask:0xf bound_ctrl:1
	v_add_f32_dpp v127, v127, v127 row_shr:1 row_mask:0xf bank_mask:0xf bound_ctrl:1
	v_add_f32_dpp v132, v120, v120 row_shr:1 row_mask:0xf bank_mask:0xf bound_ctrl:1
	v_add_f32_dpp v120, v128, v132 row_shl:15 row_mask:0xf bank_mask:0xf bound_ctrl:1
	v_add_f32_dpp v128, v128, v128 row_shr:1 row_mask:0xf bank_mask:0xf bound_ctrl:1
	v_add_f32_dpp v132, v121, v121 row_shr:1 row_mask:0xf bank_mask:0xf bound_ctrl:1
	v_add_f32_dpp v121, v129, v132 row_shl:15 row_mask:0xf bank_mask:0xf bound_ctrl:1
	v_add_f32_dpp v129, v129, v129 row_shr:1 row_mask:0xf bank_mask:0xf bound_ctrl:1
	v_add_f32_dpp v132, v122, v122 row_shr:1 row_mask:0xf bank_mask:0xf bound_ctrl:1
	v_add_f32_dpp v122, v130, v132 row_shl:15 row_mask:0xf bank_mask:0xf bound_ctrl:1
	v_add_f32_dpp v130, v130, v130 row_shr:1 row_mask:0xf bank_mask:0xf bound_ctrl:1
	v_add_f32_dpp v132, v123, v123 row_shr:1 row_mask:0xf bank_mask:0xf bound_ctrl:1
	v_add_f32_dpp v123, v131, v132 row_shl:15 row_mask:0xf bank_mask:0xf bound_ctrl:1
	v_add_f32_dpp v131, v131, v131 row_shr:1 row_mask:0xf bank_mask:0xf bound_ctrl:1
; __device__ __forceinline__ v4u pack8(const float (&f)[8]) { v4u w; w.x = cvt_pk_bf16(f[0], f[1]); w.y = cvt_pk_bf16(f[2], f[3]); w.z = cvt_pk_bf16(f[4], f[5]); w.w = cvt_pk_bf16(f[6], f[7]); return w; }
; template <int SH> __device__ __forceinline__ float row_shr(float v) { return __int_as_float(__builtin_amdgcn_update_dpp(0, __float_as_int(v), 0x110 + SH, 0xf, 0xf, true)); }
; template <int SH> __device__ __forceinline__ float row_shl(float v) { return __int_as_float(__builtin_amdgcn_update_dpp(0, __float_as_int(v), 0x100 + SH, 0xf, 0xf, true)); }
; template <int S> __device__ __forceinline__ void win_step(float (&c)[8], float (&p)[8]) {
; #pragma unroll
;     for (int j = 0; j < 8; ++j) { const float cn = c[j] + row_shr<S>(c[j]) + row_shl<16 - S>(p[j]); p[j] += row_shr<S>(p[j]); c[j] = cn; }
; }
; template <int W> __device__ __forceinline__ void pool_group(const bf16* zrow  , const bf16* pw  , bf16* orow  , int pos, bool prev_ok) {
;     ...
;         win_step<1>(c, p);
;         if (W >= 4) win_step<2>(c, p);
;         if (W >= 8) win_step<4>(c, p);
;         if (W >= 16) win_step<8>(c, p);
;         float pl[8];
; #pragma unroll
;         for (int j = 0; j < 8; ++j) pl[j] = c[j] * inv - own[j];
;         const v4u pwk = pack8(pl); const bf16x8 pf = __builtin_bit_cast(bf16x8, pwk);
; #pragma unroll
;         for (int dt = 0; dt < 8; ++dt) acc[dt] = __builtin_amdgcn_mfma_f32_16x16x32_bf16(__builtin_bit_cast(bf16x8, aw[kk & 1][dt]), pf, acc[dt], 0, 0, 0);
;     }
	v_add_f32_dpp v132, v116, v116 row_shr:2 row_mask:0xf bank_mask:0xf bound_ctrl:1
	v_add_f32_dpp v116, v124, v132 row_shl:14 row_mask:0xf bank_mask:0xf bound_ctrl:1
	v_add_f32_dpp v124, v124, v124 row_shr:2 row_mask:0xf bank_mask:0xf bound_ctrl:1
	v_add_f32_dpp v132, v117, v117 row_shr:2 row_mask:0xf bank_mask:0xf bound_ctrl:1
	v_add_f32_dpp v117, v125, v132 row_shl:14 row_mask:0xf bank_mask:0xf bound_ctrl:1
	v_add_f32_dpp v125, v125, v125 row_shr:2 row_mask:0xf bank_mask:0xf bound_ctrl:1
	v_add_f32_dpp v132, v118, v118 row_shr:2 row_mask:0xf bank_mask:0xf bound_ctrl:1
	v_add_f32_dpp v118, v126, v132 row_shl:14 row_mask:0xf bank_mask:0xf bound_ctrl:1
	v_add_f32_dpp v126, v126, v126 row_shr:2 row_mask:0xf bank_mask:0xf bound_ctrl:1
	v_add_f32_dpp v132, v119, v119 row_shr:2 row_mask:0xf bank_mask:0xf bound_ctrl:1
	v_add_f32_dpp v119, v127, v132 row_shl:14 row_mask:0xf bank_mask:0xf bound_ctrl:1
	v_add_f32_dpp v127, v127, v127 row_shr:2 row_mask:0xf bank_mask:0xf bound_ctrl:1
	v_add_f32_dpp v132, v120, v120 row_shr:2 row_mask:0xf bank_mask:0xf bound_ctrl:1
	v_add_f32_dpp v120, v128, v132 row_shl:14 row_mask:0xf bank_mask:0xf bound_ctrl:1
	v_add_f32_dpp v128, v128, v128 row_shr:2 row_mask:0xf bank_mask:0xf bound_ctrl:1
	v_add_f32_dpp v132, v121, v121 row_shr:2 row_mask:0xf bank_mask:0xf bound_ctrl:1
	v_add_f32_dpp v121, v129, v132 row_shl:14 row_mask:0xf bank_mask:0xf bound_ctrl:1
	v_add_f32_dpp v129, v129, v129 row_shr:2 row_mask:0xf bank_mask:0xf bound_ctrl:1
	v_add_f32_dpp v132, v122, v122 row_shr:2 row_mask:0xf bank_mask:0xf bound_ctrl:1
	v_add_f32_dpp v122, v130, v132 row_shl:14 row_mask:0xf bank_mask:0xf bound_ctrl:1
	v_add_f32_dpp v130, v130, v130 row_shr:2 row_mask:0xf bank_mask:0xf bound_ctrl:1
	v_add_f32_dpp v132, v123, v123 row_shr:2 row_mask:0xf bank_mask:0xf bound_ctrl:1
	v_add_f32_dpp v123, v131, v132 row_shl:14 row_mask:0xf bank_mask:0xf bound_ctrl:1
	v_add_f32_dpp v131, v131, v131 row_shr:2 row_mask:0xf bank_mask:0xf bound_ctrl:1
	v_add_f32_dpp v132, v116, v116 row_shr:4 row_mask:0xf bank_mask:0xf bound_ctrl:1
	v_add_f32_dpp v116, v124, v132 row_shl:12 row_mask:0xf bank_mask:0xf bound_ctrl:1
	v_add_f32_dpp v124, v124, v124 row_shr:4 row_mask:0xf bank_mask:0xf bound_ctrl:1
	v_add_f32_dpp v132, v117, v117 row_shr:4 row_mask:0xf bank_mask:0xf bound_ctrl:1
	v_add_f32_dpp v117, v125, v132 row_shl:12 row_mask:0xf bank_mask:0xf bound_ctrl:1
	v_add_f32_dpp v125, v125, v125 row_shr:4 row_mask:0xf bank_mask:0xf bound_ctrl:1
	v_add_f32_dpp v132, v118, v118 row_shr:4 row_mask:0xf bank_mask:0xf bound_ctrl:1
	v_add_f32_dpp v118, v126, v132 row_shl:12 row_mask:0xf bank_mask:0xf bound_ctrl:1
	v_add_f32_dpp v126, v126, v126 row_shr:4 row_mask:0xf bank_mask:0xf bound_ctrl:1
	v_add_f32_dpp v132, v119, v119 row_shr:4 row_mask:0xf bank_mask:0xf bound_ctrl:1
	v_add_f32_dpp v119, v127, v132 row_shl:12 row_mask:0xf bank_mask:0xf bound_ctrl:1
	v_add_f32_dpp v127, v127, v127 row_shr:4 row_mask:0xf bank_mask:0xf bound_ctrl:1
	v_add_f32_dpp v132, v120, v120 row_shr:4 row_mask:0xf bank_mask:0xf bound_ctrl:1
	v_add_f32_dpp v120, v128, v132 row_shl:12 row_mask:0xf bank_mask:0xf bound_ctrl:1
	v_add_f32_dpp v128, v128, v128 row_shr:4 row_mask:0xf bank_mask:0xf bound_ctrl:1
	v_add_f32_dpp v132, v121, v121 row_shr:4 row_mask:0xf bank_mask:0xf bound_ctrl:1
	v_add_f32_dpp v121, v129, v132 row_shl:12 row_mask:0xf bank_mask:0xf bound_ctrl:1
	v_add_f32_dpp v129, v129, v129 row_shr:4 row_mask:0xf bank_mask:0xf bound_ctrl:1
	v_add_f32_dpp v132, v122, v122 row_shr:4 row_mask:0xf bank_mask:0xf bound_ctrl:1
	v_add_f32_dpp v122, v130, v132 row_shl:12 row_mask:0xf bank_mask:0xf bound_ctrl:1
	v_add_f32_dpp v130, v130, v130 row_shr:4 row_mask:0xf bank_mask:0xf bound_ctrl:1
	v_add_f32_dpp v132, v123, v123 row_shr:4 row_mask:0xf bank_mask:0xf bound_ctrl:1
	v_add_f32_dpp v123, v131, v132 row_shl:12 row_mask:0xf bank_mask:0xf bound_ctrl:1
	v_add_f32_dpp v131, v131, v131 row_shr:4 row_mask:0xf bank_mask:0xf bound_ctrl:1
	v_fma_f32 v116, v116, v138, -v108
	v_fma_f32 v117, v117, v138, -v109
	v_fma_f32 v118, v118, v138, -v110
	v_fma_f32 v119, v119, v138, -v111
	v_fma_f32 v120, v120, v138, -v112
	v_fma_f32 v121, v121, v138, -v113
	v_fma_f32 v122, v122, v138, -v114
	v_fma_f32 v123, v123, v138, -v115
	v_cvt_pk_bf16_f32 v134, v116, v117
	v_cvt_pk_bf16_f32 v135, v118, v119
	v_cvt_pk_bf16_f32 v136, v120, v121
	v_cvt_pk_bf16_f32 v137, v122, v123
	s_waitcnt lgkmcnt(0)
	s_nop 0
	v_mfma_f32_16x16x32_bf16 v[76:79], v[44:47], v[134:137], 0
	v_mfma_f32_16x16x32_bf16 v[80:83], v[48:51], v[134:137], 0
	v_mfma_f32_16x16x32_bf16 v[84:87], v[52:55], v[134:137], 0
	v_mfma_f32_16x16x32_bf16 v[88:91], v[56:59], v[134:137], 0
	v_mfma_f32_16x16x32_bf16 v[92:95], v[60:63], v[134:137], 0
	v_mfma_f32_16x16x32_bf16 v[96:99], v[64:67], v[134:137], 0
	v_mfma_f32_16x16x32_bf16 v[100:103], v[68:71], v[134:137], 0
	v_mfma_f32_16x16x32_bf16 v[104:107], v[72:75], v[134:137], 0
	v_add_u32_e32 v147, 65536, v144
	ds_read_b128 v[44:47], v147
	ds_read_b128 v[48:51], v147 offset:4096
	ds_read_b128 v[52:55], v147 offset:8192
	ds_read_b128 v[56:59], v147 offset:12288
	ds_read_b128 v[60:63], v147 offset:16384
	ds_read_b128 v[64:67], v147 offset:20480
	ds_read_b128 v[68:71], v147 offset:24576
	ds_read_b128 v[72:75], v147 offset:28672
	s_waitcnt vmcnt(14)
; #define GAS __attribute__((address_space(1)))
; __device__ __forceinline__ void unpack8(const v4u w, float (&f)[8]) { f[0] = bf_lo(w.x); f[1] = bf_hi(w.x); f[2] = bf_lo(w.y); f[3] = bf_hi(w.y); f[4] = bf_lo(w.z); f[5] = bf_hi(w.z); f[6] = bf_lo(w.w); f[7] = bf_hi(w.w); }
; template <int SH> __device__ __forceinline__ float row_shr(float v) { return __int_as_float(__builtin_amdgcn_update_dpp(0, __float_as_int(v), 0x110 + SH, 0xf, 0xf, true)); }
; template <int SH> __device__ __forceinline__ float row_shl(float v) { return __int_as_float(__builtin_amdgcn_update_dpp(0, __float_as_int(v), 0x100 + SH, 0xf, 0xf, true)); }
; template <int S> __device__ __forceinline__ void win_step(float (&c)[8], float (&p)[8]) {
; #pragma unroll
;     for (int j = 0; j < 8; ++j) { const float cn = c[j] + row_shr<S>(c[j]) + row_shl<16 - S>(p[j]); p[j] += row_shr<S>(p[j]); c[j] = cn; }
; }
; template <int W> __device__ __forceinline__ void pool_group(const bf16* zrow  , const bf16* pw  , bf16* orow  , int pos, bool prev_ok) {
;     ...
;     for (int kk = 0; kk < 4; ++kk) {
;         if (kk < 3) {
; #pragma unroll
;             for (int dt = 0; dt < 8; ++dt) aw[(kk + 1) & 1][dt] = *(const GAS v4u*)(pw + (size_t)16 * dt * 128 + 32 * (kk + 1)); }
;         float own[8], c[8], p[8];
;         unpack8(cw[kk], own); unpack8(pv[kk], p);
; #pragma unroll
;         for (int j = 0; j < 8; ++j) c[j] = own[j];
;         win_step<1>(c, p);
;         if (W >= 4) win_step<2>(c, p);
;         if (W >= 8) win_step<4>(c, p);
;         if (W >= 16) win_step<8>(c, p);
	v_lshlrev_b32_e32 v108, 16, v20
	v_and_b32_e32 v109, 0xffff0000, v20
	v_lshlrev_b32_e32 v110, 16, v21
	v_and_b32_e32 v111, 0xffff0000, v21
	v_lshlrev_b32_e32 v112, 16, v22
	v_and_b32_e32 v113, 0xffff0000, v22
	v_lshlrev_b32_e32 v114, 16, v23
	v_and_b32_e32 v115, 0xffff0000, v23
	v_lshlrev_b32_e32 v124, 16, v24
	v_and_b32_e32 v125, 0xffff0000, v24
	v_lshlrev_b32_e32 v126, 16, v25
	v_and_b32_e32 v127, 0xffff0000, v25
	v_lshlrev_b32_e32 v128, 16, v26
	v_and_b32_e32 v129, 0xffff0000, v26
	v_lshlrev_b32_e32 v130, 16, v27
	v_and_b32_e32 v131, 0xffff0000, v27
	v_cndmask_b32_e64 v124, 0, v124, s[40:41]
	v_cndmask_b32_e64 v125, 0, v125, s[40:41]
	v_cndmask_b32_e64 v126, 0, v126, s[40:41]
	v_cndmask_b32_e64 v127, 0, v127, s[40:41]
	v_cndmask_b32_e64 v128, 0, v128, s[40:41]
	v_cndmask_b32_e64 v129, 0, v129, s[40:41]
	v_cndmask_b32_e64 v130, 0, v130, s[40:41]
	v_cndmask_b32_e64 v131, 0, v131, s[40:41]
	global_load_dwordx4 v[20:23], v11, s[38:39] offset:832
	global_load_dwordx4 v[24:27], v11, s[48:49] offset:832
	v_mov_b32_e32 v116, v108
	v_mov_b32_e32 v117, v109
	v_mov_b32_e32 v118, v110
	v_mov_b32_e32 v119, v111
	v_mov_b32_e32 v120, v112
	v_mov_b32_e32 v121, v113
	v_mov_b32_e32 v122, v114
	v_mov_b32_e32 v123, v115
	v_add_f32_dpp v132, v116, v116 row_shr:1 row_mask:0xf bank_mask:0xf bound_ctrl:1
	v_add_f32_dpp v116, v124, v132 row_shl:15 row_mask:0xf bank_mask:0xf bound_ctrl:1
	v_add_f32_dpp v124, v124, v124 row_shr:1 row_mask:0xf bank_mask:0xf bound_ctrl:1
	v_add_f32_dpp v132, v117, v117 row_shr:1 row_mask:0xf bank_mask:0xf bound_ctrl:1
	v_add_f32_dpp v117, v125, v132 row_shl:15 row_mask:0xf bank_mask:0xf bound_ctrl:1
	v_add_f32_dpp v125, v125, v125 row_shr:1 row_mask:0xf bank_mask:0xf bound_ctrl:1
	v_add_f32_dpp v132, v118, v118 row_shr:1 row_mask:0xf bank_mask:0xf bound_ctrl:1
	v_add_f32_dpp v118, v126, v132 row_shl:15 row_mask:0xf bank_mask:0xf bound_ctrl:1
	v_add_f32_dpp v126, v126, v126 row_shr:1 row_mask:0xf bank_mask:0xf bound_ctrl:1
	v_add_f32_dpp v132, v119, v119 row_shr:1 row_mask:0xf bank_mask:0xf bound_ctrl:1
	v_add_f32_dpp v119, v127, v132 row_shl:15 row_mask:0xf bank_mask:0xf bound_ctrl:1
	v_add_f32_dpp v127, v127, v127 row_shr:1 row_mask:0xf bank_mask:0xf bound_ctrl:1
	v_add_f32_dpp v132, v120, v120 row_shr:1 row_mask:0xf bank_mask:0xf bound_ctrl:1
	v_add_f32_dpp v120, v128, v132 row_shl:15 row_mask:0xf bank_mask:0xf bound_ctrl:1
	v_add_f32_dpp v128, v128, v128 row_shr:1 row_mask:0xf bank_mask:0xf bound_ctrl:1
	v_add_f32_dpp v132, v121, v121 row_shr:1 row_mask:0xf bank_mask:0xf bound_ctrl:1
	v_add_f32_dpp v121, v129, v132 row_shl:15 row_mask:0xf bank_mask:0xf bound_ctrl:1
	v_add_f32_dpp v129, v129, v129 row_shr:1 row_mask:0xf bank_mask:0xf bound_ctrl:1
	v_add_f32_dpp v132, v122, v122 row_shr:1 row_mask:0xf bank_mask:0xf bound_ctrl:1
	v_add_f32_dpp v122, v130, v132 row_shl:15 row_mask:0xf bank_mask:0xf bound_ctrl:1
	v_add_f32_dpp v130, v130, v130 row_shr:1 row_mask:0xf bank_mask:0xf bound_ctrl:1
	v_add_f32_dpp v132, v123, v123 row_shr:1 row_mask:0xf bank_mask:0xf bound_ctrl:1
	v_add_f32_dpp v123, v131, v132 row_shl:15 row_mask:0xf bank_mask:0xf bound_ctrl:1
	v_add_f32_dpp v131, v131, v131 row_shr:1 row_mask:0xf bank_mask:0xf bound_ctrl:1
	v_add_f32_dpp v132, v116, v116 row_shr:2 row_mask:0xf bank_mask:0xf bound_ctrl:1
	v_add_f32_dpp v116, v124, v132 row_shl:14 row_mask:0xf bank_mask:0xf bound_ctrl:1
	v_add_f32_dpp v124, v124, v124 row_shr:2 row_mask:0xf bank_mask:0xf bound_ctrl:1
	v_add_f32_dpp v132, v117, v117 row_shr:2 row_mask:0xf bank_mask:0xf bound_ctrl:1
	v_add_f32_dpp v117, v125, v132 row_shl:14 row_mask:0xf bank_mask:0xf bound_ctrl:1
	v_add_f32_dpp v125, v125, v125 row_shr:2 row_mask:0xf bank_mask:0xf bound_ctrl:1
	v_add_f32_dpp v132, v118, v118 row_shr:2 row_mask:0xf bank_mask:0xf bound_ctrl:1
	v_add_f32_dpp v118, v126, v132 row_shl:14 row_mask:0xf bank_mask:0xf bound_ctrl:1
	v_add_f32_dpp v126, v126, v126 row_shr:2 row_mask:0xf bank_mask:0xf bound_ctrl:1
	v_add_f32_dpp v132, v119, v119 row_shr:2 row_mask:0xf bank_mask:0xf bound_ctrl:1
	v_add_f32_dpp v119, v127, v132 row_shl:14 row_mask:0xf bank_mask:0xf bound_ctrl:1
	v_add_f32_dpp v127, v127, v127 row_shr:2 row_mask:0xf bank_mask:0xf bound_ctrl:1
	v_add_f32_dpp v132, v120, v120 row_shr:2 row_mask:0xf bank_mask:0xf bound_ctrl:1
	v_add_f32_dpp v120, v128, v132 row_shl:14 row_mask:0xf bank_mask:0xf bound_ctrl:1
	v_add_f32_dpp v128, v128, v128 row_shr:2 row_mask:0xf bank_mask:0xf bound_ctrl:1
	v_add_f32_dpp v132, v121, v121 row_shr:2 row_mask:0xf bank_mask:0xf bound_ctrl:1
	v_add_f32_dpp v121, v129, v132 row_shl:14 row_mask:0xf bank_mask:0xf bound_ctrl:1
	v_add_f32_dpp v129, v129, v129 row_shr:2 row_mask:0xf bank_mask:0xf bound_ctrl:1
	v_add_f32_dpp v132, v122, v122 row_shr:2 row_mask:0xf bank_mask:0xf bound_ctrl:1
	v_add_f32_dpp v122, v130, v132 row_shl:14 row_mask:0xf bank_mask:0xf bound_ctrl:1
	v_add_f32_dpp v130, v130, v130 row_shr:2 row_mask:0xf bank_mask:0xf bound_ctrl:1
	v_add_f32_dpp v132, v123, v123 row_shr:2 row_mask:0xf bank_mask:0xf bound_ctrl:1
	v_add_f32_dpp v123, v131, v132 row_shl:14 row_mask:0xf bank_mask:0xf bound_ctrl:1
	v_add_f32_dpp v131, v131, v131 row_shr:2 row_mask:0xf bank_mask:0xf bound_ctrl:1
	v_add_f32_dpp v132, v116, v116 row_shr:4 row_mask:0xf bank_mask:0xf bound_ctrl:1
	v_add_f32_dpp v116, v124, v132 row_shl:12 row_mask:0xf bank_mask:0xf bound_ctrl:1
	v_add_f32_dpp v124, v124, v124 row_shr:4 row_mask:0xf bank_mask:0xf bound_ctrl:1
	v_add_f32_dpp v132, v117, v117 row_shr:4 row_mask:0xf bank_mask:0xf bound_ctrl:1
	v_add_f32_dpp v117, v125, v132 row_shl:12 row_mask:0xf bank_mask:0xf bound_ctrl:1
	v_add_f32_dpp v125, v125, v125 row_shr:4 row_mask:0xf bank_mask:0xf bound_ctrl:1
; #define GAS __attribute__((address_space(1)))
; __device__ __forceinline__ void unpack8(const v4u w, float (&f)[8]) { f[0] = bf_lo(w.x); f[1] = bf_hi(w.x); f[2] = bf_lo(w.y); f[3] = bf_hi(w.y); f[4] = bf_lo(w.z); f[5] = bf_hi(w.z); f[6] = bf_lo(w.w); f[7] = bf_hi(w.w); }
; __device__ __forceinline__ v4u pack8(const float (&f)[8]) { v4u w; w.x = cvt_pk_bf16(f[0], f[1]); w.y = cvt_pk_bf16(f[2], f[3]); w.z = cvt_pk_bf16(f[4], f[5]); w.w = cvt_pk_bf16(f[6], f[7]); return w; }
; template <int W> __device__ __forceinline__ void pool_group(const bf16* zrow  , const bf16* pw  , bf16* orow  , int pos, bool prev_ok) {
;     ...
;     for (int kk = 0; kk < 4; ++kk) {
;         if (kk < 3) {
; #pragma unroll
;             for (int dt = 0; dt < 8; ++dt) aw[(kk + 1) & 1][dt] = *(const GAS v4u*)(pw + (size_t)16 * dt * 128 + 32 * (kk + 1)); }
;         float own[8], c[8], p[8];
;         unpack8(cw[kk], own); unpack8(pv[kk], p);
; #pragma unroll
;         for (int j = 0; j < 8; ++j) c[j] = own[j];
;         win_step<1>(c, p);
;     ...
;         if (W >= 16) win_step<8>(c, p);
;         float pl[8];
; #pragma unroll
;         for (int j = 0; j < 8; ++j) pl[j] = c[j] * inv - own[j];
;         const v4u pwk = pack8(pl); const bf16x8 pf = __builtin_bit_cast(bf16x8, pwk);
; #pragma unroll
;         for (int dt = 0; dt < 8; ++dt) acc[dt] = __builtin_amdgcn_mfma_f32_16x16x32_bf16(__builtin_bit_cast(bf16x8, aw[kk & 1][dt]), pf, acc[dt], 0, 0, 0);
;     }
	v_add_f32_dpp v132, v118, v118 row_shr:4 row_mask:0xf bank_mask:0xf bound_ctrl:1
	v_add_f32_dpp v118, v126, v132 row_shl:12 row_mask:0xf bank_mask:0xf bound_ctrl:1
	v_add_f32_dpp v126, v126, v126 row_shr:4 row_mask:0xf bank_mask:0xf bound_ctrl:1
	v_add_f32_dpp v132, v119, v119 row_shr:4 row_mask:0xf bank_mask:0xf bound_ctrl:1
	v_add_f32_dpp v119, v127, v132 row_shl:12 row_mask:0xf bank_mask:0xf bound_ctrl:1
	v_add_f32_dpp v127, v127, v127 row_shr:4 row_mask:0xf bank_mask:0xf bound_ctrl:1
	v_add_f32_dpp v132, v120, v120 row_shr:4 row_mask:0xf bank_mask:0xf bound_ctrl:1
	v_add_f32_dpp v120, v128, v132 row_shl:12 row_mask:0xf bank_mask:0xf bound_ctrl:1
	v_add_f32_dpp v128, v128, v128 row_shr:4 row_mask:0xf bank_mask:0xf bound_ctrl:1
	v_add_f32_dpp v132, v121, v121 row_shr:4 row_mask:0xf bank_mask:0xf bound_ctrl:1
	v_add_f32_dpp v121, v129, v132 row_shl:12 row_mask:0xf bank_mask:0xf bound_ctrl:1
	v_add_f32_dpp v129, v129, v129 row_shr:4 row_mask:0xf bank_mask:0xf bound_ctrl:1
	v_add_f32_dpp v132, v122, v122 row_shr:4 row_mask:0xf bank_mask:0xf bound_ctrl:1
	v_add_f32_dpp v122, v130, v132 row_shl:12 row_mask:0xf bank_mask:0xf bound_ctrl:1
	v_add_f32_dpp v130, v130, v130 row_shr:4 row_mask:0xf bank_mask:0xf bound_ctrl:1
	v_add_f32_dpp v132, v123, v123 row_shr:4 row_mask:0xf bank_mask:0xf bound_ctrl:1
	v_add_f32_dpp v123, v131, v132 row_shl:12 row_mask:0xf bank_mask:0xf bound_ctrl:1
	v_add_f32_dpp v131, v131, v131 row_shr:4 row_mask:0xf bank_mask:0xf bound_ctrl:1
	v_fma_f32 v116, v116, v138, -v108
	v_fma_f32 v117, v117, v138, -v109
	v_fma_f32 v118, v118, v138, -v110
	v_fma_f32 v119, v119, v138, -v111
	v_fma_f32 v120, v120, v138, -v112
	v_fma_f32 v121, v121, v138, -v113
	v_fma_f32 v122, v122, v138, -v114
	v_fma_f32 v123, v123, v138, -v115
	v_cvt_pk_bf16_f32 v134, v116, v117
	v_cvt_pk_bf16_f32 v135, v118, v119
	v_cvt_pk_bf16_f32 v136, v120, v121
	v_cvt_pk_bf16_f32 v137, v122, v123
	s_waitcnt lgkmcnt(0)
	s_nop 0
	v_mfma_f32_16x16x32_bf16 v[76:79], v[44:47], v[134:137], v[76:79]
	v_mfma_f32_16x16x32_bf16 v[80:83], v[48:51], v[134:137], v[80:83]
	v_mfma_f32_16x16x32_bf16 v[84:87], v[52:55], v[134:137], v[84:87]
	v_mfma_f32_16x16x32_bf16 v[88:91], v[56:59], v[134:137], v[88:91]
	v_mfma_f32_16x16x32_bf16 v[92:95], v[60:63], v[134:137], v[92:95]
	v_mfma_f32_16x16x32_bf16 v[96:99], v[64:67], v[134:137], v[96:99]
	v_mfma_f32_16x16x32_bf16 v[100:103], v[68:71], v[134:137], v[100:103]
	v_mfma_f32_16x16x32_bf16 v[104:107], v[72:75], v[134:137], v[104:107]
	v_add_u32_e32 v147, 65536, v145
	ds_read_b128 v[44:47], v147
	ds_read_b128 v[48:51], v147 offset:4096
	ds_read_b128 v[52:55], v147 offset:8192
	ds_read_b128 v[56:59], v147 offset:12288
	ds_read_b128 v[60:63], v147 offset:16384
	ds_read_b128 v[64:67], v147 offset:20480
	ds_read_b128 v[68:71], v147 offset:24576
	ds_read_b128 v[72:75], v147 offset:28672
	s_waitcnt vmcnt(14)
	v_lshlrev_b32_e32 v108, 16, v28
	v_and_b32_e32 v109, 0xffff0000, v28
	v_lshlrev_b32_e32 v110, 16, v29
	v_and_b32_e32 v111, 0xffff0000, v29
	v_lshlrev_b32_e32 v112, 16, v30
	v_and_b32_e32 v113, 0xffff0000, v30
	v_lshlrev_b32_e32 v114, 16, v31
	v_and_b32_e32 v115, 0xffff0000, v31
	v_lshlrev_b32_e32 v124, 16, v32
	v_and_b32_e32 v125, 0xffff0000, v32
	v_lshlrev_b32_e32 v126, 16, v33
	v_and_b32_e32 v127, 0xffff0000, v33
	v_lshlrev_b32_e32 v128, 16, v34
	v_and_b32_e32 v129, 0xffff0000, v34
	v_lshlrev_b32_e32 v130, 16, v35
	v_and_b32_e32 v131, 0xffff0000, v35
	v_cndmask_b32_e64 v124, 0, v124, s[40:41]
	v_cndmask_b32_e64 v125, 0, v125, s[40:41]
	v_cndmask_b32_e64 v126, 0, v126, s[40:41]
	v_cndmask_b32_e64 v127, 0, v127, s[40:41]
	v_cndmask_b32_e64 v128, 0, v128, s[40:41]
	v_cndmask_b32_e64 v129, 0, v129, s[40:41]
	v_cndmask_b32_e64 v130, 0, v130, s[40:41]
	v_cndmask_b32_e64 v131, 0, v131, s[40:41]
	global_load_dwordx4 v[28:31], v11, s[38:39] offset:896
	global_load_dwordx4 v[32:35], v11, s[48:49] offset:896
	v_mov_b32_e32 v116, v108
	v_mov_b32_e32 v117, v109
	v_mov_b32_e32 v118, v110
	v_mov_b32_e32 v119, v111
	v_mov_b32_e32 v120, v112
	v_mov_b32_e32 v121, v113
	v_mov_b32_e32 v122, v114
	v_mov_b32_e32 v123, v115
	v_add_f32_dpp v132, v116, v116 row_shr:1 row_mask:0xf bank_mask:0xf bound_ctrl:1
	v_add_f32_dpp v116, v124, v132 row_shl:15 row_mask:0xf bank_mask:0xf bound_ctrl:1
	v_add_f32_dpp v124, v124, v124 row_shr:1 row_mask:0xf bank_mask:0xf bound_ctrl:1
	v_add_f32_dpp v132, v117, v117 row_shr:1 row_mask:0xf bank_mask:0xf bound_ctrl:1
	v_add_f32_dpp v117, v125, v132 row_shl:15 row_mask:0xf bank_mask:0xf bound_ctrl:1
	v_add_f32_dpp v125, v125, v125 row_shr:1 row_mask:0xf bank_mask:0xf bound_ctrl:1
	v_add_f32_dpp v132, v118, v118 row_shr:1 row_mask:0xf bank_mask:0xf bound_ctrl:1
	v_add_f32_dpp v118, v126, v132 row_shl:15 row_mask:0xf bank_mask:0xf bound_ctrl:1
	v_add_f32_dpp v126, v126, v126 row_shr:1 row_mask:0xf bank_mask:0xf bound_ctrl:1
	v_add_f32_dpp v132, v119, v119 row_shr:1 row_mask:0xf bank_mask:0xf bound_ctrl:1
	v_add_f32_dpp v119, v127, v132 row_shl:15 row_mask:0xf bank_mask:0xf bound_ctrl:1
	v_add_f32_dpp v127, v127, v127 row_shr:1 row_mask:0xf bank_mask:0xf bound_ctrl:1
	v_add_f32_dpp v132, v120, v120 row_shr:1 row_mask:0xf bank_mask:0xf bound_ctrl:1
	v_add_f32_dpp v120, v128, v132 row_shl:15 row_mask:0xf bank_mask:0xf bound_ctrl:1
	v_add_f32_dpp v128, v128, v128 row_shr:1 row_mask:0xf bank_mask:0xf bound_ctrl:1
	v_add_f32_dpp v132, v121, v121 row_shr:1 row_mask:0xf bank_mask:0xf bound_ctrl:1
	v_add_f32_dpp v121, v129, v132 row_shl:15 row_mask:0xf bank_mask:0xf bound_ctrl:1
	v_add_f32_dpp v129, v129, v129 row_shr:1 row_mask:0xf bank_mask:0xf bound_ctrl:1
	v_add_f32_dpp v132, v122, v122 row_shr:1 row_mask:0xf bank_mask:0xf bound_ctrl:1
; __device__ __forceinline__ v4u pack8(const float (&f)[8]) { v4u w; w.x = cvt_pk_bf16(f[0], f[1]); w.y = cvt_pk_bf16(f[2], f[3]); w.z = cvt_pk_bf16(f[4], f[5]); w.w = cvt_pk_bf16(f[6], f[7]); return w; }
; template <int SH> __device__ __forceinline__ float row_shr(float v) { return __int_as_float(__builtin_amdgcn_update_dpp(0, __float_as_int(v), 0x110 + SH, 0xf, 0xf, true)); }
; template <int SH> __device__ __forceinline__ float row_shl(float v) { return __int_as_float(__builtin_amdgcn_update_dpp(0, __float_as_int(v), 0x100 + SH, 0xf, 0xf, true)); }
; template <int S> __device__ __forceinline__ void win_step(float (&c)[8], float (&p)[8]) {
; #pragma unroll
;     for (int j = 0; j < 8; ++j) { const float cn = c[j] + row_shr<S>(c[j]) + row_shl<16 - S>(p[j]); p[j] += row_shr<S>(p[j]); c[j] = cn; }
; }
; template <int W> __device__ __forceinline__ void pool_group(const bf16* zrow  , const bf16* pw  , bf16* orow  , int pos, bool prev_ok) {
;     ...
;         win_step<1>(c, p);
;         if (W >= 4) win_step<2>(c, p);
;         if (W >= 8) win_step<4>(c, p);
;         if (W >= 16) win_step<8>(c, p);
;         float pl[8];
; #pragma unroll
;         for (int j = 0; j < 8; ++j) pl[j] = c[j] * inv - own[j];
;         const v4u pwk = pack8(pl); const bf16x8 pf = __builtin_bit_cast(bf16x8, pwk);
; #pragma unroll
;         for (int dt = 0; dt < 8; ++dt) acc[dt] = __builtin_amdgcn_mfma_f32_16x16x32_bf16(__builtin_bit_cast(bf16x8, aw[kk & 1][dt]), pf, acc[dt], 0, 0, 0);
;     }
	v_add_f32_dpp v122, v130, v132 row_shl:15 row_mask:0xf bank_mask:0xf bound_ctrl:1
	v_add_f32_dpp v130, v130, v130 row_shr:1 row_mask:0xf bank_mask:0xf bound_ctrl:1
	v_add_f32_dpp v132, v123, v123 row_shr:1 row_mask:0xf bank_mask:0xf bound_ctrl:1
	v_add_f32_dpp v123, v131, v132 row_shl:15 row_mask:0xf bank_mask:0xf bound_ctrl:1
	v_add_f32_dpp v131, v131, v131 row_shr:1 row_mask:0xf bank_mask:0xf bound_ctrl:1
	v_add_f32_dpp v132, v116, v116 row_shr:2 row_mask:0xf bank_mask:0xf bound_ctrl:1
	v_add_f32_dpp v116, v124, v132 row_shl:14 row_mask:0xf bank_mask:0xf bound_ctrl:1
	v_add_f32_dpp v124, v124, v124 row_shr:2 row_mask:0xf bank_mask:0xf bound_ctrl:1
	v_add_f32_dpp v132, v117, v117 row_shr:2 row_mask:0xf bank_mask:0xf bound_ctrl:1
	v_add_f32_dpp v117, v125, v132 row_shl:14 row_mask:0xf bank_mask:0xf bound_ctrl:1
	v_add_f32_dpp v125, v125, v125 row_shr:2 row_mask:0xf bank_mask:0xf bound_ctrl:1
	v_add_f32_dpp v132, v118, v118 row_shr:2 row_mask:0xf bank_mask:0xf bound_ctrl:1
	v_add_f32_dpp v118, v126, v132 row_shl:14 row_mask:0xf bank_mask:0xf bound_ctrl:1
	v_add_f32_dpp v126, v126, v126 row_shr:2 row_mask:0xf bank_mask:0xf bound_ctrl:1
	v_add_f32_dpp v132, v119, v119 row_shr:2 row_mask:0xf bank_mask:0xf bound_ctrl:1
	v_add_f32_dpp v119, v127, v132 row_shl:14 row_mask:0xf bank_mask:0xf bound_ctrl:1
	v_add_f32_dpp v127, v127, v127 row_shr:2 row_mask:0xf bank_mask:0xf bound_ctrl:1
	v_add_f32_dpp v132, v120, v120 row_shr:2 row_mask:0xf bank_mask:0xf bound_ctrl:1
	v_add_f32_dpp v120, v128, v132 row_shl:14 row_mask:0xf bank_mask:0xf bound_ctrl:1
	v_add_f32_dpp v128, v128, v128 row_shr:2 row_mask:0xf bank_mask:0xf bound_ctrl:1
	v_add_f32_dpp v132, v121, v121 row_shr:2 row_mask:0xf bank_mask:0xf bound_ctrl:1
	v_add_f32_dpp v121, v129, v132 row_shl:14 row_mask:0xf bank_mask:0xf bound_ctrl:1
	v_add_f32_dpp v129, v129, v129 row_shr:2 row_mask:0xf bank_mask:0xf bound_ctrl:1
	v_add_f32_dpp v132, v122, v122 row_shr:2 row_mask:0xf bank_mask:0xf bound_ctrl:1
	v_add_f32_dpp v122, v130, v132 row_shl:14 row_mask:0xf bank_mask:0xf bound_ctrl:1
	v_add_f32_dpp v130, v130, v130 row_shr:2 row_mask:0xf bank_mask:0xf bound_ctrl:1
	v_add_f32_dpp v132, v123, v123 row_shr:2 row_mask:0xf bank_mask:0xf bound_ctrl:1
	v_add_f32_dpp v123, v131, v132 row_shl:14 row_mask:0xf bank_mask:0xf bound_ctrl:1
	v_add_f32_dpp v131, v131, v131 row_shr:2 row_mask:0xf bank_mask:0xf bound_ctrl:1
	v_add_f32_dpp v132, v116, v116 row_shr:4 row_mask:0xf bank_mask:0xf bound_ctrl:1
	v_add_f32_dpp v116, v124, v132 row_shl:12 row_mask:0xf bank_mask:0xf bound_ctrl:1
	v_add_f32_dpp v124, v124, v124 row_shr:4 row_mask:0xf bank_mask:0xf bound_ctrl:1
	v_add_f32_dpp v132, v117, v117 row_shr:4 row_mask:0xf bank_mask:0xf bound_ctrl:1
	v_add_f32_dpp v117, v125, v132 row_shl:12 row_mask:0xf bank_mask:0xf bound_ctrl:1
	v_add_f32_dpp v125, v125, v125 row_shr:4 row_mask:0xf bank_mask:0xf bound_ctrl:1
	v_add_f32_dpp v132, v118, v118 row_shr:4 row_mask:0xf bank_mask:0xf bound_ctrl:1
	v_add_f32_dpp v118, v126, v132 row_shl:12 row_mask:0xf bank_mask:0xf bound_ctrl:1
	v_add_f32_dpp v126, v126, v126 row_shr:4 row_mask:0xf bank_mask:0xf bound_ctrl:1
	v_add_f32_dpp v132, v119, v119 row_shr:4 row_mask:0xf bank_mask:0xf bound_ctrl:1
	v_add_f32_dpp v119, v127, v132 row_shl:12 row_mask:0xf bank_mask:0xf bound_ctrl:1
	v_add_f32_dpp v127, v127, v127 row_shr:4 row_mask:0xf bank_mask:0xf bound_ctrl:1
	v_add_f32_dpp v132, v120, v120 row_shr:4 row_mask:0xf bank_mask:0xf bound_ctrl:1
	v_add_f32_dpp v120, v128, v132 row_shl:12 row_mask:0xf bank_mask:0xf bound_ctrl:1
	v_add_f32_dpp v128, v128, v128 row_shr:4 row_mask:0xf bank_mask:0xf bound_ctrl:1
	v_add_f32_dpp v132, v121, v121 row_shr:4 row_mask:0xf bank_mask:0xf bound_ctrl:1
	v_add_f32_dpp v121, v129, v132 row_shl:12 row_mask:0xf bank_mask:0xf bound_ctrl:1
	v_add_f32_dpp v129, v129, v129 row_shr:4 row_mask:0xf bank_mask:0xf bound_ctrl:1
	v_add_f32_dpp v132, v122, v122 row_shr:4 row_mask:0xf bank_mask:0xf bound_ctrl:1
	v_add_f32_dpp v122, v130, v132 row_shl:12 row_mask:0xf bank_mask:0xf bound_ctrl:1
	v_add_f32_dpp v130, v130, v130 row_shr:4 row_mask:0xf bank_mask:0xf bound_ctrl:1
	v_add_f32_dpp v132, v123, v123 row_shr:4 row_mask:0xf bank_mask:0xf bound_ctrl:1
	v_add_f32_dpp v123, v131, v132 row_shl:12 row_mask:0xf bank_mask:0xf bound_ctrl:1
	v_add_f32_dpp v131, v131, v131 row_shr:4 row_mask:0xf bank_mask:0xf bound_ctrl:1
	v_fma_f32 v116, v116, v138, -v108
	v_fma_f32 v117, v117, v138, -v109
	v_fma_f32 v118, v118, v138, -v110
	v_fma_f32 v119, v119, v138, -v111
	v_fma_f32 v120, v120, v138, -v112
	v_fma_f32 v121, v121, v138, -v113
	v_fma_f32 v122, v122, v138, -v114
	v_fma_f32 v123, v123, v138, -v115
	v_cvt_pk_bf16_f32 v134, v116, v117
	v_cvt_pk_bf16_f32 v135, v118, v119
	v_cvt_pk_bf16_f32 v136, v120, v121
	v_cvt_pk_bf16_f32 v137, v122, v123
	s_waitcnt lgkmcnt(0)
	s_nop 0
	v_mfma_f32_16x16x32_bf16 v[76:79], v[44:47], v[134:137], v[76:79]
	v_mfma_f32_16x16x32_bf16 v[80:83], v[48:51], v[134:137], v[80:83]
	v_mfma_f32_16x16x32_bf16 v[84:87], v[52:55], v[134:137], v[84:87]
	v_mfma_f32_16x16x32_bf16 v[88:91], v[56:59], v[134:137], v[88:91]
	v_mfma_f32_16x16x32_bf16 v[92:95], v[60:63], v[134:137], v[92:95]
	v_mfma_f32_16x16x32_bf16 v[96:99], v[64:67], v[134:137], v[96:99]
	v_mfma_f32_16x16x32_bf16 v[100:103], v[68:71], v[134:137], v[100:103]
	v_mfma_f32_16x16x32_bf16 v[104:107], v[72:75], v[134:137], v[104:107]
	v_add_u32_e32 v147, 65536, v146
	ds_read_b128 v[44:47], v147
	ds_read_b128 v[48:51], v147 offset:4096
	ds_read_b128 v[52:55], v147 offset:8192
	ds_read_b128 v[56:59], v147 offset:12288
	ds_read_b128 v[60:63], v147 offset:16384
	ds_read_b128 v[64:67], v147 offset:20480
	ds_read_b128 v[68:71], v147 offset:24576
	ds_read_b128 v[72:75], v147 offset:28672
	s_waitcnt vmcnt(14)
; #define GAS __attribute__((address_space(1)))
; __device__ __forceinline__ void unpack8(const v4u w, float (&f)[8]) { f[0] = bf_lo(w.x); f[1] = bf_hi(w.x); f[2] = bf_lo(w.y); f[3] = bf_hi(w.y); f[4] = bf_lo(w.z); f[5] = bf_hi(w.z); f[6] = bf_lo(w.w); f[7] = bf_hi(w.w); }
; template <int SH> __device__ __forceinline__ float row_shr(float v) { return __int_as_float(__builtin_amdgcn_update_dpp(0, __float_as_int(v), 0x110 + SH, 0xf, 0xf, true)); }
; template <int SH> __device__ __forceinline__ float row_shl(float v) { return __int_as_float(__builtin_amdgcn_update_dpp(0, __float_as_int(v), 0x100 + SH, 0xf, 0xf, true)); }
; template <int S> __device__ __forceinline__ void win_step(float (&c)[8], float (&p)[8]) {
; #pragma unroll
;     for (int j = 0; j < 8; ++j) { const float cn = c[j] + row_shr<S>(c[j]) + row_shl<16 - S>(p[j]); p[j] += row_shr<S>(p[j]); c[j] = cn; }
; }
; template <int W> __device__ __forceinline__ void pool_group(const bf16* zrow  , const bf16* pw  , bf16* orow  , int pos, bool prev_ok) {
;     ...
;     for (int kk = 0; kk < 4; ++kk) {
;         if (kk < 3) {
; #pragma unroll
;             for (int dt = 0; dt < 8; ++dt) aw[(kk + 1) & 1][dt] = *(const GAS v4u*)(pw + (size_t)16 * dt * 128 + 32 * (kk + 1)); }
;         float own[8], c[8], p[8];
;         unpack8(cw[kk], own); unpack8(pv[kk], p);
; #pragma unroll
;         for (int j = 0; j < 8; ++j) c[j] = own[j];
;         win_step<1>(c, p);
;         if (W >= 4) win_step<2>(c, p);
;         if (W >= 8) win_step<4>(c, p);
;         if (W >= 16) win_step<8>(c, p);
	v_lshlrev_b32_e32 v108, 16, v36
	v_and_b32_e32 v109, 0xffff0000, v36
	v_lshlrev_b32_e32 v110, 16, v37
	v_and_b32_e32 v111, 0xffff0000, v37
	v_lshlrev_b32_e32 v112, 16, v38
	v_and_b32_e32 v113, 0xffff0000, v38
	v_lshlrev_b32_e32 v114, 16, v39
	v_and_b32_e32 v115, 0xffff0000, v39
	v_lshlrev_b32_e32 v124, 16, v40
	v_and_b32_e32 v125, 0xffff0000, v40
	v_lshlrev_b32_e32 v126, 16, v41
	v_and_b32_e32 v127, 0xffff0000, v41
	v_lshlrev_b32_e32 v128, 16, v42
	v_and_b32_e32 v129, 0xffff0000, v42
	v_lshlrev_b32_e32 v130, 16, v43
	v_and_b32_e32 v131, 0xffff0000, v43
	v_cndmask_b32_e64 v124, 0, v124, s[40:41]
	v_cndmask_b32_e64 v125, 0, v125, s[40:41]
	v_cndmask_b32_e64 v126, 0, v126, s[40:41]
	v_cndmask_b32_e64 v127, 0, v127, s[40:41]
	v_cndmask_b32_e64 v128, 0, v128, s[40:41]
	v_cndmask_b32_e64 v129, 0, v129, s[40:41]
	v_cndmask_b32_e64 v130, 0, v130, s[40:41]
	v_cndmask_b32_e64 v131, 0, v131, s[40:41]
	global_load_dwordx4 v[36:39], v11, s[38:39] offset:960
	global_load_dwordx4 v[40:43], v11, s[48:49] offset:960
	v_mov_b32_e32 v116, v108
	v_mov_b32_e32 v117, v109
	v_mov_b32_e32 v118, v110
	v_mov_b32_e32 v119, v111
	v_mov_b32_e32 v120, v112
	v_mov_b32_e32 v121, v113
	v_mov_b32_e32 v122, v114
	v_mov_b32_e32 v123, v115
	v_add_f32_dpp v132, v116, v116 row_shr:1 row_mask:0xf bank_mask:0xf bound_ctrl:1
	v_add_f32_dpp v116, v124, v132 row_shl:15 row_mask:0xf bank_mask:0xf bound_ctrl:1
	v_add_f32_dpp v124, v124, v124 row_shr:1 row_mask:0xf bank_mask:0xf bound_ctrl:1
	v_add_f32_dpp v132, v117, v117 row_shr:1 row_mask:0xf bank_mask:0xf bound_ctrl:1
	v_add_f32_dpp v117, v125, v132 row_shl:15 row_mask:0xf bank_mask:0xf bound_ctrl:1
	v_add_f32_dpp v125, v125, v125 row_shr:1 row_mask:0xf bank_mask:0xf bound_ctrl:1
	v_add_f32_dpp v132, v118, v118 row_shr:1 row_mask:0xf bank_mask:0xf bound_ctrl:1
	v_add_f32_dpp v118, v126, v132 row_shl:15 row_mask:0xf bank_mask:0xf bound_ctrl:1
	v_add_f32_dpp v126, v126, v126 row_shr:1 row_mask:0xf bank_mask:0xf bound_ctrl:1
	v_add_f32_dpp v132, v119, v119 row_shr:1 row_mask:0xf bank_mask:0xf bound_ctrl:1
	v_add_f32_dpp v119, v127, v132 row_shl:15 row_mask:0xf bank_mask:0xf bound_ctrl:1
	v_add_f32_dpp v127, v127, v127 row_shr:1 row_mask:0xf bank_mask:0xf bound_ctrl:1
	v_add_f32_dpp v132, v120, v120 row_shr:1 row_mask:0xf bank_mask:0xf bound_ctrl:1
	v_add_f32_dpp v120, v128, v132 row_shl:15 row_mask:0xf bank_mask:0xf bound_ctrl:1
	v_add_f32_dpp v128, v128, v128 row_shr:1 row_mask:0xf bank_mask:0xf bound_ctrl:1
	v_add_f32_dpp v132, v121, v121 row_shr:1 row_mask:0xf bank_mask:0xf bound_ctrl:1
	v_add_f32_dpp v121, v129, v132 row_shl:15 row_mask:0xf bank_mask:0xf bound_ctrl:1
	v_add_f32_dpp v129, v129, v129 row_shr:1 row_mask:0xf bank_mask:0xf bound_ctrl:1
	v_add_f32_dpp v132, v122, v122 row_shr:1 row_mask:0xf bank_mask:0xf bound_ctrl:1
	v_add_f32_dpp v122, v130, v132 row_shl:15 row_mask:0xf bank_mask:0xf bound_ctrl:1
	v_add_f32_dpp v130, v130, v130 row_shr:1 row_mask:0xf bank_mask:0xf bound_ctrl:1
	v_add_f32_dpp v132, v123, v123 row_shr:1 row_mask:0xf bank_mask:0xf bound_ctrl:1
	v_add_f32_dpp v123, v131, v132 row_shl:15 row_mask:0xf bank_mask:0xf bound_ctrl:1
	v_add_f32_dpp v131, v131, v131 row_shr:1 row_mask:0xf bank_mask:0xf bound_ctrl:1
	v_add_f32_dpp v132, v116, v116 row_shr:2 row_mask:0xf bank_mask:0xf bound_ctrl:1
	v_add_f32_dpp v116, v124, v132 row_shl:14 row_mask:0xf bank_mask:0xf bound_ctrl:1
	v_add_f32_dpp v124, v124, v124 row_shr:2 row_mask:0xf bank_mask:0xf bound_ctrl:1
	v_add_f32_dpp v132, v117, v117 row_shr:2 row_mask:0xf bank_mask:0xf bound_ctrl:1
	v_add_f32_dpp v117, v125, v132 row_shl:14 row_mask:0xf bank_mask:0xf bound_ctrl:1
	v_add_f32_dpp v125, v125, v125 row_shr:2 row_mask:0xf bank_mask:0xf bound_ctrl:1
	v_add_f32_dpp v132, v118, v118 row_shr:2 row_mask:0xf bank_mask:0xf bound_ctrl:1
	v_add_f32_dpp v118, v126, v132 row_shl:14 row_mask:0xf bank_mask:0xf bound_ctrl:1
	v_add_f32_dpp v126, v126, v126 row_shr:2 row_mask:0xf bank_mask:0xf bound_ctrl:1
	v_add_f32_dpp v132, v119, v119 row_shr:2 row_mask:0xf bank_mask:0xf bound_ctrl:1
	v_add_f32_dpp v119, v127, v132 row_shl:14 row_mask:0xf bank_mask:0xf bound_ctrl:1
	v_add_f32_dpp v127, v127, v127 row_shr:2 row_mask:0xf bank_mask:0xf bound_ctrl:1
	v_add_f32_dpp v132, v120, v120 row_shr:2 row_mask:0xf bank_mask:0xf bound_ctrl:1
	v_add_f32_dpp v120, v128, v132 row_shl:14 row_mask:0xf bank_mask:0xf bound_ctrl:1
	v_add_f32_dpp v128, v128, v128 row_shr:2 row_mask:0xf bank_mask:0xf bound_ctrl:1
	v_add_f32_dpp v132, v121, v121 row_shr:2 row_mask:0xf bank_mask:0xf bound_ctrl:1
	v_add_f32_dpp v121, v129, v132 row_shl:14 row_mask:0xf bank_mask:0xf bound_ctrl:1
	v_add_f32_dpp v129, v129, v129 row_shr:2 row_mask:0xf bank_mask:0xf bound_ctrl:1
	v_add_f32_dpp v132, v122, v122 row_shr:2 row_mask:0xf bank_mask:0xf bound_ctrl:1
	v_add_f32_dpp v122, v130, v132 row_shl:14 row_mask:0xf bank_mask:0xf bound_ctrl:1
	v_add_f32_dpp v130, v130, v130 row_shr:2 row_mask:0xf bank_mask:0xf bound_ctrl:1
	v_add_f32_dpp v132, v123, v123 row_shr:2 row_mask:0xf bank_mask:0xf bound_ctrl:1
	v_add_f32_dpp v123, v131, v132 row_shl:14 row_mask:0xf bank_mask:0xf bound_ctrl:1
	v_add_f32_dpp v131, v131, v131 row_shr:2 row_mask:0xf bank_mask:0xf bound_ctrl:1
	v_add_f32_dpp v132, v116, v116 row_shr:4 row_mask:0xf bank_mask:0xf bound_ctrl:1
	v_add_f32_dpp v116, v124, v132 row_shl:12 row_mask:0xf bank_mask:0xf bound_ctrl:1
	v_add_f32_dpp v124, v124, v124 row_shr:4 row_mask:0xf bank_mask:0xf bound_ctrl:1
	v_add_f32_dpp v132, v117, v117 row_shr:4 row_mask:0xf bank_mask:0xf bound_ctrl:1
	v_add_f32_dpp v117, v125, v132 row_shl:12 row_mask:0xf bank_mask:0xf bound_ctrl:1
	v_add_f32_dpp v125, v125, v125 row_shr:4 row_mask:0xf bank_mask:0xf bound_ctrl:1
; __device__ __forceinline__ unsigned cvt_pk_bf16(float lo, float hi) { return __builtin_bit_cast(unsigned, __builtin_convertvector((f32x2_t){lo, hi}, bf16x2_t)); }
; #define GAS __attribute__((address_space(1)))
; __device__ __forceinline__ v4u pack8(const float (&f)[8]) { v4u w; w.x = cvt_pk_bf16(f[0], f[1]); w.y = cvt_pk_bf16(f[2], f[3]); w.z = cvt_pk_bf16(f[4], f[5]); w.w = cvt_pk_bf16(f[6], f[7]); return w; }
; template <int W> __device__ __forceinline__ void pool_group(const bf16* zrow  , const bf16* pw  , bf16* orow  , int pos, bool prev_ok) {
;     const float inv = 1.0f / (float)((pos + 1) < W ? (pos + 1) : W);
;     ...
;         if (W >= 16) win_step<8>(c, p);
;         float pl[8];
; #pragma unroll
;         for (int j = 0; j < 8; ++j) pl[j] = c[j] * inv - own[j];
;         const v4u pwk = pack8(pl); const bf16x8 pf = __builtin_bit_cast(bf16x8, pwk);
; #pragma unroll
;         for (int dt = 0; dt < 8; ++dt) acc[dt] = __builtin_amdgcn_mfma_f32_16x16x32_bf16(__builtin_bit_cast(bf16x8, aw[kk & 1][dt]), pf, acc[dt], 0, 0, 0);
;     }
; #pragma unroll
;     for (int dt = 0; dt < 8; ++dt) { v2u w; w.x = cvt_pk_bf16(acc[dt][0], acc[dt][1]); w.y = cvt_pk_bf16(acc[dt][2], acc[dt][3]); *(GAS v2u*)(orow + 16 * dt) = w; }
	v_add_f32_dpp v132, v118, v118 row_shr:4 row_mask:0xf bank_mask:0xf bound_ctrl:1
	v_add_f32_dpp v118, v126, v132 row_shl:12 row_mask:0xf bank_mask:0xf bound_ctrl:1
	v_add_f32_dpp v126, v126, v126 row_shr:4 row_mask:0xf bank_mask:0xf bound_ctrl:1
	v_add_f32_dpp v132, v119, v119 row_shr:4 row_mask:0xf bank_mask:0xf bound_ctrl:1
	v_add_f32_dpp v119, v127, v132 row_shl:12 row_mask:0xf bank_mask:0xf bound_ctrl:1
	v_add_f32_dpp v127, v127, v127 row_shr:4 row_mask:0xf bank_mask:0xf bound_ctrl:1
	v_add_f32_dpp v132, v120, v120 row_shr:4 row_mask:0xf bank_mask:0xf bound_ctrl:1
	v_add_f32_dpp v120, v128, v132 row_shl:12 row_mask:0xf bank_mask:0xf bound_ctrl:1
	v_add_f32_dpp v128, v128, v128 row_shr:4 row_mask:0xf bank_mask:0xf bound_ctrl:1
	v_add_f32_dpp v132, v121, v121 row_shr:4 row_mask:0xf bank_mask:0xf bound_ctrl:1
	v_add_f32_dpp v121, v129, v132 row_shl:12 row_mask:0xf bank_mask:0xf bound_ctrl:1
	v_add_f32_dpp v129, v129, v129 row_shr:4 row_mask:0xf bank_mask:0xf bound_ctrl:1
	v_add_f32_dpp v132, v122, v122 row_shr:4 row_mask:0xf bank_mask:0xf bound_ctrl:1
	v_add_f32_dpp v122, v130, v132 row_shl:12 row_mask:0xf bank_mask:0xf bound_ctrl:1
	v_add_f32_dpp v130, v130, v130 row_shr:4 row_mask:0xf bank_mask:0xf bound_ctrl:1
	v_add_f32_dpp v132, v123, v123 row_shr:4 row_mask:0xf bank_mask:0xf bound_ctrl:1
	v_add_f32_dpp v123, v131, v132 row_shl:12 row_mask:0xf bank_mask:0xf bound_ctrl:1
	v_add_f32_dpp v131, v131, v131 row_shr:4 row_mask:0xf bank_mask:0xf bound_ctrl:1
	v_fma_f32 v116, v116, v138, -v108
	v_fma_f32 v117, v117, v138, -v109
	v_fma_f32 v118, v118, v138, -v110
	v_fma_f32 v119, v119, v138, -v111
	v_fma_f32 v120, v120, v138, -v112
	v_fma_f32 v121, v121, v138, -v113
	v_fma_f32 v122, v122, v138, -v114
	v_fma_f32 v123, v123, v138, -v115
	v_cvt_pk_bf16_f32 v134, v116, v117
	v_cvt_pk_bf16_f32 v135, v118, v119
	v_cvt_pk_bf16_f32 v136, v120, v121
	v_cvt_pk_bf16_f32 v137, v122, v123
	s_waitcnt lgkmcnt(0)
	s_nop 0
	v_mfma_f32_16x16x32_bf16 v[76:79], v[44:47], v[134:137], v[76:79]
	v_mfma_f32_16x16x32_bf16 v[80:83], v[48:51], v[134:137], v[80:83]
	v_mfma_f32_16x16x32_bf16 v[84:87], v[52:55], v[134:137], v[84:87]
	v_mfma_f32_16x16x32_bf16 v[88:91], v[56:59], v[134:137], v[88:91]
	v_mfma_f32_16x16x32_bf16 v[92:95], v[60:63], v[134:137], v[92:95]
	v_mfma_f32_16x16x32_bf16 v[96:99], v[64:67], v[134:137], v[96:99]
	v_mfma_f32_16x16x32_bf16 v[100:103], v[68:71], v[134:137], v[100:103]
	v_mfma_f32_16x16x32_bf16 v[104:107], v[72:75], v[134:137], v[104:107]
	s_nop 7
	s_nop 1
	v_cvt_pk_bf16_f32 v132, v76, v77
	v_cvt_pk_bf16_f32 v133, v78, v79
	global_store_dwordx2 v142, v[132:133], s[46:47] offset:512
	s_nop 0
	v_cvt_pk_bf16_f32 v132, v80, v81
	v_cvt_pk_bf16_f32 v133, v82, v83
	global_store_dwordx2 v142, v[132:133], s[46:47] offset:544
	s_nop 0
	v_cvt_pk_bf16_f32 v132, v84, v85
	v_cvt_pk_bf16_f32 v133, v86, v87
	global_store_dwordx2 v142, v[132:133], s[46:47] offset:576
	s_nop 0
	v_cvt_pk_bf16_f32 v132, v88, v89
	v_cvt_pk_bf16_f32 v133, v90, v91
	global_store_dwordx2 v142, v[132:133], s[46:47] offset:608
	s_nop 0
	v_cvt_pk_bf16_f32 v132, v92, v93
	v_cvt_pk_bf16_f32 v133, v94, v95
	global_store_dwordx2 v142, v[132:133], s[46:47] offset:640
	s_nop 0
	v_cvt_pk_bf16_f32 v132, v96, v97
	v_cvt_pk_bf16_f32 v133, v98, v99
	global_store_dwordx2 v142, v[132:133], s[46:47] offset:672
	s_nop 0
	v_cvt_pk_bf16_f32 v132, v100, v101
	v_cvt_pk_bf16_f32 v133, v102, v103
	global_store_dwordx2 v142, v[132:133], s[46:47] offset:704
	s_nop 0
	v_cvt_pk_bf16_f32 v132, v104, v105
	v_cvt_pk_bf16_f32 v133, v106, v107
	global_store_dwordx2 v142, v[132:133], s[46:47] offset:736
	s_nop 0
	v_min_i32_e32 v139, 16, v140
	v_cvt_f32_i32_e32 v139, v139
	v_div_scale_f32 v1, s[42:43], v139, v139, 1.0
	v_rcp_f32_e32 v2, v1
	s_nop 0
	v_fma_f32 v7, -v1, v2, 1.0
	v_fmac_f32_e32 v2, v7, v2
	v_div_scale_f32 v3, vcc, 1.0, v139, 1.0
	v_mul_f32_e32 v6, v3, v2
	v_fma_f32 v7, -v1, v6, v3
	v_fmac_f32_e32 v6, v7, v2
	v_fma_f32 v1, -v1, v6, v3
	s_nop 1
	v_div_fmas_f32 v1, v1, v2, v6
	v_div_fixup_f32 v138, v1, v139, 1.0
	v_add_u32_e32 v147, 98304, v143
	ds_read_b128 v[44:47], v147
	ds_read_b128 v[48:51], v147 offset:4096
	ds_read_b128 v[52:55], v147 offset:8192
	ds_read_b128 v[56:59], v147 offset:12288
	ds_read_b128 v[60:63], v147 offset:16384
	ds_read_b128 v[64:67], v147 offset:20480
	ds_read_b128 v[68:71], v147 offset:24576
	ds_read_b128 v[72:75], v147 offset:28672
	s_waitcnt vmcnt(14)
; #define GAS __attribute__((address_space(1)))
; __device__ __forceinline__ void unpack8(const v4u w, float (&f)[8]) { f[0] = bf_lo(w.x); f[1] = bf_hi(w.x); f[2] = bf_lo(w.y); f[3] = bf_hi(w.y); f[4] = bf_lo(w.z); f[5] = bf_hi(w.z); f[6] = bf_lo(w.w); f[7] = bf_hi(w.w); }
; template <int SH> __device__ __forceinline__ float row_shr(float v) { return __int_as_float(__builtin_amdgcn_update_dpp(0, __float_as_int(v), 0x110 + SH, 0xf, 0xf, true)); }
; template <int SH> __device__ __forceinline__ float row_shl(float v) { return __int_as_float(__builtin_amdgcn_update_dpp(0, __float_as_int(v), 0x100 + SH, 0xf, 0xf, true)); }
; template <int S> __device__ __forceinline__ void win_step(float (&c)[8], float (&p)[8]) {
; #pragma unroll
;     for (int j = 0; j < 8; ++j) { const float cn = c[j] + row_shr<S>(c[j]) + row_shl<16 - S>(p[j]); p[j] += row_shr<S>(p[j]); c[j] = cn; }
; }
; template <int W> __device__ __forceinline__ void pool_group(const bf16* zrow  , const bf16* pw  , bf16* orow  , int pos, bool prev_ok) {
;     ...
;     for (int kk = 0; kk < 4; ++kk) {
;         if (kk < 3) {
; #pragma unroll
;             for (int dt = 0; dt < 8; ++dt) aw[(kk + 1) & 1][dt] = *(const GAS v4u*)(pw + (size_t)16 * dt * 128 + 32 * (kk + 1)); }
;         float own[8], c[8], p[8];
;         unpack8(cw[kk], own); unpack8(pv[kk], p);
; #pragma unroll
;         for (int j = 0; j < 8; ++j) c[j] = own[j];
;         win_step<1>(c, p);
;         if (W >= 4) win_step<2>(c, p);
;         if (W >= 8) win_step<4>(c, p);
;         if (W >= 16) win_step<8>(c, p);
	v_lshlrev_b32_e32 v108, 16, v12
	v_and_b32_e32 v109, 0xffff0000, v12
	v_lshlrev_b32_e32 v110, 16, v13
	v_and_b32_e32 v111, 0xffff0000, v13
	v_lshlrev_b32_e32 v112, 16, v14
	v_and_b32_e32 v113, 0xffff0000, v14
	v_lshlrev_b32_e32 v114, 16, v15
	v_and_b32_e32 v115, 0xffff0000, v15
	v_lshlrev_b32_e32 v124, 16, v16
	v_and_b32_e32 v125, 0xffff0000, v16
	v_lshlrev_b32_e32 v126, 16, v17
	v_and_b32_e32 v127, 0xffff0000, v17
	v_lshlrev_b32_e32 v128, 16, v18
	v_and_b32_e32 v129, 0xffff0000, v18
	v_lshlrev_b32_e32 v130, 16, v19
	v_and_b32_e32 v131, 0xffff0000, v19
	v_cndmask_b32_e64 v124, 0, v124, s[40:41]
	v_cndmask_b32_e64 v125, 0, v125, s[40:41]
	v_cndmask_b32_e64 v126, 0, v126, s[40:41]
	v_cndmask_b32_e64 v127, 0, v127, s[40:41]
	v_cndmask_b32_e64 v128, 0, v128, s[40:41]
	v_cndmask_b32_e64 v129, 0, v129, s[40:41]
	v_cndmask_b32_e64 v130, 0, v130, s[40:41]
	v_cndmask_b32_e64 v131, 0, v131, s[40:41]
	v_mov_b32_e32 v116, v108
	v_mov_b32_e32 v117, v109
	v_mov_b32_e32 v118, v110
	v_mov_b32_e32 v119, v111
	v_mov_b32_e32 v120, v112
	v_mov_b32_e32 v121, v113
	v_mov_b32_e32 v122, v114
	v_mov_b32_e32 v123, v115
	v_add_f32_dpp v132, v116, v116 row_shr:1 row_mask:0xf bank_mask:0xf bound_ctrl:1
	v_add_f32_dpp v116, v124, v132 row_shl:15 row_mask:0xf bank_mask:0xf bound_ctrl:1
	v_add_f32_dpp v124, v124, v124 row_shr:1 row_mask:0xf bank_mask:0xf bound_ctrl:1
	v_add_f32_dpp v132, v117, v117 row_shr:1 row_mask:0xf bank_mask:0xf bound_ctrl:1
	v_add_f32_dpp v117, v125, v132 row_shl:15 row_mask:0xf bank_mask:0xf bound_ctrl:1
	v_add_f32_dpp v125, v125, v125 row_shr:1 row_mask:0xf bank_mask:0xf bound_ctrl:1
	v_add_f32_dpp v132, v118, v118 row_shr:1 row_mask:0xf bank_mask:0xf bound_ctrl:1
	v_add_f32_dpp v118, v126, v132 row_shl:15 row_mask:0xf bank_mask:0xf bound_ctrl:1
	v_add_f32_dpp v126, v126, v126 row_shr:1 row_mask:0xf bank_mask:0xf bound_ctrl:1
	v_add_f32_dpp v132, v119, v119 row_shr:1 row_mask:0xf bank_mask:0xf bound_ctrl:1
	v_add_f32_dpp v119, v127, v132 row_shl:15 row_mask:0xf bank_mask:0xf bound_ctrl:1
	v_add_f32_dpp v127, v127, v127 row_shr:1 row_mask:0xf bank_mask:0xf bound_ctrl:1
	v_add_f32_dpp v132, v120, v120 row_shr:1 row_mask:0xf bank_mask:0xf bound_ctrl:1
	v_add_f32_dpp v120, v128, v132 row_shl:15 row_mask:0xf bank_mask:0xf bound_ctrl:1
	v_add_f32_dpp v128, v128, v128 row_shr:1 row_mask:0xf bank_mask:0xf bound_ctrl:1
	v_add_f32_dpp v132, v121, v121 row_shr:1 row_mask:0xf bank_mask:0xf bound_ctrl:1
	v_add_f32_dpp v121, v129, v132 row_shl:15 row_mask:0xf bank_mask:0xf bound_ctrl:1
	v_add_f32_dpp v129, v129, v129 row_shr:1 row_mask:0xf bank_mask:0xf bound_ctrl:1
	v_add_f32_dpp v132, v122, v122 row_shr:1 row_mask:0xf bank_mask:0xf bound_ctrl:1
	v_add_f32_dpp v122, v130, v132 row_shl:15 row_mask:0xf bank_mask:0xf bound_ctrl:1
	v_add_f32_dpp v130, v130, v130 row_shr:1 row_mask:0xf bank_mask:0xf bound_ctrl:1
	v_add_f32_dpp v132, v123, v123 row_shr:1 row_mask:0xf bank_mask:0xf bound_ctrl:1
	v_add_f32_dpp v123, v131, v132 row_shl:15 row_mask:0xf bank_mask:0xf bound_ctrl:1
	v_add_f32_dpp v131, v131, v131 row_shr:1 row_mask:0xf bank_mask:0xf bound_ctrl:1
	v_add_f32_dpp v132, v116, v116 row_shr:2 row_mask:0xf bank_mask:0xf bound_ctrl:1
	v_add_f32_dpp v116, v124, v132 row_shl:14 row_mask:0xf bank_mask:0xf bound_ctrl:1
	v_add_f32_dpp v124, v124, v124 row_shr:2 row_mask:0xf bank_mask:0xf bound_ctrl:1
	v_add_f32_dpp v132, v117, v117 row_shr:2 row_mask:0xf bank_mask:0xf bound_ctrl:1
	v_add_f32_dpp v117, v125, v132 row_shl:14 row_mask:0xf bank_mask:0xf bound_ctrl:1
	v_add_f32_dpp v125, v125, v125 row_shr:2 row_mask:0xf bank_mask:0xf bound_ctrl:1
	v_add_f32_dpp v132, v118, v118 row_shr:2 row_mask:0xf bank_mask:0xf bound_ctrl:1
	v_add_f32_dpp v118, v126, v132 row_shl:14 row_mask:0xf bank_mask:0xf bound_ctrl:1
	v_add_f32_dpp v126, v126, v126 row_shr:2 row_mask:0xf bank_mask:0xf bound_ctrl:1
	v_add_f32_dpp v132, v119, v119 row_shr:2 row_mask:0xf bank_mask:0xf bound_ctrl:1
	v_add_f32_dpp v119, v127, v132 row_shl:14 row_mask:0xf bank_mask:0xf bound_ctrl:1
	v_add_f32_dpp v127, v127, v127 row_shr:2 row_mask:0xf bank_mask:0xf bound_ctrl:1
	v_add_f32_dpp v132, v120, v120 row_shr:2 row_mask:0xf bank_mask:0xf bound_ctrl:1
	v_add_f32_dpp v120, v128, v132 row_shl:14 row_mask:0xf bank_mask:0xf bound_ctrl:1
	v_add_f32_dpp v128, v128, v128 row_shr:2 row_mask:0xf bank_mask:0xf bound_ctrl:1
	v_add_f32_dpp v132, v121, v121 row_shr:2 row_mask:0xf bank_mask:0xf bound_ctrl:1
	v_add_f32_dpp v121, v129, v132 row_shl:14 row_mask:0xf bank_mask:0xf bound_ctrl:1
	v_add_f32_dpp v129, v129, v129 row_shr:2 row_mask:0xf bank_mask:0xf bound_ctrl:1
	v_add_f32_dpp v132, v122, v122 row_shr:2 row_mask:0xf bank_mask:0xf bound_ctrl:1
	v_add_f32_dpp v122, v130, v132 row_shl:14 row_mask:0xf bank_mask:0xf bound_ctrl:1
	v_add_f32_dpp v130, v130, v130 row_shr:2 row_mask:0xf bank_mask:0xf bound_ctrl:1
	v_add_f32_dpp v132, v123, v123 row_shr:2 row_mask:0xf bank_mask:0xf bound_ctrl:1
	v_add_f32_dpp v123, v131, v132 row_shl:14 row_mask:0xf bank_mask:0xf bound_ctrl:1
	v_add_f32_dpp v131, v131, v131 row_shr:2 row_mask:0xf bank_mask:0xf bound_ctrl:1
	v_add_f32_dpp v132, v116, v116 row_shr:4 row_mask:0xf bank_mask:0xf bound_ctrl:1
	v_add_f32_dpp v116, v124, v132 row_shl:12 row_mask:0xf bank_mask:0xf bound_ctrl:1
	v_add_f32_dpp v124, v124, v124 row_shr:4 row_mask:0xf bank_mask:0xf bound_ctrl:1
	v_add_f32_dpp v132, v117, v117 row_shr:4 row_mask:0xf bank_mask:0xf bound_ctrl:1
	v_add_f32_dpp v117, v125, v132 row_shl:12 row_mask:0xf bank_mask:0xf bound_ctrl:1
	v_add_f32_dpp v125, v125, v125 row_shr:4 row_mask:0xf bank_mask:0xf bound_ctrl:1
	v_add_f32_dpp v132, v118, v118 row_shr:4 row_mask:0xf bank_mask:0xf bound_ctrl:1
; #define GAS __attribute__((address_space(1)))
; __device__ __forceinline__ void unpack8(const v4u w, float (&f)[8]) { f[0] = bf_lo(w.x); f[1] = bf_hi(w.x); f[2] = bf_lo(w.y); f[3] = bf_hi(w.y); f[4] = bf_lo(w.z); f[5] = bf_hi(w.z); f[6] = bf_lo(w.w); f[7] = bf_hi(w.w); }
; __device__ __forceinline__ v4u pack8(const float (&f)[8]) { v4u w; w.x = cvt_pk_bf16(f[0], f[1]); w.y = cvt_pk_bf16(f[2], f[3]); w.z = cvt_pk_bf16(f[4], f[5]); w.w = cvt_pk_bf16(f[6], f[7]); return w; }
; template <int W> __device__ __forceinline__ void pool_group(const bf16* zrow  , const bf16* pw  , bf16* orow  , int pos, bool prev_ok) {
;     ...
;         if (kk < 3) {
; #pragma unroll
;             for (int dt = 0; dt < 8; ++dt) aw[(kk + 1) & 1][dt] = *(const GAS v4u*)(pw + (size_t)16 * dt * 128 + 32 * (kk + 1)); }
;         float own[8], c[8], p[8];
;         unpack8(cw[kk], own); unpack8(pv[kk], p);
; #pragma unroll
;         for (int j = 0; j < 8; ++j) c[j] = own[j];
;         win_step<1>(c, p);
;         if (W >= 4) win_step<2>(c, p);
;         if (W >= 8) win_step<4>(c, p);
;         if (W >= 16) win_step<8>(c, p);
;         float pl[8];
; #pragma unroll
;         for (int j = 0; j < 8; ++j) pl[j] = c[j] * inv - own[j];
;         const v4u pwk = pack8(pl); const bf16x8 pf = __builtin_bit_cast(bf16x8, pwk);
; #pragma unroll
;         for (int dt = 0; dt < 8; ++dt) acc[dt] = __builtin_amdgcn_mfma_f32_16x16x32_bf16(__builtin_bit_cast(bf16x8, aw[kk & 1][dt]), pf, acc[dt], 0, 0, 0);
	v_add_f32_dpp v118, v126, v132 row_shl:12 row_mask:0xf bank_mask:0xf bound_ctrl:1
	v_add_f32_dpp v126, v126, v126 row_shr:4 row_mask:0xf bank_mask:0xf bound_ctrl:1
	v_add_f32_dpp v132, v119, v119 row_shr:4 row_mask:0xf bank_mask:0xf bound_ctrl:1
	v_add_f32_dpp v119, v127, v132 row_shl:12 row_mask:0xf bank_mask:0xf bound_ctrl:1
	v_add_f32_dpp v127, v127, v127 row_shr:4 row_mask:0xf bank_mask:0xf bound_ctrl:1
	v_add_f32_dpp v132, v120, v120 row_shr:4 row_mask:0xf bank_mask:0xf bound_ctrl:1
	v_add_f32_dpp v120, v128, v132 row_shl:12 row_mask:0xf bank_mask:0xf bound_ctrl:1
	v_add_f32_dpp v128, v128, v128 row_shr:4 row_mask:0xf bank_mask:0xf bound_ctrl:1
	v_add_f32_dpp v132, v121, v121 row_shr:4 row_mask:0xf bank_mask:0xf bound_ctrl:1
	v_add_f32_dpp v121, v129, v132 row_shl:12 row_mask:0xf bank_mask:0xf bound_ctrl:1
	v_add_f32_dpp v129, v129, v129 row_shr:4 row_mask:0xf bank_mask:0xf bound_ctrl:1
	v_add_f32_dpp v132, v122, v122 row_shr:4 row_mask:0xf bank_mask:0xf bound_ctrl:1
	v_add_f32_dpp v122, v130, v132 row_shl:12 row_mask:0xf bank_mask:0xf bound_ctrl:1
	v_add_f32_dpp v130, v130, v130 row_shr:4 row_mask:0xf bank_mask:0xf bound_ctrl:1
	v_add_f32_dpp v132, v123, v123 row_shr:4 row_mask:0xf bank_mask:0xf bound_ctrl:1
	v_add_f32_dpp v123, v131, v132 row_shl:12 row_mask:0xf bank_mask:0xf bound_ctrl:1
	v_add_f32_dpp v131, v131, v131 row_shr:4 row_mask:0xf bank_mask:0xf bound_ctrl:1
	v_add_f32_dpp v132, v116, v116 row_shr:8 row_mask:0xf bank_mask:0xf bound_ctrl:1
	v_add_f32_dpp v116, v124, v132 row_shl:8 row_mask:0xf bank_mask:0xf bound_ctrl:1
	v_add_f32_dpp v124, v124, v124 row_shr:8 row_mask:0xf bank_mask:0xf bound_ctrl:1
	v_add_f32_dpp v132, v117, v117 row_shr:8 row_mask:0xf bank_mask:0xf bound_ctrl:1
	v_add_f32_dpp v117, v125, v132 row_shl:8 row_mask:0xf bank_mask:0xf bound_ctrl:1
	v_add_f32_dpp v125, v125, v125 row_shr:8 row_mask:0xf bank_mask:0xf bound_ctrl:1
	v_add_f32_dpp v132, v118, v118 row_shr:8 row_mask:0xf bank_mask:0xf bound_ctrl:1
	v_add_f32_dpp v118, v126, v132 row_shl:8 row_mask:0xf bank_mask:0xf bound_ctrl:1
	v_add_f32_dpp v126, v126, v126 row_shr:8 row_mask:0xf bank_mask:0xf bound_ctrl:1
	v_add_f32_dpp v132, v119, v119 row_shr:8 row_mask:0xf bank_mask:0xf bound_ctrl:1
	v_add_f32_dpp v119, v127, v132 row_shl:8 row_mask:0xf bank_mask:0xf bound_ctrl:1
	v_add_f32_dpp v127, v127, v127 row_shr:8 row_mask:0xf bank_mask:0xf bound_ctrl:1
	v_add_f32_dpp v132, v120, v120 row_shr:8 row_mask:0xf bank_mask:0xf bound_ctrl:1
	v_add_f32_dpp v120, v128, v132 row_shl:8 row_mask:0xf bank_mask:0xf bound_ctrl:1
	v_add_f32_dpp v128, v128, v128 row_shr:8 row_mask:0xf bank_mask:0xf bound_ctrl:1
	v_add_f32_dpp v132, v121, v121 row_shr:8 row_mask:0xf bank_mask:0xf bound_ctrl:1
	v_add_f32_dpp v121, v129, v132 row_shl:8 row_mask:0xf bank_mask:0xf bound_ctrl:1
	v_add_f32_dpp v129, v129, v129 row_shr:8 row_mask:0xf bank_mask:0xf bound_ctrl:1
	v_add_f32_dpp v132, v122, v122 row_shr:8 row_mask:0xf bank_mask:0xf bound_ctrl:1
	v_add_f32_dpp v122, v130, v132 row_shl:8 row_mask:0xf bank_mask:0xf bound_ctrl:1
	v_add_f32_dpp v130, v130, v130 row_shr:8 row_mask:0xf bank_mask:0xf bound_ctrl:1
	v_add_f32_dpp v132, v123, v123 row_shr:8 row_mask:0xf bank_mask:0xf bound_ctrl:1
	v_add_f32_dpp v123, v131, v132 row_shl:8 row_mask:0xf bank_mask:0xf bound_ctrl:1
	v_add_f32_dpp v131, v131, v131 row_shr:8 row_mask:0xf bank_mask:0xf bound_ctrl:1
	v_fma_f32 v116, v116, v138, -v108
	v_fma_f32 v117, v117, v138, -v109
	v_fma_f32 v118, v118, v138, -v110
	v_fma_f32 v119, v119, v138, -v111
	v_fma_f32 v120, v120, v138, -v112
	v_fma_f32 v121, v121, v138, -v113
	v_fma_f32 v122, v122, v138, -v114
	v_fma_f32 v123, v123, v138, -v115
	v_cvt_pk_bf16_f32 v134, v116, v117
	v_cvt_pk_bf16_f32 v135, v118, v119
	v_cvt_pk_bf16_f32 v136, v120, v121
	v_cvt_pk_bf16_f32 v137, v122, v123
	s_waitcnt lgkmcnt(0)
	s_nop 0
	v_mfma_f32_16x16x32_bf16 v[76:79], v[44:47], v[134:137], 0
	v_mfma_f32_16x16x32_bf16 v[80:83], v[48:51], v[134:137], 0
	v_mfma_f32_16x16x32_bf16 v[84:87], v[52:55], v[134:137], 0
	v_mfma_f32_16x16x32_bf16 v[88:91], v[56:59], v[134:137], 0
	v_mfma_f32_16x16x32_bf16 v[92:95], v[60:63], v[134:137], 0
	v_mfma_f32_16x16x32_bf16 v[96:99], v[64:67], v[134:137], 0
	v_mfma_f32_16x16x32_bf16 v[100:103], v[68:71], v[134:137], 0
	v_mfma_f32_16x16x32_bf16 v[104:107], v[72:75], v[134:137], 0
	v_add_u32_e32 v147, 98304, v144
	ds_read_b128 v[44:47], v147
	ds_read_b128 v[48:51], v147 offset:4096
	ds_read_b128 v[52:55], v147 offset:8192
	ds_read_b128 v[56:59], v147 offset:12288
	ds_read_b128 v[60:63], v147 offset:16384
	ds_read_b128 v[64:67], v147 offset:20480
	ds_read_b128 v[68:71], v147 offset:24576
	ds_read_b128 v[72:75], v147 offset:28672
	s_waitcnt vmcnt(12)
; __device__ __forceinline__ void unpack8(const v4u w, float (&f)[8]) { f[0] = bf_lo(w.x); f[1] = bf_hi(w.x); f[2] = bf_lo(w.y); f[3] = bf_hi(w.y); f[4] = bf_lo(w.z); f[5] = bf_hi(w.z); f[6] = bf_lo(w.w); f[7] = bf_hi(w.w); }
; template <int SH> __device__ __forceinline__ float row_shr(float v) { return __int_as_float(__builtin_amdgcn_update_dpp(0, __float_as_int(v), 0x110 + SH, 0xf, 0xf, true)); }
; template <int SH> __device__ __forceinline__ float row_shl(float v) { return __int_as_float(__builtin_amdgcn_update_dpp(0, __float_as_int(v), 0x100 + SH, 0xf, 0xf, true)); }
; template <int S> __device__ __forceinline__ void win_step(float (&c)[8], float (&p)[8]) {
; #pragma unroll
;     for (int j = 0; j < 8; ++j) { const float cn = c[j] + row_shr<S>(c[j]) + row_shl<16 - S>(p[j]); p[j] += row_shr<S>(p[j]); c[j] = cn; }
; }
; template <int W> __device__ __forceinline__ void pool_group(const bf16* zrow  , const bf16* pw  , bf16* orow  , int pos, bool prev_ok) {
;     ...
;         float own[8], c[8], p[8];
;         unpack8(cw[kk], own); unpack8(pv[kk], p);
; #pragma unroll
;         for (int j = 0; j < 8; ++j) c[j] = own[j];
;         win_step<1>(c, p);
;         if (W >= 4) win_step<2>(c, p);
;         if (W >= 8) win_step<4>(c, p);
;         if (W >= 16) win_step<8>(c, p);
	v_lshlrev_b32_e32 v108, 16, v20
	v_and_b32_e32 v109, 0xffff0000, v20
	v_lshlrev_b32_e32 v110, 16, v21
	v_and_b32_e32 v111, 0xffff0000, v21
	v_lshlrev_b32_e32 v112, 16, v22
	v_and_b32_e32 v113, 0xffff0000, v22
	v_lshlrev_b32_e32 v114, 16, v23
	v_and_b32_e32 v115, 0xffff0000, v23
	v_lshlrev_b32_e32 v124, 16, v24
	v_and_b32_e32 v125, 0xffff0000, v24
	v_lshlrev_b32_e32 v126, 16, v25
	v_and_b32_e32 v127, 0xffff0000, v25
	v_lshlrev_b32_e32 v128, 16, v26
	v_and_b32_e32 v129, 0xffff0000, v26
	v_lshlrev_b32_e32 v130, 16, v27
	v_and_b32_e32 v131, 0xffff0000, v27
	v_cndmask_b32_e64 v124, 0, v124, s[40:41]
	v_cndmask_b32_e64 v125, 0, v125, s[40:41]
	v_cndmask_b32_e64 v126, 0, v126, s[40:41]
	v_cndmask_b32_e64 v127, 0, v127, s[40:41]
	v_cndmask_b32_e64 v128, 0, v128, s[40:41]
	v_cndmask_b32_e64 v129, 0, v129, s[40:41]
	v_cndmask_b32_e64 v130, 0, v130, s[40:41]
	v_cndmask_b32_e64 v131, 0, v131, s[40:41]
	v_mov_b32_e32 v116, v108
	v_mov_b32_e32 v117, v109
	v_mov_b32_e32 v118, v110
	v_mov_b32_e32 v119, v111
	v_mov_b32_e32 v120, v112
	v_mov_b32_e32 v121, v113
	v_mov_b32_e32 v122, v114
	v_mov_b32_e32 v123, v115
	v_add_f32_dpp v132, v116, v116 row_shr:1 row_mask:0xf bank_mask:0xf bound_ctrl:1
	v_add_f32_dpp v116, v124, v132 row_shl:15 row_mask:0xf bank_mask:0xf bound_ctrl:1
	v_add_f32_dpp v124, v124, v124 row_shr:1 row_mask:0xf bank_mask:0xf bound_ctrl:1
	v_add_f32_dpp v132, v117, v117 row_shr:1 row_mask:0xf bank_mask:0xf bound_ctrl:1
	v_add_f32_dpp v117, v125, v132 row_shl:15 row_mask:0xf bank_mask:0xf bound_ctrl:1
	v_add_f32_dpp v125, v125, v125 row_shr:1 row_mask:0xf bank_mask:0xf bound_ctrl:1
	v_add_f32_dpp v132, v118, v118 row_shr:1 row_mask:0xf bank_mask:0xf bound_ctrl:1
	v_add_f32_dpp v118, v126, v132 row_shl:15 row_mask:0xf bank_mask:0xf bound_ctrl:1
	v_add_f32_dpp v126, v126, v126 row_shr:1 row_mask:0xf bank_mask:0xf bound_ctrl:1
	v_add_f32_dpp v132, v119, v119 row_shr:1 row_mask:0xf bank_mask:0xf bound_ctrl:1
	v_add_f32_dpp v119, v127, v132 row_shl:15 row_mask:0xf bank_mask:0xf bound_ctrl:1
	v_add_f32_dpp v127, v127, v127 row_shr:1 row_mask:0xf bank_mask:0xf bound_ctrl:1
	v_add_f32_dpp v132, v120, v120 row_shr:1 row_mask:0xf bank_mask:0xf bound_ctrl:1
	v_add_f32_dpp v120, v128, v132 row_shl:15 row_mask:0xf bank_mask:0xf bound_ctrl:1
	v_add_f32_dpp v128, v128, v128 row_shr:1 row_mask:0xf bank_mask:0xf bound_ctrl:1
	v_add_f32_dpp v132, v121, v121 row_shr:1 row_mask:0xf bank_mask:0xf bound_ctrl:1
	v_add_f32_dpp v121, v129, v132 row_shl:15 row_mask:0xf bank_mask:0xf bound_ctrl:1
	v_add_f32_dpp v129, v129, v129 row_shr:1 row_mask:0xf bank_mask:0xf bound_ctrl:1
	v_add_f32_dpp v132, v122, v122 row_shr:1 row_mask:0xf bank_mask:0xf bound_ctrl:1
	v_add_f32_dpp v122, v130, v132 row_shl:15 row_mask:0xf bank_mask:0xf bound_ctrl:1
	v_add_f32_dpp v130, v130, v130 row_shr:1 row_mask:0xf bank_mask:0xf bound_ctrl:1
	v_add_f32_dpp v132, v123, v123 row_shr:1 row_mask:0xf bank_mask:0xf bound_ctrl:1
	v_add_f32_dpp v123, v131, v132 row_shl:15 row_mask:0xf bank_mask:0xf bound_ctrl:1
	v_add_f32_dpp v131, v131, v131 row_shr:1 row_mask:0xf bank_mask:0xf bound_ctrl:1
	v_add_f32_dpp v132, v116, v116 row_shr:2 row_mask:0xf bank_mask:0xf bound_ctrl:1
	v_add_f32_dpp v116, v124, v132 row_shl:14 row_mask:0xf bank_mask:0xf bound_ctrl:1
	v_add_f32_dpp v124, v124, v124 row_shr:2 row_mask:0xf bank_mask:0xf bound_ctrl:1
	v_add_f32_dpp v132, v117, v117 row_shr:2 row_mask:0xf bank_mask:0xf bound_ctrl:1
	v_add_f32_dpp v117, v125, v132 row_shl:14 row_mask:0xf bank_mask:0xf bound_ctrl:1
	v_add_f32_dpp v125, v125, v125 row_shr:2 row_mask:0xf bank_mask:0xf bound_ctrl:1
	v_add_f32_dpp v132, v118, v118 row_shr:2 row_mask:0xf bank_mask:0xf bound_ctrl:1
	v_add_f32_dpp v118, v126, v132 row_shl:14 row_mask:0xf bank_mask:0xf bound_ctrl:1
	v_add_f32_dpp v126, v126, v126 row_shr:2 row_mask:0xf bank_mask:0xf bound_ctrl:1
	v_add_f32_dpp v132, v119, v119 row_shr:2 row_mask:0xf bank_mask:0xf bound_ctrl:1
	v_add_f32_dpp v119, v127, v132 row_shl:14 row_mask:0xf bank_mask:0xf bound_ctrl:1
	v_add_f32_dpp v127, v127, v127 row_shr:2 row_mask:0xf bank_mask:0xf bound_ctrl:1
	v_add_f32_dpp v132, v120, v120 row_shr:2 row_mask:0xf bank_mask:0xf bound_ctrl:1
	v_add_f32_dpp v120, v128, v132 row_shl:14 row_mask:0xf bank_mask:0xf bound_ctrl:1
	v_add_f32_dpp v128, v128, v128 row_shr:2 row_mask:0xf bank_mask:0xf bound_ctrl:1
	v_add_f32_dpp v132, v121, v121 row_shr:2 row_mask:0xf bank_mask:0xf bound_ctrl:1
	v_add_f32_dpp v121, v129, v132 row_shl:14 row_mask:0xf bank_mask:0xf bound_ctrl:1
	v_add_f32_dpp v129, v129, v129 row_shr:2 row_mask:0xf bank_mask:0xf bound_ctrl:1
	v_add_f32_dpp v132, v122, v122 row_shr:2 row_mask:0xf bank_mask:0xf bound_ctrl:1
	v_add_f32_dpp v122, v130, v132 row_shl:14 row_mask:0xf bank_mask:0xf bound_ctrl:1
	v_add_f32_dpp v130, v130, v130 row_shr:2 row_mask:0xf bank_mask:0xf bound_ctrl:1
	v_add_f32_dpp v132, v123, v123 row_shr:2 row_mask:0xf bank_mask:0xf bound_ctrl:1
	v_add_f32_dpp v123, v131, v132 row_shl:14 row_mask:0xf bank_mask:0xf bound_ctrl:1
	v_add_f32_dpp v131, v131, v131 row_shr:2 row_mask:0xf bank_mask:0xf bound_ctrl:1
	v_add_f32_dpp v132, v116, v116 row_shr:4 row_mask:0xf bank_mask:0xf bound_ctrl:1
	v_add_f32_dpp v116, v124, v132 row_shl:12 row_mask:0xf bank_mask:0xf bound_ctrl:1
	v_add_f32_dpp v124, v124, v124 row_shr:4 row_mask:0xf bank_mask:0xf bound_ctrl:1
	v_add_f32_dpp v132, v117, v117 row_shr:4 row_mask:0xf bank_mask:0xf bound_ctrl:1
	v_add_f32_dpp v117, v125, v132 row_shl:12 row_mask:0xf bank_mask:0xf bound_ctrl:1
	v_add_f32_dpp v125, v125, v125 row_shr:4 row_mask:0xf bank_mask:0xf bound_ctrl:1
	v_add_f32_dpp v132, v118, v118 row_shr:4 row_mask:0xf bank_mask:0xf bound_ctrl:1
; #define GAS __attribute__((address_space(1)))
; __device__ __forceinline__ void unpack8(const v4u w, float (&f)[8]) { f[0] = bf_lo(w.x); f[1] = bf_hi(w.x); f[2] = bf_lo(w.y); f[3] = bf_hi(w.y); f[4] = bf_lo(w.z); f[5] = bf_hi(w.z); f[6] = bf_lo(w.w); f[7] = bf_hi(w.w); }
; __device__ __forceinline__ v4u pack8(const float (&f)[8]) { v4u w; w.x = cvt_pk_bf16(f[0], f[1]); w.y = cvt_pk_bf16(f[2], f[3]); w.z = cvt_pk_bf16(f[4], f[5]); w.w = cvt_pk_bf16(f[6], f[7]); return w; }
; template <int W> __device__ __forceinline__ void pool_group(const bf16* zrow  , const bf16* pw  , bf16* orow  , int pos, bool prev_ok) {
;     ...
;         if (kk < 3) {
; #pragma unroll
;             for (int dt = 0; dt < 8; ++dt) aw[(kk + 1) & 1][dt] = *(const GAS v4u*)(pw + (size_t)16 * dt * 128 + 32 * (kk + 1)); }
;         float own[8], c[8], p[8];
;         unpack8(cw[kk], own); unpack8(pv[kk], p);
; #pragma unroll
;         for (int j = 0; j < 8; ++j) c[j] = own[j];
;         win_step<1>(c, p);
;         if (W >= 4) win_step<2>(c, p);
;         if (W >= 8) win_step<4>(c, p);
;         if (W >= 16) win_step<8>(c, p);
;         float pl[8];
; #pragma unroll
;         for (int j = 0; j < 8; ++j) pl[j] = c[j] * inv - own[j];
;         const v4u pwk = pack8(pl); const bf16x8 pf = __builtin_bit_cast(bf16x8, pwk);
; #pragma unroll
;         for (int dt = 0; dt < 8; ++dt) acc[dt] = __builtin_amdgcn_mfma_f32_16x16x32_bf16(__builtin_bit_cast(bf16x8, aw[kk & 1][dt]), pf, acc[dt], 0, 0, 0);
	v_add_f32_dpp v118, v126, v132 row_shl:12 row_mask:0xf bank_mask:0xf bound_ctrl:1
	v_add_f32_dpp v126, v126, v126 row_shr:4 row_mask:0xf bank_mask:0xf bound_ctrl:1
	v_add_f32_dpp v132, v119, v119 row_shr:4 row_mask:0xf bank_mask:0xf bound_ctrl:1
	v_add_f32_dpp v119, v127, v132 row_shl:12 row_mask:0xf bank_mask:0xf bound_ctrl:1
	v_add_f32_dpp v127, v127, v127 row_shr:4 row_mask:0xf bank_mask:0xf bound_ctrl:1
	v_add_f32_dpp v132, v120, v120 row_shr:4 row_mask:0xf bank_mask:0xf bound_ctrl:1
	v_add_f32_dpp v120, v128, v132 row_shl:12 row_mask:0xf bank_mask:0xf bound_ctrl:1
	v_add_f32_dpp v128, v128, v128 row_shr:4 row_mask:0xf bank_mask:0xf bound_ctrl:1
	v_add_f32_dpp v132, v121, v121 row_shr:4 row_mask:0xf bank_mask:0xf bound_ctrl:1
	v_add_f32_dpp v121, v129, v132 row_shl:12 row_mask:0xf bank_mask:0xf bound_ctrl:1
	v_add_f32_dpp v129, v129, v129 row_shr:4 row_mask:0xf bank_mask:0xf bound_ctrl:1
	v_add_f32_dpp v132, v122, v122 row_shr:4 row_mask:0xf bank_mask:0xf bound_ctrl:1
	v_add_f32_dpp v122, v130, v132 row_shl:12 row_mask:0xf bank_mask:0xf bound_ctrl:1
	v_add_f32_dpp v130, v130, v130 row_shr:4 row_mask:0xf bank_mask:0xf bound_ctrl:1
	v_add_f32_dpp v132, v123, v123 row_shr:4 row_mask:0xf bank_mask:0xf bound_ctrl:1
	v_add_f32_dpp v123, v131, v132 row_shl:12 row_mask:0xf bank_mask:0xf bound_ctrl:1
	v_add_f32_dpp v131, v131, v131 row_shr:4 row_mask:0xf bank_mask:0xf bound_ctrl:1
	v_add_f32_dpp v132, v116, v116 row_shr:8 row_mask:0xf bank_mask:0xf bound_ctrl:1
	v_add_f32_dpp v116, v124, v132 row_shl:8 row_mask:0xf bank_mask:0xf bound_ctrl:1
	v_add_f32_dpp v124, v124, v124 row_shr:8 row_mask:0xf bank_mask:0xf bound_ctrl:1
	v_add_f32_dpp v132, v117, v117 row_shr:8 row_mask:0xf bank_mask:0xf bound_ctrl:1
	v_add_f32_dpp v117, v125, v132 row_shl:8 row_mask:0xf bank_mask:0xf bound_ctrl:1
	v_add_f32_dpp v125, v125, v125 row_shr:8 row_mask:0xf bank_mask:0xf bound_ctrl:1
	v_add_f32_dpp v132, v118, v118 row_shr:8 row_mask:0xf bank_mask:0xf bound_ctrl:1
	v_add_f32_dpp v118, v126, v132 row_shl:8 row_mask:0xf bank_mask:0xf bound_ctrl:1
	v_add_f32_dpp v126, v126, v126 row_shr:8 row_mask:0xf bank_mask:0xf bound_ctrl:1
	v_add_f32_dpp v132, v119, v119 row_shr:8 row_mask:0xf bank_mask:0xf bound_ctrl:1
	v_add_f32_dpp v119, v127, v132 row_shl:8 row_mask:0xf bank_mask:0xf bound_ctrl:1
	v_add_f32_dpp v127, v127, v127 row_shr:8 row_mask:0xf bank_mask:0xf bound_ctrl:1
	v_add_f32_dpp v132, v120, v120 row_shr:8 row_mask:0xf bank_mask:0xf bound_ctrl:1
	v_add_f32_dpp v120, v128, v132 row_shl:8 row_mask:0xf bank_mask:0xf bound_ctrl:1
	v_add_f32_dpp v128, v128, v128 row_shr:8 row_mask:0xf bank_mask:0xf bound_ctrl:1
	v_add_f32_dpp v132, v121, v121 row_shr:8 row_mask:0xf bank_mask:0xf bound_ctrl:1
	v_add_f32_dpp v121, v129, v132 row_shl:8 row_mask:0xf bank_mask:0xf bound_ctrl:1
	v_add_f32_dpp v129, v129, v129 row_shr:8 row_mask:0xf bank_mask:0xf bound_ctrl:1
	v_add_f32_dpp v132, v122, v122 row_shr:8 row_mask:0xf bank_mask:0xf bound_ctrl:1
	v_add_f32_dpp v122, v130, v132 row_shl:8 row_mask:0xf bank_mask:0xf bound_ctrl:1
	v_add_f32_dpp v130, v130, v130 row_shr:8 row_mask:0xf bank_mask:0xf bound_ctrl:1
	v_add_f32_dpp v132, v123, v123 row_shr:8 row_mask:0xf bank_mask:0xf bound_ctrl:1
	v_add_f32_dpp v123, v131, v132 row_shl:8 row_mask:0xf bank_mask:0xf bound_ctrl:1
	v_add_f32_dpp v131, v131, v131 row_shr:8 row_mask:0xf bank_mask:0xf bound_ctrl:1
	v_fma_f32 v116, v116, v138, -v108
	v_fma_f32 v117, v117, v138, -v109
	v_fma_f32 v118, v118, v138, -v110
	v_fma_f32 v119, v119, v138, -v111
	v_fma_f32 v120, v120, v138, -v112
	v_fma_f32 v121, v121, v138, -v113
	v_fma_f32 v122, v122, v138, -v114
	v_fma_f32 v123, v123, v138, -v115
	v_cvt_pk_bf16_f32 v134, v116, v117
	v_cvt_pk_bf16_f32 v135, v118, v119
	v_cvt_pk_bf16_f32 v136, v120, v121
	v_cvt_pk_bf16_f32 v137, v122, v123
	s_waitcnt lgkmcnt(0)
	s_nop 0
	v_mfma_f32_16x16x32_bf16 v[76:79], v[44:47], v[134:137], v[76:79]
	v_mfma_f32_16x16x32_bf16 v[80:83], v[48:51], v[134:137], v[80:83]
	v_mfma_f32_16x16x32_bf16 v[84:87], v[52:55], v[134:137], v[84:87]
	v_mfma_f32_16x16x32_bf16 v[88:91], v[56:59], v[134:137], v[88:91]
	v_mfma_f32_16x16x32_bf16 v[92:95], v[60:63], v[134:137], v[92:95]
	v_mfma_f32_16x16x32_bf16 v[96:99], v[64:67], v[134:137], v[96:99]
	v_mfma_f32_16x16x32_bf16 v[100:103], v[68:71], v[134:137], v[100:103]
	v_mfma_f32_16x16x32_bf16 v[104:107], v[72:75], v[134:137], v[104:107]
	v_add_u32_e32 v147, 98304, v145
	ds_read_b128 v[44:47], v147
	ds_read_b128 v[48:51], v147 offset:4096
	ds_read_b128 v[52:55], v147 offset:8192
	ds_read_b128 v[56:59], v147 offset:12288
	ds_read_b128 v[60:63], v147 offset:16384
	ds_read_b128 v[64:67], v147 offset:20480
	ds_read_b128 v[68:71], v147 offset:24576
	ds_read_b128 v[72:75], v147 offset:28672
	s_waitcnt vmcnt(10)
; __device__ __forceinline__ void unpack8(const v4u w, float (&f)[8]) { f[0] = bf_lo(w.x); f[1] = bf_hi(w.x); f[2] = bf_lo(w.y); f[3] = bf_hi(w.y); f[4] = bf_lo(w.z); f[5] = bf_hi(w.z); f[6] = bf_lo(w.w); f[7] = bf_hi(w.w); }
; template <int SH> __device__ __forceinline__ float row_shr(float v) { return __int_as_float(__builtin_amdgcn_update_dpp(0, __float_as_int(v), 0x110 + SH, 0xf, 0xf, true)); }
; template <int SH> __device__ __forceinline__ float row_shl(float v) { return __int_as_float(__builtin_amdgcn_update_dpp(0, __float_as_int(v), 0x100 + SH, 0xf, 0xf, true)); }
; template <int S> __device__ __forceinline__ void win_step(float (&c)[8], float (&p)[8]) {
; #pragma unroll
;     for (int j = 0; j < 8; ++j) { const float cn = c[j] + row_shr<S>(c[j]) + row_shl<16 - S>(p[j]); p[j] += row_shr<S>(p[j]); c[j] = cn; }
; }
; template <int W> __device__ __forceinline__ void pool_group(const bf16* zrow  , const bf16* pw  , bf16* orow  , int pos, bool prev_ok) {
;     ...
;         float own[8], c[8], p[8];
;         unpack8(cw[kk], own); unpack8(pv[kk], p);
; #pragma unroll
;         for (int j = 0; j < 8; ++j) c[j] = own[j];
;         win_step<1>(c, p);
;         if (W >= 4) win_step<2>(c, p);
;         if (W >= 8) win_step<4>(c, p);
;         if (W >= 16) win_step<8>(c, p);
	v_lshlrev_b32_e32 v108, 16, v28
	v_and_b32_e32 v109, 0xffff0000, v28
	v_lshlrev_b32_e32 v110, 16, v29
	v_and_b32_e32 v111, 0xffff0000, v29
	v_lshlrev_b32_e32 v112, 16, v30
	v_and_b32_e32 v113, 0xffff0000, v30
	v_lshlrev_b32_e32 v114, 16, v31
	v_and_b32_e32 v115, 0xffff0000, v31
	v_lshlrev_b32_e32 v124, 16, v32
	v_and_b32_e32 v125, 0xffff0000, v32
	v_lshlrev_b32_e32 v126, 16, v33
	v_and_b32_e32 v127, 0xffff0000, v33
	v_lshlrev_b32_e32 v128, 16, v34
	v_and_b32_e32 v129, 0xffff0000, v34
	v_lshlrev_b32_e32 v130, 16, v35
	v_and_b32_e32 v131, 0xffff0000, v35
	v_cndmask_b32_e64 v124, 0, v124, s[40:41]
	v_cndmask_b32_e64 v125, 0, v125, s[40:41]
	v_cndmask_b32_e64 v126, 0, v126, s[40:41]
	v_cndmask_b32_e64 v127, 0, v127, s[40:41]
	v_cndmask_b32_e64 v128, 0, v128, s[40:41]
	v_cndmask_b32_e64 v129, 0, v129, s[40:41]
	v_cndmask_b32_e64 v130, 0, v130, s[40:41]
	v_cndmask_b32_e64 v131, 0, v131, s[40:41]
	v_mov_b32_e32 v116, v108
	v_mov_b32_e32 v117, v109
	v_mov_b32_e32 v118, v110
	v_mov_b32_e32 v119, v111
	v_mov_b32_e32 v120, v112
	v_mov_b32_e32 v121, v113
	v_mov_b32_e32 v122, v114
	v_mov_b32_e32 v123, v115
	v_add_f32_dpp v132, v116, v116 row_shr:1 row_mask:0xf bank_mask:0xf bound_ctrl:1
	v_add_f32_dpp v116, v124, v132 row_shl:15 row_mask:0xf bank_mask:0xf bound_ctrl:1
	v_add_f32_dpp v124, v124, v124 row_shr:1 row_mask:0xf bank_mask:0xf bound_ctrl:1
	v_add_f32_dpp v132, v117, v117 row_shr:1 row_mask:0xf bank_mask:0xf bound_ctrl:1
	v_add_f32_dpp v117, v125, v132 row_shl:15 row_mask:0xf bank_mask:0xf bound_ctrl:1
	v_add_f32_dpp v125, v125, v125 row_shr:1 row_mask:0xf bank_mask:0xf bound_ctrl:1
	v_add_f32_dpp v132, v118, v118 row_shr:1 row_mask:0xf bank_mask:0xf bound_ctrl:1
	v_add_f32_dpp v118, v126, v132 row_shl:15 row_mask:0xf bank_mask:0xf bound_ctrl:1
	v_add_f32_dpp v126, v126, v126 row_shr:1 row_mask:0xf bank_mask:0xf bound_ctrl:1
	v_add_f32_dpp v132, v119, v119 row_shr:1 row_mask:0xf bank_mask:0xf bound_ctrl:1
	v_add_f32_dpp v119, v127, v132 row_shl:15 row_mask:0xf bank_mask:0xf bound_ctrl:1
	v_add_f32_dpp v127, v127, v127 row_shr:1 row_mask:0xf bank_mask:0xf bound_ctrl:1
	v_add_f32_dpp v132, v120, v120 row_shr:1 row_mask:0xf bank_mask:0xf bound_ctrl:1
	v_add_f32_dpp v120, v128, v132 row_shl:15 row_mask:0xf bank_mask:0xf bound_ctrl:1
	v_add_f32_dpp v128, v128, v128 row_shr:1 row_mask:0xf bank_mask:0xf bound_ctrl:1
	v_add_f32_dpp v132, v121, v121 row_shr:1 row_mask:0xf bank_mask:0xf bound_ctrl:1
	v_add_f32_dpp v121, v129, v132 row_shl:15 row_mask:0xf bank_mask:0xf bound_ctrl:1
	v_add_f32_dpp v129, v129, v129 row_shr:1 row_mask:0xf bank_mask:0xf bound_ctrl:1
	v_add_f32_dpp v132, v122, v122 row_shr:1 row_mask:0xf bank_mask:0xf bound_ctrl:1
	v_add_f32_dpp v122, v130, v132 row_shl:15 row_mask:0xf bank_mask:0xf bound_ctrl:1
	v_add_f32_dpp v130, v130, v130 row_shr:1 row_mask:0xf bank_mask:0xf bound_ctrl:1
	v_add_f32_dpp v132, v123, v123 row_shr:1 row_mask:0xf bank_mask:0xf bound_ctrl:1
	v_add_f32_dpp v123, v131, v132 row_shl:15 row_mask:0xf bank_mask:0xf bound_ctrl:1
	v_add_f32_dpp v131, v131, v131 row_shr:1 row_mask:0xf bank_mask:0xf bound_ctrl:1
	v_add_f32_dpp v132, v116, v116 row_shr:2 row_mask:0xf bank_mask:0xf bound_ctrl:1
	v_add_f32_dpp v116, v124, v132 row_shl:14 row_mask:0xf bank_mask:0xf bound_ctrl:1
	v_add_f32_dpp v124, v124, v124 row_shr:2 row_mask:0xf bank_mask:0xf bound_ctrl:1
	v_add_f32_dpp v132, v117, v117 row_shr:2 row_mask:0xf bank_mask:0xf bound_ctrl:1
	v_add_f32_dpp v117, v125, v132 row_shl:14 row_mask:0xf bank_mask:0xf bound_ctrl:1
	v_add_f32_dpp v125, v125, v125 row_shr:2 row_mask:0xf bank_mask:0xf bound_ctrl:1
	v_add_f32_dpp v132, v118, v118 row_shr:2 row_mask:0xf bank_mask:0xf bound_ctrl:1
	v_add_f32_dpp v118, v126, v132 row_shl:14 row_mask:0xf bank_mask:0xf bound_ctrl:1
	v_add_f32_dpp v126, v126, v126 row_shr:2 row_mask:0xf bank_mask:0xf bound_ctrl:1
	v_add_f32_dpp v132, v119, v119 row_shr:2 row_mask:0xf bank_mask:0xf bound_ctrl:1
	v_add_f32_dpp v119, v127, v132 row_shl:14 row_mask:0xf bank_mask:0xf bound_ctrl:1
	v_add_f32_dpp v127, v127, v127 row_shr:2 row_mask:0xf bank_mask:0xf bound_ctrl:1
	v_add_f32_dpp v132, v120, v120 row_shr:2 row_mask:0xf bank_mask:0xf bound_ctrl:1
	v_add_f32_dpp v120, v128, v132 row_shl:14 row_mask:0xf bank_mask:0xf bound_ctrl:1
	v_add_f32_dpp v128, v128, v128 row_shr:2 row_mask:0xf bank_mask:0xf bound_ctrl:1
	v_add_f32_dpp v132, v121, v121 row_shr:2 row_mask:0xf bank_mask:0xf bound_ctrl:1
	v_add_f32_dpp v121, v129, v132 row_shl:14 row_mask:0xf bank_mask:0xf bound_ctrl:1
	v_add_f32_dpp v129, v129, v129 row_shr:2 row_mask:0xf bank_mask:0xf bound_ctrl:1
	v_add_f32_dpp v132, v122, v122 row_shr:2 row_mask:0xf bank_mask:0xf bound_ctrl:1
	v_add_f32_dpp v122, v130, v132 row_shl:14 row_mask:0xf bank_mask:0xf bound_ctrl:1
	v_add_f32_dpp v130, v130, v130 row_shr:2 row_mask:0xf bank_mask:0xf bound_ctrl:1
	v_add_f32_dpp v132, v123, v123 row_shr:2 row_mask:0xf bank_mask:0xf bound_ctrl:1
	v_add_f32_dpp v123, v131, v132 row_shl:14 row_mask:0xf bank_mask:0xf bound_ctrl:1
	v_add_f32_dpp v131, v131, v131 row_shr:2 row_mask:0xf bank_mask:0xf bound_ctrl:1
	v_add_f32_dpp v132, v116, v116 row_shr:4 row_mask:0xf bank_mask:0xf bound_ctrl:1
	v_add_f32_dpp v116, v124, v132 row_shl:12 row_mask:0xf bank_mask:0xf bound_ctrl:1
	v_add_f32_dpp v124, v124, v124 row_shr:4 row_mask:0xf bank_mask:0xf bound_ctrl:1
	v_add_f32_dpp v132, v117, v117 row_shr:4 row_mask:0xf bank_mask:0xf bound_ctrl:1
	v_add_f32_dpp v117, v125, v132 row_shl:12 row_mask:0xf bank_mask:0xf bound_ctrl:1
	v_add_f32_dpp v125, v125, v125 row_shr:4 row_mask:0xf bank_mask:0xf bound_ctrl:1
	v_add_f32_dpp v132, v118, v118 row_shr:4 row_mask:0xf bank_mask:0xf bound_ctrl:1
; #define GAS __attribute__((address_space(1)))
; __device__ __forceinline__ void unpack8(const v4u w, float (&f)[8]) { f[0] = bf_lo(w.x); f[1] = bf_hi(w.x); f[2] = bf_lo(w.y); f[3] = bf_hi(w.y); f[4] = bf_lo(w.z); f[5] = bf_hi(w.z); f[6] = bf_lo(w.w); f[7] = bf_hi(w.w); }
; __device__ __forceinline__ v4u pack8(const float (&f)[8]) { v4u w; w.x = cvt_pk_bf16(f[0], f[1]); w.y = cvt_pk_bf16(f[2], f[3]); w.z = cvt_pk_bf16(f[4], f[5]); w.w = cvt_pk_bf16(f[6], f[7]); return w; }
; template <int W> __device__ __forceinline__ void pool_group(const bf16* zrow  , const bf16* pw  , bf16* orow  , int pos, bool prev_ok) {
;     ...
;         if (kk < 3) {
; #pragma unroll
;             for (int dt = 0; dt < 8; ++dt) aw[(kk + 1) & 1][dt] = *(const GAS v4u*)(pw + (size_t)16 * dt * 128 + 32 * (kk + 1)); }
;         float own[8], c[8], p[8];
;         unpack8(cw[kk], own); unpack8(pv[kk], p);
; #pragma unroll
;         for (int j = 0; j < 8; ++j) c[j] = own[j];
;         win_step<1>(c, p);
;         if (W >= 4) win_step<2>(c, p);
;         if (W >= 8) win_step<4>(c, p);
;         if (W >= 16) win_step<8>(c, p);
;         float pl[8];
; #pragma unroll
;         for (int j = 0; j < 8; ++j) pl[j] = c[j] * inv - own[j];
;         const v4u pwk = pack8(pl); const bf16x8 pf = __builtin_bit_cast(bf16x8, pwk);
; #pragma unroll
;         for (int dt = 0; dt < 8; ++dt) acc[dt] = __builtin_amdgcn_mfma_f32_16x16x32_bf16(__builtin_bit_cast(bf16x8, aw[kk & 1][dt]), pf, acc[dt], 0, 0, 0);
	v_add_f32_dpp v118, v126, v132 row_shl:12 row_mask:0xf bank_mask:0xf bound_ctrl:1
	v_add_f32_dpp v126, v126, v126 row_shr:4 row_mask:0xf bank_mask:0xf bound_ctrl:1
	v_add_f32_dpp v132, v119, v119 row_shr:4 row_mask:0xf bank_mask:0xf bound_ctrl:1
	v_add_f32_dpp v119, v127, v132 row_shl:12 row_mask:0xf bank_mask:0xf bound_ctrl:1
	v_add_f32_dpp v127, v127, v127 row_shr:4 row_mask:0xf bank_mask:0xf bound_ctrl:1
	v_add_f32_dpp v132, v120, v120 row_shr:4 row_mask:0xf bank_mask:0xf bound_ctrl:1
	v_add_f32_dpp v120, v128, v132 row_shl:12 row_mask:0xf bank_mask:0xf bound_ctrl:1
	v_add_f32_dpp v128, v128, v128 row_shr:4 row_mask:0xf bank_mask:0xf bound_ctrl:1
	v_add_f32_dpp v132, v121, v121 row_shr:4 row_mask:0xf bank_mask:0xf bound_ctrl:1
	v_add_f32_dpp v121, v129, v132 row_shl:12 row_mask:0xf bank_mask:0xf bound_ctrl:1
	v_add_f32_dpp v129, v129, v129 row_shr:4 row_mask:0xf bank_mask:0xf bound_ctrl:1
	v_add_f32_dpp v132, v122, v122 row_shr:4 row_mask:0xf bank_mask:0xf bound_ctrl:1
	v_add_f32_dpp v122, v130, v132 row_shl:12 row_mask:0xf bank_mask:0xf bound_ctrl:1
	v_add_f32_dpp v130, v130, v130 row_shr:4 row_mask:0xf bank_mask:0xf bound_ctrl:1
	v_add_f32_dpp v132, v123, v123 row_shr:4 row_mask:0xf bank_mask:0xf bound_ctrl:1
	v_add_f32_dpp v123, v131, v132 row_shl:12 row_mask:0xf bank_mask:0xf bound_ctrl:1
	v_add_f32_dpp v131, v131, v131 row_shr:4 row_mask:0xf bank_mask:0xf bound_ctrl:1
	v_add_f32_dpp v132, v116, v116 row_shr:8 row_mask:0xf bank_mask:0xf bound_ctrl:1
	v_add_f32_dpp v116, v124, v132 row_shl:8 row_mask:0xf bank_mask:0xf bound_ctrl:1
	v_add_f32_dpp v124, v124, v124 row_shr:8 row_mask:0xf bank_mask:0xf bound_ctrl:1
	v_add_f32_dpp v132, v117, v117 row_shr:8 row_mask:0xf bank_mask:0xf bound_ctrl:1
	v_add_f32_dpp v117, v125, v132 row_shl:8 row_mask:0xf bank_mask:0xf bound_ctrl:1
	v_add_f32_dpp v125, v125, v125 row_shr:8 row_mask:0xf bank_mask:0xf bound_ctrl:1
	v_add_f32_dpp v132, v118, v118 row_shr:8 row_mask:0xf bank_mask:0xf bound_ctrl:1
	v_add_f32_dpp v118, v126, v132 row_shl:8 row_mask:0xf bank_mask:0xf bound_ctrl:1
	v_add_f32_dpp v126, v126, v126 row_shr:8 row_mask:0xf bank_mask:0xf bound_ctrl:1
	v_add_f32_dpp v132, v119, v119 row_shr:8 row_mask:0xf bank_mask:0xf bound_ctrl:1
	v_add_f32_dpp v119, v127, v132 row_shl:8 row_mask:0xf bank_mask:0xf bound_ctrl:1
	v_add_f32_dpp v127, v127, v127 row_shr:8 row_mask:0xf bank_mask:0xf bound_ctrl:1
	v_add_f32_dpp v132, v120, v120 row_shr:8 row_mask:0xf bank_mask:0xf bound_ctrl:1
	v_add_f32_dpp v120, v128, v132 row_shl:8 row_mask:0xf bank_mask:0xf bound_ctrl:1
	v_add_f32_dpp v128, v128, v128 row_shr:8 row_mask:0xf bank_mask:0xf bound_ctrl:1
	v_add_f32_dpp v132, v121, v121 row_shr:8 row_mask:0xf bank_mask:0xf bound_ctrl:1
	v_add_f32_dpp v121, v129, v132 row_shl:8 row_mask:0xf bank_mask:0xf bound_ctrl:1
	v_add_f32_dpp v129, v129, v129 row_shr:8 row_mask:0xf bank_mask:0xf bound_ctrl:1
	v_add_f32_dpp v132, v122, v122 row_shr:8 row_mask:0xf bank_mask:0xf bound_ctrl:1
	v_add_f32_dpp v122, v130, v132 row_shl:8 row_mask:0xf bank_mask:0xf bound_ctrl:1
	v_add_f32_dpp v130, v130, v130 row_shr:8 row_mask:0xf bank_mask:0xf bound_ctrl:1
	v_add_f32_dpp v132, v123, v123 row_shr:8 row_mask:0xf bank_mask:0xf bound_ctrl:1
	v_add_f32_dpp v123, v131, v132 row_shl:8 row_mask:0xf bank_mask:0xf bound_ctrl:1
	v_add_f32_dpp v131, v131, v131 row_shr:8 row_mask:0xf bank_mask:0xf bound_ctrl:1
	v_fma_f32 v116, v116, v138, -v108
	v_fma_f32 v117, v117, v138, -v109
	v_fma_f32 v118, v118, v138, -v110
	v_fma_f32 v119, v119, v138, -v111
	v_fma_f32 v120, v120, v138, -v112
	v_fma_f32 v121, v121, v138, -v113
	v_fma_f32 v122, v122, v138, -v114
	v_fma_f32 v123, v123, v138, -v115
	v_cvt_pk_bf16_f32 v134, v116, v117
	v_cvt_pk_bf16_f32 v135, v118, v119
	v_cvt_pk_bf16_f32 v136, v120, v121
	v_cvt_pk_bf16_f32 v137, v122, v123
	s_waitcnt lgkmcnt(0)
	s_nop 0
	v_mfma_f32_16x16x32_bf16 v[76:79], v[44:47], v[134:137], v[76:79]
	v_mfma_f32_16x16x32_bf16 v[80:83], v[48:51], v[134:137], v[80:83]
	v_mfma_f32_16x16x32_bf16 v[84:87], v[52:55], v[134:137], v[84:87]
	v_mfma_f32_16x16x32_bf16 v[88:91], v[56:59], v[134:137], v[88:91]
	v_mfma_f32_16x16x32_bf16 v[92:95], v[60:63], v[134:137], v[92:95]
	v_mfma_f32_16x16x32_bf16 v[96:99], v[64:67], v[134:137], v[96:99]
	v_mfma_f32_16x16x32_bf16 v[100:103], v[68:71], v[134:137], v[100:103]
	v_mfma_f32_16x16x32_bf16 v[104:107], v[72:75], v[134:137], v[104:107]
	v_add_u32_e32 v147, 98304, v146
	ds_read_b128 v[44:47], v147
	ds_read_b128 v[48:51], v147 offset:4096
	ds_read_b128 v[52:55], v147 offset:8192
	ds_read_b128 v[56:59], v147 offset:12288
	ds_read_b128 v[60:63], v147 offset:16384
	ds_read_b128 v[64:67], v147 offset:20480
	ds_read_b128 v[68:71], v147 offset:24576
	ds_read_b128 v[72:75], v147 offset:28672
	s_waitcnt vmcnt(8)
; __device__ __forceinline__ void unpack8(const v4u w, float (&f)[8]) { f[0] = bf_lo(w.x); f[1] = bf_hi(w.x); f[2] = bf_lo(w.y); f[3] = bf_hi(w.y); f[4] = bf_lo(w.z); f[5] = bf_hi(w.z); f[6] = bf_lo(w.w); f[7] = bf_hi(w.w); }
; template <int SH> __device__ __forceinline__ float row_shr(float v) { return __int_as_float(__builtin_amdgcn_update_dpp(0, __float_as_int(v), 0x110 + SH, 0xf, 0xf, true)); }
; template <int SH> __device__ __forceinline__ float row_shl(float v) { return __int_as_float(__builtin_amdgcn_update_dpp(0, __float_as_int(v), 0x100 + SH, 0xf, 0xf, true)); }
; template <int S> __device__ __forceinline__ void win_step(float (&c)[8], float (&p)[8]) {
; #pragma unroll
;     for (int j = 0; j < 8; ++j) { const float cn = c[j] + row_shr<S>(c[j]) + row_shl<16 - S>(p[j]); p[j] += row_shr<S>(p[j]); c[j] = cn; }
; }
; template <int W> __device__ __forceinline__ void pool_group(const bf16* zrow  , const bf16* pw  , bf16* orow  , int pos, bool prev_ok) {
;     ...
;         float own[8], c[8], p[8];
;         unpack8(cw[kk], own); unpack8(pv[kk], p);
; #pragma unroll
;         for (int j = 0; j < 8; ++j) c[j] = own[j];
;         win_step<1>(c, p);
;         if (W >= 4) win_step<2>(c, p);
;         if (W >= 8) win_step<4>(c, p);
;         if (W >= 16) win_step<8>(c, p);
	v_lshlrev_b32_e32 v108, 16, v36
	v_and_b32_e32 v109, 0xffff0000, v36
	v_lshlrev_b32_e32 v110, 16, v37
	v_and_b32_e32 v111, 0xffff0000, v37
	v_lshlrev_b32_e32 v112, 16, v38
	v_and_b32_e32 v113, 0xffff0000, v38
	v_lshlrev_b32_e32 v114, 16, v39
	v_and_b32_e32 v115, 0xffff0000, v39
	v_lshlrev_b32_e32 v124, 16, v40
	v_and_b32_e32 v125, 0xffff0000, v40
	v_lshlrev_b32_e32 v126, 16, v41
	v_and_b32_e32 v127, 0xffff0000, v41
	v_lshlrev_b32_e32 v128, 16, v42
	v_and_b32_e32 v129, 0xffff0000, v42
	v_lshlrev_b32_e32 v130, 16, v43
	v_and_b32_e32 v131, 0xffff0000, v43
	v_cndmask_b32_e64 v124, 0, v124, s[40:41]
	v_cndmask_b32_e64 v125, 0, v125, s[40:41]
	v_cndmask_b32_e64 v126, 0, v126, s[40:41]
	v_cndmask_b32_e64 v127, 0, v127, s[40:41]
	v_cndmask_b32_e64 v128, 0, v128, s[40:41]
	v_cndmask_b32_e64 v129, 0, v129, s[40:41]
	v_cndmask_b32_e64 v130, 0, v130, s[40:41]
	v_cndmask_b32_e64 v131, 0, v131, s[40:41]
	v_mov_b32_e32 v116, v108
	v_mov_b32_e32 v117, v109
	v_mov_b32_e32 v118, v110
	v_mov_b32_e32 v119, v111
	v_mov_b32_e32 v120, v112
	v_mov_b32_e32 v121, v113
	v_mov_b32_e32 v122, v114
	v_mov_b32_e32 v123, v115
	v_add_f32_dpp v132, v116, v116 row_shr:1 row_mask:0xf bank_mask:0xf bound_ctrl:1
	v_add_f32_dpp v116, v124, v132 row_shl:15 row_mask:0xf bank_mask:0xf bound_ctrl:1
	v_add_f32_dpp v124, v124, v124 row_shr:1 row_mask:0xf bank_mask:0xf bound_ctrl:1
	v_add_f32_dpp v132, v117, v117 row_shr:1 row_mask:0xf bank_mask:0xf bound_ctrl:1
	v_add_f32_dpp v117, v125, v132 row_shl:15 row_mask:0xf bank_mask:0xf bound_ctrl:1
	v_add_f32_dpp v125, v125, v125 row_shr:1 row_mask:0xf bank_mask:0xf bound_ctrl:1
	v_add_f32_dpp v132, v118, v118 row_shr:1 row_mask:0xf bank_mask:0xf bound_ctrl:1
	v_add_f32_dpp v118, v126, v132 row_shl:15 row_mask:0xf bank_mask:0xf bound_ctrl:1
	v_add_f32_dpp v126, v126, v126 row_shr:1 row_mask:0xf bank_mask:0xf bound_ctrl:1
	v_add_f32_dpp v132, v119, v119 row_shr:1 row_mask:0xf bank_mask:0xf bound_ctrl:1
	v_add_f32_dpp v119, v127, v132 row_shl:15 row_mask:0xf bank_mask:0xf bound_ctrl:1
	v_add_f32_dpp v127, v127, v127 row_shr:1 row_mask:0xf bank_mask:0xf bound_ctrl:1
	v_add_f32_dpp v132, v120, v120 row_shr:1 row_mask:0xf bank_mask:0xf bound_ctrl:1
	v_add_f32_dpp v120, v128, v132 row_shl:15 row_mask:0xf bank_mask:0xf bound_ctrl:1
	v_add_f32_dpp v128, v128, v128 row_shr:1 row_mask:0xf bank_mask:0xf bound_ctrl:1
	v_add_f32_dpp v132, v121, v121 row_shr:1 row_mask:0xf bank_mask:0xf bound_ctrl:1
	v_add_f32_dpp v121, v129, v132 row_shl:15 row_mask:0xf bank_mask:0xf bound_ctrl:1
	v_add_f32_dpp v129, v129, v129 row_shr:1 row_mask:0xf bank_mask:0xf bound_ctrl:1
	v_add_f32_dpp v132, v122, v122 row_shr:1 row_mask:0xf bank_mask:0xf bound_ctrl:1
	v_add_f32_dpp v122, v130, v132 row_shl:15 row_mask:0xf bank_mask:0xf bound_ctrl:1
	v_add_f32_dpp v130, v130, v130 row_shr:1 row_mask:0xf bank_mask:0xf bound_ctrl:1
	v_add_f32_dpp v132, v123, v123 row_shr:1 row_mask:0xf bank_mask:0xf bound_ctrl:1
	v_add_f32_dpp v123, v131, v132 row_shl:15 row_mask:0xf bank_mask:0xf bound_ctrl:1
	v_add_f32_dpp v131, v131, v131 row_shr:1 row_mask:0xf bank_mask:0xf bound_ctrl:1
	v_add_f32_dpp v132, v116, v116 row_shr:2 row_mask:0xf bank_mask:0xf bound_ctrl:1
	v_add_f32_dpp v116, v124, v132 row_shl:14 row_mask:0xf bank_mask:0xf bound_ctrl:1
	v_add_f32_dpp v124, v124, v124 row_shr:2 row_mask:0xf bank_mask:0xf bound_ctrl:1
	v_add_f32_dpp v132, v117, v117 row_shr:2 row_mask:0xf bank_mask:0xf bound_ctrl:1
	v_add_f32_dpp v117, v125, v132 row_shl:14 row_mask:0xf bank_mask:0xf bound_ctrl:1
	v_add_f32_dpp v125, v125, v125 row_shr:2 row_mask:0xf bank_mask:0xf bound_ctrl:1
	v_add_f32_dpp v132, v118, v118 row_shr:2 row_mask:0xf bank_mask:0xf bound_ctrl:1
	v_add_f32_dpp v118, v126, v132 row_shl:14 row_mask:0xf bank_mask:0xf bound_ctrl:1
	v_add_f32_dpp v126, v126, v126 row_shr:2 row_mask:0xf bank_mask:0xf bound_ctrl:1
	v_add_f32_dpp v132, v119, v119 row_shr:2 row_mask:0xf bank_mask:0xf bound_ctrl:1
	v_add_f32_dpp v119, v127, v132 row_shl:14 row_mask:0xf bank_mask:0xf bound_ctrl:1
	v_add_f32_dpp v127, v127, v127 row_shr:2 row_mask:0xf bank_mask:0xf bound_ctrl:1
	v_add_f32_dpp v132, v120, v120 row_shr:2 row_mask:0xf bank_mask:0xf bound_ctrl:1
	v_add_f32_dpp v120, v128, v132 row_shl:14 row_mask:0xf bank_mask:0xf bound_ctrl:1
	v_add_f32_dpp v128, v128, v128 row_shr:2 row_mask:0xf bank_mask:0xf bound_ctrl:1
	v_add_f32_dpp v132, v121, v121 row_shr:2 row_mask:0xf bank_mask:0xf bound_ctrl:1
	v_add_f32_dpp v121, v129, v132 row_shl:14 row_mask:0xf bank_mask:0xf bound_ctrl:1
	v_add_f32_dpp v129, v129, v129 row_shr:2 row_mask:0xf bank_mask:0xf bound_ctrl:1
	v_add_f32_dpp v132, v122, v122 row_shr:2 row_mask:0xf bank_mask:0xf bound_ctrl:1
	v_add_f32_dpp v122, v130, v132 row_shl:14 row_mask:0xf bank_mask:0xf bound_ctrl:1
	v_add_f32_dpp v130, v130, v130 row_shr:2 row_mask:0xf bank_mask:0xf bound_ctrl:1
	v_add_f32_dpp v132, v123, v123 row_shr:2 row_mask:0xf bank_mask:0xf bound_ctrl:1
	v_add_f32_dpp v123, v131, v132 row_shl:14 row_mask:0xf bank_mask:0xf bound_ctrl:1
	v_add_f32_dpp v131, v131, v131 row_shr:2 row_mask:0xf bank_mask:0xf bound_ctrl:1
	v_add_f32_dpp v132, v116, v116 row_shr:4 row_mask:0xf bank_mask:0xf bound_ctrl:1
	v_add_f32_dpp v116, v124, v132 row_shl:12 row_mask:0xf bank_mask:0xf bound_ctrl:1
	v_add_f32_dpp v124, v124, v124 row_shr:4 row_mask:0xf bank_mask:0xf bound_ctrl:1
	v_add_f32_dpp v132, v117, v117 row_shr:4 row_mask:0xf bank_mask:0xf bound_ctrl:1
	v_add_f32_dpp v117, v125, v132 row_shl:12 row_mask:0xf bank_mask:0xf bound_ctrl:1
	v_add_f32_dpp v125, v125, v125 row_shr:4 row_mask:0xf bank_mask:0xf bound_ctrl:1
	v_add_f32_dpp v132, v118, v118 row_shr:4 row_mask:0xf bank_mask:0xf bound_ctrl:1
; __device__ __forceinline__ unsigned cvt_pk_bf16(float lo, float hi) { return __builtin_bit_cast(unsigned, __builtin_convertvector((f32x2_t){lo, hi}, bf16x2_t)); }
; #define GAS __attribute__((address_space(1)))
; __device__ __forceinline__ v4u pack8(const float (&f)[8]) { v4u w; w.x = cvt_pk_bf16(f[0], f[1]); w.y = cvt_pk_bf16(f[2], f[3]); w.z = cvt_pk_bf16(f[4], f[5]); w.w = cvt_pk_bf16(f[6], f[7]); return w; }
; template <int W> __device__ __forceinline__ void pool_group(const bf16* zrow  , const bf16* pw  , bf16* orow  , int pos, bool prev_ok) {
;     ...
;         win_step<1>(c, p);
;         if (W >= 4) win_step<2>(c, p);
;         if (W >= 8) win_step<4>(c, p);
;         if (W >= 16) win_step<8>(c, p);
;         float pl[8];
; #pragma unroll
;         for (int j = 0; j < 8; ++j) pl[j] = c[j] * inv - own[j];
;         const v4u pwk = pack8(pl); const bf16x8 pf = __builtin_bit_cast(bf16x8, pwk);
; #pragma unroll
;         for (int dt = 0; dt < 8; ++dt) acc[dt] = __builtin_amdgcn_mfma_f32_16x16x32_bf16(__builtin_bit_cast(bf16x8, aw[kk & 1][dt]), pf, acc[dt], 0, 0, 0);
;     }
; #pragma unroll
;     for (int dt = 0; dt < 8; ++dt) { v2u w; w.x = cvt_pk_bf16(acc[dt][0], acc[dt][1]); w.y = cvt_pk_bf16(acc[dt][2], acc[dt][3]); *(GAS v2u*)(orow + 16 * dt) = w; }
	v_add_f32_dpp v118, v126, v132 row_shl:12 row_mask:0xf bank_mask:0xf bound_ctrl:1
	v_add_f32_dpp v126, v126, v126 row_shr:4 row_mask:0xf bank_mask:0xf bound_ctrl:1
	v_add_f32_dpp v132, v119, v119 row_shr:4 row_mask:0xf bank_mask:0xf bound_ctrl:1
	v_add_f32_dpp v119, v127, v132 row_shl:12 row_mask:0xf bank_mask:0xf bound_ctrl:1
	v_add_f32_dpp v127, v127, v127 row_shr:4 row_mask:0xf bank_mask:0xf bound_ctrl:1
	v_add_f32_dpp v132, v120, v120 row_shr:4 row_mask:0xf bank_mask:0xf bound_ctrl:1
	v_add_f32_dpp v120, v128, v132 row_shl:12 row_mask:0xf bank_mask:0xf bound_ctrl:1
	v_add_f32_dpp v128, v128, v128 row_shr:4 row_mask:0xf bank_mask:0xf bound_ctrl:1
	v_add_f32_dpp v132, v121, v121 row_shr:4 row_mask:0xf bank_mask:0xf bound_ctrl:1
	v_add_f32_dpp v121, v129, v132 row_shl:12 row_mask:0xf bank_mask:0xf bound_ctrl:1
	v_add_f32_dpp v129, v129, v129 row_shr:4 row_mask:0xf bank_mask:0xf bound_ctrl:1
	v_add_f32_dpp v132, v122, v122 row_shr:4 row_mask:0xf bank_mask:0xf bound_ctrl:1
	v_add_f32_dpp v122, v130, v132 row_shl:12 row_mask:0xf bank_mask:0xf bound_ctrl:1
	v_add_f32_dpp v130, v130, v130 row_shr:4 row_mask:0xf bank_mask:0xf bound_ctrl:1
	v_add_f32_dpp v132, v123, v123 row_shr:4 row_mask:0xf bank_mask:0xf bound_ctrl:1
	v_add_f32_dpp v123, v131, v132 row_shl:12 row_mask:0xf bank_mask:0xf bound_ctrl:1
	v_add_f32_dpp v131, v131, v131 row_shr:4 row_mask:0xf bank_mask:0xf bound_ctrl:1
	v_add_f32_dpp v132, v116, v116 row_shr:8 row_mask:0xf bank_mask:0xf bound_ctrl:1
	v_add_f32_dpp v116, v124, v132 row_shl:8 row_mask:0xf bank_mask:0xf bound_ctrl:1
	v_add_f32_dpp v124, v124, v124 row_shr:8 row_mask:0xf bank_mask:0xf bound_ctrl:1
	v_add_f32_dpp v132, v117, v117 row_shr:8 row_mask:0xf bank_mask:0xf bound_ctrl:1
	v_add_f32_dpp v117, v125, v132 row_shl:8 row_mask:0xf bank_mask:0xf bound_ctrl:1
	v_add_f32_dpp v125, v125, v125 row_shr:8 row_mask:0xf bank_mask:0xf bound_ctrl:1
	v_add_f32_dpp v132, v118, v118 row_shr:8 row_mask:0xf bank_mask:0xf bound_ctrl:1
	v_add_f32_dpp v118, v126, v132 row_shl:8 row_mask:0xf bank_mask:0xf bound_ctrl:1
	v_add_f32_dpp v126, v126, v126 row_shr:8 row_mask:0xf bank_mask:0xf bound_ctrl:1
	v_add_f32_dpp v132, v119, v119 row_shr:8 row_mask:0xf bank_mask:0xf bound_ctrl:1
	v_add_f32_dpp v119, v127, v132 row_shl:8 row_mask:0xf bank_mask:0xf bound_ctrl:1
	v_add_f32_dpp v127, v127, v127 row_shr:8 row_mask:0xf bank_mask:0xf bound_ctrl:1
	v_add_f32_dpp v132, v120, v120 row_shr:8 row_mask:0xf bank_mask:0xf bound_ctrl:1
	v_add_f32_dpp v120, v128, v132 row_shl:8 row_mask:0xf bank_mask:0xf bound_ctrl:1
	v_add_f32_dpp v128, v128, v128 row_shr:8 row_mask:0xf bank_mask:0xf bound_ctrl:1
	v_add_f32_dpp v132, v121, v121 row_shr:8 row_mask:0xf bank_mask:0xf bound_ctrl:1
	v_add_f32_dpp v121, v129, v132 row_shl:8 row_mask:0xf bank_mask:0xf bound_ctrl:1
	v_add_f32_dpp v129, v129, v129 row_shr:8 row_mask:0xf bank_mask:0xf bound_ctrl:1
	v_add_f32_dpp v132, v122, v122 row_shr:8 row_mask:0xf bank_mask:0xf bound_ctrl:1
	v_add_f32_dpp v122, v130, v132 row_shl:8 row_mask:0xf bank_mask:0xf bound_ctrl:1
	v_add_f32_dpp v130, v130, v130 row_shr:8 row_mask:0xf bank_mask:0xf bound_ctrl:1
	v_add_f32_dpp v132, v123, v123 row_shr:8 row_mask:0xf bank_mask:0xf bound_ctrl:1
	v_add_f32_dpp v123, v131, v132 row_shl:8 row_mask:0xf bank_mask:0xf bound_ctrl:1
	v_add_f32_dpp v131, v131, v131 row_shr:8 row_mask:0xf bank_mask:0xf bound_ctrl:1
	v_fma_f32 v116, v116, v138, -v108
	v_fma_f32 v117, v117, v138, -v109
	v_fma_f32 v118, v118, v138, -v110
	v_fma_f32 v119, v119, v138, -v111
	v_fma_f32 v120, v120, v138, -v112
	v_fma_f32 v121, v121, v138, -v113
	v_fma_f32 v122, v122, v138, -v114
	v_fma_f32 v123, v123, v138, -v115
	v_cvt_pk_bf16_f32 v134, v116, v117
	v_cvt_pk_bf16_f32 v135, v118, v119
	v_cvt_pk_bf16_f32 v136, v120, v121
	v_cvt_pk_bf16_f32 v137, v122, v123
	s_waitcnt lgkmcnt(0)
	s_nop 0
	v_mfma_f32_16x16x32_bf16 v[76:79], v[44:47], v[134:137], v[76:79]
	v_mfma_f32_16x16x32_bf16 v[80:83], v[48:51], v[134:137], v[80:83]
	v_mfma_f32_16x16x32_bf16 v[84:87], v[52:55], v[134:137], v[84:87]
	v_mfma_f32_16x16x32_bf16 v[88:91], v[56:59], v[134:137], v[88:91]
	v_mfma_f32_16x16x32_bf16 v[92:95], v[60:63], v[134:137], v[92:95]
	v_mfma_f32_16x16x32_bf16 v[96:99], v[64:67], v[134:137], v[96:99]
	v_mfma_f32_16x16x32_bf16 v[100:103], v[68:71], v[134:137], v[100:103]
	v_mfma_f32_16x16x32_bf16 v[104:107], v[72:75], v[134:137], v[104:107]
	s_nop 7
	s_nop 1
	v_cvt_pk_bf16_f32 v132, v76, v77
	v_cvt_pk_bf16_f32 v133, v78, v79
	global_store_dwordx2 v142, v[132:133], s[46:47] offset:768
	s_nop 0
	v_cvt_pk_bf16_f32 v132, v80, v81
	v_cvt_pk_bf16_f32 v133, v82, v83
	global_store_dwordx2 v142, v[132:133], s[46:47] offset:800
	s_nop 0
	v_cvt_pk_bf16_f32 v132, v84, v85
	v_cvt_pk_bf16_f32 v133, v86, v87
	global_store_dwordx2 v142, v[132:133], s[46:47] offset:832
	s_nop 0
	v_cvt_pk_bf16_f32 v132, v88, v89
	v_cvt_pk_bf16_f32 v133, v90, v91
	global_store_dwordx2 v142, v[132:133], s[46:47] offset:864
	s_nop 0
	v_cvt_pk_bf16_f32 v132, v92, v93
	v_cvt_pk_bf16_f32 v133, v94, v95
	global_store_dwordx2 v142, v[132:133], s[46:47] offset:896
	s_nop 0
	v_cvt_pk_bf16_f32 v132, v96, v97
	v_cvt_pk_bf16_f32 v133, v98, v99
	global_store_dwordx2 v142, v[132:133], s[46:47] offset:928
	s_nop 0
	v_cvt_pk_bf16_f32 v132, v100, v101
	v_cvt_pk_bf16_f32 v133, v102, v103
	global_store_dwordx2 v142, v[132:133], s[46:47] offset:960
	s_nop 0
	v_cvt_pk_bf16_f32 v132, v104, v105
	v_cvt_pk_bf16_f32 v133, v106, v107
	global_store_dwordx2 v142, v[132:133], s[46:47] offset:992
	s_nop 0
	s_waitcnt lgkmcnt(0)
	s_barrier
; __device__ __forceinline__ float sum_xor1_2(float v) { v += dpp_f<0xB1>(v); v += dpp_f<0x4E>(v); return v; }
; #define GAS __attribute__((address_space(1)))
; #define LAS __attribute__((address_space(3)))
; __device__ __forceinline__ int lane_opaque() { int l; asm volatile("v_mbcnt_lo_u32_b32 %0, -1, 0\n\tv_mbcnt_hi_u32_b32 %0, -1, %0" : "=v"(l)); return l; }
; __device__ __forceinline__ void unpack8(const v4u w, float (&f)[8]) { f[0] = bf_lo(w.x); f[1] = bf_hi(w.x); f[2] = bf_lo(w.y); f[3] = bf_hi(w.y); f[4] = bf_lo(w.z); f[5] = bf_hi(w.z); f[6] = bf_lo(w.w); f[7] = bf_hi(w.w); }
; __device__ __forceinline__ void mixer_sgu(const Frame& F, const Args& A, int l, int chunk, const bf16* Z, bf16* MIX) {
;     const int lane = lane_opaque(), tid = F.wave * 64 + lane;
;     const int row0 = chunk * 128;
;     const bf16* wsb = (const bf16*)(F.ws + WS_WSB) + (size_t)l * 4 * 128 * 128;
;     const int t1 = tid >> 2, q = tid & 3, i = lane & 15, g4 = lane >> 4, w = F.wave, t2 = 16 * w + i, kkmax = w >> 1;
;     const bf16* zv = Z + (size_t)(row0 + t1) * ZC + 512 + 32 * q;
;     const bf16* zu = Z + (size_t)(row0 + t2) * ZC + 4 * g4;
;     bf16* mo = MIX + (size_t)(row0 + t2) * D + 4 * g4;
;     v4u vr[4];
; #pragma unroll
;     for (int j = 0; j < 4; ++j) vr[j] = *(const GAS v4u*)(zv + 8 * j);
; #pragma unroll 1
;     for (int hd = 0; hd < 4; ++hd) {
;         LAS bf16* VT = (LAS bf16*)(F.lds + (hd & 1) * (128 * VT_STRIDE * 2));
;         {
;             const float* lg = A.in[4] + (size_t)(l * 4 + hd) * 128 + 32 * q; const float* lb = A.in[5] + (size_t)(l * 4 + hd) * 128 + 32 * q;
;             f32x4 g4v[8], b4v[8];
; #pragma unroll
;             for (int j = 0; j < 8; ++j) { g4v[j] = *(const GAS f32x4*)(lg + 4 * j); b4v[j] = *(const GAS f32x4*)(lb + 4 * j); }
;             float v[32];
; #pragma unroll
;             for (int j = 0; j < 4; ++j) { float f[8]; unpack8(vr[j], f);
; #pragma unroll
;                 for (int e = 0; e < 8; ++e) v[8 * j + e] = f[e]; }
;             float s = 0.f;
; #pragma unroll
;             for (int j = 0; j < 32; ++j) s += v[j];
;             s = pg8::sum_xor1_2(s);
;             const float mean = s * (1.0f / 128.0f); float s2 = 0.f;
; #pragma unroll
;             for (int j = 0; j < 32; ++j) { v[j] -= mean; s2 += v[j] * v[j]; }
	s_mov_b32 s52, 0
	s_mov_b64 s[44:45], 0
	s_mov_b64 s[46:47], 0
	v_mbcnt_lo_u32_b32 v1, -1, 0
	v_mbcnt_hi_u32_b32 v1, -1, v1
	v_add_u32_e32 v10, s77, v1
	v_lshrrev_b32_e32 v11, 2, v10
	v_and_b32_e32 v10, 3, v10
	v_mul_u32_u24_e32 v2, 0x1800, v11
	v_lshl_add_u32 v2, v10, 6, v2
	v_add_u32_e32 v2, 0x400, v2
	v_mul_u32_u24_e32 v7, 8720, v10
	v_lshl_add_u32 v7, v11, 1, v7
	v_mul_u32_u24_e32 v9, 144, v10
	v_add_u32_e32 v9, 135168, v9
	v_and_b32_e32 v10, 15, v1
	v_lshrrev_b32_e32 v11, 4, v1
	v_mul_u32_u24_e32 v8, 272, v10
	v_lshl_add_u32 v8, v11, 4, v8
	v_add_u32_e32 v10, s56, v10
	v_mul_u32_u24_e32 v3, 0x1800, v10
	v_lshl_add_u32 v3, v11, 3, v3
	v_lshlrev_b32_e32 v4, 12, v10
	v_lshl_add_u32 v4, v11, 3, v4
	v_lshlrev_b32_e32 v5, 8, v10
	v_lshl_add_u32 v5, v11, 4, v5
	v_lshlrev_b32_e32 v6, 2, v10
	s_mul_i32 s36, s21, s33
	s_add_u32 s36, s82, s36
	s_addc_u32 s37, s83, 0
	s_lshl_b32 s38, s21, 12
	s_add_u32 s38, s2, s38
	s_addc_u32 s39, s3, 0
	s_mov_b64 s[40:41], s[8:9]
	s_lshr_b32 s42, s56, 5
	s_mov_b32 s43, 0
	s_mov_b64 s[44:45], s[66:67]
	s_mov_b32 s50, 0
	global_load_dwordx4 v[12:15], v2, s[36:37]
	global_load_dwordx4 v[16:19], v2, s[36:37] offset:16
	global_load_dwordx4 v[20:23], v2, s[36:37] offset:32
	global_load_dwordx4 v[24:27], v2, s[36:37] offset:48
	global_load_dwordx4 v[124:127], v5, s[40:41]
	global_load_dwordx4 v[128:131], v5, s[40:41] offset:64
	global_load_dwordx4 v[132:135], v5, s[40:41] offset:128
	global_load_dwordx4 v[136:139], v5, s[40:41] offset:192
	global_load_dword v156, v6, s[44:45]
	global_load_dwordx2 v[140:141], v3, s[36:37]
	global_load_dwordx2 v[142:143], v3, s[36:37] offset:32
	global_load_dwordx2 v[144:145], v3, s[36:37] offset:64
	global_load_dwordx2 v[146:147], v3, s[36:37] offset:96
	global_load_dwordx2 v[148:149], v3, s[36:37] offset:128
	global_load_dwordx2 v[150:151], v3, s[36:37] offset:160
	global_load_dwordx2 v[152:153], v3, s[36:37] offset:192
	global_load_dwordx2 v[154:155], v3, s[36:37] offset:224
	s_waitcnt vmcnt(13)
.Lsgu_head:
	v_add_u32_e32 v160, s50, v7
	v_add_u32_e32 v161, s50, v8
	ds_read_b128 v[60:63], v9
	ds_read_b128 v[64:67], v9 offset:16
	ds_read_b128 v[68:71], v9 offset:32
	ds_read_b128 v[72:75], v9 offset:48
	ds_read_b128 v[76:79], v9 offset:64
	ds_read_b128 v[80:83], v9 offset:80
	ds_read_b128 v[84:87], v9 offset:96
	ds_read_b128 v[88:91], v9 offset:112
	ds_read_b128 v[92:95], v9 offset:2304
	ds_read_b128 v[96:99], v9 offset:2320
	ds_read_b128 v[100:103], v9 offset:2336
	ds_read_b128 v[104:107], v9 offset:2352
	ds_read_b128 v[108:111], v9 offset:2368
	ds_read_b128 v[112:115], v9 offset:2384
	ds_read_b128 v[116:119], v9 offset:2400
	ds_read_b128 v[120:123], v9 offset:2416
	v_lshlrev_b32_e32 v28, 16, v12
	v_and_b32_e32 v29, 0xffff0000, v12
	v_lshlrev_b32_e32 v30, 16, v13
	v_and_b32_e32 v31, 0xffff0000, v13
	v_lshlrev_b32_e32 v32, 16, v14
	v_and_b32_e32 v33, 0xffff0000, v14
	v_lshlrev_b32_e32 v34, 16, v15
	v_and_b32_e32 v35, 0xffff0000, v15
	v_lshlrev_b32_e32 v36, 16, v16
	v_and_b32_e32 v37, 0xffff0000, v16
	v_lshlrev_b32_e32 v38, 16, v17
	v_and_b32_e32 v39, 0xffff0000, v17
	v_lshlrev_b32_e32 v40, 16, v18
	v_and_b32_e32 v41, 0xffff0000, v18
	v_lshlrev_b32_e32 v42, 16, v19
	v_and_b32_e32 v43, 0xffff0000, v19
	v_lshlrev_b32_e32 v44, 16, v20
	v_and_b32_e32 v45, 0xffff0000, v20
	v_lshlrev_b32_e32 v46, 16, v21
	v_and_b32_e32 v47, 0xffff0000, v21
	v_lshlrev_b32_e32 v48, 16, v22
	v_and_b32_e32 v49, 0xffff0000, v22
	v_lshlrev_b32_e32 v50, 16, v23
	v_and_b32_e32 v51, 0xffff0000, v23
	v_lshlrev_b32_e32 v52, 16, v24
	v_and_b32_e32 v53, 0xffff0000, v24
	v_lshlrev_b32_e32 v54, 16, v25
	v_and_b32_e32 v55, 0xffff0000, v25
	v_lshlrev_b32_e32 v56, 16, v26
	v_and_b32_e32 v57, 0xffff0000, v26
	v_lshlrev_b32_e32 v58, 16, v27
	v_and_b32_e32 v59, 0xffff0000, v27
	s_cmp_lt_u32 s43, 3
	s_cselect_b32 s5, 0x100, 0
	s_add_u32 s46, s36, s5
	s_addc_u32 s47, s37, 0
	global_load_dwordx4 v[12:15], v2, s[46:47]
	global_load_dwordx4 v[16:19], v2, s[46:47] offset:16
	global_load_dwordx4 v[20:23], v2, s[46:47] offset:32
	global_load_dwordx4 v[24:27], v2, s[46:47] offset:48
	v_add_f32_e32 v157, 0, v28
	v_add_f32_e32 v157, v157, v29
	v_add_f32_e32 v157, v157, v30
	v_add_f32_e32 v157, v157, v31
	v_add_f32_e32 v157, v157, v32
	v_add_f32_e32 v157, v157, v33
	v_add_f32_e32 v157, v157, v34
	v_add_f32_e32 v157, v157, v35
	v_add_f32_e32 v157, v157, v36
	v_add_f32_e32 v157, v157, v37
	v_add_f32_e32 v157, v157, v38
	v_add_f32_e32 v157, v157, v39
	v_add_f32_e32 v157, v157, v40
	v_add_f32_e32 v157, v157, v41
	v_add_f32_e32 v157, v157, v42
	v_add_f32_e32 v157, v157, v43
	v_add_f32_e32 v157, v157, v44
	v_add_f32_e32 v157, v157, v45
	v_add_f32_e32 v157, v157, v46
	v_add_f32_e32 v157, v157, v47
	v_add_f32_e32 v157, v157, v48
	v_add_f32_e32 v157, v157, v49
	v_add_f32_e32 v157, v157, v50
	v_add_f32_e32 v157, v157, v51
	v_add_f32_e32 v157, v157, v52
	v_add_f32_e32 v157, v157, v53
	v_add_f32_e32 v157, v157, v54
	v_add_f32_e32 v157, v157, v55
	v_add_f32_e32 v157, v157, v56
	v_add_f32_e32 v157, v157, v57
	v_add_f32_e32 v157, v157, v58
	v_add_f32_e32 v157, v157, v59
	s_nop 1
	v_add_f32_dpp v157, v157, v157 quad_perm:[1,0,3,2] row_mask:0xf bank_mask:0xf bound_ctrl:1
	s_nop 1
	v_add_f32_dpp v157, v157, v157 quad_perm:[2,3,0,1] row_mask:0xf bank_mask:0xf bound_ctrl:1
	v_fmac_f32_e32 v29, 0xbc000000, v157
	v_fmac_f32_e32 v28, 0xbc000000, v157
	v_mul_f32_e32 v158, v29, v29
	v_fmac_f32_e32 v158, v28, v28
	v_fmac_f32_e32 v30, 0xbc000000, v157
	v_fmac_f32_e32 v158, v30, v30
	v_fmac_f32_e32 v31, 0xbc000000, v157
	v_fmac_f32_e32 v158, v31, v31
	v_fmac_f32_e32 v32, 0xbc000000, v157
	v_fmac_f32_e32 v158, v32, v32
	v_fmac_f32_e32 v33, 0xbc000000, v157
; __device__ __forceinline__ float sum_xor1_2(float v) { v += dpp_f<0xB1>(v); v += dpp_f<0x4E>(v); return v; }
; #define GAS __attribute__((address_space(1)))
; __device__ __forceinline__ bf16 f2bf(float f) { return (bf16)(cvt_pk_bf16(f, 0.f) & 0xffffu); }
; __device__ __forceinline__ void mixer_sgu(const Frame& F, const Args& A, int l, int chunk, const bf16* Z, bf16* MIX) {
;     ...
;             for (int j = 0; j < 32; ++j) { v[j] -= mean; s2 += v[j] * v[j]; }
;             s2 = pg8::sum_xor1_2(s2);
;             const float rstd = __builtin_amdgcn_rsqf(s2 * (1.0f / 128.0f) + EPS);
; #pragma unroll
;             for (int j = 0; j < 32; ++j) { const float y = v[j] * rstd * g4v[j >> 2][j & 3] + b4v[j >> 2][j & 3]; VT[(32 * q + j) * VT_STRIDE + t1] = f2bf(y); }
;         }
;         if (hd < 3) {
; #pragma unroll
;             for (int j = 0; j < 4; ++j) vr[j] = *(const GAS v4u*)(zv + 128 * (hd + 1) + 8 * j); }
;         bf16x8 bfrag[4];
; #pragma unroll
;         for (int kk = 0; kk < 4; ++kk) { v4u bw = (v4u){0u, 0u, 0u, 0u}; if (kk <= kkmax) bw = *(const GAS v4u*)(wsb + ((size_t)hd * 128 + t2) * 128 + 32 * kk + 8 * g4); bfrag[kk] = __builtin_bit_cast(bf16x8, bw); }
;         const float bs = A.in[7][(size_t)(l * 4 + hd) * 128 + t2];
;         v2u uw[8];
; #pragma unroll
;         for (int dt = 0; dt < 8; ++dt) uw[dt] = *(const GAS v2u*)(zu + 128 * hd + 16 * dt);
;         __syncthreads();
	v_fmac_f32_e32 v158, v33, v33
	v_fmac_f32_e32 v34, 0xbc000000, v157
	v_fmac_f32_e32 v158, v34, v34
	v_fmac_f32_e32 v35, 0xbc000000, v157
	v_fmac_f32_e32 v158, v35, v35
	v_fmac_f32_e32 v36, 0xbc000000, v157
	v_fmac_f32_e32 v158, v36, v36
	v_fmac_f32_e32 v37, 0xbc000000, v157
	v_fmac_f32_e32 v158, v37, v37
	v_fmac_f32_e32 v38, 0xbc000000, v157
	v_fmac_f32_e32 v158, v38, v38
	v_fmac_f32_e32 v39, 0xbc000000, v157
	v_fmac_f32_e32 v158, v39, v39
	v_fmac_f32_e32 v40, 0xbc000000, v157
	v_fmac_f32_e32 v158, v40, v40
	v_fmac_f32_e32 v41, 0xbc000000, v157
	v_fmac_f32_e32 v158, v41, v41
	v_fmac_f32_e32 v42, 0xbc000000, v157
	v_fmac_f32_e32 v158, v42, v42
	v_fmac_f32_e32 v43, 0xbc000000, v157
	v_fmac_f32_e32 v158, v43, v43
	v_fmac_f32_e32 v44, 0xbc000000, v157
	v_fmac_f32_e32 v158, v44, v44
	v_fmac_f32_e32 v45, 0xbc000000, v157
	v_fmac_f32_e32 v158, v45, v45
	v_fmac_f32_e32 v46, 0xbc000000, v157
	v_fmac_f32_e32 v158, v46, v46
	v_fmac_f32_e32 v47, 0xbc000000, v157
	v_fmac_f32_e32 v158, v47, v47
	v_fmac_f32_e32 v48, 0xbc000000, v157
	v_fmac_f32_e32 v158, v48, v48
	v_fmac_f32_e32 v49, 0xbc000000, v157
	v_fmac_f32_e32 v158, v49, v49
	v_fmac_f32_e32 v50, 0xbc000000, v157
	v_fmac_f32_e32 v158, v50, v50
	v_fmac_f32_e32 v51, 0xbc000000, v157
	v_fmac_f32_e32 v158, v51, v51
	v_fmac_f32_e32 v52, 0xbc000000, v157
	v_fmac_f32_e32 v158, v52, v52
	v_fmac_f32_e32 v53, 0xbc000000, v157
	v_fmac_f32_e32 v158, v53, v53
	v_fmac_f32_e32 v54, 0xbc000000, v157
	v_fmac_f32_e32 v158, v54, v54
	v_fmac_f32_e32 v55, 0xbc000000, v157
	v_fmac_f32_e32 v158, v55, v55
	v_fmac_f32_e32 v56, 0xbc000000, v157
	v_fmac_f32_e32 v158, v56, v56
	v_fmac_f32_e32 v57, 0xbc000000, v157
	v_fmac_f32_e32 v158, v57, v57
	v_fmac_f32_e32 v58, 0xbc000000, v157
	v_fmac_f32_e32 v158, v58, v58
	v_fmac_f32_e32 v59, 0xbc000000, v157
	v_fmac_f32_e32 v158, v59, v59
	s_nop 1
	v_add_f32_dpp v158, v158, v158 quad_perm:[1,0,3,2] row_mask:0xf bank_mask:0xf bound_ctrl:1
	s_nop 1
	v_add_f32_dpp v158, v158, v158 quad_perm:[2,3,0,1] row_mask:0xf bank_mask:0xf bound_ctrl:1
	v_fmamk_f32 v158, v158, 0x3c000000, v221
	v_rsq_f32_e32 v159, v158
	s_waitcnt lgkmcnt(0)
	v_mul_f32_e32 v162, v28, v159
	v_fma_f32 v162, v60, v162, v92
	v_cvt_pk_bf16_f32 v162, v162, v162
	ds_write_b16 v160, v162
	v_mul_f32_e32 v163, v29, v159
	v_fma_f32 v163, v61, v163, v93
	v_cvt_pk_bf16_f32 v163, v163, v163
	ds_write_b16 v160, v163 offset:272
	v_mul_f32_e32 v162, v30, v159
	v_fma_f32 v162, v62, v162, v94
	v_cvt_pk_bf16_f32 v162, v162, v162
	ds_write_b16 v160, v162 offset:544
	v_mul_f32_e32 v163, v31, v159
	v_fma_f32 v163, v63, v163, v95
	v_cvt_pk_bf16_f32 v163, v163, v163
	ds_write_b16 v160, v163 offset:816
	v_mul_f32_e32 v162, v32, v159
	v_fma_f32 v162, v64, v162, v96
	v_cvt_pk_bf16_f32 v162, v162, v162
	ds_write_b16 v160, v162 offset:1088
	v_mul_f32_e32 v163, v33, v159
	v_fma_f32 v163, v65, v163, v97
	v_cvt_pk_bf16_f32 v163, v163, v163
	ds_write_b16 v160, v163 offset:1360
	v_mul_f32_e32 v162, v34, v159
	v_fma_f32 v162, v66, v162, v98
	v_cvt_pk_bf16_f32 v162, v162, v162
	ds_write_b16 v160, v162 offset:1632
	v_mul_f32_e32 v163, v35, v159
	v_fma_f32 v163, v67, v163, v99
	v_cvt_pk_bf16_f32 v163, v163, v163
	ds_write_b16 v160, v163 offset:1904
	v_mul_f32_e32 v162, v36, v159
	v_fma_f32 v162, v68, v162, v100
	v_cvt_pk_bf16_f32 v162, v162, v162
	ds_write_b16 v160, v162 offset:2176
	v_mul_f32_e32 v163, v37, v159
	v_fma_f32 v163, v69, v163, v101
	v_cvt_pk_bf16_f32 v163, v163, v163
	ds_write_b16 v160, v163 offset:2448
	v_mul_f32_e32 v162, v38, v159
	v_fma_f32 v162, v70, v162, v102
	v_cvt_pk_bf16_f32 v162, v162, v162
	ds_write_b16 v160, v162 offset:2720
	v_mul_f32_e32 v163, v39, v159
	v_fma_f32 v163, v71, v163, v103
	v_cvt_pk_bf16_f32 v163, v163, v163
	ds_write_b16 v160, v163 offset:2992
	v_mul_f32_e32 v162, v40, v159
	v_fma_f32 v162, v72, v162, v104
	v_cvt_pk_bf16_f32 v162, v162, v162
	ds_write_b16 v160, v162 offset:3264
	v_mul_f32_e32 v163, v41, v159
	v_fma_f32 v163, v73, v163, v105
	v_cvt_pk_bf16_f32 v163, v163, v163
	ds_write_b16 v160, v163 offset:3536
	v_mul_f32_e32 v162, v42, v159
	v_fma_f32 v162, v74, v162, v106
	v_cvt_pk_bf16_f32 v162, v162, v162
	ds_write_b16 v160, v162 offset:3808
	v_mul_f32_e32 v163, v43, v159
	v_fma_f32 v163, v75, v163, v107
	v_cvt_pk_bf16_f32 v163, v163, v163
	ds_write_b16 v160, v163 offset:4080
	v_mul_f32_e32 v162, v44, v159
	v_fma_f32 v162, v76, v162, v108
	v_cvt_pk_bf16_f32 v162, v162, v162
	ds_write_b16 v160, v162 offset:4352
	v_mul_f32_e32 v163, v45, v159
	v_fma_f32 v163, v77, v163, v109
	v_cvt_pk_bf16_f32 v163, v163, v163
	ds_write_b16 v160, v163 offset:4624
	v_mul_f32_e32 v162, v46, v159
	v_fma_f32 v162, v78, v162, v110
	v_cvt_pk_bf16_f32 v162, v162, v162
	ds_write_b16 v160, v162 offset:4896
	v_mul_f32_e32 v163, v47, v159
	v_fma_f32 v163, v79, v163, v111
	v_cvt_pk_bf16_f32 v163, v163, v163
	ds_write_b16 v160, v163 offset:5168
	v_mul_f32_e32 v162, v48, v159
	v_fma_f32 v162, v80, v162, v112
	v_cvt_pk_bf16_f32 v162, v162, v162
	ds_write_b16 v160, v162 offset:5440
	v_mul_f32_e32 v163, v49, v159
	v_fma_f32 v163, v81, v163, v113
	v_cvt_pk_bf16_f32 v163, v163, v163
	ds_write_b16 v160, v163 offset:5712
	v_mul_f32_e32 v162, v50, v159
	v_fma_f32 v162, v82, v162, v114
	v_cvt_pk_bf16_f32 v162, v162, v162
	ds_write_b16 v160, v162 offset:5984
	v_mul_f32_e32 v163, v51, v159
	v_fma_f32 v163, v83, v163, v115
	v_cvt_pk_bf16_f32 v163, v163, v163
	ds_write_b16 v160, v163 offset:6256
	v_mul_f32_e32 v162, v52, v159
	v_fma_f32 v162, v84, v162, v116
	v_cvt_pk_bf16_f32 v162, v162, v162
	ds_write_b16 v160, v162 offset:6528
	v_mul_f32_e32 v163, v53, v159
	v_fma_f32 v163, v85, v163, v117
	v_cvt_pk_bf16_f32 v163, v163, v163
	ds_write_b16 v160, v163 offset:6800
	v_mul_f32_e32 v162, v54, v159
	v_fma_f32 v162, v86, v162, v118
	v_cvt_pk_bf16_f32 v162, v162, v162
	ds_write_b16 v160, v162 offset:7072
	v_mul_f32_e32 v163, v55, v159
	v_fma_f32 v163, v87, v163, v119
	v_cvt_pk_bf16_f32 v163, v163, v163
	ds_write_b16 v160, v163 offset:7344
	v_mul_f32_e32 v162, v56, v159
	v_fma_f32 v162, v88, v162, v120
	v_cvt_pk_bf16_f32 v162, v162, v162
	ds_write_b16 v160, v162 offset:7616
	v_mul_f32_e32 v163, v57, v159
	v_fma_f32 v163, v89, v163, v121
	v_cvt_pk_bf16_f32 v163, v163, v163
	ds_write_b16 v160, v163 offset:7888
	v_mul_f32_e32 v162, v58, v159
	v_fma_f32 v162, v90, v162, v122
	v_cvt_pk_bf16_f32 v162, v162, v162
	ds_write_b16 v160, v162 offset:8160
	v_mul_f32_e32 v163, v59, v159
	v_fma_f32 v163, v91, v163, v123
	v_cvt_pk_bf16_f32 v163, v163, v163
	ds_write_b16 v160, v163 offset:8432
	s_waitcnt lgkmcnt(0)
	s_barrier
; #define LAS __attribute__((address_space(3)))
; __device__ __forceinline__ void mixer_sgu(const Frame& F, const Args& A, int l, int chunk, const bf16* Z, bf16* MIX) {
;     ...
; #pragma unroll
;         for (int dt = 0; dt < 8; ++dt) {
;             f32x4 acc = (f32x4){0.f, 0.f, 0.f, 0.f};
; #pragma unroll
;             for (int kk = 0; kk < 4; ++kk) if (kk <= kkmax) { const bf16x8 af = *(const LAS bf16x8*)(VT + (16 * dt + i) * VT_STRIDE + 32 * kk + 8 * g4);
;                 acc = __builtin_amdgcn_mfma_f32_16x16x32_bf16(af, bfrag[kk], acc, 0, 0, 0); }
	s_waitcnt vmcnt(4)
	s_cmp_eq_u32 s42, 0
	s_cbranch_scc1 .Lsgu_k0
	s_cmp_eq_u32 s42, 1
	s_cbranch_scc1 .Lsgu_k1
	s_cmp_eq_u32 s42, 2
	s_cbranch_scc1 .Lsgu_k2
	ds_read_b128 v[28:31], v161
	ds_read_b128 v[32:35], v161 offset:4352
	ds_read_b128 v[36:39], v161 offset:8720
	ds_read_b128 v[40:43], v161 offset:13072
	ds_read_b128 v[44:47], v161 offset:17440
	ds_read_b128 v[48:51], v161 offset:21792
	ds_read_b128 v[52:55], v161 offset:26160
	ds_read_b128 v[56:59], v161 offset:30512
	ds_read_b128 v[60:63], v161 offset:64
	ds_read_b128 v[64:67], v161 offset:4416
	ds_read_b128 v[68:71], v161 offset:8784
	ds_read_b128 v[72:75], v161 offset:13136
	ds_read_b128 v[76:79], v161 offset:17504
	ds_read_b128 v[80:83], v161 offset:21856
	ds_read_b128 v[84:87], v161 offset:26224
	ds_read_b128 v[88:91], v161 offset:30576
	s_waitcnt lgkmcnt(8)
	v_mfma_f32_16x16x32_bf16 v[92:95], v[28:31], v[124:127], 0
	v_mfma_f32_16x16x32_bf16 v[96:99], v[32:35], v[124:127], 0
	v_mfma_f32_16x16x32_bf16 v[100:103], v[36:39], v[124:127], 0
	v_mfma_f32_16x16x32_bf16 v[104:107], v[40:43], v[124:127], 0
	v_mfma_f32_16x16x32_bf16 v[108:111], v[44:47], v[124:127], 0
	v_mfma_f32_16x16x32_bf16 v[112:115], v[48:51], v[124:127], 0
	v_mfma_f32_16x16x32_bf16 v[116:119], v[52:55], v[124:127], 0
	v_mfma_f32_16x16x32_bf16 v[120:123], v[56:59], v[124:127], 0
	ds_read_b128 v[28:31], v161 offset:128
	ds_read_b128 v[32:35], v161 offset:4480
	ds_read_b128 v[36:39], v161 offset:8848
	ds_read_b128 v[40:43], v161 offset:13200
	ds_read_b128 v[44:47], v161 offset:17568
	ds_read_b128 v[48:51], v161 offset:21920
	ds_read_b128 v[52:55], v161 offset:26288
	ds_read_b128 v[56:59], v161 offset:30640
	s_waitcnt lgkmcnt(8)
	v_mfma_f32_16x16x32_bf16 v[92:95], v[60:63], v[128:131], v[92:95]
	v_mfma_f32_16x16x32_bf16 v[96:99], v[64:67], v[128:131], v[96:99]
	v_mfma_f32_16x16x32_bf16 v[100:103], v[68:71], v[128:131], v[100:103]
	v_mfma_f32_16x16x32_bf16 v[104:107], v[72:75], v[128:131], v[104:107]
	v_mfma_f32_16x16x32_bf16 v[108:111], v[76:79], v[128:131], v[108:111]
	v_mfma_f32_16x16x32_bf16 v[112:115], v[80:83], v[128:131], v[112:115]
	v_mfma_f32_16x16x32_bf16 v[116:119], v[84:87], v[128:131], v[116:119]
	v_mfma_f32_16x16x32_bf16 v[120:123], v[88:91], v[128:131], v[120:123]
	ds_read_b128 v[60:63], v161 offset:192
	ds_read_b128 v[64:67], v161 offset:4544
	ds_read_b128 v[68:71], v161 offset:8912
	ds_read_b128 v[72:75], v161 offset:13264
	ds_read_b128 v[76:79], v161 offset:17632
	ds_read_b128 v[80:83], v161 offset:21984
	ds_read_b128 v[84:87], v161 offset:26352
	ds_read_b128 v[88:91], v161 offset:30704
	s_waitcnt lgkmcnt(8)
	v_mfma_f32_16x16x32_bf16 v[92:95], v[28:31], v[132:135], v[92:95]
	v_mfma_f32_16x16x32_bf16 v[96:99], v[32:35], v[132:135], v[96:99]
	v_mfma_f32_16x16x32_bf16 v[100:103], v[36:39], v[132:135], v[100:103]
	v_mfma_f32_16x16x32_bf16 v[104:107], v[40:43], v[132:135], v[104:107]
	v_mfma_f32_16x16x32_bf16 v[108:111], v[44:47], v[132:135], v[108:111]
	v_mfma_f32_16x16x32_bf16 v[112:115], v[48:51], v[132:135], v[112:115]
	v_mfma_f32_16x16x32_bf16 v[116:119], v[52:55], v[132:135], v[116:119]
	v_mfma_f32_16x16x32_bf16 v[120:123], v[56:59], v[132:135], v[120:123]
	s_waitcnt lgkmcnt(0)
	v_mfma_f32_16x16x32_bf16 v[92:95], v[60:63], v[136:139], v[92:95]
	v_mfma_f32_16x16x32_bf16 v[96:99], v[64:67], v[136:139], v[96:99]
	v_mfma_f32_16x16x32_bf16 v[100:103], v[68:71], v[136:139], v[100:103]
	v_mfma_f32_16x16x32_bf16 v[104:107], v[72:75], v[136:139], v[104:107]
	v_mfma_f32_16x16x32_bf16 v[108:111], v[76:79], v[136:139], v[108:111]
	v_mfma_f32_16x16x32_bf16 v[112:115], v[80:83], v[136:139], v[112:115]
	v_mfma_f32_16x16x32_bf16 v[116:119], v[84:87], v[136:139], v[116:119]
	v_mfma_f32_16x16x32_bf16 v[120:123], v[88:91], v[136:139], v[120:123]
	s_branch .Lsgu_out
.Lsgu_k2:
	ds_read_b128 v[28:31], v161
	ds_read_b128 v[32:35], v161 offset:4352
	ds_read_b128 v[36:39], v161 offset:8720
	ds_read_b128 v[40:43], v161 offset:13072
	ds_read_b128 v[44:47], v161 offset:17440
	ds_read_b128 v[48:51], v161 offset:21792
	ds_read_b128 v[52:55], v161 offset:26160
	ds_read_b128 v[56:59], v161 offset:30512
	ds_read_b128 v[60:63], v161 offset:64
	ds_read_b128 v[64:67], v161 offset:4416
	ds_read_b128 v[68:71], v161 offset:8784
	ds_read_b128 v[72:75], v161 offset:13136
	ds_read_b128 v[76:79], v161 offset:17504
	ds_read_b128 v[80:83], v161 offset:21856
	ds_read_b128 v[84:87], v161 offset:26224
	ds_read_b128 v[88:91], v161 offset:30576
	s_waitcnt lgkmcnt(8)
	v_mfma_f32_16x16x32_bf16 v[92:95], v[28:31], v[124:127], 0
	v_mfma_f32_16x16x32_bf16 v[96:99], v[32:35], v[124:127], 0
	v_mfma_f32_16x16x32_bf16 v[100:103], v[36:39], v[124:127], 0
	v_mfma_f32_16x16x32_bf16 v[104:107], v[40:43], v[124:127], 0
	v_mfma_f32_16x16x32_bf16 v[108:111], v[44:47], v[124:127], 0
	v_mfma_f32_16x16x32_bf16 v[112:115], v[48:51], v[124:127], 0
	v_mfma_f32_16x16x32_bf16 v[116:119], v[52:55], v[124:127], 0
	v_mfma_f32_16x16x32_bf16 v[120:123], v[56:59], v[124:127], 0
	ds_read_b128 v[28:31], v161 offset:128
	ds_read_b128 v[32:35], v161 offset:4480
	ds_read_b128 v[36:39], v161 offset:8848
	ds_read_b128 v[40:43], v161 offset:13200
	ds_read_b128 v[44:47], v161 offset:17568
	ds_read_b128 v[48:51], v161 offset:21920
	ds_read_b128 v[52:55], v161 offset:26288
	ds_read_b128 v[56:59], v161 offset:30640
	s_waitcnt lgkmcnt(8)
	v_mfma_f32_16x16x32_bf16 v[92:95], v[60:63], v[128:131], v[92:95]
	v_mfma_f32_16x16x32_bf16 v[96:99], v[64:67], v[128:131], v[96:99]
	v_mfma_f32_16x16x32_bf16 v[100:103], v[68:71], v[128:131], v[100:103]
	v_mfma_f32_16x16x32_bf16 v[104:107], v[72:75], v[128:131], v[104:107]
	v_mfma_f32_16x16x32_bf16 v[108:111], v[76:79], v[128:131], v[108:111]
	v_mfma_f32_16x16x32_bf16 v[112:115], v[80:83], v[128:131], v[112:115]
	v_mfma_f32_16x16x32_bf16 v[116:119], v[84:87], v[128:131], v[116:119]
	v_mfma_f32_16x16x32_bf16 v[120:123], v[88:91], v[128:131], v[120:123]
	s_waitcnt lgkmcnt(0)
	v_mfma_f32_16x16x32_bf16 v[92:95], v[28:31], v[132:135], v[92:95]
	v_mfma_f32_16x16x32_bf16 v[96:99], v[32:35], v[132:135], v[96:99]
	v_mfma_f32_16x16x32_bf16 v[100:103], v[36:39], v[132:135], v[100:103]
	v_mfma_f32_16x16x32_bf16 v[104:107], v[40:43], v[132:135], v[104:107]
	v_mfma_f32_16x16x32_bf16 v[108:111], v[44:47], v[132:135], v[108:111]
	v_mfma_f32_16x16x32_bf16 v[112:115], v[48:51], v[132:135], v[112:115]
	v_mfma_f32_16x16x32_bf16 v[116:119], v[52:55], v[132:135], v[116:119]
	v_mfma_f32_16x16x32_bf16 v[120:123], v[56:59], v[132:135], v[120:123]
	s_branch .Lsgu_out
; #define LAS __attribute__((address_space(3)))
; __device__ __forceinline__ void mixer_sgu(const Frame& F, const Args& A, int l, int chunk, const bf16* Z, bf16* MIX) {
;     ...
; #pragma unroll
;         for (int dt = 0; dt < 8; ++dt) {
;             f32x4 acc = (f32x4){0.f, 0.f, 0.f, 0.f};
; #pragma unroll
;             for (int kk = 0; kk < 4; ++kk) if (kk <= kkmax) { const bf16x8 af = *(const LAS bf16x8*)(VT + (16 * dt + i) * VT_STRIDE + 32 * kk + 8 * g4);
;                 acc = __builtin_amdgcn_mfma_f32_16x16x32_bf16(af, bfrag[kk], acc, 0, 0, 0); }
.Lsgu_k1:
	ds_read_b128 v[28:31], v161
	ds_read_b128 v[32:35], v161 offset:4352
	ds_read_b128 v[36:39], v161 offset:8720
	ds_read_b128 v[40:43], v161 offset:13072
	ds_read_b128 v[44:47], v161 offset:17440
	ds_read_b128 v[48:51], v161 offset:21792
	ds_read_b128 v[52:55], v161 offset:26160
	ds_read_b128 v[56:59], v161 offset:30512
	ds_read_b128 v[60:63], v161 offset:64
	ds_read_b128 v[64:67], v161 offset:4416
	ds_read_b128 v[68:71], v161 offset:8784
	ds_read_b128 v[72:75], v161 offset:13136
	ds_read_b128 v[76:79], v161 offset:17504
	ds_read_b128 v[80:83], v161 offset:21856
	ds_read_b128 v[84:87], v161 offset:26224
	ds_read_b128 v[88:91], v161 offset:30576
	s_waitcnt lgkmcnt(8)
	v_mfma_f32_16x16x32_bf16 v[92:95], v[28:31], v[124:127], 0
	v_mfma_f32_16x16x32_bf16 v[96:99], v[32:35], v[124:127], 0
	v_mfma_f32_16x16x32_bf16 v[100:103], v[36:39], v[124:127], 0
	v_mfma_f32_16x16x32_bf16 v[104:107], v[40:43], v[124:127], 0
	v_mfma_f32_16x16x32_bf16 v[108:111], v[44:47], v[124:127], 0
	v_mfma_f32_16x16x32_bf16 v[112:115], v[48:51], v[124:127], 0
	v_mfma_f32_16x16x32_bf16 v[116:119], v[52:55], v[124:127], 0
	v_mfma_f32_16x16x32_bf16 v[120:123], v[56:59], v[124:127], 0
	s_waitcnt lgkmcnt(0)
	v_mfma_f32_16x16x32_bf16 v[92:95], v[60:63], v[128:131], v[92:95]
	v_mfma_f32_16x16x32_bf16 v[96:99], v[64:67], v[128:131], v[96:99]
	v_mfma_f32_16x16x32_bf16 v[100:103], v[68:71], v[128:131], v[100:103]
	v_mfma_f32_16x16x32_bf16 v[104:107], v[72:75], v[128:131], v[104:107]
	v_mfma_f32_16x16x32_bf16 v[108:111], v[76:79], v[128:131], v[108:111]
	v_mfma_f32_16x16x32_bf16 v[112:115], v[80:83], v[128:131], v[112:115]
	v_mfma_f32_16x16x32_bf16 v[116:119], v[84:87], v[128:131], v[116:119]
	v_mfma_f32_16x16x32_bf16 v[120:123], v[88:91], v[128:131], v[120:123]
	s_branch .Lsgu_out
.Lsgu_k0:
	ds_read_b128 v[28:31], v161
	ds_read_b128 v[32:35], v161 offset:4352
	ds_read_b128 v[36:39], v161 offset:8720
	ds_read_b128 v[40:43], v161 offset:13072
	ds_read_b128 v[44:47], v161 offset:17440
	ds_read_b128 v[48:51], v161 offset:21792
	ds_read_b128 v[52:55], v161 offset:26160
	ds_read_b128 v[56:59], v161 offset:30512
	s_waitcnt lgkmcnt(0)
	v_mfma_f32_16x16x32_bf16 v[92:95], v[28:31], v[124:127], 0
	v_mfma_f32_16x16x32_bf16 v[96:99], v[32:35], v[124:127], 0
	v_mfma_f32_16x16x32_bf16 v[100:103], v[36:39], v[124:127], 0
	v_mfma_f32_16x16x32_bf16 v[104:107], v[40:43], v[124:127], 0
	v_mfma_f32_16x16x32_bf16 v[108:111], v[44:47], v[124:127], 0
	v_mfma_f32_16x16x32_bf16 v[112:115], v[48:51], v[124:127], 0
	v_mfma_f32_16x16x32_bf16 v[116:119], v[52:55], v[124:127], 0
	v_mfma_f32_16x16x32_bf16 v[120:123], v[56:59], v[124:127], 0
; __device__ __forceinline__ unsigned cvt_pk_bf16(float lo, float hi) { return __builtin_bit_cast(unsigned, __builtin_convertvector((f32x2_t){lo, hi}, bf16x2_t)); }
; __device__ __forceinline__ float bf_lo(unsigned w) { return __uint_as_float(w << 16); }
; __device__ __forceinline__ float bf_hi(unsigned w) { return __uint_as_float(w & 0xffff0000u); }
; #define GAS __attribute__((address_space(1)))
; __device__ __forceinline__ void mixer_sgu(const Frame& F, const Args& A, int l, int chunk, const bf16* Z, bf16* MIX) {
;     ...
;         if (hd < 3) {
; #pragma unroll
;             for (int j = 0; j < 4; ++j) vr[j] = *(const GAS v4u*)(zv + 128 * (hd + 1) + 8 * j); }
;         bf16x8 bfrag[4];
; #pragma unroll
;         for (int kk = 0; kk < 4; ++kk) { v4u bw = (v4u){0u, 0u, 0u, 0u}; if (kk <= kkmax) bw = *(const GAS v4u*)(wsb + ((size_t)hd * 128 + t2) * 128 + 32 * kk + 8 * g4); bfrag[kk] = __builtin_bit_cast(bf16x8, bw); }
;         const float bs = A.in[7][(size_t)(l * 4 + hd) * 128 + t2];
;         v2u uw[8];
; #pragma unroll
;         for (int dt = 0; dt < 8; ++dt) uw[dt] = *(const GAS v2u*)(zu + 128 * hd + 16 * dt);
;     ...
;             v2u o; o.x = cvt_pk_bf16(bf_lo(uw[dt].x) * (acc[0] + bs), bf_hi(uw[dt].x) * (acc[1] + bs)); o.y = cvt_pk_bf16(bf_lo(uw[dt].y) * (acc[2] + bs), bf_hi(uw[dt].y) * (acc[3] + bs));
;             *(GAS v2u*)(mo + 128 * hd + 16 * dt) = o;
.Lsgu_out:
	s_nop 7
	s_nop 1
	v_lshlrev_b32_e32 v28, 16, v140
	v_and_b32_e32 v29, 0xffff0000, v140
	v_lshlrev_b32_e32 v30, 16, v141
	v_and_b32_e32 v31, 0xffff0000, v141
	v_add_f32_e32 v32, v156, v92
	v_add_f32_e32 v33, v156, v93
	v_add_f32_e32 v34, v156, v94
	v_add_f32_e32 v35, v156, v95
	v_mul_f32_e32 v32, v32, v28
	v_mul_f32_e32 v33, v33, v29
	v_mul_f32_e32 v34, v34, v30
	v_mul_f32_e32 v35, v35, v31
	v_cvt_pk_bf16_f32 v28, v32, v33
	v_cvt_pk_bf16_f32 v29, v34, v35
	global_store_dwordx2 v4, v[28:29], s[38:39]
	v_lshlrev_b32_e32 v36, 16, v142
	v_and_b32_e32 v37, 0xffff0000, v142
	v_lshlrev_b32_e32 v38, 16, v143
	v_and_b32_e32 v39, 0xffff0000, v143
	v_add_f32_e32 v40, v156, v96
	v_add_f32_e32 v41, v156, v97
	v_add_f32_e32 v42, v156, v98
	v_add_f32_e32 v43, v156, v99
	v_mul_f32_e32 v40, v40, v36
	v_mul_f32_e32 v41, v41, v37
	v_mul_f32_e32 v42, v42, v38
	v_mul_f32_e32 v43, v43, v39
	v_cvt_pk_bf16_f32 v36, v40, v41
	v_cvt_pk_bf16_f32 v37, v42, v43
	global_store_dwordx2 v4, v[36:37], s[38:39] offset:32
	v_lshlrev_b32_e32 v28, 16, v144
	v_and_b32_e32 v29, 0xffff0000, v144
	v_lshlrev_b32_e32 v30, 16, v145
	v_and_b32_e32 v31, 0xffff0000, v145
	v_add_f32_e32 v32, v156, v100
	v_add_f32_e32 v33, v156, v101
	v_add_f32_e32 v34, v156, v102
	v_add_f32_e32 v35, v156, v103
	v_mul_f32_e32 v32, v32, v28
	v_mul_f32_e32 v33, v33, v29
	v_mul_f32_e32 v34, v34, v30
	v_mul_f32_e32 v35, v35, v31
	v_cvt_pk_bf16_f32 v28, v32, v33
	v_cvt_pk_bf16_f32 v29, v34, v35
	global_store_dwordx2 v4, v[28:29], s[38:39] offset:64
	v_lshlrev_b32_e32 v36, 16, v146
	v_and_b32_e32 v37, 0xffff0000, v146
	v_lshlrev_b32_e32 v38, 16, v147
	v_and_b32_e32 v39, 0xffff0000, v147
	v_add_f32_e32 v40, v156, v104
	v_add_f32_e32 v41, v156, v105
	v_add_f32_e32 v42, v156, v106
	v_add_f32_e32 v43, v156, v107
	v_mul_f32_e32 v40, v40, v36
	v_mul_f32_e32 v41, v41, v37
	v_mul_f32_e32 v42, v42, v38
	v_mul_f32_e32 v43, v43, v39
	v_cvt_pk_bf16_f32 v36, v40, v41
	v_cvt_pk_bf16_f32 v37, v42, v43
	global_store_dwordx2 v4, v[36:37], s[38:39] offset:96
	v_lshlrev_b32_e32 v28, 16, v148
	v_and_b32_e32 v29, 0xffff0000, v148
	v_lshlrev_b32_e32 v30, 16, v149
	v_and_b32_e32 v31, 0xffff0000, v149
	v_add_f32_e32 v32, v156, v108
	v_add_f32_e32 v33, v156, v109
	v_add_f32_e32 v34, v156, v110
	v_add_f32_e32 v35, v156, v111
	v_mul_f32_e32 v32, v32, v28
	v_mul_f32_e32 v33, v33, v29
	v_mul_f32_e32 v34, v34, v30
	v_mul_f32_e32 v35, v35, v31
	v_cvt_pk_bf16_f32 v28, v32, v33
	v_cvt_pk_bf16_f32 v29, v34, v35
	global_store_dwordx2 v4, v[28:29], s[38:39] offset:128
	v_lshlrev_b32_e32 v36, 16, v150
	v_and_b32_e32 v37, 0xffff0000, v150
	v_lshlrev_b32_e32 v38, 16, v151
	v_and_b32_e32 v39, 0xffff0000, v151
	v_add_f32_e32 v40, v156, v112
	v_add_f32_e32 v41, v156, v113
	v_add_f32_e32 v42, v156, v114
	v_add_f32_e32 v43, v156, v115
	v_mul_f32_e32 v40, v40, v36
	v_mul_f32_e32 v41, v41, v37
	v_mul_f32_e32 v42, v42, v38
	v_mul_f32_e32 v43, v43, v39
	v_cvt_pk_bf16_f32 v36, v40, v41
	v_cvt_pk_bf16_f32 v37, v42, v43
	global_store_dwordx2 v4, v[36:37], s[38:39] offset:160
	v_lshlrev_b32_e32 v28, 16, v152
	v_and_b32_e32 v29, 0xffff0000, v152
	v_lshlrev_b32_e32 v30, 16, v153
	v_and_b32_e32 v31, 0xffff0000, v153
	v_add_f32_e32 v32, v156, v116
	v_add_f32_e32 v33, v156, v117
	v_add_f32_e32 v34, v156, v118
	v_add_f32_e32 v35, v156, v119
	v_mul_f32_e32 v32, v32, v28
	v_mul_f32_e32 v33, v33, v29
	v_mul_f32_e32 v34, v34, v30
	v_mul_f32_e32 v35, v35, v31
	v_cvt_pk_bf16_f32 v28, v32, v33
	v_cvt_pk_bf16_f32 v29, v34, v35
	global_store_dwordx2 v4, v[28:29], s[38:39] offset:192
	v_lshlrev_b32_e32 v36, 16, v154
	v_and_b32_e32 v37, 0xffff0000, v154
	v_lshlrev_b32_e32 v38, 16, v155
	v_and_b32_e32 v39, 0xffff0000, v155
	v_add_f32_e32 v40, v156, v120
	v_add_f32_e32 v41, v156, v121
	v_add_f32_e32 v42, v156, v122
	v_add_f32_e32 v43, v156, v123
	v_mul_f32_e32 v40, v40, v36
	v_mul_f32_e32 v41, v41, v37
	v_mul_f32_e32 v42, v42, v38
	v_mul_f32_e32 v43, v43, v39
	v_cvt_pk_bf16_f32 v36, v40, v41
	v_cvt_pk_bf16_f32 v37, v42, v43
	global_store_dwordx2 v4, v[36:37], s[38:39] offset:224
	s_cmp_eq_u32 s43, 3
	s_cbranch_scc1 .Lsgu_done
	s_mov_b64 s[36:37], s[46:47]
	s_add_u32 s38, s38, 0x100
	s_addc_u32 s39, s39, 0
	s_add_u32 s40, s40, 0x8000
	s_addc_u32 s41, s41, 0
	s_add_u32 s44, s44, 0x200
	s_addc_u32 s45, s45, 0
	global_load_dwordx4 v[124:127], v5, s[40:41]
	global_load_dwordx4 v[128:131], v5, s[40:41] offset:64
	global_load_dwordx4 v[132:135], v5, s[40:41] offset:128
	global_load_dwordx4 v[136:139], v5, s[40:41] offset:192
	global_load_dword v156, v6, s[44:45]
	global_load_dwordx2 v[140:141], v3, s[36:37]
	global_load_dwordx2 v[142:143], v3, s[36:37] offset:32
	global_load_dwordx2 v[144:145], v3, s[36:37] offset:64
	global_load_dwordx2 v[146:147], v3, s[36:37] offset:96
	global_load_dwordx2 v[148:149], v3, s[36:37] offset:128
	global_load_dwordx2 v[150:151], v3, s[36:37] offset:160
	global_load_dwordx2 v[152:153], v3, s[36:37] offset:192
	global_load_dwordx2 v[154:155], v3, s[36:37] offset:224
	s_add_i32 s43, s43, 1
	s_xor_b32 s50, s50, 35072
	v_add_u32_e32 v9, 576, v9
	s_waitcnt vmcnt(21)
	s_branch .Lsgu_head
